# K-loops: back-edge rotation - loop tail pointer bumps, exit test and next iteration's last?next:cur operand-pointer select moved in front of the closing barrier (exit path gets its own barrier copy),
# baseline (speedup 1.0000x reference)
; template <class Epi, class Sched, bool ALIGN_EPI = false, bool SP2 = false>
; __device__ __forceinline__ void gemm_phase(PG8_LAS unsigned char* lds, const Gemm g, const Sched& S, const Epi& E) {
;     ...
;             const bool last = (t == nt - 2);
;             const char* a1 = cA + (size_t)(t + 1) * kstep;
;             const char* a2 = last ? nA : cA + (size_t)(t + 2) * kstep; const char* b2 = last ? nB : cB + (size_t)(t + 2) * kstep;
;     ...
; #pragma unroll
;         for (int a = 0; a < 2; ++a)
; #pragma unroll
;             for (int b = 0; b < 2; ++b)
; #pragma unroll
;                 for (int m = 0; m < 4; ++m)
; #pragma unroll
;                     for (int n = 0; n < 2; ++n) acc[a][b][m][n] = (f32x4){0.f, 0.f, 0.f, 0.f};
.LBB0_302:
	v_mov_b32_e32 v127, 0
	s_and_b64 vcc, exec, s[6:7]
	v_mov_b32_e32 v126, v127
	v_mov_b32_e32 v125, v127
	v_mov_b32_e32 v124, v127
	v_mov_b32_e32 v119, v127
	v_mov_b32_e32 v118, v127
	v_mov_b32_e32 v117, v127
	v_mov_b32_e32 v116, v127
	v_mov_b32_e32 v111, v127
	v_mov_b32_e32 v110, v127
	v_mov_b32_e32 v109, v127
	v_mov_b32_e32 v108, v127
	v_mov_b32_e32 v103, v127
	v_mov_b32_e32 v102, v127
	v_mov_b32_e32 v101, v127
	v_mov_b32_e32 v100, v127
	v_mov_b32_e32 v95, v127
	v_mov_b32_e32 v94, v127
	v_mov_b32_e32 v93, v127
	v_mov_b32_e32 v92, v127
	v_mov_b32_e32 v87, v127
	v_mov_b32_e32 v86, v127
	v_mov_b32_e32 v85, v127
	v_mov_b32_e32 v84, v127
	v_mov_b32_e32 v79, v127
	v_mov_b32_e32 v78, v127
	v_mov_b32_e32 v77, v127
	v_mov_b32_e32 v76, v127
	v_mov_b32_e32 v71, v127
	v_mov_b32_e32 v70, v127
	v_mov_b32_e32 v69, v127
	v_mov_b32_e32 v68, v127
	v_mov_b32_e32 v123, v127
	v_mov_b32_e32 v122, v127
	v_mov_b32_e32 v121, v127
	v_mov_b32_e32 v120, v127
	v_mov_b32_e32 v115, v127
	v_mov_b32_e32 v114, v127
	v_mov_b32_e32 v113, v127
	v_mov_b32_e32 v112, v127
	v_mov_b32_e32 v107, v127
	v_mov_b32_e32 v106, v127
	v_mov_b32_e32 v105, v127
	v_mov_b32_e32 v104, v127
	v_mov_b32_e32 v99, v127
	v_mov_b32_e32 v98, v127
	v_mov_b32_e32 v97, v127
	v_mov_b32_e32 v96, v127
	v_mov_b32_e32 v91, v127
	v_mov_b32_e32 v90, v127
	v_mov_b32_e32 v89, v127
	v_mov_b32_e32 v88, v127
	v_mov_b32_e32 v83, v127
	v_mov_b32_e32 v82, v127
	v_mov_b32_e32 v81, v127
	v_mov_b32_e32 v80, v127
	v_mov_b32_e32 v75, v127
	v_mov_b32_e32 v74, v127
	v_mov_b32_e32 v73, v127
	v_mov_b32_e32 v72, v127
	v_mov_b32_e32 v67, v127
	v_mov_b32_e32 v66, v127
	v_mov_b32_e32 v65, v127
	v_mov_b32_e32 v64, v127
	v_mov_b32_e32 v63, v127
	v_mov_b32_e32 v62, v127
	v_mov_b32_e32 v61, v127
	v_mov_b32_e32 v60, v127
	v_mov_b32_e32 v55, v127
	v_mov_b32_e32 v54, v127
	v_mov_b32_e32 v53, v127
	v_mov_b32_e32 v52, v127
	v_mov_b32_e32 v47, v127
	v_mov_b32_e32 v46, v127
	v_mov_b32_e32 v45, v127
	v_mov_b32_e32 v44, v127
	v_mov_b32_e32 v39, v127
	v_mov_b32_e32 v38, v127
	v_mov_b32_e32 v37, v127
	v_mov_b32_e32 v36, v127
	v_mov_b32_e32 v31, v127
	v_mov_b32_e32 v30, v127
	v_mov_b32_e32 v29, v127
	v_mov_b32_e32 v28, v127
	v_mov_b32_e32 v23, v127
	v_mov_b32_e32 v22, v127
	v_mov_b32_e32 v21, v127
	v_mov_b32_e32 v20, v127
	v_mov_b32_e32 v15, v127
	v_mov_b32_e32 v14, v127
	v_mov_b32_e32 v13, v127
	v_mov_b32_e32 v12, v127
	v_mov_b32_e32 v7, v127
	v_mov_b32_e32 v6, v127
	v_mov_b32_e32 v5, v127
	v_mov_b32_e32 v4, v127
	v_mov_b32_e32 v59, v127
	v_mov_b32_e32 v58, v127
	v_mov_b32_e32 v57, v127
	v_mov_b32_e32 v56, v127
	v_mov_b32_e32 v51, v127
	v_mov_b32_e32 v50, v127
	v_mov_b32_e32 v49, v127
	v_mov_b32_e32 v48, v127
	v_mov_b32_e32 v43, v127
	v_mov_b32_e32 v42, v127
	v_mov_b32_e32 v41, v127
	v_mov_b32_e32 v40, v127
	v_mov_b32_e32 v35, v127
	v_mov_b32_e32 v34, v127
	v_mov_b32_e32 v33, v127
	v_mov_b32_e32 v32, v127
	v_mov_b32_e32 v27, v127
	v_mov_b32_e32 v26, v127
	v_mov_b32_e32 v25, v127
	v_mov_b32_e32 v24, v127
	v_mov_b32_e32 v19, v127
	v_mov_b32_e32 v18, v127
	v_mov_b32_e32 v17, v127
	v_mov_b32_e32 v16, v127
	v_mov_b32_e32 v11, v127
	v_mov_b32_e32 v10, v127
	v_mov_b32_e32 v9, v127
	v_mov_b32_e32 v8, v127
	v_mov_b32_e32 v3, v127
	v_mov_b32_e32 v2, v127
	v_mov_b32_e32 v1, v127
	v_mov_b32_e32 v0, v127
	s_cbranch_vccnz .LBB0_305
	v_mov_b32_e32 v0, 0
	v_lshl_add_u64 v[158:159], v[158:159], 0, s[26:27]
	v_lshl_add_u64 v[160:161], v[160:161], 0, s[22:23]
	s_mov_b32 s10, 0
	v_mov_b32_e32 v1, v0
	v_mov_b32_e32 v2, v0
	v_mov_b32_e32 v3, v0
	v_mov_b32_e32 v8, v0
	v_mov_b32_e32 v9, v0
	v_mov_b32_e32 v10, v0
	v_mov_b32_e32 v11, v0
	v_mov_b32_e32 v16, v0
	v_mov_b32_e32 v17, v0
	v_mov_b32_e32 v18, v0
	v_mov_b32_e32 v19, v0
	v_mov_b32_e32 v24, v0
	v_mov_b32_e32 v25, v0
	v_mov_b32_e32 v26, v0
	v_mov_b32_e32 v27, v0
	v_mov_b32_e32 v32, v0
	v_mov_b32_e32 v33, v0
	v_mov_b32_e32 v34, v0
	v_mov_b32_e32 v35, v0
	v_mov_b32_e32 v40, v0
	v_mov_b32_e32 v41, v0
	v_mov_b32_e32 v42, v0
	v_mov_b32_e32 v43, v0
	v_mov_b32_e32 v48, v0
	v_mov_b32_e32 v49, v0
	v_mov_b32_e32 v50, v0
	v_mov_b32_e32 v51, v0
	v_mov_b32_e32 v56, v0
	v_mov_b32_e32 v57, v0
	v_mov_b32_e32 v58, v0
	v_mov_b32_e32 v59, v0
	v_mov_b32_e32 v4, v0
	v_mov_b32_e32 v5, v0
	v_mov_b32_e32 v6, v0
	v_mov_b32_e32 v7, v0
	v_mov_b32_e32 v12, v0
	v_mov_b32_e32 v13, v0
	v_mov_b32_e32 v14, v0
	v_mov_b32_e32 v15, v0
	v_mov_b32_e32 v20, v0
	v_mov_b32_e32 v21, v0
	v_mov_b32_e32 v22, v0
	v_mov_b32_e32 v23, v0
	v_mov_b32_e32 v28, v0
	v_mov_b32_e32 v29, v0
	v_mov_b32_e32 v30, v0
	v_mov_b32_e32 v31, v0
	v_mov_b32_e32 v36, v0
	v_mov_b32_e32 v37, v0
	v_mov_b32_e32 v38, v0
	v_mov_b32_e32 v39, v0
	v_mov_b32_e32 v44, v0
	v_mov_b32_e32 v45, v0
	v_mov_b32_e32 v46, v0
	v_mov_b32_e32 v47, v0
	v_mov_b32_e32 v52, v0
	v_mov_b32_e32 v53, v0
	v_mov_b32_e32 v54, v0
	v_mov_b32_e32 v55, v0
	v_mov_b32_e32 v60, v0
	v_mov_b32_e32 v61, v0
	v_mov_b32_e32 v62, v0
	v_mov_b32_e32 v63, v0
	v_mov_b32_e32 v64, v0
	v_mov_b32_e32 v65, v0
	v_mov_b32_e32 v66, v0
	v_mov_b32_e32 v67, v0
	v_mov_b32_e32 v72, v0
	v_mov_b32_e32 v73, v0
	v_mov_b32_e32 v74, v0
	v_mov_b32_e32 v75, v0
	v_mov_b32_e32 v80, v0
	v_mov_b32_e32 v81, v0
	v_mov_b32_e32 v82, v0
	v_mov_b32_e32 v83, v0
	v_mov_b32_e32 v88, v0
	v_mov_b32_e32 v89, v0
	v_mov_b32_e32 v90, v0
	v_mov_b32_e32 v91, v0
	v_mov_b32_e32 v96, v0
	v_mov_b32_e32 v97, v0
	v_mov_b32_e32 v98, v0
	v_mov_b32_e32 v99, v0
	v_mov_b32_e32 v104, v0
	v_mov_b32_e32 v105, v0
	v_mov_b32_e32 v106, v0
	v_mov_b32_e32 v107, v0
	v_mov_b32_e32 v112, v0
	v_mov_b32_e32 v113, v0
	v_mov_b32_e32 v114, v0
	v_mov_b32_e32 v115, v0
	v_mov_b32_e32 v120, v0
	v_mov_b32_e32 v121, v0
	v_mov_b32_e32 v122, v0
	v_mov_b32_e32 v123, v0
	v_mov_b32_e32 v68, v0
	v_mov_b32_e32 v69, v0
	v_mov_b32_e32 v70, v0
	v_mov_b32_e32 v71, v0
	v_mov_b32_e32 v76, v0
	v_mov_b32_e32 v77, v0
	v_mov_b32_e32 v78, v0
	v_mov_b32_e32 v79, v0
	v_mov_b32_e32 v84, v0
	v_mov_b32_e32 v85, v0
	v_mov_b32_e32 v86, v0
	v_mov_b32_e32 v87, v0
	v_mov_b32_e32 v92, v0
	v_mov_b32_e32 v93, v0
	v_mov_b32_e32 v94, v0
	v_mov_b32_e32 v95, v0
	v_mov_b32_e32 v100, v0
	v_mov_b32_e32 v101, v0
	v_mov_b32_e32 v102, v0
	v_mov_b32_e32 v103, v0
	v_mov_b32_e32 v108, v0
	v_mov_b32_e32 v109, v0
	v_mov_b32_e32 v110, v0
	v_mov_b32_e32 v111, v0
	v_mov_b32_e32 v116, v0
	v_mov_b32_e32 v117, v0
	v_mov_b32_e32 v118, v0
	v_mov_b32_e32 v119, v0
	v_mov_b32_e32 v124, v0
	v_mov_b32_e32 v125, v0
	v_mov_b32_e32 v126, v0
	v_mov_b32_e32 v127, v0
	s_cmp_eq_u32 s53, s10
	v_lshl_add_u64 v[172:173], v[160:161], 0, s[22:23]
	s_cselect_b64 vcc, -1, 0
	s_add_i32 s10, s10, 2
	v_cndmask_b32_e32 v173, v173, v153, vcc
	v_cndmask_b32_e32 v172, v172, v152, vcc
	v_cndmask_b32_e32 v245, v159, v155, vcc
	v_cndmask_b32_e32 v244, v158, v154, vcc
	.p2align	6
; #define PG8_STAGE(bufoff, gbase, voff) do { _Pragma("unroll") for (int _i = 0; _i < 2; ++_i) \
;         __builtin_amdgcn_global_load_lds((const unsigned*)((const char*)(gbase) + (voff)[_i]), (PG8_LAS unsigned*)(lds + (bufoff) + ldsw + _i * 8192), 16, 0, 0); } while (0)
; #define PG8_LDA(dst, b, h) do { _Pragma("unroll") for (int m = 0; m < 4; ++m) _Pragma("unroll") for (int k = 0; k < 2; ++k) dst[m][k] = *(const PG8_LAS bf16x8*)(lds + PG8_SA(b, h) + aoff + m * 2048 + k * 1024); } while (0)
; #define PG8_LDB(dst, b, h) do { _Pragma("unroll") for (int n = 0; n < 2; ++n) _Pragma("unroll") for (int k = 0; k < 2; ++k) dst[n][k] = *(const PG8_LAS bf16x8*)(lds + PG8_SB(b, h) + boff + n * 2048 + k * 1024); } while (0)
; #define PG8_MMA(ai, bj, At, Bt) do { __builtin_amdgcn_s_setprio(1); _Pragma("unroll") for (int m = 0; m < 4; ++m) _Pragma("unroll") for (int n = 0; n < 2; ++n) _Pragma("unroll") for (int k = 0; k < 2; ++k) \
;         acc[ai][bj][m][n] = __builtin_amdgcn_mfma_f32_16x16x32_bf16(Bt[n][k], At[m][k], acc[ai][bj][m][n], 0, 0, 0); __builtin_amdgcn_s_setprio(0); } while (0)
; #define PG8_WAIT_V(n) asm volatile("s_waitcnt vmcnt(" #n ")" ::: "memory")
; #define PG8_WAIT_L(n) asm volatile("s_waitcnt lgkmcnt(" #n ")" ::: "memory")
; #define PG8_BAR __builtin_amdgcn_s_barrier()
; #define PG8_SCHED __builtin_amdgcn_sched_barrier(0)
; template <class Epi, class Sched, bool ALIGN_EPI = false, bool SP2 = false>
; __device__ __forceinline__ void gemm_phase(PG8_LAS unsigned char* lds, const Gemm g, const Sched& S, const Epi& E) {
;     ...
;             PG8_LDB(B0, 0, 0); PG8_LDB(B1, 0, 1); PG8_SCHED; PG8_LDA(At, 0, 0); PG8_STAGE(PG8_SA(1, 1), a1 + hstep, voffA);
;             PG8_WAIT_V(8); PG8_WAIT_L(0); PG8_BAR; PG8_MMA(0, 0, At, B0); PG8_MMA(0, 1, At, B1); PG8_BAR; PG8_SCHED;
;             PG8_LDA(At, 0, 1); PG8_STAGE(PG8_SB(0, 0), b2, voffB); PG8_STAGE(PG8_SB(0, 1), b2 + hstep, voffB); PG8_STAGE(PG8_SA(0, 0), a2, voffA);
;             PG8_WAIT_V(8); PG8_WAIT_L(0); PG8_BAR; PG8_MMA(1, 0, At, B0); PG8_MMA(1, 1, At, B1); PG8_BAR; PG8_SCHED;
.LBB0_304:
	v_add_u32_e32 v166, s54, v169
	v_add_u32_e32 v168, s55, v169
	ds_read_b128 v[162:165], v166
	ds_read_b128 v[182:185], v166 offset:1024
	ds_read_b128 v[186:189], v166 offset:2048
	ds_read_b128 v[190:193], v166 offset:3072
	ds_read_b128 v[194:197], v168
	ds_read_b128 v[198:201], v168 offset:1024
	ds_read_b128 v[202:205], v168 offset:2048
	ds_read_b128 v[206:209], v168 offset:3072
	s_mov_b32 m0, s56
	v_lshl_add_u64 v[246:247], v[160:161], 0, v[148:149]
	ds_read_b128 v[210:213], v179
	ds_read_b128 v[216:219], v179 offset:1024
	ds_read_b128 v[220:223], v179 offset:2048
	ds_read_b128 v[224:227], v179 offset:3072
	ds_read_b128 v[228:231], v179 offset:4096
	ds_read_b128 v[232:235], v179 offset:5120
	ds_read_b128 v[236:239], v179 offset:6144
	ds_read_b128 v[240:243], v179 offset:7168
	global_load_lds_dwordx4 v[246:247], off
	s_mov_b32 m0, s57
	v_lshl_add_u64 v[246:247], v[160:161], 0, v[146:147]
	global_load_lds_dwordx4 v[246:247], off
	s_waitcnt vmcnt(8) lgkmcnt(0)
	s_setprio 1
	s_barrier
	v_mfma_f32_16x16x32_bf16 v[124:127], v[162:165], v[210:213], v[124:127]
	v_mfma_f32_16x16x32_bf16 v[116:119], v[186:189], v[210:213], v[116:119]
	v_mfma_f32_16x16x32_bf16 v[108:111], v[162:165], v[220:223], v[108:111]
	v_mfma_f32_16x16x32_bf16 v[100:103], v[186:189], v[220:223], v[100:103]
	v_mfma_f32_16x16x32_bf16 v[92:95], v[162:165], v[228:231], v[92:95]
	v_mfma_f32_16x16x32_bf16 v[84:87], v[186:189], v[228:231], v[84:87]
	v_mfma_f32_16x16x32_bf16 v[76:79], v[162:165], v[236:239], v[76:79]
	v_mfma_f32_16x16x32_bf16 v[68:71], v[186:189], v[236:239], v[68:71]
	v_mfma_f32_16x16x32_bf16 v[124:127], v[182:185], v[216:219], v[124:127]
	v_mfma_f32_16x16x32_bf16 v[116:119], v[190:193], v[216:219], v[116:119]
	v_mfma_f32_16x16x32_bf16 v[108:111], v[182:185], v[224:227], v[108:111]
	v_mfma_f32_16x16x32_bf16 v[100:103], v[190:193], v[224:227], v[100:103]
	v_mfma_f32_16x16x32_bf16 v[92:95], v[182:185], v[232:235], v[92:95]
	v_mfma_f32_16x16x32_bf16 v[84:87], v[190:193], v[232:235], v[84:87]
	v_mfma_f32_16x16x32_bf16 v[76:79], v[182:185], v[240:243], v[76:79]
	v_mfma_f32_16x16x32_bf16 v[68:71], v[190:193], v[240:243], v[68:71]
	v_mfma_f32_16x16x32_bf16 v[120:123], v[194:197], v[210:213], v[120:123]
	v_mfma_f32_16x16x32_bf16 v[112:115], v[202:205], v[210:213], v[112:115]
	v_mfma_f32_16x16x32_bf16 v[104:107], v[194:197], v[220:223], v[104:107]
	v_mfma_f32_16x16x32_bf16 v[96:99], v[202:205], v[220:223], v[96:99]
	v_mfma_f32_16x16x32_bf16 v[88:91], v[194:197], v[228:231], v[88:91]
	v_mfma_f32_16x16x32_bf16 v[80:83], v[202:205], v[228:231], v[80:83]
	v_mfma_f32_16x16x32_bf16 v[72:75], v[194:197], v[236:239], v[72:75]
	v_mfma_f32_16x16x32_bf16 v[64:67], v[202:205], v[236:239], v[64:67]
	v_mfma_f32_16x16x32_bf16 v[120:123], v[198:201], v[216:219], v[120:123]
	v_mfma_f32_16x16x32_bf16 v[112:115], v[206:209], v[216:219], v[112:115]
	v_mfma_f32_16x16x32_bf16 v[104:107], v[198:201], v[224:227], v[104:107]
	v_mfma_f32_16x16x32_bf16 v[96:99], v[206:209], v[224:227], v[96:99]
	v_mfma_f32_16x16x32_bf16 v[88:91], v[198:201], v[232:235], v[88:91]
	v_mfma_f32_16x16x32_bf16 v[80:83], v[206:209], v[232:235], v[80:83]
	v_mfma_f32_16x16x32_bf16 v[72:75], v[198:201], v[240:243], v[72:75]
	v_mfma_f32_16x16x32_bf16 v[64:67], v[206:209], v[240:243], v[64:67]
	s_setprio 0
	s_barrier
	s_mov_b32 m0, s60
	v_lshl_add_u64 v[246:247], v[244:245], 0, v[138:139]
	ds_read_b128 v[210:213], v179 offset:16384
	ds_read_b128 v[216:219], v179 offset:17408
	ds_read_b128 v[220:223], v179 offset:18432
	ds_read_b128 v[224:227], v179 offset:19456
	ds_read_b128 v[228:231], v179 offset:20480
	ds_read_b128 v[232:235], v179 offset:21504
	ds_read_b128 v[236:239], v179 offset:22528
	ds_read_b128 v[240:243], v179 offset:23552
	global_load_lds_dwordx4 v[246:247], off
	v_lshl_add_u64 v[248:249], v[244:245], 0, v[134:135]
	s_mov_b32 m0, s61
	v_lshl_add_u64 v[244:245], v[244:245], 0, s[14:15]
	global_load_lds_dwordx4 v[248:249], off
	v_lshl_add_u64 v[250:251], v[244:245], 0, v[138:139]
	s_mov_b32 m0, s62
	v_lshl_add_u64 v[244:245], v[244:245], 0, v[134:135]
	global_load_lds_dwordx4 v[250:251], off
	s_add_i32 m0, s62, 0x2000
	v_lshl_add_u64 v[252:253], v[172:173], 0, v[140:141]
	global_load_lds_dwordx4 v[244:245], off
	s_mov_b32 m0, s46
	v_lshl_add_u64 v[214:215], v[172:173], 0, v[136:137]
	global_load_lds_dwordx4 v[252:253], off
	s_mov_b32 m0, s47
	s_nop 0
	global_load_lds_dwordx4 v[214:215], off
	s_waitcnt vmcnt(8) lgkmcnt(0)
	s_setprio 1
	s_barrier
	v_mfma_f32_16x16x32_bf16 v[60:63], v[162:165], v[210:213], v[60:63]
	v_mfma_f32_16x16x32_bf16 v[52:55], v[186:189], v[210:213], v[52:55]
	v_mfma_f32_16x16x32_bf16 v[44:47], v[162:165], v[220:223], v[44:47]
	v_mfma_f32_16x16x32_bf16 v[36:39], v[186:189], v[220:223], v[36:39]
	v_mfma_f32_16x16x32_bf16 v[28:31], v[162:165], v[228:231], v[28:31]
	v_mfma_f32_16x16x32_bf16 v[20:23], v[186:189], v[228:231], v[20:23]
	v_mfma_f32_16x16x32_bf16 v[12:15], v[162:165], v[236:239], v[12:15]
	v_mfma_f32_16x16x32_bf16 v[4:7], v[186:189], v[236:239], v[4:7]
	v_mfma_f32_16x16x32_bf16 v[60:63], v[182:185], v[216:219], v[60:63]
	v_mfma_f32_16x16x32_bf16 v[52:55], v[190:193], v[216:219], v[52:55]
	v_mfma_f32_16x16x32_bf16 v[44:47], v[182:185], v[224:227], v[44:47]
	v_mfma_f32_16x16x32_bf16 v[36:39], v[190:193], v[224:227], v[36:39]
	v_mfma_f32_16x16x32_bf16 v[28:31], v[182:185], v[232:235], v[28:31]
	v_mfma_f32_16x16x32_bf16 v[20:23], v[190:193], v[232:235], v[20:23]
	v_mfma_f32_16x16x32_bf16 v[12:15], v[182:185], v[240:243], v[12:15]
	v_mfma_f32_16x16x32_bf16 v[4:7], v[190:193], v[240:243], v[4:7]
	v_mfma_f32_16x16x32_bf16 v[56:59], v[194:197], v[210:213], v[56:59]
	v_mfma_f32_16x16x32_bf16 v[48:51], v[202:205], v[210:213], v[48:51]
	v_mfma_f32_16x16x32_bf16 v[40:43], v[194:197], v[220:223], v[40:43]
	v_mfma_f32_16x16x32_bf16 v[32:35], v[202:205], v[220:223], v[32:35]
	v_mfma_f32_16x16x32_bf16 v[24:27], v[194:197], v[228:231], v[24:27]
	v_mfma_f32_16x16x32_bf16 v[16:19], v[202:205], v[228:231], v[16:19]
	v_mfma_f32_16x16x32_bf16 v[8:11], v[194:197], v[236:239], v[8:11]
	v_mfma_f32_16x16x32_bf16 v[0:3], v[202:205], v[236:239], v[0:3]
	v_mfma_f32_16x16x32_bf16 v[56:59], v[198:201], v[216:219], v[56:59]
	v_mfma_f32_16x16x32_bf16 v[48:51], v[206:209], v[216:219], v[48:51]
	v_mfma_f32_16x16x32_bf16 v[40:43], v[198:201], v[224:227], v[40:43]
	v_mfma_f32_16x16x32_bf16 v[32:35], v[206:209], v[224:227], v[32:35]
	v_mfma_f32_16x16x32_bf16 v[24:27], v[198:201], v[232:235], v[24:27]
	v_mfma_f32_16x16x32_bf16 v[16:19], v[206:209], v[232:235], v[16:19]
	v_mfma_f32_16x16x32_bf16 v[8:11], v[198:201], v[240:243], v[8:11]
	v_mfma_f32_16x16x32_bf16 v[0:3], v[206:209], v[240:243], v[0:3]
	s_setprio 0
	s_barrier
; #define PG8_STAGE(bufoff, gbase, voff) do { _Pragma("unroll") for (int _i = 0; _i < 2; ++_i) \
;         __builtin_amdgcn_global_load_lds((const unsigned*)((const char*)(gbase) + (voff)[_i]), (PG8_LAS unsigned*)(lds + (bufoff) + ldsw + _i * 8192), 16, 0, 0); } while (0)
; #define PG8_LDA(dst, b, h) do { _Pragma("unroll") for (int m = 0; m < 4; ++m) _Pragma("unroll") for (int k = 0; k < 2; ++k) dst[m][k] = *(const PG8_LAS bf16x8*)(lds + PG8_SA(b, h) + aoff + m * 2048 + k * 1024); } while (0)
; #define PG8_LDB(dst, b, h) do { _Pragma("unroll") for (int n = 0; n < 2; ++n) _Pragma("unroll") for (int k = 0; k < 2; ++k) dst[n][k] = *(const PG8_LAS bf16x8*)(lds + PG8_SB(b, h) + boff + n * 2048 + k * 1024); } while (0)
; #define PG8_MMA(ai, bj, At, Bt) do { __builtin_amdgcn_s_setprio(1); _Pragma("unroll") for (int m = 0; m < 4; ++m) _Pragma("unroll") for (int n = 0; n < 2; ++n) _Pragma("unroll") for (int k = 0; k < 2; ++k) \
;         acc[ai][bj][m][n] = __builtin_amdgcn_mfma_f32_16x16x32_bf16(Bt[n][k], At[m][k], acc[ai][bj][m][n], 0, 0, 0); __builtin_amdgcn_s_setprio(0); } while (0)
; #define PG8_WAIT_V(n) asm volatile("s_waitcnt vmcnt(" #n ")" ::: "memory")
; #define PG8_WAIT_L(n) asm volatile("s_waitcnt lgkmcnt(" #n ")" ::: "memory")
; #define PG8_BAR __builtin_amdgcn_s_barrier()
; #define PG8_SCHED __builtin_amdgcn_sched_barrier(0)
; template <class Epi, class Sched, bool ALIGN_EPI = false, bool SP2 = false>
; __device__ __forceinline__ void gemm_phase(PG8_LAS unsigned char* lds, const Gemm g, const Sched& S, const Epi& E) {
;     ...
;         for (int t = 0; t < nt; t += 2) {
;     ...
;             PG8_LDB(B0, 1, 0); PG8_LDB(B1, 1, 1); PG8_SCHED; PG8_LDA(At, 1, 0); PG8_STAGE(PG8_SA(0, 1), a2 + hstep, voffA);
;             PG8_WAIT_V(8); PG8_WAIT_L(0); PG8_BAR; PG8_MMA(0, 0, At, B0); PG8_MMA(0, 1, At, B1); PG8_BAR; PG8_SCHED;
;             PG8_LDA(At, 1, 1); PG8_STAGE(PG8_SB(1, 0), b3, voffB); PG8_STAGE(PG8_SB(1, 1), b3 + hstep, voffB); PG8_STAGE(PG8_SA(1, 0), a3, voffA);
;             PG8_WAIT_V(8); PG8_WAIT_L(0); PG8_BAR; PG8_MMA(1, 0, At, B0); PG8_MMA(1, 1, At, B1); PG8_BAR; PG8_SCHED;
	s_add_i32 s11, 0, 0x18000
	v_add_u32_e32 v166, s11, v169
	s_add_i32 s13, 0, 0x1c000
	ds_read_b128 v[162:165], v166
	ds_read_b128 v[182:185], v166 offset:1024
	ds_read_b128 v[186:189], v166 offset:2048
	ds_read_b128 v[190:193], v166 offset:3072
	v_add_u32_e32 v166, s13, v169
	ds_read_b128 v[194:197], v166
	ds_read_b128 v[198:201], v166 offset:1024
	ds_read_b128 v[202:205], v166 offset:2048
	ds_read_b128 v[206:209], v166 offset:3072
	v_lshl_add_u64 v[172:173], v[172:173], 0, s[14:15]
	s_mov_b32 m0, s48
	v_lshl_add_u64 v[170:171], v[172:173], 0, v[140:141]
	ds_read_b128 v[210:213], v179 offset:32768
	ds_read_b128 v[216:219], v179 offset:33792
	ds_read_b128 v[220:223], v179 offset:34816
	ds_read_b128 v[224:227], v179 offset:35840
	ds_read_b128 v[228:231], v179 offset:36864
	ds_read_b128 v[232:235], v179 offset:37888
	ds_read_b128 v[236:239], v179 offset:38912
	ds_read_b128 v[240:243], v179 offset:39936
	global_load_lds_dwordx4 v[170:171], off
	s_mov_b32 m0, s49
	v_lshl_add_u64 v[170:171], v[172:173], 0, v[136:137]
	global_load_lds_dwordx4 v[170:171], off
	s_waitcnt vmcnt(8) lgkmcnt(0)
	s_setprio 1
	s_barrier
	v_mfma_f32_16x16x32_bf16 v[124:127], v[162:165], v[210:213], v[124:127]
	v_mfma_f32_16x16x32_bf16 v[116:119], v[186:189], v[210:213], v[116:119]
	v_mfma_f32_16x16x32_bf16 v[108:111], v[162:165], v[220:223], v[108:111]
	v_mfma_f32_16x16x32_bf16 v[100:103], v[186:189], v[220:223], v[100:103]
	v_mfma_f32_16x16x32_bf16 v[92:95], v[162:165], v[228:231], v[92:95]
	v_mfma_f32_16x16x32_bf16 v[84:87], v[186:189], v[228:231], v[84:87]
	v_mfma_f32_16x16x32_bf16 v[76:79], v[162:165], v[236:239], v[76:79]
	v_mfma_f32_16x16x32_bf16 v[68:71], v[186:189], v[236:239], v[68:71]
	v_mfma_f32_16x16x32_bf16 v[124:127], v[182:185], v[216:219], v[124:127]
	v_mfma_f32_16x16x32_bf16 v[116:119], v[190:193], v[216:219], v[116:119]
	v_mfma_f32_16x16x32_bf16 v[108:111], v[182:185], v[224:227], v[108:111]
	v_mfma_f32_16x16x32_bf16 v[100:103], v[190:193], v[224:227], v[100:103]
	v_mfma_f32_16x16x32_bf16 v[92:95], v[182:185], v[232:235], v[92:95]
	v_mfma_f32_16x16x32_bf16 v[84:87], v[190:193], v[232:235], v[84:87]
	v_mfma_f32_16x16x32_bf16 v[76:79], v[182:185], v[240:243], v[76:79]
	v_mfma_f32_16x16x32_bf16 v[68:71], v[190:193], v[240:243], v[68:71]
	v_mfma_f32_16x16x32_bf16 v[120:123], v[194:197], v[210:213], v[120:123]
	v_mfma_f32_16x16x32_bf16 v[112:115], v[202:205], v[210:213], v[112:115]
	v_mfma_f32_16x16x32_bf16 v[104:107], v[194:197], v[220:223], v[104:107]
	v_mfma_f32_16x16x32_bf16 v[96:99], v[202:205], v[220:223], v[96:99]
	v_mfma_f32_16x16x32_bf16 v[88:91], v[194:197], v[228:231], v[88:91]
	v_mfma_f32_16x16x32_bf16 v[80:83], v[202:205], v[228:231], v[80:83]
	v_mfma_f32_16x16x32_bf16 v[72:75], v[194:197], v[236:239], v[72:75]
	v_mfma_f32_16x16x32_bf16 v[64:67], v[202:205], v[236:239], v[64:67]
	v_mfma_f32_16x16x32_bf16 v[120:123], v[198:201], v[216:219], v[120:123]
	v_mfma_f32_16x16x32_bf16 v[112:115], v[206:209], v[216:219], v[112:115]
	v_mfma_f32_16x16x32_bf16 v[104:107], v[198:201], v[224:227], v[104:107]
	v_mfma_f32_16x16x32_bf16 v[96:99], v[206:209], v[224:227], v[96:99]
	v_mfma_f32_16x16x32_bf16 v[88:91], v[198:201], v[232:235], v[88:91]
	v_mfma_f32_16x16x32_bf16 v[80:83], v[206:209], v[232:235], v[80:83]
	v_mfma_f32_16x16x32_bf16 v[72:75], v[198:201], v[240:243], v[72:75]
	v_mfma_f32_16x16x32_bf16 v[64:67], v[206:209], v[240:243], v[64:67]
	s_setprio 0
	s_barrier
	s_add_i32 s11, s11, s29
	s_add_i32 m0, s11, 0xffffff80
	ds_read_b128 v[210:213], v179 offset:49152
	ds_read_b128 v[216:219], v179 offset:50176
	ds_read_b128 v[220:223], v179 offset:51200
	ds_read_b128 v[224:227], v179 offset:52224
	global_load_lds_dwordx4 v[246:247], off offset:128
	s_add_i32 m0, s11, 0x1f80
	s_add_i32 s11, s13, s29
	global_load_lds_dwordx4 v[248:249], off offset:128
	s_add_i32 m0, s11, 0xffffff80
	ds_read_b128 v[240:243], v179 offset:56320
	global_load_lds_dwordx4 v[250:251], off offset:128
	s_add_i32 m0, s11, 0x1f80
	ds_read_b128 v[236:239], v179 offset:55296
	global_load_lds_dwordx4 v[244:245], off offset:128
	s_add_i32 m0, s50, 0xffffff80
	ds_read_b128 v[232:235], v179 offset:54272
	global_load_lds_dwordx4 v[252:253], off offset:128
	s_add_i32 m0, s51, 0xffffff80
	ds_read_b128 v[228:231], v179 offset:53248
	global_load_lds_dwordx4 v[214:215], off offset:128
	s_waitcnt vmcnt(8) lgkmcnt(0)
	s_setprio 1
	s_barrier
	v_mfma_f32_16x16x32_bf16 v[60:63], v[162:165], v[210:213], v[60:63]
	v_mfma_f32_16x16x32_bf16 v[52:55], v[186:189], v[210:213], v[52:55]
	v_mfma_f32_16x16x32_bf16 v[44:47], v[162:165], v[220:223], v[44:47]
	v_mfma_f32_16x16x32_bf16 v[36:39], v[186:189], v[220:223], v[36:39]
	v_mfma_f32_16x16x32_bf16 v[28:31], v[162:165], v[228:231], v[28:31]
	v_mfma_f32_16x16x32_bf16 v[20:23], v[186:189], v[228:231], v[20:23]
	v_mfma_f32_16x16x32_bf16 v[12:15], v[162:165], v[236:239], v[12:15]
	v_mfma_f32_16x16x32_bf16 v[4:7], v[186:189], v[236:239], v[4:7]
	v_mfma_f32_16x16x32_bf16 v[60:63], v[182:185], v[216:219], v[60:63]
	v_mfma_f32_16x16x32_bf16 v[52:55], v[190:193], v[216:219], v[52:55]
	v_mfma_f32_16x16x32_bf16 v[44:47], v[182:185], v[224:227], v[44:47]
	v_mfma_f32_16x16x32_bf16 v[36:39], v[190:193], v[224:227], v[36:39]
	v_mfma_f32_16x16x32_bf16 v[28:31], v[182:185], v[232:235], v[28:31]
	v_mfma_f32_16x16x32_bf16 v[20:23], v[190:193], v[232:235], v[20:23]
	v_mfma_f32_16x16x32_bf16 v[12:15], v[182:185], v[240:243], v[12:15]
	v_mfma_f32_16x16x32_bf16 v[4:7], v[190:193], v[240:243], v[4:7]
	v_mfma_f32_16x16x32_bf16 v[56:59], v[194:197], v[210:213], v[56:59]
	v_mfma_f32_16x16x32_bf16 v[48:51], v[202:205], v[210:213], v[48:51]
	v_mfma_f32_16x16x32_bf16 v[40:43], v[194:197], v[220:223], v[40:43]
	v_mfma_f32_16x16x32_bf16 v[32:35], v[202:205], v[220:223], v[32:35]
	v_mfma_f32_16x16x32_bf16 v[24:27], v[194:197], v[228:231], v[24:27]
	v_mfma_f32_16x16x32_bf16 v[16:19], v[202:205], v[228:231], v[16:19]
	v_mfma_f32_16x16x32_bf16 v[8:11], v[194:197], v[236:239], v[8:11]
	v_mfma_f32_16x16x32_bf16 v[0:3], v[202:205], v[236:239], v[0:3]
	v_mfma_f32_16x16x32_bf16 v[56:59], v[198:201], v[216:219], v[56:59]
	v_mfma_f32_16x16x32_bf16 v[48:51], v[206:209], v[216:219], v[48:51]
	v_mfma_f32_16x16x32_bf16 v[40:43], v[198:201], v[224:227], v[40:43]
	v_mfma_f32_16x16x32_bf16 v[32:35], v[206:209], v[224:227], v[32:35]
	v_mfma_f32_16x16x32_bf16 v[24:27], v[198:201], v[232:235], v[24:27]
	v_mfma_f32_16x16x32_bf16 v[16:19], v[206:209], v[232:235], v[16:19]
	v_mfma_f32_16x16x32_bf16 v[8:11], v[198:201], v[240:243], v[8:11]
	v_mfma_f32_16x16x32_bf16 v[0:3], v[206:209], v[240:243], v[0:3]
	v_lshl_add_u64 v[158:159], v[158:159], 0, s[26:27]
	v_lshl_add_u64 v[160:161], v[160:161], 0, s[26:27]
	s_cmp_ge_i32 s10, s52
	s_cbranch_scc1 .Lrot_exit_17
	s_cmp_eq_u32 s53, s10
	v_lshl_add_u64 v[172:173], v[160:161], 0, s[22:23]
	s_cselect_b64 vcc, -1, 0
	s_add_i32 s10, s10, 2
	v_cndmask_b32_e32 v173, v173, v153, vcc
	v_cndmask_b32_e32 v172, v172, v152, vcc
	v_cndmask_b32_e32 v245, v159, v155, vcc
	v_cndmask_b32_e32 v244, v158, v154, vcc
	s_setprio 0
	s_barrier
	s_branch .LBB0_304
; #define PG8_MMA(ai, bj, At, Bt) do { __builtin_amdgcn_s_setprio(1); _Pragma("unroll") for (int m = 0; m < 4; ++m) _Pragma("unroll") for (int n = 0; n < 2; ++n) _Pragma("unroll") for (int k = 0; k < 2; ++k) \
;         acc[ai][bj][m][n] = __builtin_amdgcn_mfma_f32_16x16x32_bf16(Bt[n][k], At[m][k], acc[ai][bj][m][n], 0, 0, 0); __builtin_amdgcn_s_setprio(0); } while (0)
; #define PG8_WAIT_V(n) asm volatile("s_waitcnt vmcnt(" #n ")" ::: "memory")
; #define PG8_WAIT_L(n) asm volatile("s_waitcnt lgkmcnt(" #n ")" ::: "memory")
; #define PG8_BAR __builtin_amdgcn_s_barrier()
; #define PG8_SCHED __builtin_amdgcn_sched_barrier(0)
; template <class Epi, class Sched, bool ALIGN_EPI = false, bool SP2 = false>
; __device__ __forceinline__ void gemm_phase(PG8_LAS unsigned char* lds, const Gemm g, const Sched& S, const Epi& E) {
;     ...
;             PG8_WAIT_V(8); PG8_WAIT_L(0); PG8_BAR; PG8_MMA(1, 0, At, B0); PG8_MMA(1, 1, At, B1); PG8_BAR; PG8_SCHED;
;     ...
;         if constexpr (ALIGN_EPI) { if (wr == 0) PG8_BAR; }
.Lrot_exit_17:
	s_setprio 0
	s_barrier
.LBB0_305:
	s_and_b64 vcc, exec, s[24:25]
	s_cbranch_vccz .LBB0_307
	s_barrier

; template <class Epi, class Sched, bool ALIGN_EPI = false, bool SP2 = false>
; __device__ __forceinline__ void gemm_phase(PG8_LAS unsigned char* lds, const Gemm g, const Sched& S, const Epi& E) {
;     ...
;         for (int t = 0; t < nt; t += 2) {
;             const bool last = (t == nt - 2);
;             const char* a1 = cA + (size_t)(t + 1) * kstep;
;             const char* a2 = last ? nA : cA + (size_t)(t + 2) * kstep; const char* b2 = last ? nB : cB + (size_t)(t + 2) * kstep;
;     ...
; #pragma unroll
;         for (int a = 0; a < 2; ++a)
; #pragma unroll
;             for (int b = 0; b < 2; ++b)
; #pragma unroll
;                 for (int m = 0; m < 4; ++m)
; #pragma unroll
;                     for (int n = 0; n < 2; ++n) acc[a][b][m][n] = (f32x4){0.f, 0.f, 0.f, 0.f};
.LBB0_369:
	v_mov_b32_e32 v127, 0
	s_and_b64 vcc, exec, s[8:9]
	v_mov_b32_e32 v126, v127
	v_mov_b32_e32 v125, v127
	v_mov_b32_e32 v124, v127
	v_mov_b32_e32 v131, v127
	v_mov_b32_e32 v130, v127
	v_mov_b32_e32 v129, v127
	v_mov_b32_e32 v128, v127
	v_mov_b32_e32 v115, v127
	v_mov_b32_e32 v114, v127
	v_mov_b32_e32 v113, v127
	v_mov_b32_e32 v112, v127
	v_mov_b32_e32 v111, v127
	v_mov_b32_e32 v110, v127
	v_mov_b32_e32 v109, v127
	v_mov_b32_e32 v108, v127
	v_mov_b32_e32 v99, v127
	v_mov_b32_e32 v98, v127
	v_mov_b32_e32 v97, v127
	v_mov_b32_e32 v96, v127
	v_mov_b32_e32 v95, v127
	v_mov_b32_e32 v94, v127
	v_mov_b32_e32 v93, v127
	v_mov_b32_e32 v92, v127
	v_mov_b32_e32 v83, v127
	v_mov_b32_e32 v82, v127
	v_mov_b32_e32 v81, v127
	v_mov_b32_e32 v80, v127
	v_mov_b32_e32 v79, v127
	v_mov_b32_e32 v78, v127
	v_mov_b32_e32 v77, v127
	v_mov_b32_e32 v76, v127
	v_mov_b32_e32 v123, v127
	v_mov_b32_e32 v122, v127
	v_mov_b32_e32 v121, v127
	v_mov_b32_e32 v120, v127
	v_mov_b32_e32 v119, v127
	v_mov_b32_e32 v118, v127
	v_mov_b32_e32 v117, v127
	v_mov_b32_e32 v116, v127
	v_mov_b32_e32 v107, v127
	v_mov_b32_e32 v106, v127
	v_mov_b32_e32 v105, v127
	v_mov_b32_e32 v104, v127
	v_mov_b32_e32 v103, v127
	v_mov_b32_e32 v102, v127
	v_mov_b32_e32 v101, v127
	v_mov_b32_e32 v100, v127
	v_mov_b32_e32 v91, v127
	v_mov_b32_e32 v90, v127
	v_mov_b32_e32 v89, v127
	v_mov_b32_e32 v88, v127
	v_mov_b32_e32 v87, v127
	v_mov_b32_e32 v86, v127
	v_mov_b32_e32 v85, v127
	v_mov_b32_e32 v84, v127
	v_mov_b32_e32 v75, v127
	v_mov_b32_e32 v74, v127
	v_mov_b32_e32 v73, v127
	v_mov_b32_e32 v72, v127
	v_mov_b32_e32 v71, v127
	v_mov_b32_e32 v70, v127
	v_mov_b32_e32 v69, v127
	v_mov_b32_e32 v68, v127
	v_mov_b32_e32 v67, v127
	v_mov_b32_e32 v66, v127
	v_mov_b32_e32 v65, v127
	v_mov_b32_e32 v64, v127
	v_mov_b32_e32 v63, v127
	v_mov_b32_e32 v62, v127
	v_mov_b32_e32 v61, v127
	v_mov_b32_e32 v60, v127
	v_mov_b32_e32 v51, v127
	v_mov_b32_e32 v50, v127
	v_mov_b32_e32 v49, v127
	v_mov_b32_e32 v48, v127
	v_mov_b32_e32 v47, v127
	v_mov_b32_e32 v46, v127
	v_mov_b32_e32 v45, v127
	v_mov_b32_e32 v44, v127
	v_mov_b32_e32 v35, v127
	v_mov_b32_e32 v34, v127
	v_mov_b32_e32 v33, v127
	v_mov_b32_e32 v32, v127
	v_mov_b32_e32 v31, v127
	v_mov_b32_e32 v30, v127
	v_mov_b32_e32 v29, v127
	v_mov_b32_e32 v28, v127
	v_mov_b32_e32 v19, v127
	v_mov_b32_e32 v18, v127
	v_mov_b32_e32 v17, v127
	v_mov_b32_e32 v16, v127
	v_mov_b32_e32 v15, v127
	v_mov_b32_e32 v14, v127
	v_mov_b32_e32 v13, v127
	v_mov_b32_e32 v12, v127
	v_mov_b32_e32 v59, v127
	v_mov_b32_e32 v58, v127
	v_mov_b32_e32 v57, v127
	v_mov_b32_e32 v56, v127
	v_mov_b32_e32 v55, v127
	v_mov_b32_e32 v54, v127
	v_mov_b32_e32 v53, v127
	v_mov_b32_e32 v52, v127
	v_mov_b32_e32 v43, v127
	v_mov_b32_e32 v42, v127
	v_mov_b32_e32 v41, v127
	v_mov_b32_e32 v40, v127
	v_mov_b32_e32 v39, v127
	v_mov_b32_e32 v38, v127
	v_mov_b32_e32 v37, v127
	v_mov_b32_e32 v36, v127
	v_mov_b32_e32 v27, v127
	v_mov_b32_e32 v26, v127
	v_mov_b32_e32 v25, v127
	v_mov_b32_e32 v24, v127
	v_mov_b32_e32 v23, v127
	v_mov_b32_e32 v22, v127
	v_mov_b32_e32 v21, v127
	v_mov_b32_e32 v20, v127
	v_mov_b32_e32 v11, v127
	v_mov_b32_e32 v10, v127
	v_mov_b32_e32 v9, v127
	v_mov_b32_e32 v8, v127
	v_mov_b32_e32 v7, v127
	v_mov_b32_e32 v6, v127
	s_waitcnt lgkmcnt(0)
	v_mov_b32_e32 v5, v127
	v_mov_b32_e32 v4, v127
	s_cbranch_vccnz .LBB0_372
	v_mov_b32_e32 v4, 0
	v_lshl_add_u64 v[132:133], v[132:133], 0, s[26:27]
	v_lshl_add_u64 v[134:135], v[134:135], 0, s[22:23]
	s_mov_b32 s12, 0
	v_mov_b32_e32 v5, v4
	v_mov_b32_e32 v6, v4
	v_mov_b32_e32 v7, v4
	v_mov_b32_e32 v8, v4
	v_mov_b32_e32 v9, v4
	v_mov_b32_e32 v10, v4
	v_mov_b32_e32 v11, v4
	v_mov_b32_e32 v20, v4
	v_mov_b32_e32 v21, v4
	v_mov_b32_e32 v22, v4
	v_mov_b32_e32 v23, v4
	v_mov_b32_e32 v24, v4
	v_mov_b32_e32 v25, v4
	v_mov_b32_e32 v26, v4
	v_mov_b32_e32 v27, v4
	v_mov_b32_e32 v36, v4
	v_mov_b32_e32 v37, v4
	v_mov_b32_e32 v38, v4
	v_mov_b32_e32 v39, v4
	v_mov_b32_e32 v40, v4
	v_mov_b32_e32 v41, v4
	v_mov_b32_e32 v42, v4
	v_mov_b32_e32 v43, v4
	v_mov_b32_e32 v52, v4
	v_mov_b32_e32 v53, v4
	v_mov_b32_e32 v54, v4
	v_mov_b32_e32 v55, v4
	v_mov_b32_e32 v56, v4
	v_mov_b32_e32 v57, v4
	v_mov_b32_e32 v58, v4
	v_mov_b32_e32 v59, v4
	v_mov_b32_e32 v12, v4
	v_mov_b32_e32 v13, v4
	v_mov_b32_e32 v14, v4
	v_mov_b32_e32 v15, v4
	v_mov_b32_e32 v16, v4
	v_mov_b32_e32 v17, v4
	v_mov_b32_e32 v18, v4
	v_mov_b32_e32 v19, v4
	v_mov_b32_e32 v28, v4
	v_mov_b32_e32 v29, v4
	v_mov_b32_e32 v30, v4
	v_mov_b32_e32 v31, v4
	v_mov_b32_e32 v32, v4
	v_mov_b32_e32 v33, v4
	v_mov_b32_e32 v34, v4
	v_mov_b32_e32 v35, v4
	v_mov_b32_e32 v44, v4
	v_mov_b32_e32 v45, v4
	v_mov_b32_e32 v46, v4
	v_mov_b32_e32 v47, v4
	v_mov_b32_e32 v48, v4
	v_mov_b32_e32 v49, v4
	v_mov_b32_e32 v50, v4
	v_mov_b32_e32 v51, v4
	v_mov_b32_e32 v60, v4
	v_mov_b32_e32 v61, v4
	v_mov_b32_e32 v62, v4
	v_mov_b32_e32 v63, v4
	v_mov_b32_e32 v64, v4
	v_mov_b32_e32 v65, v4
	v_mov_b32_e32 v66, v4
	v_mov_b32_e32 v67, v4
	v_mov_b32_e32 v68, v4
	v_mov_b32_e32 v69, v4
	v_mov_b32_e32 v70, v4
	v_mov_b32_e32 v71, v4
	v_mov_b32_e32 v72, v4
	v_mov_b32_e32 v73, v4
	v_mov_b32_e32 v74, v4
	v_mov_b32_e32 v75, v4
	v_mov_b32_e32 v84, v4
	v_mov_b32_e32 v85, v4
	v_mov_b32_e32 v86, v4
	v_mov_b32_e32 v87, v4
	v_mov_b32_e32 v88, v4
	v_mov_b32_e32 v89, v4
	v_mov_b32_e32 v90, v4
	v_mov_b32_e32 v91, v4
	v_mov_b32_e32 v100, v4
	v_mov_b32_e32 v101, v4
	v_mov_b32_e32 v102, v4
	v_mov_b32_e32 v103, v4
	v_mov_b32_e32 v104, v4
	v_mov_b32_e32 v105, v4
	v_mov_b32_e32 v106, v4
	v_mov_b32_e32 v107, v4
	v_mov_b32_e32 v116, v4
	v_mov_b32_e32 v117, v4
	v_mov_b32_e32 v118, v4
	v_mov_b32_e32 v119, v4
	v_mov_b32_e32 v120, v4
	v_mov_b32_e32 v121, v4
	v_mov_b32_e32 v122, v4
	v_mov_b32_e32 v123, v4
	v_mov_b32_e32 v76, v4
	v_mov_b32_e32 v77, v4
	v_mov_b32_e32 v78, v4
	v_mov_b32_e32 v79, v4
	v_mov_b32_e32 v80, v4
	v_mov_b32_e32 v81, v4
	v_mov_b32_e32 v82, v4
	v_mov_b32_e32 v83, v4
	v_mov_b32_e32 v92, v4
	v_mov_b32_e32 v93, v4
	v_mov_b32_e32 v94, v4
	v_mov_b32_e32 v95, v4
	v_mov_b32_e32 v96, v4
	v_mov_b32_e32 v97, v4
	v_mov_b32_e32 v98, v4
	v_mov_b32_e32 v99, v4
	v_mov_b32_e32 v108, v4
	v_mov_b32_e32 v109, v4
	v_mov_b32_e32 v110, v4
	v_mov_b32_e32 v111, v4
	v_mov_b32_e32 v112, v4
	v_mov_b32_e32 v113, v4
	v_mov_b32_e32 v114, v4
	v_mov_b32_e32 v115, v4
	v_mov_b32_e32 v128, v4
	v_mov_b32_e32 v129, v4
	v_mov_b32_e32 v130, v4
	v_mov_b32_e32 v131, v4
	v_mov_b32_e32 v124, v4
	v_mov_b32_e32 v125, v4
	v_mov_b32_e32 v126, v4
	v_mov_b32_e32 v127, v4
	s_cmp_eq_u32 s48, s12
	v_lshl_add_u64 v[194:195], v[134:135], 0, s[22:23]
	s_cselect_b64 vcc, -1, 0
	s_add_i32 s12, s12, 2
	v_cndmask_b32_e32 v199, v195, v179, vcc
	v_cndmask_b32_e32 v198, v194, v178, vcc
	v_cndmask_b32_e32 v215, v133, v181, vcc
	v_cndmask_b32_e32 v214, v132, v180, vcc
	.p2align	6
; #define PG8_STAGE(bufoff, gbase, voff) do { _Pragma("unroll") for (int _i = 0; _i < 2; ++_i) \
;         __builtin_amdgcn_global_load_lds((const unsigned*)((const char*)(gbase) + (voff)[_i]), (PG8_LAS unsigned*)(lds + (bufoff) + ldsw + _i * 8192), 16, 0, 0); } while (0)
; #define PG8_LDA(dst, b, h) do { _Pragma("unroll") for (int m = 0; m < 4; ++m) _Pragma("unroll") for (int k = 0; k < 2; ++k) dst[m][k] = *(const PG8_LAS bf16x8*)(lds + PG8_SA(b, h) + aoff + m * 2048 + k * 1024); } while (0)
; #define PG8_LDB(dst, b, h) do { _Pragma("unroll") for (int n = 0; n < 2; ++n) _Pragma("unroll") for (int k = 0; k < 2; ++k) dst[n][k] = *(const PG8_LAS bf16x8*)(lds + PG8_SB(b, h) + boff + n * 2048 + k * 1024); } while (0)
; #define PG8_MMA(ai, bj, At, Bt) do { __builtin_amdgcn_s_setprio(1); _Pragma("unroll") for (int m = 0; m < 4; ++m) _Pragma("unroll") for (int n = 0; n < 2; ++n) _Pragma("unroll") for (int k = 0; k < 2; ++k) \
;         acc[ai][bj][m][n] = __builtin_amdgcn_mfma_f32_16x16x32_bf16(Bt[n][k], At[m][k], acc[ai][bj][m][n], 0, 0, 0); __builtin_amdgcn_s_setprio(0); } while (0)
; #define PG8_WAIT_V(n) asm volatile("s_waitcnt vmcnt(" #n ")" ::: "memory")
; #define PG8_WAIT_L(n) asm volatile("s_waitcnt lgkmcnt(" #n ")" ::: "memory")
; #define PG8_BAR __builtin_amdgcn_s_barrier()
; #define PG8_SCHED __builtin_amdgcn_sched_barrier(0)
; template <class Epi, class Sched, bool ALIGN_EPI = false, bool SP2 = false>
; __device__ __forceinline__ void gemm_phase(PG8_LAS unsigned char* lds, const Gemm g, const Sched& S, const Epi& E) {
;     ...
;             PG8_LDB(B0, 0, 0); PG8_LDB(B1, 0, 1); PG8_SCHED; PG8_LDA(At, 0, 0); PG8_STAGE(PG8_SA(1, 1), a1 + hstep, voffA);
;             PG8_WAIT_V(8); PG8_WAIT_L(0); PG8_BAR; PG8_MMA(0, 0, At, B0); PG8_MMA(0, 1, At, B1); PG8_BAR; PG8_SCHED;
;             PG8_LDA(At, 0, 1); PG8_STAGE(PG8_SB(0, 0), b2, voffB); PG8_STAGE(PG8_SB(0, 1), b2 + hstep, voffB); PG8_STAGE(PG8_SA(0, 0), a2, voffA);
;             PG8_WAIT_V(8); PG8_WAIT_L(0); PG8_BAR; PG8_MMA(1, 0, At, B0); PG8_MMA(1, 1, At, B1); PG8_BAR; PG8_SCHED;
.LBB0_371:
	v_add_u32_e32 v148, s54, v201
	v_add_u32_e32 v190, s55, v201
	ds_read_b128 v[136:139], v148
	ds_read_b128 v[140:143], v148 offset:1024
	ds_read_b128 v[144:147], v148 offset:2048
	ds_read_b128 v[148:151], v148 offset:3072
	ds_read_b128 v[152:155], v190
	ds_read_b128 v[182:185], v190 offset:1024
	ds_read_b128 v[186:189], v190 offset:2048
	ds_read_b128 v[190:193], v190 offset:3072
	s_mov_b32 m0, s56
	v_lshl_add_u64 v[236:237], v[134:135], 0, v[174:175]
	ds_read_b128 v[194:197], v203
	ds_read_b128 v[206:209], v203 offset:1024
	ds_read_b128 v[210:213], v203 offset:2048
	ds_read_b128 v[216:219], v203 offset:3072
	ds_read_b128 v[220:223], v203 offset:4096
	ds_read_b128 v[224:227], v203 offset:5120
	ds_read_b128 v[228:231], v203 offset:6144
	ds_read_b128 v[232:235], v203 offset:7168
	global_load_lds_dwordx4 v[236:237], off
	s_mov_b32 m0, s57
	v_lshl_add_u64 v[236:237], v[134:135], 0, v[172:173]
	global_load_lds_dwordx4 v[236:237], off
	s_waitcnt vmcnt(8) lgkmcnt(0)
	s_setprio 1
	s_barrier
	v_mfma_f32_16x16x32_bf16 v[124:127], v[136:139], v[194:197], v[124:127]
	v_mfma_f32_16x16x32_bf16 v[128:131], v[144:147], v[194:197], v[128:131]
	v_mfma_f32_16x16x32_bf16 v[112:115], v[136:139], v[210:213], v[112:115]
	v_mfma_f32_16x16x32_bf16 v[108:111], v[144:147], v[210:213], v[108:111]
	v_mfma_f32_16x16x32_bf16 v[96:99], v[136:139], v[220:223], v[96:99]
	v_mfma_f32_16x16x32_bf16 v[92:95], v[144:147], v[220:223], v[92:95]
	v_mfma_f32_16x16x32_bf16 v[80:83], v[136:139], v[228:231], v[80:83]
	v_mfma_f32_16x16x32_bf16 v[76:79], v[144:147], v[228:231], v[76:79]
	v_mfma_f32_16x16x32_bf16 v[124:127], v[140:143], v[206:209], v[124:127]
	v_mfma_f32_16x16x32_bf16 v[128:131], v[148:151], v[206:209], v[128:131]
	v_mfma_f32_16x16x32_bf16 v[112:115], v[140:143], v[216:219], v[112:115]
	v_mfma_f32_16x16x32_bf16 v[108:111], v[148:151], v[216:219], v[108:111]
	v_mfma_f32_16x16x32_bf16 v[96:99], v[140:143], v[224:227], v[96:99]
	v_mfma_f32_16x16x32_bf16 v[92:95], v[148:151], v[224:227], v[92:95]
	v_mfma_f32_16x16x32_bf16 v[80:83], v[140:143], v[232:235], v[80:83]
	v_mfma_f32_16x16x32_bf16 v[76:79], v[148:151], v[232:235], v[76:79]
	v_mfma_f32_16x16x32_bf16 v[120:123], v[152:155], v[194:197], v[120:123]
	v_mfma_f32_16x16x32_bf16 v[116:119], v[186:189], v[194:197], v[116:119]
	v_mfma_f32_16x16x32_bf16 v[104:107], v[152:155], v[210:213], v[104:107]
	v_mfma_f32_16x16x32_bf16 v[100:103], v[186:189], v[210:213], v[100:103]
	v_mfma_f32_16x16x32_bf16 v[88:91], v[152:155], v[220:223], v[88:91]
	v_mfma_f32_16x16x32_bf16 v[84:87], v[186:189], v[220:223], v[84:87]
	v_mfma_f32_16x16x32_bf16 v[72:75], v[152:155], v[228:231], v[72:75]
	v_mfma_f32_16x16x32_bf16 v[68:71], v[186:189], v[228:231], v[68:71]
	v_mfma_f32_16x16x32_bf16 v[120:123], v[182:185], v[206:209], v[120:123]
	v_mfma_f32_16x16x32_bf16 v[116:119], v[190:193], v[206:209], v[116:119]
	v_mfma_f32_16x16x32_bf16 v[104:107], v[182:185], v[216:219], v[104:107]
	v_mfma_f32_16x16x32_bf16 v[100:103], v[190:193], v[216:219], v[100:103]
	v_mfma_f32_16x16x32_bf16 v[88:91], v[182:185], v[224:227], v[88:91]
	v_mfma_f32_16x16x32_bf16 v[84:87], v[190:193], v[224:227], v[84:87]
	v_mfma_f32_16x16x32_bf16 v[72:75], v[182:185], v[232:235], v[72:75]
	v_mfma_f32_16x16x32_bf16 v[68:71], v[190:193], v[232:235], v[68:71]
	s_setprio 0
	s_barrier
	s_mov_b32 m0, s58
	v_lshl_add_u64 v[236:237], v[214:215], 0, v[166:167]
	ds_read_b128 v[194:197], v203 offset:16384
	ds_read_b128 v[206:209], v203 offset:17408
	ds_read_b128 v[210:213], v203 offset:18432
	ds_read_b128 v[216:219], v203 offset:19456
	ds_read_b128 v[220:223], v203 offset:20480
	ds_read_b128 v[224:227], v203 offset:21504
	ds_read_b128 v[228:231], v203 offset:22528
	ds_read_b128 v[232:235], v203 offset:23552
	global_load_lds_dwordx4 v[236:237], off
	v_lshl_add_u64 v[238:239], v[214:215], 0, v[170:171]
	s_mov_b32 m0, s59
	v_lshl_add_u64 v[214:215], v[214:215], 0, s[14:15]
	s_add_i32 s13, s55, s30
	global_load_lds_dwordx4 v[238:239], off
	v_lshl_add_u64 v[240:241], v[214:215], 0, v[166:167]
	s_mov_b32 m0, s13
	v_lshl_add_u64 v[214:215], v[214:215], 0, v[170:171]
	global_load_lds_dwordx4 v[240:241], off
	s_add_i32 m0, s13, 0x2000
	v_lshl_add_u64 v[242:243], v[198:199], 0, v[164:165]
	global_load_lds_dwordx4 v[214:215], off
	s_mov_b32 m0, s31
	v_lshl_add_u64 v[244:245], v[198:199], 0, v[168:169]
	global_load_lds_dwordx4 v[242:243], off
	s_mov_b32 m0, s34
	s_nop 0
	global_load_lds_dwordx4 v[244:245], off
	s_waitcnt vmcnt(8) lgkmcnt(0)
	s_setprio 1
	s_barrier
	v_mfma_f32_16x16x32_bf16 v[64:67], v[136:139], v[194:197], v[64:67]
	v_mfma_f32_16x16x32_bf16 v[60:63], v[144:147], v[194:197], v[60:63]
	v_mfma_f32_16x16x32_bf16 v[48:51], v[136:139], v[210:213], v[48:51]
	v_mfma_f32_16x16x32_bf16 v[44:47], v[144:147], v[210:213], v[44:47]
	v_mfma_f32_16x16x32_bf16 v[32:35], v[136:139], v[220:223], v[32:35]
	v_mfma_f32_16x16x32_bf16 v[28:31], v[144:147], v[220:223], v[28:31]
	v_mfma_f32_16x16x32_bf16 v[16:19], v[136:139], v[228:231], v[16:19]
	v_mfma_f32_16x16x32_bf16 v[12:15], v[144:147], v[228:231], v[12:15]
	v_mfma_f32_16x16x32_bf16 v[64:67], v[140:143], v[206:209], v[64:67]
	v_mfma_f32_16x16x32_bf16 v[60:63], v[148:151], v[206:209], v[60:63]
	v_mfma_f32_16x16x32_bf16 v[48:51], v[140:143], v[216:219], v[48:51]
	v_mfma_f32_16x16x32_bf16 v[44:47], v[148:151], v[216:219], v[44:47]
	v_mfma_f32_16x16x32_bf16 v[32:35], v[140:143], v[224:227], v[32:35]
	v_mfma_f32_16x16x32_bf16 v[28:31], v[148:151], v[224:227], v[28:31]
	v_mfma_f32_16x16x32_bf16 v[16:19], v[140:143], v[232:235], v[16:19]
	v_mfma_f32_16x16x32_bf16 v[12:15], v[148:151], v[232:235], v[12:15]
	v_mfma_f32_16x16x32_bf16 v[56:59], v[152:155], v[194:197], v[56:59]
	v_mfma_f32_16x16x32_bf16 v[52:55], v[186:189], v[194:197], v[52:55]
	v_mfma_f32_16x16x32_bf16 v[40:43], v[152:155], v[210:213], v[40:43]
	v_mfma_f32_16x16x32_bf16 v[36:39], v[186:189], v[210:213], v[36:39]
	v_mfma_f32_16x16x32_bf16 v[24:27], v[152:155], v[220:223], v[24:27]
	v_mfma_f32_16x16x32_bf16 v[20:23], v[186:189], v[220:223], v[20:23]
	v_mfma_f32_16x16x32_bf16 v[8:11], v[152:155], v[228:231], v[8:11]
	v_mfma_f32_16x16x32_bf16 v[4:7], v[186:189], v[228:231], v[4:7]
	v_mfma_f32_16x16x32_bf16 v[56:59], v[182:185], v[206:209], v[56:59]
	v_mfma_f32_16x16x32_bf16 v[52:55], v[190:193], v[206:209], v[52:55]
	v_mfma_f32_16x16x32_bf16 v[40:43], v[182:185], v[216:219], v[40:43]
	v_mfma_f32_16x16x32_bf16 v[36:39], v[190:193], v[216:219], v[36:39]
	v_mfma_f32_16x16x32_bf16 v[24:27], v[182:185], v[224:227], v[24:27]
	v_mfma_f32_16x16x32_bf16 v[20:23], v[190:193], v[224:227], v[20:23]
	v_mfma_f32_16x16x32_bf16 v[8:11], v[182:185], v[232:235], v[8:11]
	v_mfma_f32_16x16x32_bf16 v[4:7], v[190:193], v[232:235], v[4:7]
	s_setprio 0
	s_barrier
; #define PG8_STAGE(bufoff, gbase, voff) do { _Pragma("unroll") for (int _i = 0; _i < 2; ++_i) \
;         __builtin_amdgcn_global_load_lds((const unsigned*)((const char*)(gbase) + (voff)[_i]), (PG8_LAS unsigned*)(lds + (bufoff) + ldsw + _i * 8192), 16, 0, 0); } while (0)
; #define PG8_LDA(dst, b, h) do { _Pragma("unroll") for (int m = 0; m < 4; ++m) _Pragma("unroll") for (int k = 0; k < 2; ++k) dst[m][k] = *(const PG8_LAS bf16x8*)(lds + PG8_SA(b, h) + aoff + m * 2048 + k * 1024); } while (0)
; #define PG8_LDB(dst, b, h) do { _Pragma("unroll") for (int n = 0; n < 2; ++n) _Pragma("unroll") for (int k = 0; k < 2; ++k) dst[n][k] = *(const PG8_LAS bf16x8*)(lds + PG8_SB(b, h) + boff + n * 2048 + k * 1024); } while (0)
; #define PG8_MMA(ai, bj, At, Bt) do { __builtin_amdgcn_s_setprio(1); _Pragma("unroll") for (int m = 0; m < 4; ++m) _Pragma("unroll") for (int n = 0; n < 2; ++n) _Pragma("unroll") for (int k = 0; k < 2; ++k) \
;         acc[ai][bj][m][n] = __builtin_amdgcn_mfma_f32_16x16x32_bf16(Bt[n][k], At[m][k], acc[ai][bj][m][n], 0, 0, 0); __builtin_amdgcn_s_setprio(0); } while (0)
; #define PG8_WAIT_V(n) asm volatile("s_waitcnt vmcnt(" #n ")" ::: "memory")
; #define PG8_WAIT_L(n) asm volatile("s_waitcnt lgkmcnt(" #n ")" ::: "memory")
; #define PG8_BAR __builtin_amdgcn_s_barrier()
; #define PG8_SCHED __builtin_amdgcn_sched_barrier(0)
; template <class Epi, class Sched, bool ALIGN_EPI = false, bool SP2 = false>
; __device__ __forceinline__ void gemm_phase(PG8_LAS unsigned char* lds, const Gemm g, const Sched& S, const Epi& E) {
;     ...
;             PG8_LDB(B0, 1, 0); PG8_LDB(B1, 1, 1); PG8_SCHED; PG8_LDA(At, 1, 0); PG8_STAGE(PG8_SA(0, 1), a2 + hstep, voffA);
;             PG8_WAIT_V(8); PG8_WAIT_L(0); PG8_BAR; PG8_MMA(0, 0, At, B0); PG8_MMA(0, 1, At, B1); PG8_BAR; PG8_SCHED;
	s_add_i32 s13, 0, 0x18000
	s_add_i32 s29, 0, 0x1c000
	v_add_u32_e32 v148, s13, v201
	v_add_u32_e32 v190, s29, v201
	ds_read_b128 v[136:139], v148
	ds_read_b128 v[140:143], v148 offset:1024
	ds_read_b128 v[144:147], v148 offset:2048
	ds_read_b128 v[148:151], v148 offset:3072
	ds_read_b128 v[152:155], v190
	ds_read_b128 v[182:185], v190 offset:1024
	ds_read_b128 v[186:189], v190 offset:2048
	ds_read_b128 v[190:193], v190 offset:3072
	v_lshl_add_u64 v[198:199], v[198:199], 0, s[14:15]
	s_mov_b32 m0, s35
	v_lshl_add_u64 v[246:247], v[198:199], 0, v[164:165]
	ds_read_b128 v[194:197], v203 offset:32768
	ds_read_b128 v[206:209], v203 offset:33792
	ds_read_b128 v[210:213], v203 offset:34816
	ds_read_b128 v[216:219], v203 offset:35840
	ds_read_b128 v[220:223], v203 offset:36864
	ds_read_b128 v[224:227], v203 offset:37888
	ds_read_b128 v[228:231], v203 offset:38912
	ds_read_b128 v[232:235], v203 offset:39936
	global_load_lds_dwordx4 v[246:247], off
	s_mov_b32 m0, s36
	v_lshl_add_u64 v[198:199], v[198:199], 0, v[168:169]
	global_load_lds_dwordx4 v[198:199], off
	s_waitcnt vmcnt(8) lgkmcnt(0)
	s_setprio 1
	s_barrier
	v_mfma_f32_16x16x32_bf16 v[124:127], v[136:139], v[194:197], v[124:127]
	v_mfma_f32_16x16x32_bf16 v[128:131], v[144:147], v[194:197], v[128:131]
	v_mfma_f32_16x16x32_bf16 v[112:115], v[136:139], v[210:213], v[112:115]
	v_mfma_f32_16x16x32_bf16 v[108:111], v[144:147], v[210:213], v[108:111]
	v_mfma_f32_16x16x32_bf16 v[96:99], v[136:139], v[220:223], v[96:99]
	v_mfma_f32_16x16x32_bf16 v[92:95], v[144:147], v[220:223], v[92:95]
	v_mfma_f32_16x16x32_bf16 v[80:83], v[136:139], v[228:231], v[80:83]
	v_mfma_f32_16x16x32_bf16 v[76:79], v[144:147], v[228:231], v[76:79]
	v_mfma_f32_16x16x32_bf16 v[124:127], v[140:143], v[206:209], v[124:127]
	v_mfma_f32_16x16x32_bf16 v[128:131], v[148:151], v[206:209], v[128:131]
	v_mfma_f32_16x16x32_bf16 v[112:115], v[140:143], v[216:219], v[112:115]
	v_mfma_f32_16x16x32_bf16 v[108:111], v[148:151], v[216:219], v[108:111]
	v_mfma_f32_16x16x32_bf16 v[96:99], v[140:143], v[224:227], v[96:99]
	v_mfma_f32_16x16x32_bf16 v[92:95], v[148:151], v[224:227], v[92:95]
	v_mfma_f32_16x16x32_bf16 v[80:83], v[140:143], v[232:235], v[80:83]
	v_mfma_f32_16x16x32_bf16 v[76:79], v[148:151], v[232:235], v[76:79]
	v_mfma_f32_16x16x32_bf16 v[120:123], v[152:155], v[194:197], v[120:123]
	v_mfma_f32_16x16x32_bf16 v[116:119], v[186:189], v[194:197], v[116:119]
	v_mfma_f32_16x16x32_bf16 v[104:107], v[152:155], v[210:213], v[104:107]
	v_mfma_f32_16x16x32_bf16 v[100:103], v[186:189], v[210:213], v[100:103]
	v_mfma_f32_16x16x32_bf16 v[88:91], v[152:155], v[220:223], v[88:91]
	v_mfma_f32_16x16x32_bf16 v[84:87], v[186:189], v[220:223], v[84:87]
	v_mfma_f32_16x16x32_bf16 v[72:75], v[152:155], v[228:231], v[72:75]
	v_mfma_f32_16x16x32_bf16 v[68:71], v[186:189], v[228:231], v[68:71]
	v_mfma_f32_16x16x32_bf16 v[120:123], v[182:185], v[206:209], v[120:123]
	v_mfma_f32_16x16x32_bf16 v[116:119], v[190:193], v[206:209], v[116:119]
	v_mfma_f32_16x16x32_bf16 v[104:107], v[182:185], v[216:219], v[104:107]
	v_mfma_f32_16x16x32_bf16 v[100:103], v[190:193], v[216:219], v[100:103]
	v_mfma_f32_16x16x32_bf16 v[88:91], v[182:185], v[224:227], v[88:91]
	v_mfma_f32_16x16x32_bf16 v[84:87], v[190:193], v[224:227], v[84:87]
	v_mfma_f32_16x16x32_bf16 v[72:75], v[182:185], v[232:235], v[72:75]
	v_mfma_f32_16x16x32_bf16 v[68:71], v[190:193], v[232:235], v[68:71]
	s_setprio 0
	s_barrier
; #define PG8_STAGE(bufoff, gbase, voff) do { _Pragma("unroll") for (int _i = 0; _i < 2; ++_i) \
;         __builtin_amdgcn_global_load_lds((const unsigned*)((const char*)(gbase) + (voff)[_i]), (PG8_LAS unsigned*)(lds + (bufoff) + ldsw + _i * 8192), 16, 0, 0); } while (0)
; #define PG8_LDA(dst, b, h) do { _Pragma("unroll") for (int m = 0; m < 4; ++m) _Pragma("unroll") for (int k = 0; k < 2; ++k) dst[m][k] = *(const PG8_LAS bf16x8*)(lds + PG8_SA(b, h) + aoff + m * 2048 + k * 1024); } while (0)
; #define PG8_MMA(ai, bj, At, Bt) do { __builtin_amdgcn_s_setprio(1); _Pragma("unroll") for (int m = 0; m < 4; ++m) _Pragma("unroll") for (int n = 0; n < 2; ++n) _Pragma("unroll") for (int k = 0; k < 2; ++k) \
;         acc[ai][bj][m][n] = __builtin_amdgcn_mfma_f32_16x16x32_bf16(Bt[n][k], At[m][k], acc[ai][bj][m][n], 0, 0, 0); __builtin_amdgcn_s_setprio(0); } while (0)
; #define PG8_WAIT_V(n) asm volatile("s_waitcnt vmcnt(" #n ")" ::: "memory")
; #define PG8_WAIT_L(n) asm volatile("s_waitcnt lgkmcnt(" #n ")" ::: "memory")
; #define PG8_BAR __builtin_amdgcn_s_barrier()
; #define PG8_SCHED __builtin_amdgcn_sched_barrier(0)
; template <class Epi, class Sched, bool ALIGN_EPI = false, bool SP2 = false>
; __device__ __forceinline__ void gemm_phase(PG8_LAS unsigned char* lds, const Gemm g, const Sched& S, const Epi& E) {
;     ...
;         for (int t = 0; t < nt; t += 2) {
;             const bool last = (t == nt - 2);
;             const char* a1 = cA + (size_t)(t + 1) * kstep;
;             const char* a2 = last ? nA : cA + (size_t)(t + 2) * kstep; const char* b2 = last ? nB : cB + (size_t)(t + 2) * kstep;
;             const char* a3 = a2 + kstep; const char* b3 = b2 + kstep;
;     ...
;             PG8_LDA(At, 1, 1); PG8_STAGE(PG8_SB(1, 0), b3, voffB); PG8_STAGE(PG8_SB(1, 1), b3 + hstep, voffB); PG8_STAGE(PG8_SA(1, 0), a3, voffA);
;             PG8_WAIT_V(8); PG8_WAIT_L(0); PG8_BAR; PG8_MMA(1, 0, At, B0); PG8_MMA(1, 1, At, B1); PG8_BAR; PG8_SCHED;
	s_add_i32 s13, s13, s30
	s_add_i32 m0, s13, 0xffffff80
	ds_read_b128 v[194:197], v203 offset:49152
	ds_read_b128 v[206:209], v203 offset:50176
	ds_read_b128 v[210:213], v203 offset:51200
	ds_read_b128 v[216:219], v203 offset:52224
	global_load_lds_dwordx4 v[236:237], off offset:128
	s_add_i32 m0, s13, 0x1f80
	s_add_i32 s13, s29, s30
	global_load_lds_dwordx4 v[238:239], off offset:128
	s_add_i32 m0, s13, 0xffffff80
	ds_read_b128 v[232:235], v203 offset:56320
	global_load_lds_dwordx4 v[240:241], off offset:128
	s_add_i32 m0, s13, 0x1f80
	ds_read_b128 v[228:231], v203 offset:55296
	global_load_lds_dwordx4 v[214:215], off offset:128
	s_add_i32 m0, s37, 0xffffff80
	ds_read_b128 v[224:227], v203 offset:54272
	global_load_lds_dwordx4 v[242:243], off offset:128
	s_add_i32 m0, s41, 0xffffff80
	ds_read_b128 v[220:223], v203 offset:53248
	global_load_lds_dwordx4 v[244:245], off offset:128
	s_waitcnt vmcnt(8) lgkmcnt(0)
	s_setprio 1
	s_barrier
	v_mfma_f32_16x16x32_bf16 v[64:67], v[136:139], v[194:197], v[64:67]
	v_mfma_f32_16x16x32_bf16 v[60:63], v[144:147], v[194:197], v[60:63]
	v_mfma_f32_16x16x32_bf16 v[48:51], v[136:139], v[210:213], v[48:51]
	v_mfma_f32_16x16x32_bf16 v[44:47], v[144:147], v[210:213], v[44:47]
	v_mfma_f32_16x16x32_bf16 v[32:35], v[136:139], v[220:223], v[32:35]
	v_mfma_f32_16x16x32_bf16 v[28:31], v[144:147], v[220:223], v[28:31]
	v_mfma_f32_16x16x32_bf16 v[16:19], v[136:139], v[228:231], v[16:19]
	v_mfma_f32_16x16x32_bf16 v[12:15], v[144:147], v[228:231], v[12:15]
	v_mfma_f32_16x16x32_bf16 v[64:67], v[140:143], v[206:209], v[64:67]
	v_mfma_f32_16x16x32_bf16 v[60:63], v[148:151], v[206:209], v[60:63]
	v_mfma_f32_16x16x32_bf16 v[48:51], v[140:143], v[216:219], v[48:51]
	v_mfma_f32_16x16x32_bf16 v[44:47], v[148:151], v[216:219], v[44:47]
	v_mfma_f32_16x16x32_bf16 v[32:35], v[140:143], v[224:227], v[32:35]
	v_mfma_f32_16x16x32_bf16 v[28:31], v[148:151], v[224:227], v[28:31]
	v_mfma_f32_16x16x32_bf16 v[16:19], v[140:143], v[232:235], v[16:19]
	v_mfma_f32_16x16x32_bf16 v[12:15], v[148:151], v[232:235], v[12:15]
	v_mfma_f32_16x16x32_bf16 v[56:59], v[152:155], v[194:197], v[56:59]
	v_mfma_f32_16x16x32_bf16 v[52:55], v[186:189], v[194:197], v[52:55]
	v_mfma_f32_16x16x32_bf16 v[40:43], v[152:155], v[210:213], v[40:43]
	v_mfma_f32_16x16x32_bf16 v[36:39], v[186:189], v[210:213], v[36:39]
	v_mfma_f32_16x16x32_bf16 v[24:27], v[152:155], v[220:223], v[24:27]
	v_mfma_f32_16x16x32_bf16 v[20:23], v[186:189], v[220:223], v[20:23]
	v_mfma_f32_16x16x32_bf16 v[8:11], v[152:155], v[228:231], v[8:11]
	v_mfma_f32_16x16x32_bf16 v[4:7], v[186:189], v[228:231], v[4:7]
	v_mfma_f32_16x16x32_bf16 v[56:59], v[182:185], v[206:209], v[56:59]
	v_mfma_f32_16x16x32_bf16 v[52:55], v[190:193], v[206:209], v[52:55]
	v_mfma_f32_16x16x32_bf16 v[40:43], v[182:185], v[216:219], v[40:43]
	v_mfma_f32_16x16x32_bf16 v[36:39], v[190:193], v[216:219], v[36:39]
	v_mfma_f32_16x16x32_bf16 v[24:27], v[182:185], v[224:227], v[24:27]
	v_mfma_f32_16x16x32_bf16 v[20:23], v[190:193], v[224:227], v[20:23]
	v_mfma_f32_16x16x32_bf16 v[8:11], v[182:185], v[232:235], v[8:11]
	v_mfma_f32_16x16x32_bf16 v[4:7], v[190:193], v[232:235], v[4:7]
	v_lshl_add_u64 v[132:133], v[132:133], 0, s[26:27]
	v_lshl_add_u64 v[134:135], v[134:135], 0, s[26:27]
	s_cmp_ge_i32 s12, s47
	s_cbranch_scc1 .Lrot_exit_16
	s_cmp_eq_u32 s48, s12
	v_lshl_add_u64 v[194:195], v[134:135], 0, s[22:23]
	s_cselect_b64 vcc, -1, 0
	s_add_i32 s12, s12, 2
	v_cndmask_b32_e32 v199, v195, v179, vcc
	v_cndmask_b32_e32 v198, v194, v178, vcc
	v_cndmask_b32_e32 v215, v133, v181, vcc
	v_cndmask_b32_e32 v214, v132, v180, vcc
	s_setprio 0
	s_barrier
	s_branch .LBB0_371
.Lrot_exit_16:
	s_setprio 0
	s_barrier
.LBB0_372:
	s_and_b64 vcc, exec, s[24:25]
	s_cbranch_vccz .LBB0_374
	s_barrier

; template <class Epi, class Sched, bool ALIGN_EPI = false, bool SP2 = false>
; __device__ __forceinline__ void gemm_phase(PG8_LAS unsigned char* lds, const Gemm g, const Sched& S, const Epi& E) {
;     ...
;         for (int t = 0; t < nt; t += 2) {
;             const bool last = (t == nt - 2);
;             const char* a1 = cA + (size_t)(t + 1) * kstep;
;             const char* a2 = last ? nA : cA + (size_t)(t + 2) * kstep; const char* b2 = last ? nB : cB + (size_t)(t + 2) * kstep;
;     ...
; #pragma unroll
;         for (int a = 0; a < 2; ++a)
; #pragma unroll
;             for (int b = 0; b < 2; ++b)
; #pragma unroll
;                 for (int m = 0; m < 4; ++m)
; #pragma unroll
;                     for (int n = 0; n < 2; ++n) acc[a][b][m][n] = (f32x4){0.f, 0.f, 0.f, 0.f};
.LBB0_452:
	v_mov_b32_e32 v127, 0
	s_andn2_b64 vcc, exec, s[26:27]
	v_mov_b32_e32 v126, v127
	v_mov_b32_e32 v125, v127
	v_mov_b32_e32 v124, v127
	v_mov_b32_e32 v123, v127
	v_mov_b32_e32 v122, v127
	v_mov_b32_e32 v121, v127
	v_mov_b32_e32 v120, v127
	v_mov_b32_e32 v111, v127
	v_mov_b32_e32 v110, v127
	v_mov_b32_e32 v109, v127
	v_mov_b32_e32 v108, v127
	v_mov_b32_e32 v107, v127
	v_mov_b32_e32 v106, v127
	v_mov_b32_e32 v105, v127
	v_mov_b32_e32 v104, v127
	v_mov_b32_e32 v95, v127
	v_mov_b32_e32 v94, v127
	v_mov_b32_e32 v93, v127
	v_mov_b32_e32 v92, v127
	v_mov_b32_e32 v91, v127
	v_mov_b32_e32 v90, v127
	v_mov_b32_e32 v89, v127
	v_mov_b32_e32 v88, v127
	v_mov_b32_e32 v79, v127
	v_mov_b32_e32 v78, v127
	v_mov_b32_e32 v77, v127
	v_mov_b32_e32 v76, v127
	v_mov_b32_e32 v75, v127
	v_mov_b32_e32 v74, v127
	v_mov_b32_e32 v73, v127
	v_mov_b32_e32 v72, v127
	v_mov_b32_e32 v119, v127
	v_mov_b32_e32 v118, v127
	v_mov_b32_e32 v117, v127
	v_mov_b32_e32 v116, v127
	v_mov_b32_e32 v115, v127
	v_mov_b32_e32 v114, v127
	v_mov_b32_e32 v113, v127
	v_mov_b32_e32 v112, v127
	v_mov_b32_e32 v103, v127
	v_mov_b32_e32 v102, v127
	v_mov_b32_e32 v101, v127
	v_mov_b32_e32 v100, v127
	v_mov_b32_e32 v99, v127
	v_mov_b32_e32 v98, v127
	v_mov_b32_e32 v97, v127
	v_mov_b32_e32 v96, v127
	v_mov_b32_e32 v87, v127
	v_mov_b32_e32 v86, v127
	v_mov_b32_e32 v85, v127
	v_mov_b32_e32 v84, v127
	v_mov_b32_e32 v83, v127
	v_mov_b32_e32 v82, v127
	v_mov_b32_e32 v81, v127
	v_mov_b32_e32 v80, v127
	v_mov_b32_e32 v71, v127
	v_mov_b32_e32 v70, v127
	v_mov_b32_e32 v69, v127
	v_mov_b32_e32 v68, v127
	v_mov_b32_e32 v67, v127
	v_mov_b32_e32 v66, v127
	v_mov_b32_e32 v65, v127
	v_mov_b32_e32 v64, v127
	v_mov_b32_e32 v63, v127
	v_mov_b32_e32 v62, v127
	v_mov_b32_e32 v61, v127
	v_mov_b32_e32 v60, v127
	v_mov_b32_e32 v59, v127
	v_mov_b32_e32 v58, v127
	v_mov_b32_e32 v57, v127
	v_mov_b32_e32 v56, v127
	v_mov_b32_e32 v47, v127
	v_mov_b32_e32 v46, v127
	v_mov_b32_e32 v45, v127
	v_mov_b32_e32 v44, v127
	v_mov_b32_e32 v43, v127
	v_mov_b32_e32 v42, v127
	v_mov_b32_e32 v41, v127
	v_mov_b32_e32 v40, v127
	v_mov_b32_e32 v31, v127
	v_mov_b32_e32 v30, v127
	v_mov_b32_e32 v29, v127
	v_mov_b32_e32 v28, v127
	v_mov_b32_e32 v27, v127
	v_mov_b32_e32 v26, v127
	v_mov_b32_e32 v25, v127
	v_mov_b32_e32 v24, v127
	v_mov_b32_e32 v15, v127
	v_mov_b32_e32 v14, v127
	v_mov_b32_e32 v13, v127
	v_mov_b32_e32 v12, v127
	v_mov_b32_e32 v11, v127
	v_mov_b32_e32 v10, v127
	v_mov_b32_e32 v9, v127
	v_mov_b32_e32 v8, v127
	v_mov_b32_e32 v55, v127
	v_mov_b32_e32 v54, v127
	v_mov_b32_e32 v53, v127
	v_mov_b32_e32 v52, v127
	v_mov_b32_e32 v51, v127
	v_mov_b32_e32 v50, v127
	v_mov_b32_e32 v49, v127
	v_mov_b32_e32 v48, v127
	v_mov_b32_e32 v39, v127
	s_waitcnt lgkmcnt(0)
	v_mov_b32_e32 v38, v127
	v_mov_b32_e32 v37, v127
	v_mov_b32_e32 v36, v127
	v_mov_b32_e32 v35, v127
	v_mov_b32_e32 v34, v127
	v_mov_b32_e32 v33, v127
	v_mov_b32_e32 v32, v127
	v_mov_b32_e32 v23, v127
	v_mov_b32_e32 v22, v127
	v_mov_b32_e32 v21, v127
	v_mov_b32_e32 v20, v127
	v_mov_b32_e32 v19, v127
	v_mov_b32_e32 v18, v127
	v_mov_b32_e32 v17, v127
	v_mov_b32_e32 v16, v127
	v_mov_b32_e32 v7, v127
	v_mov_b32_e32 v6, v127
	v_mov_b32_e32 v5, v127
	v_mov_b32_e32 v4, v127
	v_mov_b32_e32 v3, v127
	v_mov_b32_e32 v2, v127
	v_mov_b32_e32 v1, v127
	v_mov_b32_e32 v0, v127
	s_cbranch_vccnz .LBB0_455
	v_mov_b32_e32 v0, 0
	v_lshl_add_u64 v[128:129], v[128:129], 0, s[34:35]
	v_lshl_add_u64 v[130:131], v[130:131], 0, s[24:25]
	s_mov_b32 s12, 0
	v_mov_b32_e32 v1, v0
	v_mov_b32_e32 v2, v0
	v_mov_b32_e32 v3, v0
	v_mov_b32_e32 v4, v0
	v_mov_b32_e32 v5, v0
	v_mov_b32_e32 v6, v0
	v_mov_b32_e32 v7, v0
	v_mov_b32_e32 v16, v0
	v_mov_b32_e32 v17, v0
	v_mov_b32_e32 v18, v0
	v_mov_b32_e32 v19, v0
	v_mov_b32_e32 v20, v0
	v_mov_b32_e32 v21, v0
	v_mov_b32_e32 v22, v0
	v_mov_b32_e32 v23, v0
	v_mov_b32_e32 v32, v0
	v_mov_b32_e32 v33, v0
	v_mov_b32_e32 v34, v0
	v_mov_b32_e32 v35, v0
	v_mov_b32_e32 v36, v0
	v_mov_b32_e32 v37, v0
	v_mov_b32_e32 v38, v0
	v_mov_b32_e32 v39, v0
	v_mov_b32_e32 v48, v0
	v_mov_b32_e32 v49, v0
	v_mov_b32_e32 v50, v0
	v_mov_b32_e32 v51, v0
	v_mov_b32_e32 v52, v0
	v_mov_b32_e32 v53, v0
	v_mov_b32_e32 v54, v0
	v_mov_b32_e32 v55, v0
	v_mov_b32_e32 v8, v0
	v_mov_b32_e32 v9, v0
	v_mov_b32_e32 v10, v0
	v_mov_b32_e32 v11, v0
	v_mov_b32_e32 v12, v0
	v_mov_b32_e32 v13, v0
	v_mov_b32_e32 v14, v0
	v_mov_b32_e32 v15, v0
	v_mov_b32_e32 v24, v0
	v_mov_b32_e32 v25, v0
	v_mov_b32_e32 v26, v0
	v_mov_b32_e32 v27, v0
	v_mov_b32_e32 v28, v0
	v_mov_b32_e32 v29, v0
	v_mov_b32_e32 v30, v0
	v_mov_b32_e32 v31, v0
	v_mov_b32_e32 v40, v0
	v_mov_b32_e32 v41, v0
	v_mov_b32_e32 v42, v0
	v_mov_b32_e32 v43, v0
	v_mov_b32_e32 v44, v0
	v_mov_b32_e32 v45, v0
	v_mov_b32_e32 v46, v0
	v_mov_b32_e32 v47, v0
	v_mov_b32_e32 v56, v0
	v_mov_b32_e32 v57, v0
	v_mov_b32_e32 v58, v0
	v_mov_b32_e32 v59, v0
	v_mov_b32_e32 v60, v0
	v_mov_b32_e32 v61, v0
	v_mov_b32_e32 v62, v0
	v_mov_b32_e32 v63, v0
	v_mov_b32_e32 v64, v0
	v_mov_b32_e32 v65, v0
	v_mov_b32_e32 v66, v0
	v_mov_b32_e32 v67, v0
	v_mov_b32_e32 v68, v0
	v_mov_b32_e32 v69, v0
	v_mov_b32_e32 v70, v0
	v_mov_b32_e32 v71, v0
	v_mov_b32_e32 v80, v0
	v_mov_b32_e32 v81, v0
	v_mov_b32_e32 v82, v0
	v_mov_b32_e32 v83, v0
	v_mov_b32_e32 v84, v0
	v_mov_b32_e32 v85, v0
	v_mov_b32_e32 v86, v0
	v_mov_b32_e32 v87, v0
	v_mov_b32_e32 v96, v0
	v_mov_b32_e32 v97, v0
	v_mov_b32_e32 v98, v0
	v_mov_b32_e32 v99, v0
	v_mov_b32_e32 v100, v0
	v_mov_b32_e32 v101, v0
	v_mov_b32_e32 v102, v0
	v_mov_b32_e32 v103, v0
	v_mov_b32_e32 v112, v0
	v_mov_b32_e32 v113, v0
	v_mov_b32_e32 v114, v0
	v_mov_b32_e32 v115, v0
	v_mov_b32_e32 v116, v0
	v_mov_b32_e32 v117, v0
	v_mov_b32_e32 v118, v0
	v_mov_b32_e32 v119, v0
	v_mov_b32_e32 v72, v0
	v_mov_b32_e32 v73, v0
	v_mov_b32_e32 v74, v0
	v_mov_b32_e32 v75, v0
	v_mov_b32_e32 v76, v0
	v_mov_b32_e32 v77, v0
	v_mov_b32_e32 v78, v0
	v_mov_b32_e32 v79, v0
	v_mov_b32_e32 v88, v0
	v_mov_b32_e32 v89, v0
	v_mov_b32_e32 v90, v0
	v_mov_b32_e32 v91, v0
	v_mov_b32_e32 v92, v0
	v_mov_b32_e32 v93, v0
	v_mov_b32_e32 v94, v0
	v_mov_b32_e32 v95, v0
	v_mov_b32_e32 v104, v0
	v_mov_b32_e32 v105, v0
	v_mov_b32_e32 v106, v0
	v_mov_b32_e32 v107, v0
	v_mov_b32_e32 v108, v0
	v_mov_b32_e32 v109, v0
	v_mov_b32_e32 v110, v0
	v_mov_b32_e32 v111, v0
	v_mov_b32_e32 v120, v0
	v_mov_b32_e32 v121, v0
	v_mov_b32_e32 v122, v0
	v_mov_b32_e32 v123, v0
	v_mov_b32_e32 v124, v0
	v_mov_b32_e32 v125, v0
	v_mov_b32_e32 v126, v0
	v_mov_b32_e32 v127, v0
	s_cmp_eq_u32 s62, s12
	v_lshl_add_u64 v[200:201], v[130:131], 0, s[24:25]
	s_cselect_b64 vcc, -1, 0
	s_add_i32 s12, s12, 2
	v_cndmask_b32_e32 v209, v201, v173, vcc
	v_cndmask_b32_e32 v208, v200, v172, vcc
	v_cndmask_b32_e32 v213, v129, v175, vcc
	v_cndmask_b32_e32 v212, v128, v174, vcc
	.p2align	6
; #define PG8_STAGE(bufoff, gbase, voff) do { _Pragma("unroll") for (int _i = 0; _i < 2; ++_i) \
;         __builtin_amdgcn_global_load_lds((const unsigned*)((const char*)(gbase) + (voff)[_i]), (PG8_LAS unsigned*)(lds + (bufoff) + ldsw + _i * 8192), 16, 0, 0); } while (0)
; #define PG8_LDA(dst, b, h) do { _Pragma("unroll") for (int m = 0; m < 4; ++m) _Pragma("unroll") for (int k = 0; k < 2; ++k) dst[m][k] = *(const PG8_LAS bf16x8*)(lds + PG8_SA(b, h) + aoff + m * 2048 + k * 1024); } while (0)
; #define PG8_LDB(dst, b, h) do { _Pragma("unroll") for (int n = 0; n < 2; ++n) _Pragma("unroll") for (int k = 0; k < 2; ++k) dst[n][k] = *(const PG8_LAS bf16x8*)(lds + PG8_SB(b, h) + boff + n * 2048 + k * 1024); } while (0)
; #define PG8_MMA(ai, bj, At, Bt) do { __builtin_amdgcn_s_setprio(1); _Pragma("unroll") for (int m = 0; m < 4; ++m) _Pragma("unroll") for (int n = 0; n < 2; ++n) _Pragma("unroll") for (int k = 0; k < 2; ++k) \
;         acc[ai][bj][m][n] = __builtin_amdgcn_mfma_f32_16x16x32_bf16(Bt[n][k], At[m][k], acc[ai][bj][m][n], 0, 0, 0); __builtin_amdgcn_s_setprio(0); } while (0)
; #define PG8_WAIT_V(n) asm volatile("s_waitcnt vmcnt(" #n ")" ::: "memory")
; #define PG8_WAIT_L(n) asm volatile("s_waitcnt lgkmcnt(" #n ")" ::: "memory")
; #define PG8_BAR __builtin_amdgcn_s_barrier()
; #define PG8_SCHED __builtin_amdgcn_sched_barrier(0)
; template <class Epi, class Sched, bool ALIGN_EPI = false, bool SP2 = false>
; __device__ __forceinline__ void gemm_phase(PG8_LAS unsigned char* lds, const Gemm g, const Sched& S, const Epi& E) {
;     ...
;             PG8_LDB(B0, 0, 0); PG8_LDB(B1, 0, 1); PG8_SCHED; PG8_LDA(At, 0, 0); PG8_STAGE(PG8_SA(1, 1), a1 + hstep, voffA);
;             PG8_WAIT_V(8); PG8_WAIT_L(0); PG8_BAR; PG8_MMA(0, 0, At, B0); PG8_MMA(0, 1, At, B1); PG8_BAR; PG8_SCHED;
.LBB0_454:
	v_add_u32_e32 v165, s69, v171
	v_add_u32_e32 v167, s70, v171
	ds_read_b128 v[132:135], v165
	ds_read_b128 v[136:139], v165 offset:1024
	ds_read_b128 v[176:179], v165 offset:2048
	ds_read_b128 v[180:183], v165 offset:3072
	ds_read_b128 v[184:187], v167
	ds_read_b128 v[188:191], v167 offset:1024
	ds_read_b128 v[192:195], v167 offset:2048
	ds_read_b128 v[196:199], v167 offset:3072
	v_lshl_add_u64 v[214:215], v[130:131], 0, v[160:161]
	s_add_i32 m0, s41, 0xc000
	ds_read_b128 v[200:203], v216
	ds_read_b128 v[204:207], v216 offset:1024
	ds_read_b128 v[218:221], v216 offset:2048
	ds_read_b128 v[222:225], v216 offset:3072
	ds_read_b128 v[226:229], v216 offset:4096
	ds_read_b128 v[230:233], v216 offset:5120
	ds_read_b128 v[234:237], v216 offset:6144
	ds_read_b128 v[238:241], v216 offset:7168
	global_load_lds_dwordx4 v[214:215], off
	s_add_i32 m0, s41, 0xe000
	v_lshl_add_u64 v[214:215], v[130:131], 0, v[158:159]
	global_load_lds_dwordx4 v[214:215], off
	s_waitcnt vmcnt(8) lgkmcnt(0)
	s_setprio 1
	s_barrier
	v_mfma_f32_16x16x32_bf16 v[124:127], v[132:135], v[200:203], v[124:127]
	v_mfma_f32_16x16x32_bf16 v[120:123], v[176:179], v[200:203], v[120:123]
	v_mfma_f32_16x16x32_bf16 v[108:111], v[132:135], v[218:221], v[108:111]
	v_mfma_f32_16x16x32_bf16 v[104:107], v[176:179], v[218:221], v[104:107]
	v_mfma_f32_16x16x32_bf16 v[92:95], v[132:135], v[226:229], v[92:95]
	v_mfma_f32_16x16x32_bf16 v[88:91], v[176:179], v[226:229], v[88:91]
	v_mfma_f32_16x16x32_bf16 v[76:79], v[132:135], v[234:237], v[76:79]
	v_mfma_f32_16x16x32_bf16 v[72:75], v[176:179], v[234:237], v[72:75]
	v_mfma_f32_16x16x32_bf16 v[124:127], v[136:139], v[204:207], v[124:127]
	v_mfma_f32_16x16x32_bf16 v[120:123], v[180:183], v[204:207], v[120:123]
	v_mfma_f32_16x16x32_bf16 v[108:111], v[136:139], v[222:225], v[108:111]
	v_mfma_f32_16x16x32_bf16 v[104:107], v[180:183], v[222:225], v[104:107]
	v_mfma_f32_16x16x32_bf16 v[92:95], v[136:139], v[230:233], v[92:95]
	v_mfma_f32_16x16x32_bf16 v[88:91], v[180:183], v[230:233], v[88:91]
	v_mfma_f32_16x16x32_bf16 v[76:79], v[136:139], v[238:241], v[76:79]
	v_mfma_f32_16x16x32_bf16 v[72:75], v[180:183], v[238:241], v[72:75]
	s_cmp_gt_u32 s75, 3
	s_cbranch_scc1 .Lie_skipk0
	v_mfma_f32_16x16x32_bf16 v[116:119], v[184:187], v[200:203], v[116:119]
	v_mfma_f32_16x16x32_bf16 v[112:115], v[192:195], v[200:203], v[112:115]
	v_mfma_f32_16x16x32_bf16 v[100:103], v[184:187], v[218:221], v[100:103]
	v_mfma_f32_16x16x32_bf16 v[96:99], v[192:195], v[218:221], v[96:99]
	v_mfma_f32_16x16x32_bf16 v[84:87], v[184:187], v[226:229], v[84:87]
	v_mfma_f32_16x16x32_bf16 v[80:83], v[192:195], v[226:229], v[80:83]
	v_mfma_f32_16x16x32_bf16 v[68:71], v[184:187], v[234:237], v[68:71]
	v_mfma_f32_16x16x32_bf16 v[64:67], v[192:195], v[234:237], v[64:67]
	v_mfma_f32_16x16x32_bf16 v[116:119], v[188:191], v[204:207], v[116:119]
	v_mfma_f32_16x16x32_bf16 v[112:115], v[196:199], v[204:207], v[112:115]
	v_mfma_f32_16x16x32_bf16 v[100:103], v[188:191], v[222:225], v[100:103]
	v_mfma_f32_16x16x32_bf16 v[96:99], v[196:199], v[222:225], v[96:99]
	v_mfma_f32_16x16x32_bf16 v[84:87], v[188:191], v[230:233], v[84:87]
	v_mfma_f32_16x16x32_bf16 v[80:83], v[196:199], v[230:233], v[80:83]
	v_mfma_f32_16x16x32_bf16 v[68:71], v[188:191], v[238:241], v[68:71]
	v_mfma_f32_16x16x32_bf16 v[64:67], v[196:199], v[238:241], v[64:67]

; #define PG8_BAR __builtin_amdgcn_s_barrier()
; template <class Epi, class Sched, bool ALIGN_EPI = false, bool SP2 = false>
; __device__ __forceinline__ void gemm_phase(PG8_LAS unsigned char* lds, const Gemm g, const Sched& S, const Epi& E) {
;     ...
;         for (int t = 0; t < nt; t += 2) {
;             const bool last = (t == nt - 2);
;             const char* a1 = cA + (size_t)(t + 1) * kstep;
;             const char* a2 = last ? nA : cA + (size_t)(t + 2) * kstep; const char* b2 = last ? nB : cB + (size_t)(t + 2) * kstep;
;             const char* a3 = a2 + kstep; const char* b3 = b2 + kstep;
;     ...
;         if constexpr (ALIGN_EPI) { if (wr == 0) PG8_BAR; }
.Lie_skipk3:
	v_lshl_add_u64 v[128:129], v[128:129], 0, s[34:35]
	v_lshl_add_u64 v[130:131], v[130:131], 0, s[34:35]
	s_cmp_ge_i32 s12, s58
	s_cbranch_scc1 .Lrot_exit_15
	s_cmp_eq_u32 s62, s12
	v_lshl_add_u64 v[200:201], v[130:131], 0, s[24:25]
	s_cselect_b64 vcc, -1, 0
	s_add_i32 s12, s12, 2
	v_cndmask_b32_e32 v209, v201, v173, vcc
	v_cndmask_b32_e32 v208, v200, v172, vcc
	v_cndmask_b32_e32 v213, v129, v175, vcc
	v_cndmask_b32_e32 v212, v128, v174, vcc
	s_setprio 0
	s_barrier
	s_branch .LBB0_454
.Lrot_exit_15:
	s_setprio 0
	s_barrier
.LBB0_455:
	s_and_b64 vcc, exec, s[28:29]
	s_cbranch_vccz .LBB0_457
	s_barrier

; template <class Epi, class Sched, bool ALIGN_EPI = false, bool SP2 = false>
; __device__ __forceinline__ void gemm_phase(PG8_LAS unsigned char* lds, const Gemm g, const Sched& S, const Epi& E) {
;     ...
;         for (int t = 0; t < nt; t += 2) {
;             const bool last = (t == nt - 2);
;             const char* a1 = cA + (size_t)(t + 1) * kstep;
;             const char* a2 = last ? nA : cA + (size_t)(t + 2) * kstep; const char* b2 = last ? nB : cB + (size_t)(t + 2) * kstep;
;     ...
; #pragma unroll
;         for (int a = 0; a < 2; ++a)
; #pragma unroll
;             for (int b = 0; b < 2; ++b)
; #pragma unroll
;                 for (int m = 0; m < 4; ++m)
; #pragma unroll
;                     for (int n = 0; n < 2; ++n) acc[a][b][m][n] = (f32x4){0.f, 0.f, 0.f, 0.f};
.LBB0_633:
	v_mov_b32_e32 v143, 0
	s_andn2_b64 vcc, exec, s[26:27]
	v_mov_b32_e32 v142, v143
	v_mov_b32_e32 v141, v143
	v_mov_b32_e32 v140, v143
	v_mov_b32_e32 v139, v143
	v_mov_b32_e32 v138, v143
	v_mov_b32_e32 v137, v143
	v_mov_b32_e32 v136, v143
	v_mov_b32_e32 v119, v143
	v_mov_b32_e32 v118, v143
	v_mov_b32_e32 v117, v143
	v_mov_b32_e32 v116, v143
	v_mov_b32_e32 v115, v143
	v_mov_b32_e32 v114, v143
	v_mov_b32_e32 v113, v143
	v_mov_b32_e32 v112, v143
	v_mov_b32_e32 v103, v143
	v_mov_b32_e32 v102, v143
	v_mov_b32_e32 v101, v143
	v_mov_b32_e32 v100, v143
	v_mov_b32_e32 v99, v143
	v_mov_b32_e32 v98, v143
	v_mov_b32_e32 v97, v143
	v_mov_b32_e32 v96, v143
	v_mov_b32_e32 v79, v143
	v_mov_b32_e32 v78, v143
	v_mov_b32_e32 v77, v143
	v_mov_b32_e32 v76, v143
	v_mov_b32_e32 v75, v143
	v_mov_b32_e32 v74, v143
	v_mov_b32_e32 v73, v143
	v_mov_b32_e32 v72, v143
	v_mov_b32_e32 v127, v143
	v_mov_b32_e32 v126, v143
	v_mov_b32_e32 v125, v143
	v_mov_b32_e32 v124, v143
	v_mov_b32_e32 v123, v143
	v_mov_b32_e32 v122, v143
	v_mov_b32_e32 v121, v143
	v_mov_b32_e32 v120, v143
	v_mov_b32_e32 v111, v143
	v_mov_b32_e32 v110, v143
	v_mov_b32_e32 v109, v143
	v_mov_b32_e32 v108, v143
	v_mov_b32_e32 v107, v143
	v_mov_b32_e32 v106, v143
	v_mov_b32_e32 v105, v143
	v_mov_b32_e32 v104, v143
	v_mov_b32_e32 v87, v143
	v_mov_b32_e32 v86, v143
	v_mov_b32_e32 v85, v143
	v_mov_b32_e32 v84, v143
	v_mov_b32_e32 v83, v143
	v_mov_b32_e32 v82, v143
	v_mov_b32_e32 v81, v143
	v_mov_b32_e32 v80, v143
	v_mov_b32_e32 v71, v143
	v_mov_b32_e32 v70, v143
	v_mov_b32_e32 v69, v143
	v_mov_b32_e32 v68, v143
	v_mov_b32_e32 v67, v143
	v_mov_b32_e32 v66, v143
	v_mov_b32_e32 v65, v143
	v_mov_b32_e32 v64, v143
	v_mov_b32_e32 v63, v143
	v_mov_b32_e32 v62, v143
	v_mov_b32_e32 v61, v143
	v_mov_b32_e32 v60, v143
	v_mov_b32_e32 v59, v143
	v_mov_b32_e32 v58, v143
	v_mov_b32_e32 v57, v143
	v_mov_b32_e32 v56, v143
	v_mov_b32_e32 v47, v143
	v_mov_b32_e32 v46, v143
	v_mov_b32_e32 v45, v143
	v_mov_b32_e32 v44, v143
	v_mov_b32_e32 v43, v143
	v_mov_b32_e32 v42, v143
	v_mov_b32_e32 v41, v143
	v_mov_b32_e32 v40, v143
	v_mov_b32_e32 v31, v143
	v_mov_b32_e32 v30, v143
	v_mov_b32_e32 v29, v143
	v_mov_b32_e32 v28, v143
	v_mov_b32_e32 v27, v143
	v_mov_b32_e32 v26, v143
	v_mov_b32_e32 v25, v143
	v_mov_b32_e32 v24, v143
	v_mov_b32_e32 v15, v143
	v_mov_b32_e32 v14, v143
	v_mov_b32_e32 v13, v143
	v_mov_b32_e32 v12, v143
	v_mov_b32_e32 v11, v143
	v_mov_b32_e32 v10, v143
	v_mov_b32_e32 v9, v143
	v_mov_b32_e32 v8, v143
	v_mov_b32_e32 v55, v143
	v_mov_b32_e32 v54, v143
	v_mov_b32_e32 v53, v143
	v_mov_b32_e32 v52, v143
	v_mov_b32_e32 v51, v143
	v_mov_b32_e32 v50, v143
	v_mov_b32_e32 v49, v143
	v_mov_b32_e32 v48, v143
	v_mov_b32_e32 v39, v143
	v_mov_b32_e32 v38, v143
	v_mov_b32_e32 v37, v143
	v_mov_b32_e32 v36, v143
	v_mov_b32_e32 v35, v143
	v_mov_b32_e32 v34, v143
	v_mov_b32_e32 v33, v143
	v_mov_b32_e32 v32, v143
	v_mov_b32_e32 v23, v143
	v_mov_b32_e32 v22, v143
	v_mov_b32_e32 v21, v143
	v_mov_b32_e32 v20, v143
	v_mov_b32_e32 v19, v143
	v_mov_b32_e32 v18, v143
	v_mov_b32_e32 v17, v143
	v_mov_b32_e32 v16, v143
	v_mov_b32_e32 v7, v143
	v_mov_b32_e32 v6, v143
	v_mov_b32_e32 v5, v143
	v_mov_b32_e32 v4, v143
	v_mov_b32_e32 v3, v143
	v_mov_b32_e32 v2, v143
	v_mov_b32_e32 v1, v143
	v_mov_b32_e32 v0, v143
	s_cbranch_vccnz .LBB0_636
	v_mov_b32_e32 v0, 0
	v_lshl_add_u64 v[88:89], v[88:89], 0, s[30:31]
	v_lshl_add_u64 v[90:91], v[90:91], 0, s[24:25]
	s_mov_b32 s10, 0
	v_mov_b32_e32 v1, v0
	v_mov_b32_e32 v2, v0
	v_mov_b32_e32 v3, v0
	v_mov_b32_e32 v4, v0
	v_mov_b32_e32 v5, v0
	v_mov_b32_e32 v6, v0
	v_mov_b32_e32 v7, v0
	v_mov_b32_e32 v16, v0
	v_mov_b32_e32 v17, v0
	v_mov_b32_e32 v18, v0
	v_mov_b32_e32 v19, v0
	v_mov_b32_e32 v20, v0
	v_mov_b32_e32 v21, v0
	v_mov_b32_e32 v22, v0
	v_mov_b32_e32 v23, v0
	v_mov_b32_e32 v32, v0
	v_mov_b32_e32 v33, v0
	v_mov_b32_e32 v34, v0
	v_mov_b32_e32 v35, v0
	v_mov_b32_e32 v36, v0
	v_mov_b32_e32 v37, v0
	v_mov_b32_e32 v38, v0
	v_mov_b32_e32 v39, v0
	v_mov_b32_e32 v48, v0
	v_mov_b32_e32 v49, v0
	v_mov_b32_e32 v50, v0
	v_mov_b32_e32 v51, v0
	v_mov_b32_e32 v52, v0
	v_mov_b32_e32 v53, v0
	v_mov_b32_e32 v54, v0
	v_mov_b32_e32 v55, v0
	v_mov_b32_e32 v8, v0
	v_mov_b32_e32 v9, v0
	v_mov_b32_e32 v10, v0
	v_mov_b32_e32 v11, v0
	v_mov_b32_e32 v12, v0
	v_mov_b32_e32 v13, v0
	v_mov_b32_e32 v14, v0
	v_mov_b32_e32 v15, v0
	v_mov_b32_e32 v24, v0
	v_mov_b32_e32 v25, v0
	v_mov_b32_e32 v26, v0
	v_mov_b32_e32 v27, v0
	v_mov_b32_e32 v28, v0
	v_mov_b32_e32 v29, v0
	v_mov_b32_e32 v30, v0
	v_mov_b32_e32 v31, v0
	v_mov_b32_e32 v40, v0
	v_mov_b32_e32 v41, v0
	v_mov_b32_e32 v42, v0
	v_mov_b32_e32 v43, v0
	v_mov_b32_e32 v44, v0
	v_mov_b32_e32 v45, v0
	v_mov_b32_e32 v46, v0
	v_mov_b32_e32 v47, v0
	v_mov_b32_e32 v56, v0
	v_mov_b32_e32 v57, v0
	v_mov_b32_e32 v58, v0
	v_mov_b32_e32 v59, v0
	v_mov_b32_e32 v60, v0
	v_mov_b32_e32 v61, v0
	v_mov_b32_e32 v62, v0
	v_mov_b32_e32 v63, v0
	v_mov_b32_e32 v64, v0
	v_mov_b32_e32 v65, v0
	v_mov_b32_e32 v66, v0
	v_mov_b32_e32 v67, v0
	v_mov_b32_e32 v68, v0
	v_mov_b32_e32 v69, v0
	v_mov_b32_e32 v70, v0
	v_mov_b32_e32 v71, v0
	v_mov_b32_e32 v80, v0
	v_mov_b32_e32 v81, v0
	v_mov_b32_e32 v82, v0
	v_mov_b32_e32 v83, v0
	v_mov_b32_e32 v84, v0
	v_mov_b32_e32 v85, v0
	v_mov_b32_e32 v86, v0
	v_mov_b32_e32 v87, v0
	v_mov_b32_e32 v104, v0
	v_mov_b32_e32 v105, v0
	v_mov_b32_e32 v106, v0
	v_mov_b32_e32 v107, v0
	v_mov_b32_e32 v108, v0
	v_mov_b32_e32 v109, v0
	v_mov_b32_e32 v110, v0
	v_mov_b32_e32 v111, v0
	v_mov_b32_e32 v120, v0
	v_mov_b32_e32 v121, v0
	v_mov_b32_e32 v122, v0
	v_mov_b32_e32 v123, v0
	v_mov_b32_e32 v124, v0
	v_mov_b32_e32 v125, v0
	v_mov_b32_e32 v126, v0
	v_mov_b32_e32 v127, v0
	v_mov_b32_e32 v72, v0
	v_mov_b32_e32 v73, v0
	v_mov_b32_e32 v74, v0
	v_mov_b32_e32 v75, v0
	v_mov_b32_e32 v76, v0
	v_mov_b32_e32 v77, v0
	v_mov_b32_e32 v78, v0
	v_mov_b32_e32 v79, v0
	v_mov_b32_e32 v96, v0
	v_mov_b32_e32 v97, v0
	v_mov_b32_e32 v98, v0
	v_mov_b32_e32 v99, v0
	v_mov_b32_e32 v100, v0
	v_mov_b32_e32 v101, v0
	v_mov_b32_e32 v102, v0
	v_mov_b32_e32 v103, v0
	v_mov_b32_e32 v112, v0
	v_mov_b32_e32 v113, v0
	v_mov_b32_e32 v114, v0
	v_mov_b32_e32 v115, v0
	v_mov_b32_e32 v116, v0
	v_mov_b32_e32 v117, v0
	v_mov_b32_e32 v118, v0
	v_mov_b32_e32 v119, v0
	v_mov_b32_e32 v136, v0
	v_mov_b32_e32 v137, v0
	v_mov_b32_e32 v138, v0
	v_mov_b32_e32 v139, v0
	v_mov_b32_e32 v140, v0
	v_mov_b32_e32 v141, v0
	v_mov_b32_e32 v142, v0
	v_mov_b32_e32 v143, v0
	s_cmp_eq_u32 s58, s10
	v_lshl_add_u64 v[198:199], v[90:91], 0, s[24:25]
	s_cselect_b64 vcc, -1, 0
	s_add_i32 s10, s10, 2
	v_cndmask_b32_e32 v207, v199, v187, vcc
	v_cndmask_b32_e32 v206, v198, v186, vcc
	v_cndmask_b32_e32 v215, v89, v189, vcc
	v_cndmask_b32_e32 v214, v88, v188, vcc
	.p2align	6
; #define PG8_STAGE(bufoff, gbase, voff) do { _Pragma("unroll") for (int _i = 0; _i < 2; ++_i) \
;         __builtin_amdgcn_global_load_lds((const unsigned*)((const char*)(gbase) + (voff)[_i]), (PG8_LAS unsigned*)(lds + (bufoff) + ldsw + _i * 8192), 16, 0, 0); } while (0)
; #define PG8_LDA(dst, b, h) do { _Pragma("unroll") for (int m = 0; m < 4; ++m) _Pragma("unroll") for (int k = 0; k < 2; ++k) dst[m][k] = *(const PG8_LAS bf16x8*)(lds + PG8_SA(b, h) + aoff + m * 2048 + k * 1024); } while (0)
; #define PG8_LDB(dst, b, h) do { _Pragma("unroll") for (int n = 0; n < 2; ++n) _Pragma("unroll") for (int k = 0; k < 2; ++k) dst[n][k] = *(const PG8_LAS bf16x8*)(lds + PG8_SB(b, h) + boff + n * 2048 + k * 1024); } while (0)
; #define PG8_MMA(ai, bj, At, Bt) do { __builtin_amdgcn_s_setprio(1); _Pragma("unroll") for (int m = 0; m < 4; ++m) _Pragma("unroll") for (int n = 0; n < 2; ++n) _Pragma("unroll") for (int k = 0; k < 2; ++k) \
;         acc[ai][bj][m][n] = __builtin_amdgcn_mfma_f32_16x16x32_bf16(Bt[n][k], At[m][k], acc[ai][bj][m][n], 0, 0, 0); __builtin_amdgcn_s_setprio(0); } while (0)
; #define PG8_WAIT_V(n) asm volatile("s_waitcnt vmcnt(" #n ")" ::: "memory")
; #define PG8_WAIT_L(n) asm volatile("s_waitcnt lgkmcnt(" #n ")" ::: "memory")
; #define PG8_BAR __builtin_amdgcn_s_barrier()
; #define PG8_SCHED __builtin_amdgcn_sched_barrier(0)
; template <class Epi, class Sched, bool ALIGN_EPI = false, bool SP2 = false>
; __device__ __forceinline__ void gemm_phase(PG8_LAS unsigned char* lds, const Gemm g, const Sched& S, const Epi& E) {
;     ...
;             PG8_LDB(B0, 0, 0); PG8_LDB(B1, 0, 1); PG8_SCHED; PG8_LDA(At, 0, 0); PG8_STAGE(PG8_SA(1, 1), a1 + hstep, voffA);
;             PG8_WAIT_V(8); PG8_WAIT_L(0); PG8_BAR; PG8_MMA(0, 0, At, B0); PG8_MMA(0, 1, At, B1); PG8_BAR; PG8_SCHED;
;             PG8_LDA(At, 0, 1); PG8_STAGE(PG8_SB(0, 0), b2, voffB); PG8_STAGE(PG8_SB(0, 1), b2 + hstep, voffB); PG8_STAGE(PG8_SA(0, 0), a2, voffA);
;             PG8_WAIT_V(8); PG8_WAIT_L(0); PG8_BAR; PG8_MMA(1, 0, At, B0); PG8_MMA(1, 1, At, B1); PG8_BAR; PG8_SCHED;
.LBB0_635:
	v_add_u32_e32 v144, s64, v209
	v_add_u32_e32 v194, s65, v209
	ds_read_b128 v[92:95], v144
	ds_read_b128 v[128:131], v144 offset:1024
	ds_read_b128 v[132:135], v144 offset:2048
	ds_read_b128 v[144:147], v144 offset:3072
	ds_read_b128 v[148:151], v194
	ds_read_b128 v[152:155], v194 offset:1024
	ds_read_b128 v[190:193], v194 offset:2048
	ds_read_b128 v[194:197], v194 offset:3072
	v_lshl_add_u64 v[238:239], v[90:91], 0, v[180:181]
	s_add_i32 m0, s41, 0xc000
	ds_read_b128 v[198:201], v216
	ds_read_b128 v[202:205], v216 offset:1024
	ds_read_b128 v[210:213], v216 offset:2048
	ds_read_b128 v[218:221], v216 offset:3072
	ds_read_b128 v[222:225], v216 offset:4096
	ds_read_b128 v[226:229], v216 offset:5120
	ds_read_b128 v[230:233], v216 offset:6144
	ds_read_b128 v[234:237], v216 offset:7168
	global_load_lds_dwordx4 v[238:239], off
	s_add_i32 m0, s41, 0xe000
	v_lshl_add_u64 v[238:239], v[90:91], 0, v[178:179]
	global_load_lds_dwordx4 v[238:239], off
	s_waitcnt vmcnt(8) lgkmcnt(0)
	s_setprio 1
	s_barrier
	v_mfma_f32_16x16x32_bf16 v[140:143], v[92:95], v[198:201], v[140:143]
	v_mfma_f32_16x16x32_bf16 v[136:139], v[132:135], v[198:201], v[136:139]
	v_mfma_f32_16x16x32_bf16 v[116:119], v[92:95], v[210:213], v[116:119]
	v_mfma_f32_16x16x32_bf16 v[112:115], v[132:135], v[210:213], v[112:115]
	v_mfma_f32_16x16x32_bf16 v[100:103], v[92:95], v[222:225], v[100:103]
	v_mfma_f32_16x16x32_bf16 v[96:99], v[132:135], v[222:225], v[96:99]
	v_mfma_f32_16x16x32_bf16 v[76:79], v[92:95], v[230:233], v[76:79]
	v_mfma_f32_16x16x32_bf16 v[72:75], v[132:135], v[230:233], v[72:75]
	v_mfma_f32_16x16x32_bf16 v[140:143], v[128:131], v[202:205], v[140:143]
	v_mfma_f32_16x16x32_bf16 v[136:139], v[144:147], v[202:205], v[136:139]
	v_mfma_f32_16x16x32_bf16 v[116:119], v[128:131], v[218:221], v[116:119]
	v_mfma_f32_16x16x32_bf16 v[112:115], v[144:147], v[218:221], v[112:115]
	v_mfma_f32_16x16x32_bf16 v[100:103], v[128:131], v[226:229], v[100:103]
	v_mfma_f32_16x16x32_bf16 v[96:99], v[144:147], v[226:229], v[96:99]
	v_mfma_f32_16x16x32_bf16 v[76:79], v[128:131], v[234:237], v[76:79]
	v_mfma_f32_16x16x32_bf16 v[72:75], v[144:147], v[234:237], v[72:75]
	v_mfma_f32_16x16x32_bf16 v[124:127], v[148:151], v[198:201], v[124:127]
	v_mfma_f32_16x16x32_bf16 v[120:123], v[190:193], v[198:201], v[120:123]
	v_mfma_f32_16x16x32_bf16 v[108:111], v[148:151], v[210:213], v[108:111]
	v_mfma_f32_16x16x32_bf16 v[104:107], v[190:193], v[210:213], v[104:107]
	v_mfma_f32_16x16x32_bf16 v[84:87], v[148:151], v[222:225], v[84:87]
	v_mfma_f32_16x16x32_bf16 v[80:83], v[190:193], v[222:225], v[80:83]
	v_mfma_f32_16x16x32_bf16 v[68:71], v[148:151], v[230:233], v[68:71]
	v_mfma_f32_16x16x32_bf16 v[64:67], v[190:193], v[230:233], v[64:67]
	v_mfma_f32_16x16x32_bf16 v[124:127], v[152:155], v[202:205], v[124:127]
	v_mfma_f32_16x16x32_bf16 v[120:123], v[194:197], v[202:205], v[120:123]
	v_mfma_f32_16x16x32_bf16 v[108:111], v[152:155], v[218:221], v[108:111]
	v_mfma_f32_16x16x32_bf16 v[104:107], v[194:197], v[218:221], v[104:107]
	v_mfma_f32_16x16x32_bf16 v[84:87], v[152:155], v[226:229], v[84:87]
	v_mfma_f32_16x16x32_bf16 v[80:83], v[194:197], v[226:229], v[80:83]
	v_mfma_f32_16x16x32_bf16 v[68:71], v[152:155], v[234:237], v[68:71]
	v_mfma_f32_16x16x32_bf16 v[64:67], v[194:197], v[234:237], v[64:67]
	s_setprio 0
	s_barrier
	s_add_i32 s11, s64, s35
	v_lshl_add_u64 v[238:239], v[214:215], 0, v[168:169]
	s_mov_b32 m0, s11
	ds_read_b128 v[198:201], v216 offset:16384
	ds_read_b128 v[202:205], v216 offset:17408
	ds_read_b128 v[210:213], v216 offset:18432
	ds_read_b128 v[218:221], v216 offset:19456
	ds_read_b128 v[222:225], v216 offset:20480
	ds_read_b128 v[226:229], v216 offset:21504
	ds_read_b128 v[230:233], v216 offset:22528
	ds_read_b128 v[234:237], v216 offset:23552
	global_load_lds_dwordx4 v[238:239], off
	v_lshl_add_u64 v[240:241], v[214:215], 0, v[172:173]
	s_add_i32 m0, s11, 0x2000
	v_lshl_add_u64 v[214:215], v[214:215], 0, s[18:19]
	s_add_i32 s11, s65, s35
	global_load_lds_dwordx4 v[240:241], off
	v_lshl_add_u64 v[242:243], v[214:215], 0, v[168:169]
	s_mov_b32 m0, s11
	v_lshl_add_u64 v[214:215], v[214:215], 0, v[172:173]
	global_load_lds_dwordx4 v[242:243], off
	s_add_i32 m0, s11, 0x2000
	v_lshl_add_u64 v[244:245], v[206:207], 0, v[166:167]
	global_load_lds_dwordx4 v[214:215], off
	s_mov_b32 m0, s41
	v_lshl_add_u64 v[246:247], v[206:207], 0, v[170:171]
	global_load_lds_dwordx4 v[244:245], off
	s_mov_b32 m0, s50
	s_nop 0
	global_load_lds_dwordx4 v[246:247], off
	s_waitcnt vmcnt(8) lgkmcnt(0)
	s_setprio 1
	s_barrier
	v_mfma_f32_16x16x32_bf16 v[60:63], v[92:95], v[198:201], v[60:63]
	v_mfma_f32_16x16x32_bf16 v[56:59], v[132:135], v[198:201], v[56:59]
	v_mfma_f32_16x16x32_bf16 v[44:47], v[92:95], v[210:213], v[44:47]
	v_mfma_f32_16x16x32_bf16 v[40:43], v[132:135], v[210:213], v[40:43]
	v_mfma_f32_16x16x32_bf16 v[28:31], v[92:95], v[222:225], v[28:31]
	v_mfma_f32_16x16x32_bf16 v[24:27], v[132:135], v[222:225], v[24:27]
	v_mfma_f32_16x16x32_bf16 v[12:15], v[92:95], v[230:233], v[12:15]
	v_mfma_f32_16x16x32_bf16 v[8:11], v[132:135], v[230:233], v[8:11]
	v_mfma_f32_16x16x32_bf16 v[60:63], v[128:131], v[202:205], v[60:63]
	v_mfma_f32_16x16x32_bf16 v[56:59], v[144:147], v[202:205], v[56:59]
	v_mfma_f32_16x16x32_bf16 v[44:47], v[128:131], v[218:221], v[44:47]
	v_mfma_f32_16x16x32_bf16 v[40:43], v[144:147], v[218:221], v[40:43]
	v_mfma_f32_16x16x32_bf16 v[28:31], v[128:131], v[226:229], v[28:31]
	v_mfma_f32_16x16x32_bf16 v[24:27], v[144:147], v[226:229], v[24:27]
	v_mfma_f32_16x16x32_bf16 v[12:15], v[128:131], v[234:237], v[12:15]
	v_mfma_f32_16x16x32_bf16 v[8:11], v[144:147], v[234:237], v[8:11]
	v_mfma_f32_16x16x32_bf16 v[52:55], v[148:151], v[198:201], v[52:55]
	v_mfma_f32_16x16x32_bf16 v[48:51], v[190:193], v[198:201], v[48:51]
	v_mfma_f32_16x16x32_bf16 v[36:39], v[148:151], v[210:213], v[36:39]
	v_mfma_f32_16x16x32_bf16 v[32:35], v[190:193], v[210:213], v[32:35]
	v_mfma_f32_16x16x32_bf16 v[20:23], v[148:151], v[222:225], v[20:23]
	v_mfma_f32_16x16x32_bf16 v[16:19], v[190:193], v[222:225], v[16:19]
	v_mfma_f32_16x16x32_bf16 v[4:7], v[148:151], v[230:233], v[4:7]
	v_mfma_f32_16x16x32_bf16 v[0:3], v[190:193], v[230:233], v[0:3]
	v_mfma_f32_16x16x32_bf16 v[52:55], v[152:155], v[202:205], v[52:55]
	v_mfma_f32_16x16x32_bf16 v[48:51], v[194:197], v[202:205], v[48:51]
	v_mfma_f32_16x16x32_bf16 v[36:39], v[152:155], v[218:221], v[36:39]
	v_mfma_f32_16x16x32_bf16 v[32:35], v[194:197], v[218:221], v[32:35]
	v_mfma_f32_16x16x32_bf16 v[20:23], v[152:155], v[226:229], v[20:23]
	v_mfma_f32_16x16x32_bf16 v[16:19], v[194:197], v[226:229], v[16:19]
	v_mfma_f32_16x16x32_bf16 v[4:7], v[152:155], v[234:237], v[4:7]
	v_mfma_f32_16x16x32_bf16 v[0:3], v[194:197], v[234:237], v[0:3]
	s_setprio 0
	s_barrier
; #define PG8_STAGE(bufoff, gbase, voff) do { _Pragma("unroll") for (int _i = 0; _i < 2; ++_i) \
;         __builtin_amdgcn_global_load_lds((const unsigned*)((const char*)(gbase) + (voff)[_i]), (PG8_LAS unsigned*)(lds + (bufoff) + ldsw + _i * 8192), 16, 0, 0); } while (0)
; #define PG8_LDA(dst, b, h) do { _Pragma("unroll") for (int m = 0; m < 4; ++m) _Pragma("unroll") for (int k = 0; k < 2; ++k) dst[m][k] = *(const PG8_LAS bf16x8*)(lds + PG8_SA(b, h) + aoff + m * 2048 + k * 1024); } while (0)
; #define PG8_LDB(dst, b, h) do { _Pragma("unroll") for (int n = 0; n < 2; ++n) _Pragma("unroll") for (int k = 0; k < 2; ++k) dst[n][k] = *(const PG8_LAS bf16x8*)(lds + PG8_SB(b, h) + boff + n * 2048 + k * 1024); } while (0)
; #define PG8_MMA(ai, bj, At, Bt) do { __builtin_amdgcn_s_setprio(1); _Pragma("unroll") for (int m = 0; m < 4; ++m) _Pragma("unroll") for (int n = 0; n < 2; ++n) _Pragma("unroll") for (int k = 0; k < 2; ++k) \
;         acc[ai][bj][m][n] = __builtin_amdgcn_mfma_f32_16x16x32_bf16(Bt[n][k], At[m][k], acc[ai][bj][m][n], 0, 0, 0); __builtin_amdgcn_s_setprio(0); } while (0)
; #define PG8_WAIT_V(n) asm volatile("s_waitcnt vmcnt(" #n ")" ::: "memory")
; #define PG8_WAIT_L(n) asm volatile("s_waitcnt lgkmcnt(" #n ")" ::: "memory")
; #define PG8_BAR __builtin_amdgcn_s_barrier()
; #define PG8_SCHED __builtin_amdgcn_sched_barrier(0)
; template <class Epi, class Sched, bool ALIGN_EPI = false, bool SP2 = false>
; __device__ __forceinline__ void gemm_phase(PG8_LAS unsigned char* lds, const Gemm g, const Sched& S, const Epi& E) {
;     ...
;             PG8_LDB(B0, 1, 0); PG8_LDB(B1, 1, 1); PG8_SCHED; PG8_LDA(At, 1, 0); PG8_STAGE(PG8_SA(0, 1), a2 + hstep, voffA);
;             PG8_WAIT_V(8); PG8_WAIT_L(0); PG8_BAR; PG8_MMA(0, 0, At, B0); PG8_MMA(0, 1, At, B1); PG8_BAR; PG8_SCHED;
;             PG8_LDA(At, 1, 1); PG8_STAGE(PG8_SB(1, 0), b3, voffB); PG8_STAGE(PG8_SB(1, 1), b3 + hstep, voffB); PG8_STAGE(PG8_SA(1, 0), a3, voffA);
;             PG8_WAIT_V(8); PG8_WAIT_L(0); PG8_BAR; PG8_MMA(1, 0, At, B0); PG8_MMA(1, 1, At, B1); PG8_BAR; PG8_SCHED;
	s_add_i32 s11, 0, 0x18000
	s_add_i32 s14, 0, 0x1c000
	v_add_u32_e32 v144, s11, v209
	v_add_u32_e32 v194, s14, v209
	ds_read_b128 v[92:95], v144
	ds_read_b128 v[128:131], v144 offset:1024
	ds_read_b128 v[132:135], v144 offset:2048
	ds_read_b128 v[144:147], v144 offset:3072
	ds_read_b128 v[148:151], v194
	ds_read_b128 v[152:155], v194 offset:1024
	ds_read_b128 v[190:193], v194 offset:2048
	ds_read_b128 v[194:197], v194 offset:3072
	v_lshl_add_u64 v[206:207], v[206:207], 0, s[18:19]
	s_mov_b32 m0, s51
	v_lshl_add_u64 v[248:249], v[206:207], 0, v[166:167]
	ds_read_b128 v[198:201], v216 offset:32768
	ds_read_b128 v[202:205], v216 offset:33792
	ds_read_b128 v[210:213], v216 offset:34816
	ds_read_b128 v[218:221], v216 offset:35840
	ds_read_b128 v[222:225], v216 offset:36864
	ds_read_b128 v[226:229], v216 offset:37888
	ds_read_b128 v[230:233], v216 offset:38912
	ds_read_b128 v[234:237], v216 offset:39936
	global_load_lds_dwordx4 v[248:249], off
	s_mov_b32 m0, s52
	v_lshl_add_u64 v[206:207], v[206:207], 0, v[170:171]
	global_load_lds_dwordx4 v[206:207], off
	s_waitcnt vmcnt(8) lgkmcnt(0)
	s_setprio 1
	s_barrier
	v_mfma_f32_16x16x32_bf16 v[140:143], v[92:95], v[198:201], v[140:143]
	v_mfma_f32_16x16x32_bf16 v[136:139], v[132:135], v[198:201], v[136:139]
	v_mfma_f32_16x16x32_bf16 v[116:119], v[92:95], v[210:213], v[116:119]
	v_mfma_f32_16x16x32_bf16 v[112:115], v[132:135], v[210:213], v[112:115]
	v_mfma_f32_16x16x32_bf16 v[100:103], v[92:95], v[222:225], v[100:103]
	v_mfma_f32_16x16x32_bf16 v[96:99], v[132:135], v[222:225], v[96:99]
	v_mfma_f32_16x16x32_bf16 v[76:79], v[92:95], v[230:233], v[76:79]
	v_mfma_f32_16x16x32_bf16 v[72:75], v[132:135], v[230:233], v[72:75]
	v_mfma_f32_16x16x32_bf16 v[140:143], v[128:131], v[202:205], v[140:143]
	v_mfma_f32_16x16x32_bf16 v[136:139], v[144:147], v[202:205], v[136:139]
	v_mfma_f32_16x16x32_bf16 v[116:119], v[128:131], v[218:221], v[116:119]
	v_mfma_f32_16x16x32_bf16 v[112:115], v[144:147], v[218:221], v[112:115]
	v_mfma_f32_16x16x32_bf16 v[100:103], v[128:131], v[226:229], v[100:103]
	v_mfma_f32_16x16x32_bf16 v[96:99], v[144:147], v[226:229], v[96:99]
	v_mfma_f32_16x16x32_bf16 v[76:79], v[128:131], v[234:237], v[76:79]
	v_mfma_f32_16x16x32_bf16 v[72:75], v[144:147], v[234:237], v[72:75]
	v_mfma_f32_16x16x32_bf16 v[124:127], v[148:151], v[198:201], v[124:127]
	v_mfma_f32_16x16x32_bf16 v[120:123], v[190:193], v[198:201], v[120:123]
	v_mfma_f32_16x16x32_bf16 v[108:111], v[148:151], v[210:213], v[108:111]
	v_mfma_f32_16x16x32_bf16 v[104:107], v[190:193], v[210:213], v[104:107]
	v_mfma_f32_16x16x32_bf16 v[84:87], v[148:151], v[222:225], v[84:87]
	v_mfma_f32_16x16x32_bf16 v[80:83], v[190:193], v[222:225], v[80:83]
	v_mfma_f32_16x16x32_bf16 v[68:71], v[148:151], v[230:233], v[68:71]
	v_mfma_f32_16x16x32_bf16 v[64:67], v[190:193], v[230:233], v[64:67]
	v_mfma_f32_16x16x32_bf16 v[124:127], v[152:155], v[202:205], v[124:127]
	v_mfma_f32_16x16x32_bf16 v[120:123], v[194:197], v[202:205], v[120:123]
	v_mfma_f32_16x16x32_bf16 v[108:111], v[152:155], v[218:221], v[108:111]
	v_mfma_f32_16x16x32_bf16 v[104:107], v[194:197], v[218:221], v[104:107]
	v_mfma_f32_16x16x32_bf16 v[84:87], v[152:155], v[226:229], v[84:87]
	v_mfma_f32_16x16x32_bf16 v[80:83], v[194:197], v[226:229], v[80:83]
	v_mfma_f32_16x16x32_bf16 v[68:71], v[152:155], v[234:237], v[68:71]
	v_mfma_f32_16x16x32_bf16 v[64:67], v[194:197], v[234:237], v[64:67]
	s_setprio 0
	s_barrier
	s_add_i32 s11, s11, s35
	s_add_i32 m0, s11, 0xffffff80
	ds_read_b128 v[198:201], v216 offset:49152
	ds_read_b128 v[202:205], v216 offset:50176
	ds_read_b128 v[210:213], v216 offset:51200
	ds_read_b128 v[218:221], v216 offset:52224
	global_load_lds_dwordx4 v[238:239], off offset:128
	s_add_i32 m0, s11, 0x1f80
	s_add_i32 s11, s14, s35
	global_load_lds_dwordx4 v[240:241], off offset:128
	s_add_i32 m0, s11, 0xffffff80
	ds_read_b128 v[234:237], v216 offset:56320
	global_load_lds_dwordx4 v[242:243], off offset:128
	s_add_i32 m0, s11, 0x1f80
	ds_read_b128 v[230:233], v216 offset:55296
	global_load_lds_dwordx4 v[214:215], off offset:128
	s_add_i32 m0, s54, 0xffffff80
	ds_read_b128 v[226:229], v216 offset:54272
	global_load_lds_dwordx4 v[244:245], off offset:128
	s_add_i32 m0, s55, 0xffffff80
	ds_read_b128 v[222:225], v216 offset:53248
	global_load_lds_dwordx4 v[246:247], off offset:128
	s_waitcnt vmcnt(8) lgkmcnt(0)
	s_setprio 1
	s_barrier
	v_mfma_f32_16x16x32_bf16 v[60:63], v[92:95], v[198:201], v[60:63]
	v_mfma_f32_16x16x32_bf16 v[56:59], v[132:135], v[198:201], v[56:59]
	v_mfma_f32_16x16x32_bf16 v[44:47], v[92:95], v[210:213], v[44:47]
	v_mfma_f32_16x16x32_bf16 v[40:43], v[132:135], v[210:213], v[40:43]
	v_mfma_f32_16x16x32_bf16 v[28:31], v[92:95], v[222:225], v[28:31]
	v_mfma_f32_16x16x32_bf16 v[24:27], v[132:135], v[222:225], v[24:27]
	v_mfma_f32_16x16x32_bf16 v[12:15], v[92:95], v[230:233], v[12:15]
	v_mfma_f32_16x16x32_bf16 v[8:11], v[132:135], v[230:233], v[8:11]
	v_mfma_f32_16x16x32_bf16 v[60:63], v[128:131], v[202:205], v[60:63]
	v_mfma_f32_16x16x32_bf16 v[56:59], v[144:147], v[202:205], v[56:59]
	v_mfma_f32_16x16x32_bf16 v[44:47], v[128:131], v[218:221], v[44:47]
	v_mfma_f32_16x16x32_bf16 v[40:43], v[144:147], v[218:221], v[40:43]
	v_mfma_f32_16x16x32_bf16 v[28:31], v[128:131], v[226:229], v[28:31]
	v_mfma_f32_16x16x32_bf16 v[24:27], v[144:147], v[226:229], v[24:27]
	v_mfma_f32_16x16x32_bf16 v[12:15], v[128:131], v[234:237], v[12:15]
	v_mfma_f32_16x16x32_bf16 v[8:11], v[144:147], v[234:237], v[8:11]
	v_mfma_f32_16x16x32_bf16 v[52:55], v[148:151], v[198:201], v[52:55]
	v_mfma_f32_16x16x32_bf16 v[48:51], v[190:193], v[198:201], v[48:51]
	v_mfma_f32_16x16x32_bf16 v[36:39], v[148:151], v[210:213], v[36:39]
	v_mfma_f32_16x16x32_bf16 v[32:35], v[190:193], v[210:213], v[32:35]
	v_mfma_f32_16x16x32_bf16 v[20:23], v[148:151], v[222:225], v[20:23]
	v_mfma_f32_16x16x32_bf16 v[16:19], v[190:193], v[222:225], v[16:19]
	v_mfma_f32_16x16x32_bf16 v[4:7], v[148:151], v[230:233], v[4:7]
	v_mfma_f32_16x16x32_bf16 v[0:3], v[190:193], v[230:233], v[0:3]
	v_mfma_f32_16x16x32_bf16 v[52:55], v[152:155], v[202:205], v[52:55]
	v_mfma_f32_16x16x32_bf16 v[48:51], v[194:197], v[202:205], v[48:51]
	v_mfma_f32_16x16x32_bf16 v[36:39], v[152:155], v[218:221], v[36:39]
	v_mfma_f32_16x16x32_bf16 v[32:35], v[194:197], v[218:221], v[32:35]
	v_mfma_f32_16x16x32_bf16 v[20:23], v[152:155], v[226:229], v[20:23]
	v_mfma_f32_16x16x32_bf16 v[16:19], v[194:197], v[226:229], v[16:19]
	v_mfma_f32_16x16x32_bf16 v[4:7], v[152:155], v[234:237], v[4:7]
	v_mfma_f32_16x16x32_bf16 v[0:3], v[194:197], v[234:237], v[0:3]
	v_lshl_add_u64 v[88:89], v[88:89], 0, s[30:31]
	v_lshl_add_u64 v[90:91], v[90:91], 0, s[30:31]
	s_cmp_ge_i32 s10, s57
	s_cbranch_scc1 .Lrot_exit_14
	s_cmp_eq_u32 s58, s10
	v_lshl_add_u64 v[198:199], v[90:91], 0, s[24:25]
	s_cselect_b64 vcc, -1, 0
	s_add_i32 s10, s10, 2
	v_cndmask_b32_e32 v207, v199, v187, vcc
	v_cndmask_b32_e32 v206, v198, v186, vcc
	v_cndmask_b32_e32 v215, v89, v189, vcc
	v_cndmask_b32_e32 v214, v88, v188, vcc
	s_setprio 0
	s_barrier
	s_branch .LBB0_635
; #define PG8_MMA(ai, bj, At, Bt) do { __builtin_amdgcn_s_setprio(1); _Pragma("unroll") for (int m = 0; m < 4; ++m) _Pragma("unroll") for (int n = 0; n < 2; ++n) _Pragma("unroll") for (int k = 0; k < 2; ++k) \
;         acc[ai][bj][m][n] = __builtin_amdgcn_mfma_f32_16x16x32_bf16(Bt[n][k], At[m][k], acc[ai][bj][m][n], 0, 0, 0); __builtin_amdgcn_s_setprio(0); } while (0)
; #define PG8_WAIT_V(n) asm volatile("s_waitcnt vmcnt(" #n ")" ::: "memory")
; #define PG8_WAIT_L(n) asm volatile("s_waitcnt lgkmcnt(" #n ")" ::: "memory")
; #define PG8_BAR __builtin_amdgcn_s_barrier()
; #define PG8_SCHED __builtin_amdgcn_sched_barrier(0)
; template <class Epi, class Sched, bool ALIGN_EPI = false, bool SP2 = false>
; __device__ __forceinline__ void gemm_phase(PG8_LAS unsigned char* lds, const Gemm g, const Sched& S, const Epi& E) {
;     ...
;             PG8_WAIT_V(8); PG8_WAIT_L(0); PG8_BAR; PG8_MMA(1, 0, At, B0); PG8_MMA(1, 1, At, B1); PG8_BAR; PG8_SCHED;
;     ...
;         if constexpr (ALIGN_EPI) { if (wr == 0) PG8_BAR; }
.Lrot_exit_14:
	s_setprio 0
	s_barrier
.LBB0_636:
	s_and_b64 vcc, exec, s[28:29]
	s_cbranch_vccz .LBB0_638
	s_barrier

; template <class Epi, class Sched, bool ALIGN_EPI = false, bool SP2 = false>
; __device__ __forceinline__ void gemm_phase(PG8_LAS unsigned char* lds, const Gemm g, const Sched& S, const Epi& E) {
;     ...
;         for (int t = 0; t < nt; t += 2) {
;             const bool last = (t == nt - 2);
;             const char* a1 = cA + (size_t)(t + 1) * kstep;
;             const char* a2 = last ? nA : cA + (size_t)(t + 2) * kstep; const char* b2 = last ? nB : cB + (size_t)(t + 2) * kstep;
;     ...
; #pragma unroll
;         for (int a = 0; a < 2; ++a)
; #pragma unroll
;             for (int b = 0; b < 2; ++b)
; #pragma unroll
;                 for (int m = 0; m < 4; ++m)
; #pragma unroll
;                     for (int n = 0; n < 2; ++n) acc[a][b][m][n] = (f32x4){0.f, 0.f, 0.f, 0.f};
.LBB0_720:
	v_mov_b32_e32 v135, 0
	s_andn2_b64 vcc, exec, s[20:21]
	v_mov_b32_e32 v134, v135
	v_mov_b32_e32 v133, v135
	v_mov_b32_e32 v132, v135
	v_mov_b32_e32 v131, v135
	v_mov_b32_e32 v130, v135
	v_mov_b32_e32 v129, v135
	v_mov_b32_e32 v128, v135
	v_mov_b32_e32 v111, v135
	v_mov_b32_e32 v110, v135
	v_mov_b32_e32 v109, v135
	v_mov_b32_e32 v108, v135
	v_mov_b32_e32 v107, v135
	v_mov_b32_e32 v106, v135
	v_mov_b32_e32 v105, v135
	v_mov_b32_e32 v104, v135
	v_mov_b32_e32 v95, v135
	v_mov_b32_e32 v94, v135
	v_mov_b32_e32 v93, v135
	v_mov_b32_e32 v92, v135
	v_mov_b32_e32 v91, v135
	v_mov_b32_e32 v90, v135
	v_mov_b32_e32 v89, v135
	v_mov_b32_e32 v88, v135
	v_mov_b32_e32 v79, v135
	v_mov_b32_e32 v78, v135
	v_mov_b32_e32 v77, v135
	v_mov_b32_e32 v76, v135
	v_mov_b32_e32 v75, v135
	v_mov_b32_e32 v74, v135
	v_mov_b32_e32 v73, v135
	v_mov_b32_e32 v72, v135
	v_mov_b32_e32 v127, v135
	v_mov_b32_e32 v126, v135
	v_mov_b32_e32 v125, v135
	v_mov_b32_e32 v124, v135
	v_mov_b32_e32 v123, v135
	v_mov_b32_e32 v122, v135
	v_mov_b32_e32 v121, v135
	v_mov_b32_e32 v120, v135
	v_mov_b32_e32 v103, v135
	v_mov_b32_e32 v102, v135
	v_mov_b32_e32 v101, v135
	v_mov_b32_e32 v100, v135
	v_mov_b32_e32 v99, v135
	v_mov_b32_e32 v98, v135
	v_mov_b32_e32 v97, v135
	v_mov_b32_e32 v96, v135
	v_mov_b32_e32 v87, v135
	v_mov_b32_e32 v86, v135
	v_mov_b32_e32 v85, v135
	v_mov_b32_e32 v84, v135
	v_mov_b32_e32 v83, v135
	v_mov_b32_e32 v82, v135
	v_mov_b32_e32 v81, v135
	v_mov_b32_e32 v80, v135
	v_mov_b32_e32 v71, v135
	v_mov_b32_e32 v70, v135
	v_mov_b32_e32 v69, v135
	v_mov_b32_e32 v68, v135
	v_mov_b32_e32 v67, v135
	v_mov_b32_e32 v66, v135
	v_mov_b32_e32 v65, v135
	v_mov_b32_e32 v64, v135
	v_mov_b32_e32 v63, v135
	v_mov_b32_e32 v62, v135
	v_mov_b32_e32 v61, v135
	v_mov_b32_e32 v60, v135
	v_mov_b32_e32 v59, v135
	v_mov_b32_e32 v58, v135
	v_mov_b32_e32 v57, v135
	v_mov_b32_e32 v56, v135
	v_mov_b32_e32 v47, v135
	v_mov_b32_e32 v46, v135
	v_mov_b32_e32 v45, v135
	v_mov_b32_e32 v44, v135
	v_mov_b32_e32 v43, v135
	v_mov_b32_e32 v42, v135
	v_mov_b32_e32 v41, v135
	v_mov_b32_e32 v40, v135
	v_mov_b32_e32 v31, v135
	v_mov_b32_e32 v30, v135
	v_mov_b32_e32 v29, v135
	v_mov_b32_e32 v28, v135
	v_mov_b32_e32 v27, v135
	v_mov_b32_e32 v26, v135
	v_mov_b32_e32 v25, v135
	v_mov_b32_e32 v24, v135
	v_mov_b32_e32 v15, v135
	v_mov_b32_e32 v14, v135
	v_mov_b32_e32 v13, v135
	v_mov_b32_e32 v12, v135
	v_mov_b32_e32 v11, v135
	v_mov_b32_e32 v10, v135
	v_mov_b32_e32 v9, v135
	v_mov_b32_e32 v8, v135
	v_mov_b32_e32 v55, v135
	v_mov_b32_e32 v54, v135
	v_mov_b32_e32 v53, v135
	v_mov_b32_e32 v52, v135
	v_mov_b32_e32 v51, v135
	v_mov_b32_e32 v50, v135
	v_mov_b32_e32 v49, v135
	v_mov_b32_e32 v48, v135
	v_mov_b32_e32 v39, v135
	v_mov_b32_e32 v38, v135
	v_mov_b32_e32 v37, v135
	v_mov_b32_e32 v36, v135
	v_mov_b32_e32 v35, v135
	v_mov_b32_e32 v34, v135
	v_mov_b32_e32 v33, v135
	v_mov_b32_e32 v32, v135
	v_mov_b32_e32 v23, v135
	v_mov_b32_e32 v22, v135
	v_mov_b32_e32 v21, v135
	v_mov_b32_e32 v20, v135
	v_mov_b32_e32 v19, v135
	v_mov_b32_e32 v18, v135
	v_mov_b32_e32 v17, v135
	v_mov_b32_e32 v16, v135
	v_mov_b32_e32 v7, v135
	v_mov_b32_e32 v6, v135
	v_mov_b32_e32 v5, v135
	v_mov_b32_e32 v4, v135
	v_mov_b32_e32 v3, v135
	v_mov_b32_e32 v2, v135
	v_mov_b32_e32 v1, v135
	v_mov_b32_e32 v0, v135
	s_cbranch_vccnz .LBB0_723
	v_mov_b32_e32 v0, 0
	v_lshl_add_u64 v[112:113], v[112:113], 0, s[26:27]
	v_lshl_add_u64 v[114:115], v[114:115], 0, s[18:19]
	s_mov_b32 s8, 0
	v_mov_b32_e32 v1, v0
	v_mov_b32_e32 v2, v0
	v_mov_b32_e32 v3, v0
	v_mov_b32_e32 v4, v0
	v_mov_b32_e32 v5, v0
	v_mov_b32_e32 v6, v0
	v_mov_b32_e32 v7, v0
	v_mov_b32_e32 v16, v0
	v_mov_b32_e32 v17, v0
	v_mov_b32_e32 v18, v0
	v_mov_b32_e32 v19, v0
	v_mov_b32_e32 v20, v0
	v_mov_b32_e32 v21, v0
	v_mov_b32_e32 v22, v0
	v_mov_b32_e32 v23, v0
	v_mov_b32_e32 v32, v0
	v_mov_b32_e32 v33, v0
	v_mov_b32_e32 v34, v0
	v_mov_b32_e32 v35, v0
	v_mov_b32_e32 v36, v0
	v_mov_b32_e32 v37, v0
	v_mov_b32_e32 v38, v0
	v_mov_b32_e32 v39, v0
	v_mov_b32_e32 v48, v0
	v_mov_b32_e32 v49, v0
	v_mov_b32_e32 v50, v0
	v_mov_b32_e32 v51, v0
	v_mov_b32_e32 v52, v0
	v_mov_b32_e32 v53, v0
	v_mov_b32_e32 v54, v0
	v_mov_b32_e32 v55, v0
	v_mov_b32_e32 v8, v0
	v_mov_b32_e32 v9, v0
	v_mov_b32_e32 v10, v0
	v_mov_b32_e32 v11, v0
	v_mov_b32_e32 v12, v0
	v_mov_b32_e32 v13, v0
	v_mov_b32_e32 v14, v0
	v_mov_b32_e32 v15, v0
	v_mov_b32_e32 v24, v0
	v_mov_b32_e32 v25, v0
	v_mov_b32_e32 v26, v0
	v_mov_b32_e32 v27, v0
	v_mov_b32_e32 v28, v0
	v_mov_b32_e32 v29, v0
	v_mov_b32_e32 v30, v0
	v_mov_b32_e32 v31, v0
	v_mov_b32_e32 v40, v0
	v_mov_b32_e32 v41, v0
	v_mov_b32_e32 v42, v0
	v_mov_b32_e32 v43, v0
	v_mov_b32_e32 v44, v0
	v_mov_b32_e32 v45, v0
	v_mov_b32_e32 v46, v0
	v_mov_b32_e32 v47, v0
	v_mov_b32_e32 v56, v0
	v_mov_b32_e32 v57, v0
	v_mov_b32_e32 v58, v0
	v_mov_b32_e32 v59, v0
	v_mov_b32_e32 v60, v0
	v_mov_b32_e32 v61, v0
	v_mov_b32_e32 v62, v0
	v_mov_b32_e32 v63, v0
	v_mov_b32_e32 v64, v0
	v_mov_b32_e32 v65, v0
	v_mov_b32_e32 v66, v0
	v_mov_b32_e32 v67, v0
	v_mov_b32_e32 v68, v0
	v_mov_b32_e32 v69, v0
	v_mov_b32_e32 v70, v0
	v_mov_b32_e32 v71, v0
	v_mov_b32_e32 v80, v0
	v_mov_b32_e32 v81, v0
	v_mov_b32_e32 v82, v0
	v_mov_b32_e32 v83, v0
	v_mov_b32_e32 v84, v0
	v_mov_b32_e32 v85, v0
	v_mov_b32_e32 v86, v0
	v_mov_b32_e32 v87, v0
	v_mov_b32_e32 v96, v0
	v_mov_b32_e32 v97, v0
	v_mov_b32_e32 v98, v0
	v_mov_b32_e32 v99, v0
	v_mov_b32_e32 v100, v0
	v_mov_b32_e32 v101, v0
	v_mov_b32_e32 v102, v0
	v_mov_b32_e32 v103, v0
	v_mov_b32_e32 v120, v0
	v_mov_b32_e32 v121, v0
	v_mov_b32_e32 v122, v0
	v_mov_b32_e32 v123, v0
	v_mov_b32_e32 v124, v0
	v_mov_b32_e32 v125, v0
	v_mov_b32_e32 v126, v0
	v_mov_b32_e32 v127, v0
	v_mov_b32_e32 v72, v0
	v_mov_b32_e32 v73, v0
	v_mov_b32_e32 v74, v0
	v_mov_b32_e32 v75, v0
	v_mov_b32_e32 v76, v0
	v_mov_b32_e32 v77, v0
	v_mov_b32_e32 v78, v0
	v_mov_b32_e32 v79, v0
	v_mov_b32_e32 v88, v0
	v_mov_b32_e32 v89, v0
	v_mov_b32_e32 v90, v0
	v_mov_b32_e32 v91, v0
	v_mov_b32_e32 v92, v0
	v_mov_b32_e32 v93, v0
	v_mov_b32_e32 v94, v0
	v_mov_b32_e32 v95, v0
	v_mov_b32_e32 v104, v0
	v_mov_b32_e32 v105, v0
	v_mov_b32_e32 v106, v0
	v_mov_b32_e32 v107, v0
	v_mov_b32_e32 v108, v0
	v_mov_b32_e32 v109, v0
	v_mov_b32_e32 v110, v0
	v_mov_b32_e32 v111, v0
	v_mov_b32_e32 v128, v0
	v_mov_b32_e32 v129, v0
	v_mov_b32_e32 v130, v0
	v_mov_b32_e32 v131, v0
	v_mov_b32_e32 v132, v0
	v_mov_b32_e32 v133, v0
	v_mov_b32_e32 v134, v0
	v_mov_b32_e32 v135, v0
	s_cmp_eq_u32 s53, s8
	v_lshl_add_u64 v[204:205], v[114:115], 0, s[18:19]
	s_cselect_b64 vcc, -1, 0
	s_add_i32 s8, s8, 2
	v_cndmask_b32_e32 v213, v205, v185, vcc
	v_cndmask_b32_e32 v212, v204, v184, vcc
	v_cndmask_b32_e32 v215, v113, v187, vcc
	v_cndmask_b32_e32 v214, v112, v186, vcc
	.p2align	6
; #define PG8_STAGE(bufoff, gbase, voff) do { _Pragma("unroll") for (int _i = 0; _i < 2; ++_i) \
;         __builtin_amdgcn_global_load_lds((const unsigned*)((const char*)(gbase) + (voff)[_i]), (PG8_LAS unsigned*)(lds + (bufoff) + ldsw + _i * 8192), 16, 0, 0); } while (0)
; #define PG8_LDA(dst, b, h) do { _Pragma("unroll") for (int m = 0; m < 4; ++m) _Pragma("unroll") for (int k = 0; k < 2; ++k) dst[m][k] = *(const PG8_LAS bf16x8*)(lds + PG8_SA(b, h) + aoff + m * 2048 + k * 1024); } while (0)
; #define PG8_LDB(dst, b, h) do { _Pragma("unroll") for (int n = 0; n < 2; ++n) _Pragma("unroll") for (int k = 0; k < 2; ++k) dst[n][k] = *(const PG8_LAS bf16x8*)(lds + PG8_SB(b, h) + boff + n * 2048 + k * 1024); } while (0)
; #define PG8_MMA(ai, bj, At, Bt) do { __builtin_amdgcn_s_setprio(1); _Pragma("unroll") for (int m = 0; m < 4; ++m) _Pragma("unroll") for (int n = 0; n < 2; ++n) _Pragma("unroll") for (int k = 0; k < 2; ++k) \
;         acc[ai][bj][m][n] = __builtin_amdgcn_mfma_f32_16x16x32_bf16(Bt[n][k], At[m][k], acc[ai][bj][m][n], 0, 0, 0); __builtin_amdgcn_s_setprio(0); } while (0)
; #define PG8_WAIT_V(n) asm volatile("s_waitcnt vmcnt(" #n ")" ::: "memory")
; #define PG8_WAIT_L(n) asm volatile("s_waitcnt lgkmcnt(" #n ")" ::: "memory")
; #define PG8_BAR __builtin_amdgcn_s_barrier()
; #define PG8_SCHED __builtin_amdgcn_sched_barrier(0)
; template <class Epi, class Sched, bool ALIGN_EPI = false, bool SP2 = false>
; __device__ __forceinline__ void gemm_phase(PG8_LAS unsigned char* lds, const Gemm g, const Sched& S, const Epi& E) {
;     ...
;             PG8_LDB(B0, 0, 0); PG8_LDB(B1, 0, 1); PG8_SCHED; PG8_LDA(At, 0, 0); PG8_STAGE(PG8_SA(1, 1), a1 + hstep, voffA);
;             PG8_WAIT_V(8); PG8_WAIT_L(0); PG8_BAR; PG8_MMA(0, 0, At, B0); PG8_MMA(0, 1, At, B1); PG8_BAR; PG8_SCHED;
;             PG8_LDA(At, 0, 1); PG8_STAGE(PG8_SB(0, 0), b2, voffB); PG8_STAGE(PG8_SB(0, 1), b2 + hstep, voffB); PG8_STAGE(PG8_SA(0, 0), a2, voffA);
;             PG8_WAIT_V(8); PG8_WAIT_L(0); PG8_BAR; PG8_MMA(1, 0, At, B0); PG8_MMA(1, 1, At, B1); PG8_BAR; PG8_SCHED;
.LBB0_722:
	v_add_u32_e32 v144, s59, v183
	v_add_u32_e32 v170, s60, v183
	ds_read_b128 v[116:119], v144
	ds_read_b128 v[136:139], v144 offset:1024
	ds_read_b128 v[140:143], v144 offset:2048
	ds_read_b128 v[144:147], v144 offset:3072
	ds_read_b128 v[148:151], v170
	ds_read_b128 v[188:191], v170 offset:1024
	ds_read_b128 v[192:195], v170 offset:2048
	ds_read_b128 v[198:201], v170 offset:3072
	v_lshl_add_u64 v[240:241], v[114:115], 0, v[178:179]
	s_add_i32 m0, s34, 0xc000
	ds_read_b128 v[204:207], v202
	ds_read_b128 v[208:211], v202 offset:1024
	ds_read_b128 v[216:219], v202 offset:2048
	ds_read_b128 v[220:223], v202 offset:3072
	ds_read_b128 v[224:227], v202 offset:4096
	ds_read_b128 v[228:231], v202 offset:5120
	ds_read_b128 v[232:235], v202 offset:6144
	ds_read_b128 v[236:239], v202 offset:7168
	global_load_lds_dwordx4 v[240:241], off
	s_add_i32 m0, s34, 0xe000
	v_lshl_add_u64 v[240:241], v[114:115], 0, v[176:177]
	global_load_lds_dwordx4 v[240:241], off
	s_waitcnt vmcnt(8) lgkmcnt(0)
	s_setprio 1
	s_barrier
	v_mfma_f32_16x16x32_bf16 v[132:135], v[116:119], v[204:207], v[132:135]
	v_mfma_f32_16x16x32_bf16 v[128:131], v[140:143], v[204:207], v[128:131]
	v_mfma_f32_16x16x32_bf16 v[108:111], v[116:119], v[216:219], v[108:111]
	v_mfma_f32_16x16x32_bf16 v[104:107], v[140:143], v[216:219], v[104:107]
	v_mfma_f32_16x16x32_bf16 v[92:95], v[116:119], v[224:227], v[92:95]
	v_mfma_f32_16x16x32_bf16 v[88:91], v[140:143], v[224:227], v[88:91]
	v_mfma_f32_16x16x32_bf16 v[76:79], v[116:119], v[232:235], v[76:79]
	v_mfma_f32_16x16x32_bf16 v[72:75], v[140:143], v[232:235], v[72:75]
	v_mfma_f32_16x16x32_bf16 v[132:135], v[136:139], v[208:211], v[132:135]
	v_mfma_f32_16x16x32_bf16 v[128:131], v[144:147], v[208:211], v[128:131]
	v_mfma_f32_16x16x32_bf16 v[108:111], v[136:139], v[220:223], v[108:111]
	v_mfma_f32_16x16x32_bf16 v[104:107], v[144:147], v[220:223], v[104:107]
	v_mfma_f32_16x16x32_bf16 v[92:95], v[136:139], v[228:231], v[92:95]
	v_mfma_f32_16x16x32_bf16 v[88:91], v[144:147], v[228:231], v[88:91]
	v_mfma_f32_16x16x32_bf16 v[76:79], v[136:139], v[236:239], v[76:79]
	v_mfma_f32_16x16x32_bf16 v[72:75], v[144:147], v[236:239], v[72:75]
	v_mfma_f32_16x16x32_bf16 v[124:127], v[148:151], v[204:207], v[124:127]
	v_mfma_f32_16x16x32_bf16 v[120:123], v[192:195], v[204:207], v[120:123]
	v_mfma_f32_16x16x32_bf16 v[100:103], v[148:151], v[216:219], v[100:103]
	v_mfma_f32_16x16x32_bf16 v[96:99], v[192:195], v[216:219], v[96:99]
	v_mfma_f32_16x16x32_bf16 v[84:87], v[148:151], v[224:227], v[84:87]
	v_mfma_f32_16x16x32_bf16 v[80:83], v[192:195], v[224:227], v[80:83]
	v_mfma_f32_16x16x32_bf16 v[68:71], v[148:151], v[232:235], v[68:71]
	v_mfma_f32_16x16x32_bf16 v[64:67], v[192:195], v[232:235], v[64:67]
	v_mfma_f32_16x16x32_bf16 v[124:127], v[188:191], v[208:211], v[124:127]
	v_mfma_f32_16x16x32_bf16 v[120:123], v[198:201], v[208:211], v[120:123]
	v_mfma_f32_16x16x32_bf16 v[100:103], v[188:191], v[220:223], v[100:103]
	v_mfma_f32_16x16x32_bf16 v[96:99], v[198:201], v[220:223], v[96:99]
	v_mfma_f32_16x16x32_bf16 v[84:87], v[188:191], v[228:231], v[84:87]
	v_mfma_f32_16x16x32_bf16 v[80:83], v[198:201], v[228:231], v[80:83]
	v_mfma_f32_16x16x32_bf16 v[68:71], v[188:191], v[236:239], v[68:71]
	v_mfma_f32_16x16x32_bf16 v[64:67], v[198:201], v[236:239], v[64:67]
	s_setprio 0
	s_barrier
	s_add_i32 s9, s59, s29
	v_lshl_add_u64 v[240:241], v[214:215], 0, v[164:165]
	s_mov_b32 m0, s9
	ds_read_b128 v[204:207], v202 offset:16384
	ds_read_b128 v[208:211], v202 offset:17408
	ds_read_b128 v[216:219], v202 offset:18432
	ds_read_b128 v[220:223], v202 offset:19456
	ds_read_b128 v[224:227], v202 offset:20480
	ds_read_b128 v[228:231], v202 offset:21504
	ds_read_b128 v[232:235], v202 offset:22528
	ds_read_b128 v[236:239], v202 offset:23552
	global_load_lds_dwordx4 v[240:241], off
	v_lshl_add_u64 v[242:243], v[214:215], 0, v[168:169]
	s_add_i32 m0, s9, 0x2000
	v_lshl_add_u64 v[214:215], v[214:215], 0, s[12:13]
	s_add_i32 s9, s60, s29
	global_load_lds_dwordx4 v[242:243], off
	v_lshl_add_u64 v[244:245], v[214:215], 0, v[164:165]
	s_mov_b32 m0, s9
	v_lshl_add_u64 v[214:215], v[214:215], 0, v[168:169]
	global_load_lds_dwordx4 v[244:245], off
	s_add_i32 m0, s9, 0x2000
	v_lshl_add_u64 v[246:247], v[212:213], 0, v[162:163]
	global_load_lds_dwordx4 v[214:215], off
	s_mov_b32 m0, s34
	v_lshl_add_u64 v[248:249], v[212:213], 0, v[166:167]
	global_load_lds_dwordx4 v[246:247], off
	s_mov_b32 m0, s36
	s_nop 0
	global_load_lds_dwordx4 v[248:249], off
	s_waitcnt vmcnt(8) lgkmcnt(0)
	s_setprio 1
	s_barrier
	v_mfma_f32_16x16x32_bf16 v[60:63], v[116:119], v[204:207], v[60:63]
	v_mfma_f32_16x16x32_bf16 v[56:59], v[140:143], v[204:207], v[56:59]
	v_mfma_f32_16x16x32_bf16 v[44:47], v[116:119], v[216:219], v[44:47]
	v_mfma_f32_16x16x32_bf16 v[40:43], v[140:143], v[216:219], v[40:43]
	v_mfma_f32_16x16x32_bf16 v[28:31], v[116:119], v[224:227], v[28:31]
	v_mfma_f32_16x16x32_bf16 v[24:27], v[140:143], v[224:227], v[24:27]
	v_mfma_f32_16x16x32_bf16 v[12:15], v[116:119], v[232:235], v[12:15]
	v_mfma_f32_16x16x32_bf16 v[8:11], v[140:143], v[232:235], v[8:11]
	v_mfma_f32_16x16x32_bf16 v[60:63], v[136:139], v[208:211], v[60:63]
	v_mfma_f32_16x16x32_bf16 v[56:59], v[144:147], v[208:211], v[56:59]
	v_mfma_f32_16x16x32_bf16 v[44:47], v[136:139], v[220:223], v[44:47]
	v_mfma_f32_16x16x32_bf16 v[40:43], v[144:147], v[220:223], v[40:43]
	v_mfma_f32_16x16x32_bf16 v[28:31], v[136:139], v[228:231], v[28:31]
	v_mfma_f32_16x16x32_bf16 v[24:27], v[144:147], v[228:231], v[24:27]
	v_mfma_f32_16x16x32_bf16 v[12:15], v[136:139], v[236:239], v[12:15]
	v_mfma_f32_16x16x32_bf16 v[8:11], v[144:147], v[236:239], v[8:11]
	v_mfma_f32_16x16x32_bf16 v[52:55], v[148:151], v[204:207], v[52:55]
	v_mfma_f32_16x16x32_bf16 v[48:51], v[192:195], v[204:207], v[48:51]
	v_mfma_f32_16x16x32_bf16 v[36:39], v[148:151], v[216:219], v[36:39]
	v_mfma_f32_16x16x32_bf16 v[32:35], v[192:195], v[216:219], v[32:35]
	v_mfma_f32_16x16x32_bf16 v[20:23], v[148:151], v[224:227], v[20:23]
	v_mfma_f32_16x16x32_bf16 v[16:19], v[192:195], v[224:227], v[16:19]
	v_mfma_f32_16x16x32_bf16 v[4:7], v[148:151], v[232:235], v[4:7]
	v_mfma_f32_16x16x32_bf16 v[0:3], v[192:195], v[232:235], v[0:3]
	v_mfma_f32_16x16x32_bf16 v[52:55], v[188:191], v[208:211], v[52:55]
	v_mfma_f32_16x16x32_bf16 v[48:51], v[198:201], v[208:211], v[48:51]
	v_mfma_f32_16x16x32_bf16 v[36:39], v[188:191], v[220:223], v[36:39]
	v_mfma_f32_16x16x32_bf16 v[32:35], v[198:201], v[220:223], v[32:35]
	v_mfma_f32_16x16x32_bf16 v[20:23], v[188:191], v[228:231], v[20:23]
	v_mfma_f32_16x16x32_bf16 v[16:19], v[198:201], v[228:231], v[16:19]
	v_mfma_f32_16x16x32_bf16 v[4:7], v[188:191], v[236:239], v[4:7]
	v_mfma_f32_16x16x32_bf16 v[0:3], v[198:201], v[236:239], v[0:3]
	s_setprio 0
	s_barrier
; #define PG8_STAGE(bufoff, gbase, voff) do { _Pragma("unroll") for (int _i = 0; _i < 2; ++_i) \
;         __builtin_amdgcn_global_load_lds((const unsigned*)((const char*)(gbase) + (voff)[_i]), (PG8_LAS unsigned*)(lds + (bufoff) + ldsw + _i * 8192), 16, 0, 0); } while (0)
; #define PG8_LDA(dst, b, h) do { _Pragma("unroll") for (int m = 0; m < 4; ++m) _Pragma("unroll") for (int k = 0; k < 2; ++k) dst[m][k] = *(const PG8_LAS bf16x8*)(lds + PG8_SA(b, h) + aoff + m * 2048 + k * 1024); } while (0)
; #define PG8_LDB(dst, b, h) do { _Pragma("unroll") for (int n = 0; n < 2; ++n) _Pragma("unroll") for (int k = 0; k < 2; ++k) dst[n][k] = *(const PG8_LAS bf16x8*)(lds + PG8_SB(b, h) + boff + n * 2048 + k * 1024); } while (0)
; #define PG8_MMA(ai, bj, At, Bt) do { __builtin_amdgcn_s_setprio(1); _Pragma("unroll") for (int m = 0; m < 4; ++m) _Pragma("unroll") for (int n = 0; n < 2; ++n) _Pragma("unroll") for (int k = 0; k < 2; ++k) \
;         acc[ai][bj][m][n] = __builtin_amdgcn_mfma_f32_16x16x32_bf16(Bt[n][k], At[m][k], acc[ai][bj][m][n], 0, 0, 0); __builtin_amdgcn_s_setprio(0); } while (0)
; #define PG8_WAIT_V(n) asm volatile("s_waitcnt vmcnt(" #n ")" ::: "memory")
; #define PG8_WAIT_L(n) asm volatile("s_waitcnt lgkmcnt(" #n ")" ::: "memory")
; #define PG8_BAR __builtin_amdgcn_s_barrier()
; #define PG8_SCHED __builtin_amdgcn_sched_barrier(0)
; template <class Epi, class Sched, bool ALIGN_EPI = false, bool SP2 = false>
; __device__ __forceinline__ void gemm_phase(PG8_LAS unsigned char* lds, const Gemm g, const Sched& S, const Epi& E) {
;     ...
;             PG8_LDB(B0, 1, 0); PG8_LDB(B1, 1, 1); PG8_SCHED; PG8_LDA(At, 1, 0); PG8_STAGE(PG8_SA(0, 1), a2 + hstep, voffA);
;             PG8_WAIT_V(8); PG8_WAIT_L(0); PG8_BAR; PG8_MMA(0, 0, At, B0); PG8_MMA(0, 1, At, B1); PG8_BAR; PG8_SCHED;
;             PG8_LDA(At, 1, 1); PG8_STAGE(PG8_SB(1, 0), b3, voffB); PG8_STAGE(PG8_SB(1, 1), b3 + hstep, voffB); PG8_STAGE(PG8_SA(1, 0), a3, voffA);
;             PG8_WAIT_V(8); PG8_WAIT_L(0); PG8_BAR; PG8_MMA(1, 0, At, B0); PG8_MMA(1, 1, At, B1); PG8_BAR; PG8_SCHED;
	s_add_i32 s9, 0, 0x18000
	s_add_i32 s10, 0, 0x1c000
	v_add_u32_e32 v144, s9, v183
	v_add_u32_e32 v170, s10, v183
	ds_read_b128 v[116:119], v144
	ds_read_b128 v[136:139], v144 offset:1024
	ds_read_b128 v[140:143], v144 offset:2048
	ds_read_b128 v[144:147], v144 offset:3072
	ds_read_b128 v[148:151], v170
	ds_read_b128 v[188:191], v170 offset:1024
	ds_read_b128 v[192:195], v170 offset:2048
	ds_read_b128 v[198:201], v170 offset:3072
	v_lshl_add_u64 v[212:213], v[212:213], 0, s[12:13]
	s_mov_b32 m0, s37
	v_lshl_add_u64 v[250:251], v[212:213], 0, v[162:163]
	ds_read_b128 v[204:207], v202 offset:32768
	ds_read_b128 v[208:211], v202 offset:33792
	ds_read_b128 v[216:219], v202 offset:34816
	ds_read_b128 v[220:223], v202 offset:35840
	ds_read_b128 v[224:227], v202 offset:36864
	ds_read_b128 v[228:231], v202 offset:37888
	ds_read_b128 v[232:235], v202 offset:38912
	ds_read_b128 v[236:239], v202 offset:39936
	global_load_lds_dwordx4 v[250:251], off
	s_mov_b32 m0, s41
	v_lshl_add_u64 v[212:213], v[212:213], 0, v[166:167]
	global_load_lds_dwordx4 v[212:213], off
	s_waitcnt vmcnt(8) lgkmcnt(0)
	s_setprio 1
	s_barrier
	v_mfma_f32_16x16x32_bf16 v[132:135], v[116:119], v[204:207], v[132:135]
	v_mfma_f32_16x16x32_bf16 v[128:131], v[140:143], v[204:207], v[128:131]
	v_mfma_f32_16x16x32_bf16 v[108:111], v[116:119], v[216:219], v[108:111]
	v_mfma_f32_16x16x32_bf16 v[104:107], v[140:143], v[216:219], v[104:107]
	v_mfma_f32_16x16x32_bf16 v[92:95], v[116:119], v[224:227], v[92:95]
	v_mfma_f32_16x16x32_bf16 v[88:91], v[140:143], v[224:227], v[88:91]
	v_mfma_f32_16x16x32_bf16 v[76:79], v[116:119], v[232:235], v[76:79]
	v_mfma_f32_16x16x32_bf16 v[72:75], v[140:143], v[232:235], v[72:75]
	v_mfma_f32_16x16x32_bf16 v[132:135], v[136:139], v[208:211], v[132:135]
	v_mfma_f32_16x16x32_bf16 v[128:131], v[144:147], v[208:211], v[128:131]
	v_mfma_f32_16x16x32_bf16 v[108:111], v[136:139], v[220:223], v[108:111]
	v_mfma_f32_16x16x32_bf16 v[104:107], v[144:147], v[220:223], v[104:107]
	v_mfma_f32_16x16x32_bf16 v[92:95], v[136:139], v[228:231], v[92:95]
	v_mfma_f32_16x16x32_bf16 v[88:91], v[144:147], v[228:231], v[88:91]
	v_mfma_f32_16x16x32_bf16 v[76:79], v[136:139], v[236:239], v[76:79]
	v_mfma_f32_16x16x32_bf16 v[72:75], v[144:147], v[236:239], v[72:75]
	v_mfma_f32_16x16x32_bf16 v[124:127], v[148:151], v[204:207], v[124:127]
	v_mfma_f32_16x16x32_bf16 v[120:123], v[192:195], v[204:207], v[120:123]
	v_mfma_f32_16x16x32_bf16 v[100:103], v[148:151], v[216:219], v[100:103]
	v_mfma_f32_16x16x32_bf16 v[96:99], v[192:195], v[216:219], v[96:99]
	v_mfma_f32_16x16x32_bf16 v[84:87], v[148:151], v[224:227], v[84:87]
	v_mfma_f32_16x16x32_bf16 v[80:83], v[192:195], v[224:227], v[80:83]
	v_mfma_f32_16x16x32_bf16 v[68:71], v[148:151], v[232:235], v[68:71]
	v_mfma_f32_16x16x32_bf16 v[64:67], v[192:195], v[232:235], v[64:67]
	v_mfma_f32_16x16x32_bf16 v[124:127], v[188:191], v[208:211], v[124:127]
	v_mfma_f32_16x16x32_bf16 v[120:123], v[198:201], v[208:211], v[120:123]
	v_mfma_f32_16x16x32_bf16 v[100:103], v[188:191], v[220:223], v[100:103]
	v_mfma_f32_16x16x32_bf16 v[96:99], v[198:201], v[220:223], v[96:99]
	v_mfma_f32_16x16x32_bf16 v[84:87], v[188:191], v[228:231], v[84:87]
	v_mfma_f32_16x16x32_bf16 v[80:83], v[198:201], v[228:231], v[80:83]
	v_mfma_f32_16x16x32_bf16 v[68:71], v[188:191], v[236:239], v[68:71]
	v_mfma_f32_16x16x32_bf16 v[64:67], v[198:201], v[236:239], v[64:67]
	s_setprio 0
	s_barrier
	s_add_i32 s9, s9, s29
	s_add_i32 m0, s9, 0xffffff80
	ds_read_b128 v[204:207], v202 offset:49152
	ds_read_b128 v[208:211], v202 offset:50176
	ds_read_b128 v[216:219], v202 offset:51200
	ds_read_b128 v[220:223], v202 offset:52224
	global_load_lds_dwordx4 v[240:241], off offset:128
	s_add_i32 m0, s9, 0x1f80
	s_add_i32 s9, s10, s29
	global_load_lds_dwordx4 v[242:243], off offset:128
	s_add_i32 m0, s9, 0xffffff80
	ds_read_b128 v[236:239], v202 offset:56320
	global_load_lds_dwordx4 v[244:245], off offset:128
	s_add_i32 m0, s9, 0x1f80
	ds_read_b128 v[232:235], v202 offset:55296
	global_load_lds_dwordx4 v[214:215], off offset:128
	s_add_i32 m0, s49, 0xffffff80
	ds_read_b128 v[228:231], v202 offset:54272
	global_load_lds_dwordx4 v[246:247], off offset:128
	s_add_i32 m0, s50, 0xffffff80
	ds_read_b128 v[224:227], v202 offset:53248
	global_load_lds_dwordx4 v[248:249], off offset:128
	s_waitcnt vmcnt(8) lgkmcnt(0)
	s_setprio 1
	s_barrier
	v_mfma_f32_16x16x32_bf16 v[60:63], v[116:119], v[204:207], v[60:63]
	v_mfma_f32_16x16x32_bf16 v[56:59], v[140:143], v[204:207], v[56:59]
	v_mfma_f32_16x16x32_bf16 v[44:47], v[116:119], v[216:219], v[44:47]
	v_mfma_f32_16x16x32_bf16 v[40:43], v[140:143], v[216:219], v[40:43]
	v_mfma_f32_16x16x32_bf16 v[28:31], v[116:119], v[224:227], v[28:31]
	v_mfma_f32_16x16x32_bf16 v[24:27], v[140:143], v[224:227], v[24:27]
	v_mfma_f32_16x16x32_bf16 v[12:15], v[116:119], v[232:235], v[12:15]
	v_mfma_f32_16x16x32_bf16 v[8:11], v[140:143], v[232:235], v[8:11]
	v_mfma_f32_16x16x32_bf16 v[60:63], v[136:139], v[208:211], v[60:63]
	v_mfma_f32_16x16x32_bf16 v[56:59], v[144:147], v[208:211], v[56:59]
	v_mfma_f32_16x16x32_bf16 v[44:47], v[136:139], v[220:223], v[44:47]
	v_mfma_f32_16x16x32_bf16 v[40:43], v[144:147], v[220:223], v[40:43]
	v_mfma_f32_16x16x32_bf16 v[28:31], v[136:139], v[228:231], v[28:31]
	v_mfma_f32_16x16x32_bf16 v[24:27], v[144:147], v[228:231], v[24:27]
	v_mfma_f32_16x16x32_bf16 v[12:15], v[136:139], v[236:239], v[12:15]
	v_mfma_f32_16x16x32_bf16 v[8:11], v[144:147], v[236:239], v[8:11]
	v_mfma_f32_16x16x32_bf16 v[52:55], v[148:151], v[204:207], v[52:55]
	v_mfma_f32_16x16x32_bf16 v[48:51], v[192:195], v[204:207], v[48:51]
	v_mfma_f32_16x16x32_bf16 v[36:39], v[148:151], v[216:219], v[36:39]
	v_mfma_f32_16x16x32_bf16 v[32:35], v[192:195], v[216:219], v[32:35]
	v_mfma_f32_16x16x32_bf16 v[20:23], v[148:151], v[224:227], v[20:23]
	v_mfma_f32_16x16x32_bf16 v[16:19], v[192:195], v[224:227], v[16:19]
	v_mfma_f32_16x16x32_bf16 v[4:7], v[148:151], v[232:235], v[4:7]
	v_mfma_f32_16x16x32_bf16 v[0:3], v[192:195], v[232:235], v[0:3]
	v_mfma_f32_16x16x32_bf16 v[52:55], v[188:191], v[208:211], v[52:55]
	v_mfma_f32_16x16x32_bf16 v[48:51], v[198:201], v[208:211], v[48:51]
	v_mfma_f32_16x16x32_bf16 v[36:39], v[188:191], v[220:223], v[36:39]
	v_mfma_f32_16x16x32_bf16 v[32:35], v[198:201], v[220:223], v[32:35]
	v_mfma_f32_16x16x32_bf16 v[20:23], v[188:191], v[228:231], v[20:23]
	v_mfma_f32_16x16x32_bf16 v[16:19], v[198:201], v[228:231], v[16:19]
	v_mfma_f32_16x16x32_bf16 v[4:7], v[188:191], v[236:239], v[4:7]
	v_mfma_f32_16x16x32_bf16 v[0:3], v[198:201], v[236:239], v[0:3]
	v_lshl_add_u64 v[112:113], v[112:113], 0, s[26:27]
	v_lshl_add_u64 v[114:115], v[114:115], 0, s[26:27]
	s_cmp_ge_i32 s8, s51
	s_cbranch_scc1 .Lrot_exit_13
	s_cmp_eq_u32 s53, s8
	v_lshl_add_u64 v[204:205], v[114:115], 0, s[18:19]
	s_cselect_b64 vcc, -1, 0
	s_add_i32 s8, s8, 2
	v_cndmask_b32_e32 v213, v205, v185, vcc
	v_cndmask_b32_e32 v212, v204, v184, vcc
	v_cndmask_b32_e32 v215, v113, v187, vcc
	v_cndmask_b32_e32 v214, v112, v186, vcc
	s_setprio 0
	s_barrier
	s_branch .LBB0_722
; #define PG8_MMA(ai, bj, At, Bt) do { __builtin_amdgcn_s_setprio(1); _Pragma("unroll") for (int m = 0; m < 4; ++m) _Pragma("unroll") for (int n = 0; n < 2; ++n) _Pragma("unroll") for (int k = 0; k < 2; ++k) \
;         acc[ai][bj][m][n] = __builtin_amdgcn_mfma_f32_16x16x32_bf16(Bt[n][k], At[m][k], acc[ai][bj][m][n], 0, 0, 0); __builtin_amdgcn_s_setprio(0); } while (0)
; #define PG8_WAIT_V(n) asm volatile("s_waitcnt vmcnt(" #n ")" ::: "memory")
; #define PG8_WAIT_L(n) asm volatile("s_waitcnt lgkmcnt(" #n ")" ::: "memory")
; #define PG8_BAR __builtin_amdgcn_s_barrier()
; #define PG8_SCHED __builtin_amdgcn_sched_barrier(0)
; template <class Epi, class Sched, bool ALIGN_EPI = false, bool SP2 = false>
; __device__ __forceinline__ void gemm_phase(PG8_LAS unsigned char* lds, const Gemm g, const Sched& S, const Epi& E) {
;     ...
;             PG8_WAIT_V(8); PG8_WAIT_L(0); PG8_BAR; PG8_MMA(1, 0, At, B0); PG8_MMA(1, 1, At, B1); PG8_BAR; PG8_SCHED;
;     ...
;         if constexpr (ALIGN_EPI) { if (wr == 0) PG8_BAR; }
.Lrot_exit_13:
	s_setprio 0
	s_barrier
.LBB0_723:
	s_and_b64 vcc, exec, s[22:23]
	s_cbranch_vccz .LBB0_725
	s_barrier

; template <class Epi, class Sched, bool ALIGN_EPI = false, bool SP2 = false>
; __device__ __forceinline__ void gemm_phase(PG8_LAS unsigned char* lds, const Gemm g, const Sched& S, const Epi& E) {
;     ...
;         for (int t = 0; t < nt; t += 2) {
;             const bool last = (t == nt - 2);
;             const char* a1 = cA + (size_t)(t + 1) * kstep;
;             const char* a2 = last ? nA : cA + (size_t)(t + 2) * kstep; const char* b2 = last ? nB : cB + (size_t)(t + 2) * kstep;
;     ...
; #pragma unroll
;         for (int a = 0; a < 2; ++a)
; #pragma unroll
;             for (int b = 0; b < 2; ++b)
; #pragma unroll
;                 for (int m = 0; m < 4; ++m)
; #pragma unroll
;                     for (int n = 0; n < 2; ++n) acc[a][b][m][n] = (f32x4){0.f, 0.f, 0.f, 0.f};
.LBB0_938:
	v_mov_b32_e32 v123, 0
	s_and_b64 vcc, exec, s[8:9]
	v_mov_b32_e32 v122, v123
	v_mov_b32_e32 v121, v123
	v_mov_b32_e32 v120, v123
	v_mov_b32_e32 v127, v123
	v_mov_b32_e32 v126, v123
	v_mov_b32_e32 v125, v123
	v_mov_b32_e32 v124, v123
	v_mov_b32_e32 v111, v123
	v_mov_b32_e32 v110, v123
	v_mov_b32_e32 v109, v123
	v_mov_b32_e32 v108, v123
	v_mov_b32_e32 v107, v123
	v_mov_b32_e32 v106, v123
	v_mov_b32_e32 v105, v123
	v_mov_b32_e32 v104, v123
	v_mov_b32_e32 v95, v123
	v_mov_b32_e32 v94, v123
	v_mov_b32_e32 v93, v123
	v_mov_b32_e32 v92, v123
	v_mov_b32_e32 v91, v123
	v_mov_b32_e32 v90, v123
	v_mov_b32_e32 v89, v123
	v_mov_b32_e32 v88, v123
	v_mov_b32_e32 v79, v123
	v_mov_b32_e32 v78, v123
	v_mov_b32_e32 v77, v123
	v_mov_b32_e32 v76, v123
	v_mov_b32_e32 v75, v123
	v_mov_b32_e32 v74, v123
	v_mov_b32_e32 v73, v123
	v_mov_b32_e32 v72, v123
	v_mov_b32_e32 v119, v123
	v_mov_b32_e32 v118, v123
	v_mov_b32_e32 v117, v123
	v_mov_b32_e32 v116, v123
	v_mov_b32_e32 v115, v123
	v_mov_b32_e32 v114, v123
	v_mov_b32_e32 v113, v123
	v_mov_b32_e32 v112, v123
	v_mov_b32_e32 v103, v123
	v_mov_b32_e32 v102, v123
	v_mov_b32_e32 v101, v123
	v_mov_b32_e32 v100, v123
	v_mov_b32_e32 v99, v123
	v_mov_b32_e32 v98, v123
	v_mov_b32_e32 v97, v123
	v_mov_b32_e32 v96, v123
	v_mov_b32_e32 v87, v123
	v_mov_b32_e32 v86, v123
	v_mov_b32_e32 v85, v123
	v_mov_b32_e32 v84, v123
	v_mov_b32_e32 v83, v123
	v_mov_b32_e32 v82, v123
	v_mov_b32_e32 v81, v123
	v_mov_b32_e32 v80, v123
	v_mov_b32_e32 v71, v123
	v_mov_b32_e32 v70, v123
	v_mov_b32_e32 v69, v123
	v_mov_b32_e32 v68, v123
	v_mov_b32_e32 v67, v123
	v_mov_b32_e32 v66, v123
	v_mov_b32_e32 v65, v123
	v_mov_b32_e32 v64, v123
	v_mov_b32_e32 v63, v123
	v_mov_b32_e32 v62, v123
	v_mov_b32_e32 v61, v123
	v_mov_b32_e32 v60, v123
	v_mov_b32_e32 v59, v123
	v_mov_b32_e32 v58, v123
	v_mov_b32_e32 v57, v123
	v_mov_b32_e32 v56, v123
	v_mov_b32_e32 v47, v123
	v_mov_b32_e32 v46, v123
	v_mov_b32_e32 v45, v123
	v_mov_b32_e32 v44, v123
	v_mov_b32_e32 v43, v123
	v_mov_b32_e32 v42, v123
	v_mov_b32_e32 v41, v123
	v_mov_b32_e32 v40, v123
	v_mov_b32_e32 v31, v123
	v_mov_b32_e32 v30, v123
	v_mov_b32_e32 v29, v123
	v_mov_b32_e32 v28, v123
	v_mov_b32_e32 v27, v123
	v_mov_b32_e32 v26, v123
	v_mov_b32_e32 v25, v123
	v_mov_b32_e32 v24, v123
	v_mov_b32_e32 v15, v123
	v_mov_b32_e32 v14, v123
	v_mov_b32_e32 v13, v123
	v_mov_b32_e32 v12, v123
	v_mov_b32_e32 v11, v123
	v_mov_b32_e32 v10, v123
	v_mov_b32_e32 v9, v123
	v_mov_b32_e32 v8, v123
	v_mov_b32_e32 v55, v123
	v_mov_b32_e32 v54, v123
	v_mov_b32_e32 v53, v123
	v_mov_b32_e32 v52, v123
	v_mov_b32_e32 v51, v123
	v_mov_b32_e32 v50, v123
	v_mov_b32_e32 v49, v123
	v_mov_b32_e32 v48, v123
	v_mov_b32_e32 v39, v123
	v_mov_b32_e32 v38, v123
	v_mov_b32_e32 v37, v123
	v_mov_b32_e32 v36, v123
	v_mov_b32_e32 v35, v123
	v_mov_b32_e32 v34, v123
	v_mov_b32_e32 v33, v123
	v_mov_b32_e32 v32, v123
	v_mov_b32_e32 v23, v123
	v_mov_b32_e32 v22, v123
	v_mov_b32_e32 v21, v123
	v_mov_b32_e32 v20, v123
	v_mov_b32_e32 v19, v123
	v_mov_b32_e32 v18, v123
	v_mov_b32_e32 v17, v123
	v_mov_b32_e32 v16, v123
	v_mov_b32_e32 v7, v123
	v_mov_b32_e32 v6, v123
	v_mov_b32_e32 v5, v123
	v_mov_b32_e32 v4, v123
	v_mov_b32_e32 v3, v123
	v_mov_b32_e32 v2, v123
	s_waitcnt lgkmcnt(0)
	v_mov_b32_e32 v1, v123
	v_mov_b32_e32 v0, v123
	s_cbranch_vccnz .LBB0_941
	v_mov_b32_e32 v0, 0
	v_lshl_add_u64 v[128:129], v[128:129], 0, s[26:27]
	v_lshl_add_u64 v[130:131], v[130:131], 0, s[22:23]
	s_mov_b32 s12, 0
	v_mov_b32_e32 v1, v0
	v_mov_b32_e32 v2, v0
	v_mov_b32_e32 v3, v0
	v_mov_b32_e32 v4, v0
	v_mov_b32_e32 v5, v0
	v_mov_b32_e32 v6, v0
	v_mov_b32_e32 v7, v0
	v_mov_b32_e32 v16, v0
	v_mov_b32_e32 v17, v0
	v_mov_b32_e32 v18, v0
	v_mov_b32_e32 v19, v0
	v_mov_b32_e32 v20, v0
	v_mov_b32_e32 v21, v0
	v_mov_b32_e32 v22, v0
	v_mov_b32_e32 v23, v0
	v_mov_b32_e32 v32, v0
	v_mov_b32_e32 v33, v0
	v_mov_b32_e32 v34, v0
	v_mov_b32_e32 v35, v0
	v_mov_b32_e32 v36, v0
	v_mov_b32_e32 v37, v0
	v_mov_b32_e32 v38, v0
	v_mov_b32_e32 v39, v0
	v_mov_b32_e32 v48, v0
	v_mov_b32_e32 v49, v0
	v_mov_b32_e32 v50, v0
	v_mov_b32_e32 v51, v0
	v_mov_b32_e32 v52, v0
	v_mov_b32_e32 v53, v0
	v_mov_b32_e32 v54, v0
	v_mov_b32_e32 v55, v0
	v_mov_b32_e32 v8, v0
	v_mov_b32_e32 v9, v0
	v_mov_b32_e32 v10, v0
	v_mov_b32_e32 v11, v0
	v_mov_b32_e32 v12, v0
	v_mov_b32_e32 v13, v0
	v_mov_b32_e32 v14, v0
	v_mov_b32_e32 v15, v0
	v_mov_b32_e32 v24, v0
	v_mov_b32_e32 v25, v0
	v_mov_b32_e32 v26, v0
	v_mov_b32_e32 v27, v0
	v_mov_b32_e32 v28, v0
	v_mov_b32_e32 v29, v0
	v_mov_b32_e32 v30, v0
	v_mov_b32_e32 v31, v0
	v_mov_b32_e32 v40, v0
	v_mov_b32_e32 v41, v0
	v_mov_b32_e32 v42, v0
	v_mov_b32_e32 v43, v0
	v_mov_b32_e32 v44, v0
	v_mov_b32_e32 v45, v0
	v_mov_b32_e32 v46, v0
	v_mov_b32_e32 v47, v0
	v_mov_b32_e32 v56, v0
	v_mov_b32_e32 v57, v0
	v_mov_b32_e32 v58, v0
	v_mov_b32_e32 v59, v0
	v_mov_b32_e32 v60, v0
	v_mov_b32_e32 v61, v0
	v_mov_b32_e32 v62, v0
	v_mov_b32_e32 v63, v0
	v_mov_b32_e32 v64, v0
	v_mov_b32_e32 v65, v0
	v_mov_b32_e32 v66, v0
	v_mov_b32_e32 v67, v0
	v_mov_b32_e32 v68, v0
	v_mov_b32_e32 v69, v0
	v_mov_b32_e32 v70, v0
	v_mov_b32_e32 v71, v0
	v_mov_b32_e32 v80, v0
	v_mov_b32_e32 v81, v0
	v_mov_b32_e32 v82, v0
	v_mov_b32_e32 v83, v0
	v_mov_b32_e32 v84, v0
	v_mov_b32_e32 v85, v0
	v_mov_b32_e32 v86, v0
	v_mov_b32_e32 v87, v0
	v_mov_b32_e32 v96, v0
	v_mov_b32_e32 v97, v0
	v_mov_b32_e32 v98, v0
	v_mov_b32_e32 v99, v0
	v_mov_b32_e32 v100, v0
	v_mov_b32_e32 v101, v0
	v_mov_b32_e32 v102, v0
	v_mov_b32_e32 v103, v0
	v_mov_b32_e32 v112, v0
	v_mov_b32_e32 v113, v0
	v_mov_b32_e32 v114, v0
	v_mov_b32_e32 v115, v0
	v_mov_b32_e32 v116, v0
	v_mov_b32_e32 v117, v0
	v_mov_b32_e32 v118, v0
	v_mov_b32_e32 v119, v0
	v_mov_b32_e32 v72, v0
	v_mov_b32_e32 v73, v0
	v_mov_b32_e32 v74, v0
	v_mov_b32_e32 v75, v0
	v_mov_b32_e32 v76, v0
	v_mov_b32_e32 v77, v0
	v_mov_b32_e32 v78, v0
	v_mov_b32_e32 v79, v0
	v_mov_b32_e32 v88, v0
	v_mov_b32_e32 v89, v0
	v_mov_b32_e32 v90, v0
	v_mov_b32_e32 v91, v0
	v_mov_b32_e32 v92, v0
	v_mov_b32_e32 v93, v0
	v_mov_b32_e32 v94, v0
	v_mov_b32_e32 v95, v0
	v_mov_b32_e32 v104, v0
	v_mov_b32_e32 v105, v0
	v_mov_b32_e32 v106, v0
	v_mov_b32_e32 v107, v0
	v_mov_b32_e32 v108, v0
	v_mov_b32_e32 v109, v0
	v_mov_b32_e32 v110, v0
	v_mov_b32_e32 v111, v0
	v_mov_b32_e32 v124, v0
	v_mov_b32_e32 v125, v0
	v_mov_b32_e32 v126, v0
	v_mov_b32_e32 v127, v0
	v_mov_b32_e32 v120, v0
	v_mov_b32_e32 v121, v0
	v_mov_b32_e32 v122, v0
	v_mov_b32_e32 v123, v0
	s_cmp_eq_u32 s48, s12
	v_lshl_add_u64 v[192:193], v[130:131], 0, s[22:23]
	s_cselect_b64 vcc, -1, 0
	s_add_i32 s12, s12, 2
	v_cndmask_b32_e32 v197, v193, v177, vcc
	v_cndmask_b32_e32 v196, v192, v176, vcc
	v_cndmask_b32_e32 v213, v129, v179, vcc
	v_cndmask_b32_e32 v212, v128, v178, vcc
	.p2align	6
; #define PG8_STAGE(bufoff, gbase, voff) do { _Pragma("unroll") for (int _i = 0; _i < 2; ++_i) \
;         __builtin_amdgcn_global_load_lds((const unsigned*)((const char*)(gbase) + (voff)[_i]), (PG8_LAS unsigned*)(lds + (bufoff) + ldsw + _i * 8192), 16, 0, 0); } while (0)
; #define PG8_LDA(dst, b, h) do { _Pragma("unroll") for (int m = 0; m < 4; ++m) _Pragma("unroll") for (int k = 0; k < 2; ++k) dst[m][k] = *(const PG8_LAS bf16x8*)(lds + PG8_SA(b, h) + aoff + m * 2048 + k * 1024); } while (0)
; #define PG8_LDB(dst, b, h) do { _Pragma("unroll") for (int n = 0; n < 2; ++n) _Pragma("unroll") for (int k = 0; k < 2; ++k) dst[n][k] = *(const PG8_LAS bf16x8*)(lds + PG8_SB(b, h) + boff + n * 2048 + k * 1024); } while (0)
; #define PG8_MMA(ai, bj, At, Bt) do { __builtin_amdgcn_s_setprio(1); _Pragma("unroll") for (int m = 0; m < 4; ++m) _Pragma("unroll") for (int n = 0; n < 2; ++n) _Pragma("unroll") for (int k = 0; k < 2; ++k) \
;         acc[ai][bj][m][n] = __builtin_amdgcn_mfma_f32_16x16x32_bf16(Bt[n][k], At[m][k], acc[ai][bj][m][n], 0, 0, 0); __builtin_amdgcn_s_setprio(0); } while (0)
; #define PG8_WAIT_V(n) asm volatile("s_waitcnt vmcnt(" #n ")" ::: "memory")
; #define PG8_WAIT_L(n) asm volatile("s_waitcnt lgkmcnt(" #n ")" ::: "memory")
; #define PG8_BAR __builtin_amdgcn_s_barrier()
; #define PG8_SCHED __builtin_amdgcn_sched_barrier(0)
; template <class Epi, class Sched, bool ALIGN_EPI = false, bool SP2 = false>
; __device__ __forceinline__ void gemm_phase(PG8_LAS unsigned char* lds, const Gemm g, const Sched& S, const Epi& E) {
;     ...
;             PG8_LDB(B0, 0, 0); PG8_LDB(B1, 0, 1); PG8_SCHED; PG8_LDA(At, 0, 0); PG8_STAGE(PG8_SA(1, 1), a1 + hstep, voffA);
;             PG8_WAIT_V(8); PG8_WAIT_L(0); PG8_BAR; PG8_MMA(0, 0, At, B0); PG8_MMA(0, 1, At, B1); PG8_BAR; PG8_SCHED;
;             PG8_LDA(At, 0, 1); PG8_STAGE(PG8_SB(0, 0), b2, voffB); PG8_STAGE(PG8_SB(0, 1), b2 + hstep, voffB); PG8_STAGE(PG8_SA(0, 0), a2, voffA);
;             PG8_WAIT_V(8); PG8_WAIT_L(0); PG8_BAR; PG8_MMA(1, 0, At, B0); PG8_MMA(1, 1, At, B1); PG8_BAR; PG8_SCHED;
.LBB0_940:
	v_add_u32_e32 v188, s55, v199
	ds_read_b128 v[132:135], v201
	ds_read_b128 v[136:139], v201 offset:1024
	ds_read_b128 v[140:143], v201 offset:2048
	ds_read_b128 v[144:147], v201 offset:3072
	ds_read_b128 v[148:151], v188
	ds_read_b128 v[180:183], v188 offset:1024
	ds_read_b128 v[184:187], v188 offset:2048
	ds_read_b128 v[188:191], v188 offset:3072
	s_mov_b32 m0, s56
	v_lshl_add_u64 v[214:215], v[130:131], 0, v[172:173]
	ds_read_b128 v[192:195], v202
	ds_read_b128 v[204:207], v202 offset:1024
	ds_read_b128 v[208:211], v202 offset:2048
	ds_read_b128 v[216:219], v202 offset:3072
	ds_read_b128 v[220:223], v202 offset:4096
	ds_read_b128 v[224:227], v202 offset:5120
	ds_read_b128 v[228:231], v202 offset:6144
	ds_read_b128 v[232:235], v202 offset:7168
	global_load_lds_dwordx4 v[214:215], off
	s_mov_b32 m0, s57
	v_lshl_add_u64 v[214:215], v[130:131], 0, v[170:171]
	global_load_lds_dwordx4 v[214:215], off
	s_waitcnt vmcnt(8) lgkmcnt(0)
	s_setprio 1
	s_barrier
	v_mfma_f32_16x16x32_bf16 v[120:123], v[132:135], v[192:195], v[120:123]
	v_mfma_f32_16x16x32_bf16 v[124:127], v[140:143], v[192:195], v[124:127]
	v_mfma_f32_16x16x32_bf16 v[108:111], v[132:135], v[208:211], v[108:111]
	v_mfma_f32_16x16x32_bf16 v[104:107], v[140:143], v[208:211], v[104:107]
	v_mfma_f32_16x16x32_bf16 v[92:95], v[132:135], v[220:223], v[92:95]
	v_mfma_f32_16x16x32_bf16 v[88:91], v[140:143], v[220:223], v[88:91]
	v_mfma_f32_16x16x32_bf16 v[76:79], v[132:135], v[228:231], v[76:79]
	v_mfma_f32_16x16x32_bf16 v[72:75], v[140:143], v[228:231], v[72:75]
	v_mfma_f32_16x16x32_bf16 v[120:123], v[136:139], v[204:207], v[120:123]
	v_mfma_f32_16x16x32_bf16 v[124:127], v[144:147], v[204:207], v[124:127]
	v_mfma_f32_16x16x32_bf16 v[108:111], v[136:139], v[216:219], v[108:111]
	v_mfma_f32_16x16x32_bf16 v[104:107], v[144:147], v[216:219], v[104:107]
	v_mfma_f32_16x16x32_bf16 v[92:95], v[136:139], v[224:227], v[92:95]
	v_mfma_f32_16x16x32_bf16 v[88:91], v[144:147], v[224:227], v[88:91]
	v_mfma_f32_16x16x32_bf16 v[76:79], v[136:139], v[232:235], v[76:79]
	v_mfma_f32_16x16x32_bf16 v[72:75], v[144:147], v[232:235], v[72:75]
	v_mfma_f32_16x16x32_bf16 v[116:119], v[148:151], v[192:195], v[116:119]
	v_mfma_f32_16x16x32_bf16 v[112:115], v[184:187], v[192:195], v[112:115]
	v_mfma_f32_16x16x32_bf16 v[100:103], v[148:151], v[208:211], v[100:103]
	v_mfma_f32_16x16x32_bf16 v[96:99], v[184:187], v[208:211], v[96:99]
	v_mfma_f32_16x16x32_bf16 v[84:87], v[148:151], v[220:223], v[84:87]
	v_mfma_f32_16x16x32_bf16 v[80:83], v[184:187], v[220:223], v[80:83]
	v_mfma_f32_16x16x32_bf16 v[68:71], v[148:151], v[228:231], v[68:71]
	v_mfma_f32_16x16x32_bf16 v[64:67], v[184:187], v[228:231], v[64:67]
	v_mfma_f32_16x16x32_bf16 v[116:119], v[180:183], v[204:207], v[116:119]
	v_mfma_f32_16x16x32_bf16 v[112:115], v[188:191], v[204:207], v[112:115]
	v_mfma_f32_16x16x32_bf16 v[100:103], v[180:183], v[216:219], v[100:103]
	v_mfma_f32_16x16x32_bf16 v[96:99], v[188:191], v[216:219], v[96:99]
	v_mfma_f32_16x16x32_bf16 v[84:87], v[180:183], v[224:227], v[84:87]
	v_mfma_f32_16x16x32_bf16 v[80:83], v[188:191], v[224:227], v[80:83]
	v_mfma_f32_16x16x32_bf16 v[68:71], v[180:183], v[232:235], v[68:71]
	v_mfma_f32_16x16x32_bf16 v[64:67], v[188:191], v[232:235], v[64:67]
	s_setprio 0
	s_barrier
	s_mov_b32 m0, s58
	v_lshl_add_u64 v[214:215], v[212:213], 0, v[164:165]
	ds_read_b128 v[192:195], v202 offset:16384
	ds_read_b128 v[204:207], v202 offset:17408
	ds_read_b128 v[208:211], v202 offset:18432
	ds_read_b128 v[216:219], v202 offset:19456
	ds_read_b128 v[220:223], v202 offset:20480
	ds_read_b128 v[224:227], v202 offset:21504
	ds_read_b128 v[228:231], v202 offset:22528
	ds_read_b128 v[232:235], v202 offset:23552
	global_load_lds_dwordx4 v[214:215], off
	v_lshl_add_u64 v[236:237], v[212:213], 0, v[168:169]
	s_mov_b32 m0, s59
	v_lshl_add_u64 v[212:213], v[212:213], 0, s[14:15]
	s_add_i32 s13, s55, s30
	global_load_lds_dwordx4 v[236:237], off
	v_lshl_add_u64 v[238:239], v[212:213], 0, v[164:165]
	s_mov_b32 m0, s13
	v_lshl_add_u64 v[212:213], v[212:213], 0, v[168:169]
	global_load_lds_dwordx4 v[238:239], off
	s_add_i32 m0, s13, 0x2000
	v_lshl_add_u64 v[240:241], v[196:197], 0, v[162:163]
	global_load_lds_dwordx4 v[212:213], off
	s_mov_b32 m0, s31
	v_lshl_add_u64 v[242:243], v[196:197], 0, v[166:167]
	global_load_lds_dwordx4 v[240:241], off
	s_mov_b32 m0, s34
	s_nop 0
	global_load_lds_dwordx4 v[242:243], off
	s_waitcnt vmcnt(8) lgkmcnt(0)
	s_setprio 1
	s_barrier
	v_mfma_f32_16x16x32_bf16 v[60:63], v[132:135], v[192:195], v[60:63]
	v_mfma_f32_16x16x32_bf16 v[56:59], v[140:143], v[192:195], v[56:59]
	v_mfma_f32_16x16x32_bf16 v[44:47], v[132:135], v[208:211], v[44:47]
	v_mfma_f32_16x16x32_bf16 v[40:43], v[140:143], v[208:211], v[40:43]
	v_mfma_f32_16x16x32_bf16 v[28:31], v[132:135], v[220:223], v[28:31]
	v_mfma_f32_16x16x32_bf16 v[24:27], v[140:143], v[220:223], v[24:27]
	v_mfma_f32_16x16x32_bf16 v[12:15], v[132:135], v[228:231], v[12:15]
	v_mfma_f32_16x16x32_bf16 v[8:11], v[140:143], v[228:231], v[8:11]
	v_mfma_f32_16x16x32_bf16 v[60:63], v[136:139], v[204:207], v[60:63]
	v_mfma_f32_16x16x32_bf16 v[56:59], v[144:147], v[204:207], v[56:59]
	v_mfma_f32_16x16x32_bf16 v[44:47], v[136:139], v[216:219], v[44:47]
	v_mfma_f32_16x16x32_bf16 v[40:43], v[144:147], v[216:219], v[40:43]
	v_mfma_f32_16x16x32_bf16 v[28:31], v[136:139], v[224:227], v[28:31]
	v_mfma_f32_16x16x32_bf16 v[24:27], v[144:147], v[224:227], v[24:27]
	v_mfma_f32_16x16x32_bf16 v[12:15], v[136:139], v[232:235], v[12:15]
	v_mfma_f32_16x16x32_bf16 v[8:11], v[144:147], v[232:235], v[8:11]
	v_mfma_f32_16x16x32_bf16 v[52:55], v[148:151], v[192:195], v[52:55]
	v_mfma_f32_16x16x32_bf16 v[48:51], v[184:187], v[192:195], v[48:51]
	v_mfma_f32_16x16x32_bf16 v[36:39], v[148:151], v[208:211], v[36:39]
	v_mfma_f32_16x16x32_bf16 v[32:35], v[184:187], v[208:211], v[32:35]
	v_mfma_f32_16x16x32_bf16 v[20:23], v[148:151], v[220:223], v[20:23]
	v_mfma_f32_16x16x32_bf16 v[16:19], v[184:187], v[220:223], v[16:19]
	v_mfma_f32_16x16x32_bf16 v[4:7], v[148:151], v[228:231], v[4:7]
	v_mfma_f32_16x16x32_bf16 v[0:3], v[184:187], v[228:231], v[0:3]
	v_mfma_f32_16x16x32_bf16 v[52:55], v[180:183], v[204:207], v[52:55]
	v_mfma_f32_16x16x32_bf16 v[48:51], v[188:191], v[204:207], v[48:51]
	v_mfma_f32_16x16x32_bf16 v[36:39], v[180:183], v[216:219], v[36:39]
	v_mfma_f32_16x16x32_bf16 v[32:35], v[188:191], v[216:219], v[32:35]
	v_mfma_f32_16x16x32_bf16 v[20:23], v[180:183], v[224:227], v[20:23]
	v_mfma_f32_16x16x32_bf16 v[16:19], v[188:191], v[224:227], v[16:19]
	v_mfma_f32_16x16x32_bf16 v[4:7], v[180:183], v[232:235], v[4:7]
	v_mfma_f32_16x16x32_bf16 v[0:3], v[188:191], v[232:235], v[0:3]
	s_setprio 0
	s_barrier
; #define PG8_STAGE(bufoff, gbase, voff) do { _Pragma("unroll") for (int _i = 0; _i < 2; ++_i) \
;         __builtin_amdgcn_global_load_lds((const unsigned*)((const char*)(gbase) + (voff)[_i]), (PG8_LAS unsigned*)(lds + (bufoff) + ldsw + _i * 8192), 16, 0, 0); } while (0)
; #define PG8_LDA(dst, b, h) do { _Pragma("unroll") for (int m = 0; m < 4; ++m) _Pragma("unroll") for (int k = 0; k < 2; ++k) dst[m][k] = *(const PG8_LAS bf16x8*)(lds + PG8_SA(b, h) + aoff + m * 2048 + k * 1024); } while (0)
; #define PG8_LDB(dst, b, h) do { _Pragma("unroll") for (int n = 0; n < 2; ++n) _Pragma("unroll") for (int k = 0; k < 2; ++k) dst[n][k] = *(const PG8_LAS bf16x8*)(lds + PG8_SB(b, h) + boff + n * 2048 + k * 1024); } while (0)
; #define PG8_MMA(ai, bj, At, Bt) do { __builtin_amdgcn_s_setprio(1); _Pragma("unroll") for (int m = 0; m < 4; ++m) _Pragma("unroll") for (int n = 0; n < 2; ++n) _Pragma("unroll") for (int k = 0; k < 2; ++k) \
;         acc[ai][bj][m][n] = __builtin_amdgcn_mfma_f32_16x16x32_bf16(Bt[n][k], At[m][k], acc[ai][bj][m][n], 0, 0, 0); __builtin_amdgcn_s_setprio(0); } while (0)
; #define PG8_WAIT_V(n) asm volatile("s_waitcnt vmcnt(" #n ")" ::: "memory")
; #define PG8_WAIT_L(n) asm volatile("s_waitcnt lgkmcnt(" #n ")" ::: "memory")
; #define PG8_BAR __builtin_amdgcn_s_barrier()
; #define PG8_SCHED __builtin_amdgcn_sched_barrier(0)
; template <class Epi, class Sched, bool ALIGN_EPI = false, bool SP2 = false>
; __device__ __forceinline__ void gemm_phase(PG8_LAS unsigned char* lds, const Gemm g, const Sched& S, const Epi& E) {
;     ...
;             PG8_LDB(B0, 1, 0); PG8_LDB(B1, 1, 1); PG8_SCHED; PG8_LDA(At, 1, 0); PG8_STAGE(PG8_SA(0, 1), a2 + hstep, voffA);
;             PG8_WAIT_V(8); PG8_WAIT_L(0); PG8_BAR; PG8_MMA(0, 0, At, B0); PG8_MMA(0, 1, At, B1); PG8_BAR; PG8_SCHED;
;             PG8_LDA(At, 1, 1); PG8_STAGE(PG8_SB(1, 0), b3, voffB); PG8_STAGE(PG8_SB(1, 1), b3 + hstep, voffB); PG8_STAGE(PG8_SA(1, 0), a3, voffA);
;             PG8_WAIT_V(8); PG8_WAIT_L(0); PG8_BAR; PG8_MMA(1, 0, At, B0); PG8_MMA(1, 1, At, B1); PG8_BAR; PG8_SCHED;
	s_add_i32 s13, 0, 0x18000
	s_add_i32 s29, 0, 0x1c000
	v_add_u32_e32 v144, s13, v199
	v_add_u32_e32 v188, s29, v199
	ds_read_b128 v[132:135], v144
	ds_read_b128 v[136:139], v144 offset:1024
	ds_read_b128 v[140:143], v144 offset:2048
	ds_read_b128 v[144:147], v144 offset:3072
	ds_read_b128 v[148:151], v188
	ds_read_b128 v[180:183], v188 offset:1024
	ds_read_b128 v[184:187], v188 offset:2048
	ds_read_b128 v[188:191], v188 offset:3072
	v_lshl_add_u64 v[196:197], v[196:197], 0, s[14:15]
	s_mov_b32 m0, s35
	v_lshl_add_u64 v[244:245], v[196:197], 0, v[162:163]
	ds_read_b128 v[192:195], v202 offset:32768
	ds_read_b128 v[204:207], v202 offset:33792
	ds_read_b128 v[208:211], v202 offset:34816
	ds_read_b128 v[216:219], v202 offset:35840
	ds_read_b128 v[220:223], v202 offset:36864
	ds_read_b128 v[224:227], v202 offset:37888
	ds_read_b128 v[228:231], v202 offset:38912
	ds_read_b128 v[232:235], v202 offset:39936
	global_load_lds_dwordx4 v[244:245], off
	s_mov_b32 m0, s36
	v_lshl_add_u64 v[196:197], v[196:197], 0, v[166:167]
	global_load_lds_dwordx4 v[196:197], off
	s_waitcnt vmcnt(8) lgkmcnt(0)
	s_setprio 1
	s_barrier
	v_mfma_f32_16x16x32_bf16 v[120:123], v[132:135], v[192:195], v[120:123]
	v_mfma_f32_16x16x32_bf16 v[124:127], v[140:143], v[192:195], v[124:127]
	v_mfma_f32_16x16x32_bf16 v[108:111], v[132:135], v[208:211], v[108:111]
	v_mfma_f32_16x16x32_bf16 v[104:107], v[140:143], v[208:211], v[104:107]
	v_mfma_f32_16x16x32_bf16 v[92:95], v[132:135], v[220:223], v[92:95]
	v_mfma_f32_16x16x32_bf16 v[88:91], v[140:143], v[220:223], v[88:91]
	v_mfma_f32_16x16x32_bf16 v[76:79], v[132:135], v[228:231], v[76:79]
	v_mfma_f32_16x16x32_bf16 v[72:75], v[140:143], v[228:231], v[72:75]
	v_mfma_f32_16x16x32_bf16 v[120:123], v[136:139], v[204:207], v[120:123]
	v_mfma_f32_16x16x32_bf16 v[124:127], v[144:147], v[204:207], v[124:127]
	v_mfma_f32_16x16x32_bf16 v[108:111], v[136:139], v[216:219], v[108:111]
	v_mfma_f32_16x16x32_bf16 v[104:107], v[144:147], v[216:219], v[104:107]
	v_mfma_f32_16x16x32_bf16 v[92:95], v[136:139], v[224:227], v[92:95]
	v_mfma_f32_16x16x32_bf16 v[88:91], v[144:147], v[224:227], v[88:91]
	v_mfma_f32_16x16x32_bf16 v[76:79], v[136:139], v[232:235], v[76:79]
	v_mfma_f32_16x16x32_bf16 v[72:75], v[144:147], v[232:235], v[72:75]
	v_mfma_f32_16x16x32_bf16 v[116:119], v[148:151], v[192:195], v[116:119]
	v_mfma_f32_16x16x32_bf16 v[112:115], v[184:187], v[192:195], v[112:115]
	v_mfma_f32_16x16x32_bf16 v[100:103], v[148:151], v[208:211], v[100:103]
	v_mfma_f32_16x16x32_bf16 v[96:99], v[184:187], v[208:211], v[96:99]
	v_mfma_f32_16x16x32_bf16 v[84:87], v[148:151], v[220:223], v[84:87]
	v_mfma_f32_16x16x32_bf16 v[80:83], v[184:187], v[220:223], v[80:83]
	v_mfma_f32_16x16x32_bf16 v[68:71], v[148:151], v[228:231], v[68:71]
	v_mfma_f32_16x16x32_bf16 v[64:67], v[184:187], v[228:231], v[64:67]
	v_mfma_f32_16x16x32_bf16 v[116:119], v[180:183], v[204:207], v[116:119]
	v_mfma_f32_16x16x32_bf16 v[112:115], v[188:191], v[204:207], v[112:115]
	v_mfma_f32_16x16x32_bf16 v[100:103], v[180:183], v[216:219], v[100:103]
	v_mfma_f32_16x16x32_bf16 v[96:99], v[188:191], v[216:219], v[96:99]
	v_mfma_f32_16x16x32_bf16 v[84:87], v[180:183], v[224:227], v[84:87]
	v_mfma_f32_16x16x32_bf16 v[80:83], v[188:191], v[224:227], v[80:83]
	v_mfma_f32_16x16x32_bf16 v[68:71], v[180:183], v[232:235], v[68:71]
	v_mfma_f32_16x16x32_bf16 v[64:67], v[188:191], v[232:235], v[64:67]
	s_setprio 0
	s_barrier
	s_add_i32 s13, s13, s30
	s_add_i32 m0, s13, 0xffffff80
	ds_read_b128 v[192:195], v202 offset:49152
	ds_read_b128 v[204:207], v202 offset:50176
	ds_read_b128 v[208:211], v202 offset:51200
	ds_read_b128 v[216:219], v202 offset:52224
	global_load_lds_dwordx4 v[214:215], off offset:128
	s_add_i32 m0, s13, 0x1f80
	s_add_i32 s13, s29, s30
	global_load_lds_dwordx4 v[236:237], off offset:128
	s_add_i32 m0, s13, 0xffffff80
	ds_read_b128 v[232:235], v202 offset:56320
	global_load_lds_dwordx4 v[238:239], off offset:128
	s_add_i32 m0, s13, 0x1f80
	ds_read_b128 v[228:231], v202 offset:55296
	global_load_lds_dwordx4 v[212:213], off offset:128
	s_add_i32 m0, s37, 0xffffff80
	ds_read_b128 v[224:227], v202 offset:54272
	global_load_lds_dwordx4 v[240:241], off offset:128
	s_add_i32 m0, s41, 0xffffff80
	ds_read_b128 v[220:223], v202 offset:53248
	global_load_lds_dwordx4 v[242:243], off offset:128
	s_waitcnt vmcnt(8) lgkmcnt(0)
	s_setprio 1
	s_barrier
	v_mfma_f32_16x16x32_bf16 v[60:63], v[132:135], v[192:195], v[60:63]
	v_mfma_f32_16x16x32_bf16 v[56:59], v[140:143], v[192:195], v[56:59]
	v_mfma_f32_16x16x32_bf16 v[44:47], v[132:135], v[208:211], v[44:47]
	v_mfma_f32_16x16x32_bf16 v[40:43], v[140:143], v[208:211], v[40:43]
	v_mfma_f32_16x16x32_bf16 v[28:31], v[132:135], v[220:223], v[28:31]
	v_mfma_f32_16x16x32_bf16 v[24:27], v[140:143], v[220:223], v[24:27]
	v_mfma_f32_16x16x32_bf16 v[12:15], v[132:135], v[228:231], v[12:15]
	v_mfma_f32_16x16x32_bf16 v[8:11], v[140:143], v[228:231], v[8:11]
	v_mfma_f32_16x16x32_bf16 v[60:63], v[136:139], v[204:207], v[60:63]
	v_mfma_f32_16x16x32_bf16 v[56:59], v[144:147], v[204:207], v[56:59]
	v_mfma_f32_16x16x32_bf16 v[44:47], v[136:139], v[216:219], v[44:47]
	v_mfma_f32_16x16x32_bf16 v[40:43], v[144:147], v[216:219], v[40:43]
	v_mfma_f32_16x16x32_bf16 v[28:31], v[136:139], v[224:227], v[28:31]
	v_mfma_f32_16x16x32_bf16 v[24:27], v[144:147], v[224:227], v[24:27]
	v_mfma_f32_16x16x32_bf16 v[12:15], v[136:139], v[232:235], v[12:15]
	v_mfma_f32_16x16x32_bf16 v[8:11], v[144:147], v[232:235], v[8:11]
	v_mfma_f32_16x16x32_bf16 v[52:55], v[148:151], v[192:195], v[52:55]
	v_mfma_f32_16x16x32_bf16 v[48:51], v[184:187], v[192:195], v[48:51]
	v_mfma_f32_16x16x32_bf16 v[36:39], v[148:151], v[208:211], v[36:39]
	v_mfma_f32_16x16x32_bf16 v[32:35], v[184:187], v[208:211], v[32:35]
	v_mfma_f32_16x16x32_bf16 v[20:23], v[148:151], v[220:223], v[20:23]
	v_mfma_f32_16x16x32_bf16 v[16:19], v[184:187], v[220:223], v[16:19]
	v_mfma_f32_16x16x32_bf16 v[4:7], v[148:151], v[228:231], v[4:7]
	v_mfma_f32_16x16x32_bf16 v[0:3], v[184:187], v[228:231], v[0:3]
	v_mfma_f32_16x16x32_bf16 v[52:55], v[180:183], v[204:207], v[52:55]
	v_mfma_f32_16x16x32_bf16 v[48:51], v[188:191], v[204:207], v[48:51]
	v_mfma_f32_16x16x32_bf16 v[36:39], v[180:183], v[216:219], v[36:39]
	v_mfma_f32_16x16x32_bf16 v[32:35], v[188:191], v[216:219], v[32:35]
	v_mfma_f32_16x16x32_bf16 v[20:23], v[180:183], v[224:227], v[20:23]
	v_mfma_f32_16x16x32_bf16 v[16:19], v[188:191], v[224:227], v[16:19]
	v_mfma_f32_16x16x32_bf16 v[4:7], v[180:183], v[232:235], v[4:7]
	v_mfma_f32_16x16x32_bf16 v[0:3], v[188:191], v[232:235], v[0:3]
	v_lshl_add_u64 v[128:129], v[128:129], 0, s[26:27]
	v_lshl_add_u64 v[130:131], v[130:131], 0, s[26:27]
	s_cmp_ge_i32 s12, s47
	s_cbranch_scc1 .Lrot_exit_12
	s_cmp_eq_u32 s48, s12
	v_lshl_add_u64 v[192:193], v[130:131], 0, s[22:23]
	s_cselect_b64 vcc, -1, 0
	s_add_i32 s12, s12, 2
	v_cndmask_b32_e32 v197, v193, v177, vcc
	v_cndmask_b32_e32 v196, v192, v176, vcc
	v_cndmask_b32_e32 v213, v129, v179, vcc
	v_cndmask_b32_e32 v212, v128, v178, vcc
	s_setprio 0
	s_barrier
	s_branch .LBB0_940
; #define PG8_MMA(ai, bj, At, Bt) do { __builtin_amdgcn_s_setprio(1); _Pragma("unroll") for (int m = 0; m < 4; ++m) _Pragma("unroll") for (int n = 0; n < 2; ++n) _Pragma("unroll") for (int k = 0; k < 2; ++k) \
;         acc[ai][bj][m][n] = __builtin_amdgcn_mfma_f32_16x16x32_bf16(Bt[n][k], At[m][k], acc[ai][bj][m][n], 0, 0, 0); __builtin_amdgcn_s_setprio(0); } while (0)
; #define PG8_WAIT_V(n) asm volatile("s_waitcnt vmcnt(" #n ")" ::: "memory")
; #define PG8_WAIT_L(n) asm volatile("s_waitcnt lgkmcnt(" #n ")" ::: "memory")
; #define PG8_BAR __builtin_amdgcn_s_barrier()
; #define PG8_SCHED __builtin_amdgcn_sched_barrier(0)
; template <class Epi, class Sched, bool ALIGN_EPI = false, bool SP2 = false>
; __device__ __forceinline__ void gemm_phase(PG8_LAS unsigned char* lds, const Gemm g, const Sched& S, const Epi& E) {
;     ...
;             PG8_WAIT_V(8); PG8_WAIT_L(0); PG8_BAR; PG8_MMA(1, 0, At, B0); PG8_MMA(1, 1, At, B1); PG8_BAR; PG8_SCHED;
;     ...
;         if constexpr (ALIGN_EPI) { if (wr == 0) PG8_BAR; }
.Lrot_exit_12:
	s_setprio 0
	s_barrier
.LBB0_941:
	s_and_b64 vcc, exec, s[24:25]
	s_cbranch_vccz .LBB0_943
	s_barrier

; template <class Epi, class Sched, bool ALIGN_EPI = false, bool SP2 = false>
; __device__ __forceinline__ void gemm_phase(PG8_LAS unsigned char* lds, const Gemm g, const Sched& S, const Epi& E) {
;     ...
;         for (int t = 0; t < nt; t += 2) {
;             const bool last = (t == nt - 2);
;             const char* a1 = cA + (size_t)(t + 1) * kstep;
;             const char* a2 = last ? nA : cA + (size_t)(t + 2) * kstep; const char* b2 = last ? nB : cB + (size_t)(t + 2) * kstep;
;     ...
; #pragma unroll
;         for (int a = 0; a < 2; ++a)
; #pragma unroll
;             for (int b = 0; b < 2; ++b)
; #pragma unroll
;                 for (int m = 0; m < 4; ++m)
; #pragma unroll
;                     for (int n = 0; n < 2; ++n) acc[a][b][m][n] = (f32x4){0.f, 0.f, 0.f, 0.f};
.LBB0_1019:
	v_mov_b32_e32 v127, 0
	s_and_b64 vcc, exec, s[6:7]
	v_mov_b32_e32 v126, v127
	v_mov_b32_e32 v125, v127
	v_mov_b32_e32 v124, v127
	v_mov_b32_e32 v119, v127
	v_mov_b32_e32 v118, v127
	v_mov_b32_e32 v117, v127
	v_mov_b32_e32 v116, v127
	v_mov_b32_e32 v111, v127
	v_mov_b32_e32 v110, v127
	v_mov_b32_e32 v109, v127
	v_mov_b32_e32 v108, v127
	v_mov_b32_e32 v103, v127
	v_mov_b32_e32 v102, v127
	v_mov_b32_e32 v101, v127
	v_mov_b32_e32 v100, v127
	v_mov_b32_e32 v95, v127
	v_mov_b32_e32 v94, v127
	v_mov_b32_e32 v93, v127
	v_mov_b32_e32 v92, v127
	v_mov_b32_e32 v87, v127
	v_mov_b32_e32 v86, v127
	v_mov_b32_e32 v85, v127
	v_mov_b32_e32 v84, v127
	v_mov_b32_e32 v79, v127
	v_mov_b32_e32 v78, v127
	v_mov_b32_e32 v77, v127
	v_mov_b32_e32 v76, v127
	v_mov_b32_e32 v71, v127
	v_mov_b32_e32 v70, v127
	v_mov_b32_e32 v69, v127
	v_mov_b32_e32 v68, v127
	v_mov_b32_e32 v123, v127
	v_mov_b32_e32 v122, v127
	v_mov_b32_e32 v121, v127
	v_mov_b32_e32 v120, v127
	v_mov_b32_e32 v115, v127
	v_mov_b32_e32 v114, v127
	v_mov_b32_e32 v113, v127
	v_mov_b32_e32 v112, v127
	v_mov_b32_e32 v107, v127
	v_mov_b32_e32 v106, v127
	v_mov_b32_e32 v105, v127
	v_mov_b32_e32 v104, v127
	v_mov_b32_e32 v99, v127
	v_mov_b32_e32 v98, v127
	v_mov_b32_e32 v97, v127
	v_mov_b32_e32 v96, v127
	v_mov_b32_e32 v91, v127
	v_mov_b32_e32 v90, v127
	v_mov_b32_e32 v89, v127
	v_mov_b32_e32 v88, v127
	v_mov_b32_e32 v83, v127
	v_mov_b32_e32 v82, v127
	v_mov_b32_e32 v81, v127
	v_mov_b32_e32 v80, v127
	v_mov_b32_e32 v75, v127
	v_mov_b32_e32 v74, v127
	v_mov_b32_e32 v73, v127
	v_mov_b32_e32 v72, v127
	v_mov_b32_e32 v67, v127
	v_mov_b32_e32 v66, v127
	v_mov_b32_e32 v65, v127
	v_mov_b32_e32 v64, v127
	v_mov_b32_e32 v63, v127
	v_mov_b32_e32 v62, v127
	v_mov_b32_e32 v61, v127
	v_mov_b32_e32 v60, v127
	v_mov_b32_e32 v55, v127
	v_mov_b32_e32 v54, v127
	v_mov_b32_e32 v53, v127
	v_mov_b32_e32 v52, v127
	v_mov_b32_e32 v47, v127
	v_mov_b32_e32 v46, v127
	v_mov_b32_e32 v45, v127
	v_mov_b32_e32 v44, v127
	v_mov_b32_e32 v39, v127
	v_mov_b32_e32 v38, v127
	v_mov_b32_e32 v37, v127
	v_mov_b32_e32 v36, v127
	v_mov_b32_e32 v31, v127
	v_mov_b32_e32 v30, v127
	v_mov_b32_e32 v29, v127
	v_mov_b32_e32 v28, v127
	v_mov_b32_e32 v23, v127
	v_mov_b32_e32 v22, v127
	v_mov_b32_e32 v21, v127
	v_mov_b32_e32 v20, v127
	v_mov_b32_e32 v15, v127
	v_mov_b32_e32 v14, v127
	v_mov_b32_e32 v13, v127
	v_mov_b32_e32 v12, v127
	v_mov_b32_e32 v7, v127
	v_mov_b32_e32 v6, v127
	v_mov_b32_e32 v5, v127
	v_mov_b32_e32 v4, v127
	v_mov_b32_e32 v59, v127
	v_mov_b32_e32 v58, v127
	v_mov_b32_e32 v57, v127
	v_mov_b32_e32 v56, v127
	v_mov_b32_e32 v51, v127
	v_mov_b32_e32 v50, v127
	v_mov_b32_e32 v49, v127
	v_mov_b32_e32 v48, v127
	v_mov_b32_e32 v43, v127
	v_mov_b32_e32 v42, v127
	v_mov_b32_e32 v41, v127
	v_mov_b32_e32 v40, v127
	v_mov_b32_e32 v35, v127
	v_mov_b32_e32 v34, v127
	v_mov_b32_e32 v33, v127
	v_mov_b32_e32 v32, v127
	v_mov_b32_e32 v27, v127
	v_mov_b32_e32 v26, v127
	v_mov_b32_e32 v25, v127
	v_mov_b32_e32 v24, v127
	v_mov_b32_e32 v19, v127
	v_mov_b32_e32 v18, v127
	v_mov_b32_e32 v17, v127
	v_mov_b32_e32 v16, v127
	v_mov_b32_e32 v11, v127
	v_mov_b32_e32 v10, v127
	v_mov_b32_e32 v9, v127
	v_mov_b32_e32 v8, v127
	v_mov_b32_e32 v3, v127
	v_mov_b32_e32 v2, v127
	v_mov_b32_e32 v1, v127
	v_mov_b32_e32 v0, v127
	s_cbranch_vccnz .LBB0_1022
	v_mov_b32_e32 v0, 0
	v_lshl_add_u64 v[158:159], v[158:159], 0, s[26:27]
	v_lshl_add_u64 v[160:161], v[160:161], 0, s[22:23]
	s_mov_b32 s10, 0
	v_mov_b32_e32 v1, v0
	v_mov_b32_e32 v2, v0
	v_mov_b32_e32 v3, v0
	v_mov_b32_e32 v8, v0
	v_mov_b32_e32 v9, v0
	v_mov_b32_e32 v10, v0
	v_mov_b32_e32 v11, v0
	v_mov_b32_e32 v16, v0
	v_mov_b32_e32 v17, v0
	v_mov_b32_e32 v18, v0
	v_mov_b32_e32 v19, v0
	v_mov_b32_e32 v24, v0
	v_mov_b32_e32 v25, v0
	v_mov_b32_e32 v26, v0
	v_mov_b32_e32 v27, v0
	v_mov_b32_e32 v32, v0
	v_mov_b32_e32 v33, v0
	v_mov_b32_e32 v34, v0
	v_mov_b32_e32 v35, v0
	v_mov_b32_e32 v40, v0
	v_mov_b32_e32 v41, v0
	v_mov_b32_e32 v42, v0
	v_mov_b32_e32 v43, v0
	v_mov_b32_e32 v48, v0
	v_mov_b32_e32 v49, v0
	v_mov_b32_e32 v50, v0
	v_mov_b32_e32 v51, v0
	v_mov_b32_e32 v56, v0
	v_mov_b32_e32 v57, v0
	v_mov_b32_e32 v58, v0
	v_mov_b32_e32 v59, v0
	v_mov_b32_e32 v4, v0
	v_mov_b32_e32 v5, v0
	v_mov_b32_e32 v6, v0
	v_mov_b32_e32 v7, v0
	v_mov_b32_e32 v12, v0
	v_mov_b32_e32 v13, v0
	v_mov_b32_e32 v14, v0
	v_mov_b32_e32 v15, v0
	v_mov_b32_e32 v20, v0
	v_mov_b32_e32 v21, v0
	v_mov_b32_e32 v22, v0
	v_mov_b32_e32 v23, v0
	v_mov_b32_e32 v28, v0
	v_mov_b32_e32 v29, v0
	v_mov_b32_e32 v30, v0
	v_mov_b32_e32 v31, v0
	v_mov_b32_e32 v36, v0
	v_mov_b32_e32 v37, v0
	v_mov_b32_e32 v38, v0
	v_mov_b32_e32 v39, v0
	v_mov_b32_e32 v44, v0
	v_mov_b32_e32 v45, v0
	v_mov_b32_e32 v46, v0
	v_mov_b32_e32 v47, v0
	v_mov_b32_e32 v52, v0
	v_mov_b32_e32 v53, v0
	v_mov_b32_e32 v54, v0
	v_mov_b32_e32 v55, v0
	v_mov_b32_e32 v60, v0
	v_mov_b32_e32 v61, v0
	v_mov_b32_e32 v62, v0
	v_mov_b32_e32 v63, v0
	v_mov_b32_e32 v64, v0
	v_mov_b32_e32 v65, v0
	v_mov_b32_e32 v66, v0
	v_mov_b32_e32 v67, v0
	v_mov_b32_e32 v72, v0
	v_mov_b32_e32 v73, v0
	v_mov_b32_e32 v74, v0
	v_mov_b32_e32 v75, v0
	v_mov_b32_e32 v80, v0
	v_mov_b32_e32 v81, v0
	v_mov_b32_e32 v82, v0
	v_mov_b32_e32 v83, v0
	v_mov_b32_e32 v88, v0
	v_mov_b32_e32 v89, v0
	v_mov_b32_e32 v90, v0
	v_mov_b32_e32 v91, v0
	v_mov_b32_e32 v96, v0
	v_mov_b32_e32 v97, v0
	v_mov_b32_e32 v98, v0
	v_mov_b32_e32 v99, v0
	v_mov_b32_e32 v104, v0
	v_mov_b32_e32 v105, v0
	v_mov_b32_e32 v106, v0
	v_mov_b32_e32 v107, v0
	v_mov_b32_e32 v112, v0
	v_mov_b32_e32 v113, v0
	v_mov_b32_e32 v114, v0
	v_mov_b32_e32 v115, v0
	v_mov_b32_e32 v120, v0
	v_mov_b32_e32 v121, v0
	v_mov_b32_e32 v122, v0
	v_mov_b32_e32 v123, v0
	v_mov_b32_e32 v68, v0
	v_mov_b32_e32 v69, v0
	v_mov_b32_e32 v70, v0
	v_mov_b32_e32 v71, v0
	v_mov_b32_e32 v76, v0
	v_mov_b32_e32 v77, v0
	v_mov_b32_e32 v78, v0
	v_mov_b32_e32 v79, v0
	v_mov_b32_e32 v84, v0
	v_mov_b32_e32 v85, v0
	v_mov_b32_e32 v86, v0
	v_mov_b32_e32 v87, v0
	v_mov_b32_e32 v92, v0
	v_mov_b32_e32 v93, v0
	v_mov_b32_e32 v94, v0
	v_mov_b32_e32 v95, v0
	v_mov_b32_e32 v100, v0
	v_mov_b32_e32 v101, v0
	v_mov_b32_e32 v102, v0
	v_mov_b32_e32 v103, v0
	v_mov_b32_e32 v108, v0
	v_mov_b32_e32 v109, v0
	v_mov_b32_e32 v110, v0
	v_mov_b32_e32 v111, v0
	v_mov_b32_e32 v116, v0
	v_mov_b32_e32 v117, v0
	v_mov_b32_e32 v118, v0
	v_mov_b32_e32 v119, v0
	v_mov_b32_e32 v124, v0
	v_mov_b32_e32 v125, v0
	v_mov_b32_e32 v126, v0
	v_mov_b32_e32 v127, v0
	s_cmp_eq_u32 s54, s10
	v_lshl_add_u64 v[172:173], v[160:161], 0, s[22:23]
	s_cselect_b64 vcc, -1, 0
	s_add_i32 s10, s10, 2
	v_cndmask_b32_e32 v173, v173, v153, vcc
	v_cndmask_b32_e32 v172, v172, v152, vcc
	v_cndmask_b32_e32 v215, v159, v155, vcc
	v_cndmask_b32_e32 v214, v158, v154, vcc
	.p2align	6
; #define PG8_STAGE(bufoff, gbase, voff) do { _Pragma("unroll") for (int _i = 0; _i < 2; ++_i) \
;         __builtin_amdgcn_global_load_lds((const unsigned*)((const char*)(gbase) + (voff)[_i]), (PG8_LAS unsigned*)(lds + (bufoff) + ldsw + _i * 8192), 16, 0, 0); } while (0)
; #define PG8_LDA(dst, b, h) do { _Pragma("unroll") for (int m = 0; m < 4; ++m) _Pragma("unroll") for (int k = 0; k < 2; ++k) dst[m][k] = *(const PG8_LAS bf16x8*)(lds + PG8_SA(b, h) + aoff + m * 2048 + k * 1024); } while (0)
; #define PG8_LDB(dst, b, h) do { _Pragma("unroll") for (int n = 0; n < 2; ++n) _Pragma("unroll") for (int k = 0; k < 2; ++k) dst[n][k] = *(const PG8_LAS bf16x8*)(lds + PG8_SB(b, h) + boff + n * 2048 + k * 1024); } while (0)
; #define PG8_MMA(ai, bj, At, Bt) do { __builtin_amdgcn_s_setprio(1); _Pragma("unroll") for (int m = 0; m < 4; ++m) _Pragma("unroll") for (int n = 0; n < 2; ++n) _Pragma("unroll") for (int k = 0; k < 2; ++k) \
;         acc[ai][bj][m][n] = __builtin_amdgcn_mfma_f32_16x16x32_bf16(Bt[n][k], At[m][k], acc[ai][bj][m][n], 0, 0, 0); __builtin_amdgcn_s_setprio(0); } while (0)
; #define PG8_WAIT_V(n) asm volatile("s_waitcnt vmcnt(" #n ")" ::: "memory")
; #define PG8_WAIT_L(n) asm volatile("s_waitcnt lgkmcnt(" #n ")" ::: "memory")
; #define PG8_BAR __builtin_amdgcn_s_barrier()
; #define PG8_SCHED __builtin_amdgcn_sched_barrier(0)
; template <class Epi, class Sched, bool ALIGN_EPI = false, bool SP2 = false>
; __device__ __forceinline__ void gemm_phase(PG8_LAS unsigned char* lds, const Gemm g, const Sched& S, const Epi& E) {
;     ...
;             PG8_LDB(B0, 0, 0); PG8_LDB(B1, 0, 1); PG8_SCHED; PG8_LDA(At, 0, 0); PG8_STAGE(PG8_SA(1, 1), a1 + hstep, voffA);
;             PG8_WAIT_V(8); PG8_WAIT_L(0); PG8_BAR; PG8_MMA(0, 0, At, B0); PG8_MMA(0, 1, At, B1); PG8_BAR; PG8_SCHED;
;             PG8_LDA(At, 0, 1); PG8_STAGE(PG8_SB(0, 0), b2, voffB); PG8_STAGE(PG8_SB(0, 1), b2 + hstep, voffB); PG8_STAGE(PG8_SA(0, 0), a2, voffA);
;             PG8_WAIT_V(8); PG8_WAIT_L(0); PG8_BAR; PG8_MMA(1, 0, At, B0); PG8_MMA(1, 1, At, B1); PG8_BAR; PG8_SCHED;
.LBB0_1021:
	v_add_u32_e32 v166, s55, v169
	v_add_u32_e32 v168, s56, v169
	ds_read_b128 v[162:165], v166
	ds_read_b128 v[182:185], v166 offset:1024
	ds_read_b128 v[186:189], v166 offset:2048
	ds_read_b128 v[190:193], v166 offset:3072
	ds_read_b128 v[194:197], v168
	ds_read_b128 v[198:201], v168 offset:1024
	ds_read_b128 v[202:205], v168 offset:2048
	ds_read_b128 v[206:209], v168 offset:3072
	s_mov_b32 m0, s57
	v_lshl_add_u64 v[244:245], v[160:161], 0, v[148:149]
	ds_read_b128 v[210:213], v179
	ds_read_b128 v[216:219], v179 offset:1024
	ds_read_b128 v[220:223], v179 offset:2048
	ds_read_b128 v[224:227], v179 offset:3072
	ds_read_b128 v[228:231], v179 offset:4096
	ds_read_b128 v[232:235], v179 offset:5120
	ds_read_b128 v[236:239], v179 offset:6144
	ds_read_b128 v[240:243], v179 offset:7168
	global_load_lds_dwordx4 v[244:245], off
	s_mov_b32 m0, s58
	v_lshl_add_u64 v[244:245], v[160:161], 0, v[146:147]
	global_load_lds_dwordx4 v[244:245], off
	s_waitcnt vmcnt(8) lgkmcnt(0)
	s_setprio 1
	s_barrier
	v_mfma_f32_16x16x32_bf16 v[124:127], v[162:165], v[210:213], v[124:127]
	v_mfma_f32_16x16x32_bf16 v[116:119], v[186:189], v[210:213], v[116:119]
	v_mfma_f32_16x16x32_bf16 v[108:111], v[162:165], v[220:223], v[108:111]
	v_mfma_f32_16x16x32_bf16 v[100:103], v[186:189], v[220:223], v[100:103]
	v_mfma_f32_16x16x32_bf16 v[92:95], v[162:165], v[228:231], v[92:95]
	v_mfma_f32_16x16x32_bf16 v[84:87], v[186:189], v[228:231], v[84:87]
	v_mfma_f32_16x16x32_bf16 v[76:79], v[162:165], v[236:239], v[76:79]
	v_mfma_f32_16x16x32_bf16 v[68:71], v[186:189], v[236:239], v[68:71]
	v_mfma_f32_16x16x32_bf16 v[124:127], v[182:185], v[216:219], v[124:127]
	v_mfma_f32_16x16x32_bf16 v[116:119], v[190:193], v[216:219], v[116:119]
	v_mfma_f32_16x16x32_bf16 v[108:111], v[182:185], v[224:227], v[108:111]
	v_mfma_f32_16x16x32_bf16 v[100:103], v[190:193], v[224:227], v[100:103]
	v_mfma_f32_16x16x32_bf16 v[92:95], v[182:185], v[232:235], v[92:95]
	v_mfma_f32_16x16x32_bf16 v[84:87], v[190:193], v[232:235], v[84:87]
	v_mfma_f32_16x16x32_bf16 v[76:79], v[182:185], v[240:243], v[76:79]
	v_mfma_f32_16x16x32_bf16 v[68:71], v[190:193], v[240:243], v[68:71]
	v_mfma_f32_16x16x32_bf16 v[120:123], v[194:197], v[210:213], v[120:123]
	v_mfma_f32_16x16x32_bf16 v[112:115], v[202:205], v[210:213], v[112:115]
	v_mfma_f32_16x16x32_bf16 v[104:107], v[194:197], v[220:223], v[104:107]
	v_mfma_f32_16x16x32_bf16 v[96:99], v[202:205], v[220:223], v[96:99]
	v_mfma_f32_16x16x32_bf16 v[88:91], v[194:197], v[228:231], v[88:91]
	v_mfma_f32_16x16x32_bf16 v[80:83], v[202:205], v[228:231], v[80:83]
	v_mfma_f32_16x16x32_bf16 v[72:75], v[194:197], v[236:239], v[72:75]
	v_mfma_f32_16x16x32_bf16 v[64:67], v[202:205], v[236:239], v[64:67]
	v_mfma_f32_16x16x32_bf16 v[120:123], v[198:201], v[216:219], v[120:123]
	v_mfma_f32_16x16x32_bf16 v[112:115], v[206:209], v[216:219], v[112:115]
	v_mfma_f32_16x16x32_bf16 v[104:107], v[198:201], v[224:227], v[104:107]
	v_mfma_f32_16x16x32_bf16 v[96:99], v[206:209], v[224:227], v[96:99]
	v_mfma_f32_16x16x32_bf16 v[88:91], v[198:201], v[232:235], v[88:91]
	v_mfma_f32_16x16x32_bf16 v[80:83], v[206:209], v[232:235], v[80:83]
	v_mfma_f32_16x16x32_bf16 v[72:75], v[198:201], v[240:243], v[72:75]
	v_mfma_f32_16x16x32_bf16 v[64:67], v[206:209], v[240:243], v[64:67]
	s_setprio 0
	s_barrier
	s_mov_b32 m0, s61
	v_lshl_add_u64 v[244:245], v[214:215], 0, v[138:139]
	ds_read_b128 v[210:213], v179 offset:16384
	ds_read_b128 v[216:219], v179 offset:17408
	ds_read_b128 v[220:223], v179 offset:18432
	ds_read_b128 v[224:227], v179 offset:19456
	ds_read_b128 v[228:231], v179 offset:20480
	ds_read_b128 v[232:235], v179 offset:21504
	ds_read_b128 v[236:239], v179 offset:22528
	ds_read_b128 v[240:243], v179 offset:23552
	global_load_lds_dwordx4 v[244:245], off
	v_lshl_add_u64 v[246:247], v[214:215], 0, v[134:135]
	s_mov_b32 m0, s62
	v_lshl_add_u64 v[214:215], v[214:215], 0, s[14:15]
	global_load_lds_dwordx4 v[246:247], off
	v_lshl_add_u64 v[248:249], v[214:215], 0, v[138:139]
	s_mov_b32 m0, s63
	v_lshl_add_u64 v[214:215], v[214:215], 0, v[134:135]
	global_load_lds_dwordx4 v[248:249], off
	s_add_i32 m0, s63, 0x2000
	v_lshl_add_u64 v[250:251], v[172:173], 0, v[140:141]
	global_load_lds_dwordx4 v[214:215], off
	s_mov_b32 m0, s46
	v_lshl_add_u64 v[252:253], v[172:173], 0, v[136:137]
	global_load_lds_dwordx4 v[250:251], off
	s_mov_b32 m0, s47
	s_nop 0
	global_load_lds_dwordx4 v[252:253], off
	s_waitcnt vmcnt(8) lgkmcnt(0)
	s_setprio 1
	s_barrier
	v_mfma_f32_16x16x32_bf16 v[60:63], v[162:165], v[210:213], v[60:63]
	v_mfma_f32_16x16x32_bf16 v[52:55], v[186:189], v[210:213], v[52:55]
	v_mfma_f32_16x16x32_bf16 v[44:47], v[162:165], v[220:223], v[44:47]
	v_mfma_f32_16x16x32_bf16 v[36:39], v[186:189], v[220:223], v[36:39]
	v_mfma_f32_16x16x32_bf16 v[28:31], v[162:165], v[228:231], v[28:31]
	v_mfma_f32_16x16x32_bf16 v[20:23], v[186:189], v[228:231], v[20:23]
	v_mfma_f32_16x16x32_bf16 v[12:15], v[162:165], v[236:239], v[12:15]
	v_mfma_f32_16x16x32_bf16 v[4:7], v[186:189], v[236:239], v[4:7]
	v_mfma_f32_16x16x32_bf16 v[60:63], v[182:185], v[216:219], v[60:63]
	v_mfma_f32_16x16x32_bf16 v[52:55], v[190:193], v[216:219], v[52:55]
	v_mfma_f32_16x16x32_bf16 v[44:47], v[182:185], v[224:227], v[44:47]
	v_mfma_f32_16x16x32_bf16 v[36:39], v[190:193], v[224:227], v[36:39]
	v_mfma_f32_16x16x32_bf16 v[28:31], v[182:185], v[232:235], v[28:31]
	v_mfma_f32_16x16x32_bf16 v[20:23], v[190:193], v[232:235], v[20:23]
	v_mfma_f32_16x16x32_bf16 v[12:15], v[182:185], v[240:243], v[12:15]
	v_mfma_f32_16x16x32_bf16 v[4:7], v[190:193], v[240:243], v[4:7]
	v_mfma_f32_16x16x32_bf16 v[56:59], v[194:197], v[210:213], v[56:59]
	v_mfma_f32_16x16x32_bf16 v[48:51], v[202:205], v[210:213], v[48:51]
	v_mfma_f32_16x16x32_bf16 v[40:43], v[194:197], v[220:223], v[40:43]
	v_mfma_f32_16x16x32_bf16 v[32:35], v[202:205], v[220:223], v[32:35]
	v_mfma_f32_16x16x32_bf16 v[24:27], v[194:197], v[228:231], v[24:27]
	v_mfma_f32_16x16x32_bf16 v[16:19], v[202:205], v[228:231], v[16:19]
	v_mfma_f32_16x16x32_bf16 v[8:11], v[194:197], v[236:239], v[8:11]
	v_mfma_f32_16x16x32_bf16 v[0:3], v[202:205], v[236:239], v[0:3]
	v_mfma_f32_16x16x32_bf16 v[56:59], v[198:201], v[216:219], v[56:59]
	v_mfma_f32_16x16x32_bf16 v[48:51], v[206:209], v[216:219], v[48:51]
	v_mfma_f32_16x16x32_bf16 v[40:43], v[198:201], v[224:227], v[40:43]
	v_mfma_f32_16x16x32_bf16 v[32:35], v[206:209], v[224:227], v[32:35]
	v_mfma_f32_16x16x32_bf16 v[24:27], v[198:201], v[232:235], v[24:27]
	v_mfma_f32_16x16x32_bf16 v[16:19], v[206:209], v[232:235], v[16:19]
	v_mfma_f32_16x16x32_bf16 v[8:11], v[198:201], v[240:243], v[8:11]
	v_mfma_f32_16x16x32_bf16 v[0:3], v[206:209], v[240:243], v[0:3]
	s_setprio 0
	s_barrier
; #define PG8_STAGE(bufoff, gbase, voff) do { _Pragma("unroll") for (int _i = 0; _i < 2; ++_i) \
;         __builtin_amdgcn_global_load_lds((const unsigned*)((const char*)(gbase) + (voff)[_i]), (PG8_LAS unsigned*)(lds + (bufoff) + ldsw + _i * 8192), 16, 0, 0); } while (0)
; #define PG8_LDA(dst, b, h) do { _Pragma("unroll") for (int m = 0; m < 4; ++m) _Pragma("unroll") for (int k = 0; k < 2; ++k) dst[m][k] = *(const PG8_LAS bf16x8*)(lds + PG8_SA(b, h) + aoff + m * 2048 + k * 1024); } while (0)
; #define PG8_LDB(dst, b, h) do { _Pragma("unroll") for (int n = 0; n < 2; ++n) _Pragma("unroll") for (int k = 0; k < 2; ++k) dst[n][k] = *(const PG8_LAS bf16x8*)(lds + PG8_SB(b, h) + boff + n * 2048 + k * 1024); } while (0)
; #define PG8_MMA(ai, bj, At, Bt) do { __builtin_amdgcn_s_setprio(1); _Pragma("unroll") for (int m = 0; m < 4; ++m) _Pragma("unroll") for (int n = 0; n < 2; ++n) _Pragma("unroll") for (int k = 0; k < 2; ++k) \
;         acc[ai][bj][m][n] = __builtin_amdgcn_mfma_f32_16x16x32_bf16(Bt[n][k], At[m][k], acc[ai][bj][m][n], 0, 0, 0); __builtin_amdgcn_s_setprio(0); } while (0)
; #define PG8_WAIT_V(n) asm volatile("s_waitcnt vmcnt(" #n ")" ::: "memory")
; #define PG8_WAIT_L(n) asm volatile("s_waitcnt lgkmcnt(" #n ")" ::: "memory")
; #define PG8_BAR __builtin_amdgcn_s_barrier()
; #define PG8_SCHED __builtin_amdgcn_sched_barrier(0)
; template <class Epi, class Sched, bool ALIGN_EPI = false, bool SP2 = false>
; __device__ __forceinline__ void gemm_phase(PG8_LAS unsigned char* lds, const Gemm g, const Sched& S, const Epi& E) {
;     ...
;             PG8_LDB(B0, 1, 0); PG8_LDB(B1, 1, 1); PG8_SCHED; PG8_LDA(At, 1, 0); PG8_STAGE(PG8_SA(0, 1), a2 + hstep, voffA);
;             PG8_WAIT_V(8); PG8_WAIT_L(0); PG8_BAR; PG8_MMA(0, 0, At, B0); PG8_MMA(0, 1, At, B1); PG8_BAR; PG8_SCHED;
;             PG8_LDA(At, 1, 1); PG8_STAGE(PG8_SB(1, 0), b3, voffB); PG8_STAGE(PG8_SB(1, 1), b3 + hstep, voffB); PG8_STAGE(PG8_SA(1, 0), a3, voffA);
;             PG8_WAIT_V(8); PG8_WAIT_L(0); PG8_BAR; PG8_MMA(1, 0, At, B0); PG8_MMA(1, 1, At, B1); PG8_BAR; PG8_SCHED;
	s_add_i32 s11, 0, 0x18000
	v_add_u32_e32 v166, s11, v169
	s_add_i32 s13, 0, 0x1c000
	ds_read_b128 v[162:165], v166
	ds_read_b128 v[182:185], v166 offset:1024
	ds_read_b128 v[186:189], v166 offset:2048
	ds_read_b128 v[190:193], v166 offset:3072
	v_add_u32_e32 v166, s13, v169
	ds_read_b128 v[194:197], v166
	ds_read_b128 v[198:201], v166 offset:1024
	ds_read_b128 v[202:205], v166 offset:2048
	ds_read_b128 v[206:209], v166 offset:3072
	v_lshl_add_u64 v[172:173], v[172:173], 0, s[14:15]
	s_mov_b32 m0, s48
	v_lshl_add_u64 v[170:171], v[172:173], 0, v[140:141]
	ds_read_b128 v[210:213], v179 offset:32768
	ds_read_b128 v[216:219], v179 offset:33792
	ds_read_b128 v[220:223], v179 offset:34816
	ds_read_b128 v[224:227], v179 offset:35840
	ds_read_b128 v[228:231], v179 offset:36864
	ds_read_b128 v[232:235], v179 offset:37888
	ds_read_b128 v[236:239], v179 offset:38912
	ds_read_b128 v[240:243], v179 offset:39936
	global_load_lds_dwordx4 v[170:171], off
	s_mov_b32 m0, s49
	v_lshl_add_u64 v[170:171], v[172:173], 0, v[136:137]
	global_load_lds_dwordx4 v[170:171], off
	s_waitcnt vmcnt(8) lgkmcnt(0)
	s_setprio 1
	s_barrier
	v_mfma_f32_16x16x32_bf16 v[124:127], v[162:165], v[210:213], v[124:127]
	v_mfma_f32_16x16x32_bf16 v[116:119], v[186:189], v[210:213], v[116:119]
	v_mfma_f32_16x16x32_bf16 v[108:111], v[162:165], v[220:223], v[108:111]
	v_mfma_f32_16x16x32_bf16 v[100:103], v[186:189], v[220:223], v[100:103]
	v_mfma_f32_16x16x32_bf16 v[92:95], v[162:165], v[228:231], v[92:95]
	v_mfma_f32_16x16x32_bf16 v[84:87], v[186:189], v[228:231], v[84:87]
	v_mfma_f32_16x16x32_bf16 v[76:79], v[162:165], v[236:239], v[76:79]
	v_mfma_f32_16x16x32_bf16 v[68:71], v[186:189], v[236:239], v[68:71]
	v_mfma_f32_16x16x32_bf16 v[124:127], v[182:185], v[216:219], v[124:127]
	v_mfma_f32_16x16x32_bf16 v[116:119], v[190:193], v[216:219], v[116:119]
	v_mfma_f32_16x16x32_bf16 v[108:111], v[182:185], v[224:227], v[108:111]
	v_mfma_f32_16x16x32_bf16 v[100:103], v[190:193], v[224:227], v[100:103]
	v_mfma_f32_16x16x32_bf16 v[92:95], v[182:185], v[232:235], v[92:95]
	v_mfma_f32_16x16x32_bf16 v[84:87], v[190:193], v[232:235], v[84:87]
	v_mfma_f32_16x16x32_bf16 v[76:79], v[182:185], v[240:243], v[76:79]
	v_mfma_f32_16x16x32_bf16 v[68:71], v[190:193], v[240:243], v[68:71]
	v_mfma_f32_16x16x32_bf16 v[120:123], v[194:197], v[210:213], v[120:123]
	v_mfma_f32_16x16x32_bf16 v[112:115], v[202:205], v[210:213], v[112:115]
	v_mfma_f32_16x16x32_bf16 v[104:107], v[194:197], v[220:223], v[104:107]
	v_mfma_f32_16x16x32_bf16 v[96:99], v[202:205], v[220:223], v[96:99]
	v_mfma_f32_16x16x32_bf16 v[88:91], v[194:197], v[228:231], v[88:91]
	v_mfma_f32_16x16x32_bf16 v[80:83], v[202:205], v[228:231], v[80:83]
	v_mfma_f32_16x16x32_bf16 v[72:75], v[194:197], v[236:239], v[72:75]
	v_mfma_f32_16x16x32_bf16 v[64:67], v[202:205], v[236:239], v[64:67]
	v_mfma_f32_16x16x32_bf16 v[120:123], v[198:201], v[216:219], v[120:123]
	v_mfma_f32_16x16x32_bf16 v[112:115], v[206:209], v[216:219], v[112:115]
	v_mfma_f32_16x16x32_bf16 v[104:107], v[198:201], v[224:227], v[104:107]
	v_mfma_f32_16x16x32_bf16 v[96:99], v[206:209], v[224:227], v[96:99]
	v_mfma_f32_16x16x32_bf16 v[88:91], v[198:201], v[232:235], v[88:91]
	v_mfma_f32_16x16x32_bf16 v[80:83], v[206:209], v[232:235], v[80:83]
	v_mfma_f32_16x16x32_bf16 v[72:75], v[198:201], v[240:243], v[72:75]
	v_mfma_f32_16x16x32_bf16 v[64:67], v[206:209], v[240:243], v[64:67]
	s_setprio 0
	s_barrier
	s_add_i32 s11, s11, s29
	s_add_i32 m0, s11, 0xffffff80
	ds_read_b128 v[210:213], v179 offset:49152
	ds_read_b128 v[216:219], v179 offset:50176
	ds_read_b128 v[220:223], v179 offset:51200
	ds_read_b128 v[224:227], v179 offset:52224
	global_load_lds_dwordx4 v[244:245], off offset:128
	s_add_i32 m0, s11, 0x1f80
	s_add_i32 s11, s13, s29
	global_load_lds_dwordx4 v[246:247], off offset:128
	s_add_i32 m0, s11, 0xffffff80
	ds_read_b128 v[240:243], v179 offset:56320
	global_load_lds_dwordx4 v[248:249], off offset:128
	s_add_i32 m0, s11, 0x1f80
	ds_read_b128 v[236:239], v179 offset:55296
	global_load_lds_dwordx4 v[214:215], off offset:128
	s_add_i32 m0, s50, 0xffffff80
	ds_read_b128 v[232:235], v179 offset:54272
	global_load_lds_dwordx4 v[250:251], off offset:128
	s_add_i32 m0, s51, 0xffffff80
	ds_read_b128 v[228:231], v179 offset:53248
	global_load_lds_dwordx4 v[252:253], off offset:128
	s_waitcnt vmcnt(8) lgkmcnt(0)
	s_setprio 1
	s_barrier
	v_mfma_f32_16x16x32_bf16 v[60:63], v[162:165], v[210:213], v[60:63]
	v_mfma_f32_16x16x32_bf16 v[52:55], v[186:189], v[210:213], v[52:55]
	v_mfma_f32_16x16x32_bf16 v[44:47], v[162:165], v[220:223], v[44:47]
	v_mfma_f32_16x16x32_bf16 v[36:39], v[186:189], v[220:223], v[36:39]
	v_mfma_f32_16x16x32_bf16 v[28:31], v[162:165], v[228:231], v[28:31]
	v_mfma_f32_16x16x32_bf16 v[20:23], v[186:189], v[228:231], v[20:23]
	v_mfma_f32_16x16x32_bf16 v[12:15], v[162:165], v[236:239], v[12:15]
	v_mfma_f32_16x16x32_bf16 v[4:7], v[186:189], v[236:239], v[4:7]
	v_mfma_f32_16x16x32_bf16 v[60:63], v[182:185], v[216:219], v[60:63]
	v_mfma_f32_16x16x32_bf16 v[52:55], v[190:193], v[216:219], v[52:55]
	v_mfma_f32_16x16x32_bf16 v[44:47], v[182:185], v[224:227], v[44:47]
	v_mfma_f32_16x16x32_bf16 v[36:39], v[190:193], v[224:227], v[36:39]
	v_mfma_f32_16x16x32_bf16 v[28:31], v[182:185], v[232:235], v[28:31]
	v_mfma_f32_16x16x32_bf16 v[20:23], v[190:193], v[232:235], v[20:23]
	v_mfma_f32_16x16x32_bf16 v[12:15], v[182:185], v[240:243], v[12:15]
	v_mfma_f32_16x16x32_bf16 v[4:7], v[190:193], v[240:243], v[4:7]
	v_mfma_f32_16x16x32_bf16 v[56:59], v[194:197], v[210:213], v[56:59]
	v_mfma_f32_16x16x32_bf16 v[48:51], v[202:205], v[210:213], v[48:51]
	v_mfma_f32_16x16x32_bf16 v[40:43], v[194:197], v[220:223], v[40:43]
	v_mfma_f32_16x16x32_bf16 v[32:35], v[202:205], v[220:223], v[32:35]
	v_mfma_f32_16x16x32_bf16 v[24:27], v[194:197], v[228:231], v[24:27]
	v_mfma_f32_16x16x32_bf16 v[16:19], v[202:205], v[228:231], v[16:19]
	v_mfma_f32_16x16x32_bf16 v[8:11], v[194:197], v[236:239], v[8:11]
	v_mfma_f32_16x16x32_bf16 v[0:3], v[202:205], v[236:239], v[0:3]
	v_mfma_f32_16x16x32_bf16 v[56:59], v[198:201], v[216:219], v[56:59]
	v_mfma_f32_16x16x32_bf16 v[48:51], v[206:209], v[216:219], v[48:51]
	v_mfma_f32_16x16x32_bf16 v[40:43], v[198:201], v[224:227], v[40:43]
	v_mfma_f32_16x16x32_bf16 v[32:35], v[206:209], v[224:227], v[32:35]
	v_mfma_f32_16x16x32_bf16 v[24:27], v[198:201], v[232:235], v[24:27]
	v_mfma_f32_16x16x32_bf16 v[16:19], v[206:209], v[232:235], v[16:19]
	v_mfma_f32_16x16x32_bf16 v[8:11], v[198:201], v[240:243], v[8:11]
	v_mfma_f32_16x16x32_bf16 v[0:3], v[206:209], v[240:243], v[0:3]
	v_lshl_add_u64 v[158:159], v[158:159], 0, s[26:27]
	v_lshl_add_u64 v[160:161], v[160:161], 0, s[26:27]
	s_cmp_ge_i32 s10, s52
	s_cbranch_scc1 .Lrot_exit_11
	s_cmp_eq_u32 s54, s10
	v_lshl_add_u64 v[172:173], v[160:161], 0, s[22:23]
	s_cselect_b64 vcc, -1, 0
	s_add_i32 s10, s10, 2
	v_cndmask_b32_e32 v173, v173, v153, vcc
	v_cndmask_b32_e32 v172, v172, v152, vcc
	v_cndmask_b32_e32 v215, v159, v155, vcc
	v_cndmask_b32_e32 v214, v158, v154, vcc
	s_setprio 0
	s_barrier
	s_branch .LBB0_1021
; #define PG8_MMA(ai, bj, At, Bt) do { __builtin_amdgcn_s_setprio(1); _Pragma("unroll") for (int m = 0; m < 4; ++m) _Pragma("unroll") for (int n = 0; n < 2; ++n) _Pragma("unroll") for (int k = 0; k < 2; ++k) \
;         acc[ai][bj][m][n] = __builtin_amdgcn_mfma_f32_16x16x32_bf16(Bt[n][k], At[m][k], acc[ai][bj][m][n], 0, 0, 0); __builtin_amdgcn_s_setprio(0); } while (0)
; #define PG8_WAIT_V(n) asm volatile("s_waitcnt vmcnt(" #n ")" ::: "memory")
; #define PG8_WAIT_L(n) asm volatile("s_waitcnt lgkmcnt(" #n ")" ::: "memory")
; #define PG8_BAR __builtin_amdgcn_s_barrier()
; #define PG8_SCHED __builtin_amdgcn_sched_barrier(0)
; template <class Epi, class Sched, bool ALIGN_EPI = false, bool SP2 = false>
; __device__ __forceinline__ void gemm_phase(PG8_LAS unsigned char* lds, const Gemm g, const Sched& S, const Epi& E) {
;     ...
;             PG8_WAIT_V(8); PG8_WAIT_L(0); PG8_BAR; PG8_MMA(1, 0, At, B0); PG8_MMA(1, 1, At, B1); PG8_BAR; PG8_SCHED;
;     ...
;         if constexpr (ALIGN_EPI) { if (wr == 0) PG8_BAR; }
.Lrot_exit_11:
	s_setprio 0
	s_barrier
.LBB0_1022:
	s_and_b64 vcc, exec, s[24:25]
	s_cbranch_vccz .LBB0_1024
	s_barrier

; #define PG8_MMA(ai, bj, At, Bt) do { __builtin_amdgcn_s_setprio(1); _Pragma("unroll") for (int m = 0; m < 4; ++m) _Pragma("unroll") for (int n = 0; n < 2; ++n) _Pragma("unroll") for (int k = 0; k < 2; ++k) \
;         acc[ai][bj][m][n] = __builtin_amdgcn_mfma_f32_16x16x32_bf16(Bt[n][k], At[m][k], acc[ai][bj][m][n], 0, 0, 0); __builtin_amdgcn_s_setprio(0); } while (0)
; #define PG8_WAIT_V(n) asm volatile("s_waitcnt vmcnt(" #n ")" ::: "memory")
; #define PG8_WAIT_L(n) asm volatile("s_waitcnt lgkmcnt(" #n ")" ::: "memory")
; #define PG8_BAR __builtin_amdgcn_s_barrier()
; #define PG8_SCHED __builtin_amdgcn_sched_barrier(0)
; template <class Epi, class Sched, bool ALIGN_EPI = false, bool SP2 = false>
; __device__ __forceinline__ void gemm_phase(PG8_LAS unsigned char* lds, const Gemm g, const Sched& S, const Epi& E) {
;     ...
;             PG8_WAIT_V(8); PG8_WAIT_L(0); PG8_BAR; PG8_MMA(1, 0, At, B0); PG8_MMA(1, 1, At, B1); PG8_BAR; PG8_SCHED;
;     ...
;         if constexpr (ALIGN_EPI) { if (wr == 0) PG8_BAR; }
.Lrot_exit_10:
	s_setprio 0
	s_barrier
.LBB0_1089:
	s_and_b64 vcc, exec, s[24:25]
	s_cbranch_vccz .LBB0_1091
	s_barrier

; template <class Epi, class Sched, bool ALIGN_EPI = false, bool SP2 = false>
; __device__ __forceinline__ void gemm_phase(PG8_LAS unsigned char* lds, const Gemm g, const Sched& S, const Epi& E) {
;     ...
;         for (int t = 0; t < nt; t += 2) {
;             const bool last = (t == nt - 2);
;             const char* a1 = cA + (size_t)(t + 1) * kstep;
;             const char* a2 = last ? nA : cA + (size_t)(t + 2) * kstep; const char* b2 = last ? nB : cB + (size_t)(t + 2) * kstep;
;     ...
; #pragma unroll
;         for (int a = 0; a < 2; ++a)
; #pragma unroll
;             for (int b = 0; b < 2; ++b)
; #pragma unroll
;                 for (int m = 0; m < 4; ++m)
; #pragma unroll
;                     for (int n = 0; n < 2; ++n) acc[a][b][m][n] = (f32x4){0.f, 0.f, 0.f, 0.f};
.LBB0_1167:
	v_mov_b32_e32 v127, 0
	s_and_b64 vcc, exec, s[6:7]
	v_mov_b32_e32 v126, v127
	v_mov_b32_e32 v125, v127
	v_mov_b32_e32 v124, v127
	v_mov_b32_e32 v123, v127
	v_mov_b32_e32 v122, v127
	v_mov_b32_e32 v121, v127
	v_mov_b32_e32 v120, v127
	v_mov_b32_e32 v111, v127
	v_mov_b32_e32 v110, v127
	v_mov_b32_e32 v109, v127
	v_mov_b32_e32 v108, v127
	v_mov_b32_e32 v107, v127
	v_mov_b32_e32 v106, v127
	v_mov_b32_e32 v105, v127
	v_mov_b32_e32 v104, v127
	v_mov_b32_e32 v95, v127
	v_mov_b32_e32 v94, v127
	v_mov_b32_e32 v93, v127
	v_mov_b32_e32 v92, v127
	v_mov_b32_e32 v91, v127
	v_mov_b32_e32 v90, v127
	v_mov_b32_e32 v89, v127
	v_mov_b32_e32 v88, v127
	v_mov_b32_e32 v79, v127
	v_mov_b32_e32 v78, v127
	v_mov_b32_e32 v77, v127
	v_mov_b32_e32 v76, v127
	v_mov_b32_e32 v75, v127
	v_mov_b32_e32 v74, v127
	v_mov_b32_e32 v73, v127
	v_mov_b32_e32 v72, v127
	v_mov_b32_e32 v119, v127
	v_mov_b32_e32 v118, v127
	v_mov_b32_e32 v117, v127
	v_mov_b32_e32 v116, v127
	v_mov_b32_e32 v115, v127
	v_mov_b32_e32 v114, v127
	v_mov_b32_e32 v113, v127
	v_mov_b32_e32 v112, v127
	v_mov_b32_e32 v103, v127
	v_mov_b32_e32 v102, v127
	v_mov_b32_e32 v101, v127
	v_mov_b32_e32 v100, v127
	v_mov_b32_e32 v99, v127
	v_mov_b32_e32 v98, v127
	v_mov_b32_e32 v97, v127
	v_mov_b32_e32 v96, v127
	v_mov_b32_e32 v87, v127
	v_mov_b32_e32 v86, v127
	v_mov_b32_e32 v85, v127
	v_mov_b32_e32 v84, v127
	v_mov_b32_e32 v83, v127
	v_mov_b32_e32 v82, v127
	v_mov_b32_e32 v81, v127
	v_mov_b32_e32 v80, v127
	v_mov_b32_e32 v71, v127
	v_mov_b32_e32 v70, v127
	v_mov_b32_e32 v69, v127
	v_mov_b32_e32 v68, v127
	v_mov_b32_e32 v67, v127
	v_mov_b32_e32 v66, v127
	v_mov_b32_e32 v65, v127
	v_mov_b32_e32 v64, v127
	v_mov_b32_e32 v63, v127
	v_mov_b32_e32 v62, v127
	v_mov_b32_e32 v61, v127
	v_mov_b32_e32 v60, v127
	v_mov_b32_e32 v59, v127
	v_mov_b32_e32 v58, v127
	v_mov_b32_e32 v57, v127
	v_mov_b32_e32 v56, v127
	v_mov_b32_e32 v47, v127
	v_mov_b32_e32 v46, v127
	v_mov_b32_e32 v45, v127
	v_mov_b32_e32 v44, v127
	v_mov_b32_e32 v43, v127
	v_mov_b32_e32 v42, v127
	v_mov_b32_e32 v41, v127
	v_mov_b32_e32 v40, v127
	v_mov_b32_e32 v31, v127
	v_mov_b32_e32 v30, v127
	v_mov_b32_e32 v29, v127
	v_mov_b32_e32 v28, v127
	v_mov_b32_e32 v27, v127
	v_mov_b32_e32 v26, v127
	v_mov_b32_e32 v25, v127
	v_mov_b32_e32 v24, v127
	v_mov_b32_e32 v15, v127
	v_mov_b32_e32 v14, v127
	v_mov_b32_e32 v13, v127
	v_mov_b32_e32 v12, v127
	v_mov_b32_e32 v11, v127
	v_mov_b32_e32 v10, v127
	v_mov_b32_e32 v9, v127
	v_mov_b32_e32 v8, v127
	v_mov_b32_e32 v55, v127
	v_mov_b32_e32 v54, v127
	v_mov_b32_e32 v53, v127
	v_mov_b32_e32 v52, v127
	v_mov_b32_e32 v51, v127
	v_mov_b32_e32 v50, v127
	v_mov_b32_e32 v49, v127
	v_mov_b32_e32 v48, v127
	v_mov_b32_e32 v39, v127
	v_mov_b32_e32 v38, v127
	v_mov_b32_e32 v37, v127
	v_mov_b32_e32 v36, v127
	v_mov_b32_e32 v35, v127
	v_mov_b32_e32 v34, v127
	v_mov_b32_e32 v33, v127
	v_mov_b32_e32 v32, v127
	v_mov_b32_e32 v23, v127
	v_mov_b32_e32 v22, v127
	v_mov_b32_e32 v21, v127
	v_mov_b32_e32 v20, v127
	v_mov_b32_e32 v19, v127
	v_mov_b32_e32 v18, v127
	v_mov_b32_e32 v17, v127
	v_mov_b32_e32 v16, v127
	v_mov_b32_e32 v7, v127
	v_mov_b32_e32 v6, v127
	v_mov_b32_e32 v5, v127
	v_mov_b32_e32 v4, v127
	v_mov_b32_e32 v3, v127
	v_mov_b32_e32 v2, v127
	v_mov_b32_e32 v1, v127
	v_mov_b32_e32 v0, v127
	s_cbranch_vccnz .LBB0_1170
	v_mov_b32_e32 v0, 0
	v_lshl_add_u64 v[154:155], v[154:155], 0, s[28:29]
	v_lshl_add_u64 v[158:159], v[158:159], 0, s[24:25]
	s_mov_b32 s10, 0
	v_mov_b32_e32 v1, v0
	v_mov_b32_e32 v2, v0
	v_mov_b32_e32 v3, v0
	v_mov_b32_e32 v4, v0
	v_mov_b32_e32 v5, v0
	v_mov_b32_e32 v6, v0
	v_mov_b32_e32 v7, v0
	v_mov_b32_e32 v16, v0
	v_mov_b32_e32 v17, v0
	v_mov_b32_e32 v18, v0
	v_mov_b32_e32 v19, v0
	v_mov_b32_e32 v20, v0
	v_mov_b32_e32 v21, v0
	v_mov_b32_e32 v22, v0
	v_mov_b32_e32 v23, v0
	v_mov_b32_e32 v32, v0
	v_mov_b32_e32 v33, v0
	v_mov_b32_e32 v34, v0
	v_mov_b32_e32 v35, v0
	v_mov_b32_e32 v36, v0
	v_mov_b32_e32 v37, v0
	v_mov_b32_e32 v38, v0
	v_mov_b32_e32 v39, v0
	v_mov_b32_e32 v48, v0
	v_mov_b32_e32 v49, v0
	v_mov_b32_e32 v50, v0
	v_mov_b32_e32 v51, v0
	v_mov_b32_e32 v52, v0
	v_mov_b32_e32 v53, v0
	v_mov_b32_e32 v54, v0
	v_mov_b32_e32 v55, v0
	v_mov_b32_e32 v8, v0
	v_mov_b32_e32 v9, v0
	v_mov_b32_e32 v10, v0
	v_mov_b32_e32 v11, v0
	v_mov_b32_e32 v12, v0
	v_mov_b32_e32 v13, v0
	v_mov_b32_e32 v14, v0
	v_mov_b32_e32 v15, v0
	v_mov_b32_e32 v24, v0
	v_mov_b32_e32 v25, v0
	v_mov_b32_e32 v26, v0
	v_mov_b32_e32 v27, v0
	v_mov_b32_e32 v28, v0
	v_mov_b32_e32 v29, v0
	v_mov_b32_e32 v30, v0
	v_mov_b32_e32 v31, v0
	v_mov_b32_e32 v40, v0
	v_mov_b32_e32 v41, v0
	v_mov_b32_e32 v42, v0
	v_mov_b32_e32 v43, v0
	v_mov_b32_e32 v44, v0
	v_mov_b32_e32 v45, v0
	v_mov_b32_e32 v46, v0
	v_mov_b32_e32 v47, v0
	v_mov_b32_e32 v56, v0
	v_mov_b32_e32 v57, v0
	v_mov_b32_e32 v58, v0
	v_mov_b32_e32 v59, v0
	v_mov_b32_e32 v60, v0
	v_mov_b32_e32 v61, v0
	v_mov_b32_e32 v62, v0
	v_mov_b32_e32 v63, v0
	v_mov_b32_e32 v64, v0
	v_mov_b32_e32 v65, v0
	v_mov_b32_e32 v66, v0
	v_mov_b32_e32 v67, v0
	v_mov_b32_e32 v68, v0
	v_mov_b32_e32 v69, v0
	v_mov_b32_e32 v70, v0
	v_mov_b32_e32 v71, v0
	v_mov_b32_e32 v80, v0
	v_mov_b32_e32 v81, v0
	v_mov_b32_e32 v82, v0
	v_mov_b32_e32 v83, v0
	v_mov_b32_e32 v84, v0
	v_mov_b32_e32 v85, v0
	v_mov_b32_e32 v86, v0
	v_mov_b32_e32 v87, v0
	v_mov_b32_e32 v96, v0
	v_mov_b32_e32 v97, v0
	v_mov_b32_e32 v98, v0
	v_mov_b32_e32 v99, v0
	v_mov_b32_e32 v100, v0
	v_mov_b32_e32 v101, v0
	v_mov_b32_e32 v102, v0
	v_mov_b32_e32 v103, v0
	v_mov_b32_e32 v112, v0
	v_mov_b32_e32 v113, v0
	v_mov_b32_e32 v114, v0
	v_mov_b32_e32 v115, v0
	v_mov_b32_e32 v116, v0
	v_mov_b32_e32 v117, v0
	v_mov_b32_e32 v118, v0
	v_mov_b32_e32 v119, v0
	v_mov_b32_e32 v72, v0
	v_mov_b32_e32 v73, v0
	v_mov_b32_e32 v74, v0
	v_mov_b32_e32 v75, v0
	v_mov_b32_e32 v76, v0
	v_mov_b32_e32 v77, v0
	v_mov_b32_e32 v78, v0
	v_mov_b32_e32 v79, v0
	v_mov_b32_e32 v88, v0
	v_mov_b32_e32 v89, v0
	v_mov_b32_e32 v90, v0
	v_mov_b32_e32 v91, v0
	v_mov_b32_e32 v92, v0
	v_mov_b32_e32 v93, v0
	v_mov_b32_e32 v94, v0
	v_mov_b32_e32 v95, v0
	v_mov_b32_e32 v104, v0
	v_mov_b32_e32 v105, v0
	v_mov_b32_e32 v106, v0
	v_mov_b32_e32 v107, v0
	v_mov_b32_e32 v108, v0
	v_mov_b32_e32 v109, v0
	v_mov_b32_e32 v110, v0
	v_mov_b32_e32 v111, v0
	v_mov_b32_e32 v120, v0
	v_mov_b32_e32 v121, v0
	v_mov_b32_e32 v122, v0
	v_mov_b32_e32 v123, v0
	v_mov_b32_e32 v124, v0
	v_mov_b32_e32 v125, v0
	v_mov_b32_e32 v126, v0
	v_mov_b32_e32 v127, v0
	s_cmp_eq_u32 s51, s10
	v_lshl_add_u64 v[196:197], v[158:159], 0, s[24:25]
	s_cselect_b64 vcc, -1, 0
	s_add_i32 s10, s10, 2
	v_cndmask_b32_e32 v213, v197, v151, vcc
	v_cndmask_b32_e32 v212, v196, v150, vcc
	v_cndmask_b32_e32 v215, v155, v153, vcc
	v_cndmask_b32_e32 v214, v154, v152, vcc
	.p2align	6
; #define PG8_STAGE(bufoff, gbase, voff) do { _Pragma("unroll") for (int _i = 0; _i < 2; ++_i) \
;         __builtin_amdgcn_global_load_lds((const unsigned*)((const char*)(gbase) + (voff)[_i]), (PG8_LAS unsigned*)(lds + (bufoff) + ldsw + _i * 8192), 16, 0, 0); } while (0)
; #define PG8_LDA(dst, b, h) do { _Pragma("unroll") for (int m = 0; m < 4; ++m) _Pragma("unroll") for (int k = 0; k < 2; ++k) dst[m][k] = *(const PG8_LAS bf16x8*)(lds + PG8_SA(b, h) + aoff + m * 2048 + k * 1024); } while (0)
; #define PG8_LDB(dst, b, h) do { _Pragma("unroll") for (int n = 0; n < 2; ++n) _Pragma("unroll") for (int k = 0; k < 2; ++k) dst[n][k] = *(const PG8_LAS bf16x8*)(lds + PG8_SB(b, h) + boff + n * 2048 + k * 1024); } while (0)
; #define PG8_MMA(ai, bj, At, Bt) do { __builtin_amdgcn_s_setprio(1); _Pragma("unroll") for (int m = 0; m < 4; ++m) _Pragma("unroll") for (int n = 0; n < 2; ++n) _Pragma("unroll") for (int k = 0; k < 2; ++k) \
;         acc[ai][bj][m][n] = __builtin_amdgcn_mfma_f32_16x16x32_bf16(Bt[n][k], At[m][k], acc[ai][bj][m][n], 0, 0, 0); __builtin_amdgcn_s_setprio(0); } while (0)
; #define PG8_WAIT_V(n) asm volatile("s_waitcnt vmcnt(" #n ")" ::: "memory")
; #define PG8_BAR __builtin_amdgcn_s_barrier()
; template <class Epi, class Sched, bool ALIGN_EPI = false, bool SP2 = false>
; __device__ __forceinline__ void gemm_phase(PG8_LAS unsigned char* lds, const Gemm g, const Sched& S, const Epi& E) {
;     ...
;         for (int t = 0; t < nt; t += 2) {
;             const bool last = (t == nt - 2);
;             const char* a1 = cA + (size_t)(t + 1) * kstep;
;             const char* a2 = last ? nA : cA + (size_t)(t + 2) * kstep; const char* b2 = last ? nB : cB + (size_t)(t + 2) * kstep;
;             const char* a3 = a2 + kstep; const char* b3 = b2 + kstep;
;             if (last && has_next) S.a_ready(nxt);
;             if constexpr (SP2) {
;             PG8_LDB(B0, 0, 0); PG8_LDB(B1, 0, 1); PG8_SCHED; PG8_LDA(At, 0, 0); PG8_STAGE(PG8_SA(1, 1), a1 + hstep, voffA);
;             PG8_WAIT_V(8); PG8_WAIT_L(0); PG8_BAR; PG8_MMA(0, 0, At, B0); PG8_MMA(0, 1, At, B1); PG8_BAR; PG8_SCHED;
;             PG8_LDA(At, 0, 1); PG8_STAGE(PG8_SB(0, 0), b2, voffB); PG8_STAGE(PG8_SB(0, 1), b2 + hstep, voffB); PG8_STAGE(PG8_SA(0, 0), a2, voffA);
;             PG8_WAIT_V(8); PG8_WAIT_L(0); PG8_BAR; PG8_MMA(1, 0, At, B0); PG8_MMA(1, 1, At, B1); PG8_BAR; PG8_SCHED;
.LBB0_1169:
	v_add_u32_e32 v192, s52, v161
	ds_read_b128 v[164:167], v162
	ds_read_b128 v[168:171], v162 offset:1024
	ds_read_b128 v[172:175], v162 offset:2048
	ds_read_b128 v[176:179], v162 offset:3072
	ds_read_b128 v[180:183], v192
	ds_read_b128 v[184:187], v192 offset:1024
	ds_read_b128 v[188:191], v192 offset:2048
	ds_read_b128 v[192:195], v192 offset:3072
	s_mov_b32 m0, s54
	v_lshl_add_u64 v[232:233], v[158:159], 0, v[146:147]
	ds_read_b128 v[196:199], v163
	ds_read_b128 v[200:203], v163 offset:1024
	ds_read_b128 v[204:207], v163 offset:2048
	ds_read_b128 v[208:211], v163 offset:3072
	ds_read_b128 v[216:219], v163 offset:4096
	ds_read_b128 v[220:223], v163 offset:5120
	ds_read_b128 v[224:227], v163 offset:6144
	ds_read_b128 v[228:231], v163 offset:7168
	global_load_lds_dwordx4 v[232:233], off
	s_mov_b32 m0, s55
	v_lshl_add_u64 v[232:233], v[158:159], 0, v[144:145]
	global_load_lds_dwordx4 v[232:233], off
	s_waitcnt vmcnt(8) lgkmcnt(0)
	s_setprio 1
	s_barrier
	v_mfma_f32_16x16x32_bf16 v[124:127], v[164:167], v[196:199], v[124:127]
	v_mfma_f32_16x16x32_bf16 v[120:123], v[172:175], v[196:199], v[120:123]
	v_mfma_f32_16x16x32_bf16 v[108:111], v[164:167], v[204:207], v[108:111]
	v_mfma_f32_16x16x32_bf16 v[104:107], v[172:175], v[204:207], v[104:107]
	v_mfma_f32_16x16x32_bf16 v[92:95], v[164:167], v[216:219], v[92:95]
	v_mfma_f32_16x16x32_bf16 v[88:91], v[172:175], v[216:219], v[88:91]
	v_mfma_f32_16x16x32_bf16 v[76:79], v[164:167], v[224:227], v[76:79]
	v_mfma_f32_16x16x32_bf16 v[72:75], v[172:175], v[224:227], v[72:75]
	v_mfma_f32_16x16x32_bf16 v[124:127], v[168:171], v[200:203], v[124:127]
	v_mfma_f32_16x16x32_bf16 v[120:123], v[176:179], v[200:203], v[120:123]
	v_mfma_f32_16x16x32_bf16 v[108:111], v[168:171], v[208:211], v[108:111]
	v_mfma_f32_16x16x32_bf16 v[104:107], v[176:179], v[208:211], v[104:107]
	v_mfma_f32_16x16x32_bf16 v[92:95], v[168:171], v[220:223], v[92:95]
	v_mfma_f32_16x16x32_bf16 v[88:91], v[176:179], v[220:223], v[88:91]
	v_mfma_f32_16x16x32_bf16 v[76:79], v[168:171], v[228:231], v[76:79]
	v_mfma_f32_16x16x32_bf16 v[72:75], v[176:179], v[228:231], v[72:75]
	v_mfma_f32_16x16x32_bf16 v[116:119], v[180:183], v[196:199], v[116:119]
	v_mfma_f32_16x16x32_bf16 v[112:115], v[188:191], v[196:199], v[112:115]
	v_mfma_f32_16x16x32_bf16 v[100:103], v[180:183], v[204:207], v[100:103]
	v_mfma_f32_16x16x32_bf16 v[96:99], v[188:191], v[204:207], v[96:99]
	v_mfma_f32_16x16x32_bf16 v[84:87], v[180:183], v[216:219], v[84:87]
	v_mfma_f32_16x16x32_bf16 v[80:83], v[188:191], v[216:219], v[80:83]
	v_mfma_f32_16x16x32_bf16 v[68:71], v[180:183], v[224:227], v[68:71]
	v_mfma_f32_16x16x32_bf16 v[64:67], v[188:191], v[224:227], v[64:67]
	v_mfma_f32_16x16x32_bf16 v[116:119], v[184:187], v[200:203], v[116:119]
	v_mfma_f32_16x16x32_bf16 v[112:115], v[192:195], v[200:203], v[112:115]
	v_mfma_f32_16x16x32_bf16 v[100:103], v[184:187], v[208:211], v[100:103]
	v_mfma_f32_16x16x32_bf16 v[96:99], v[192:195], v[208:211], v[96:99]
	v_mfma_f32_16x16x32_bf16 v[84:87], v[184:187], v[220:223], v[84:87]
	v_mfma_f32_16x16x32_bf16 v[80:83], v[192:195], v[220:223], v[80:83]
	v_mfma_f32_16x16x32_bf16 v[68:71], v[184:187], v[228:231], v[68:71]
	v_mfma_f32_16x16x32_bf16 v[64:67], v[192:195], v[228:231], v[64:67]
	s_setprio 0
	s_barrier
	s_mov_b32 m0, s56
	v_lshl_add_u64 v[232:233], v[214:215], 0, v[138:139]
	ds_read_b128 v[196:199], v163 offset:16384
	ds_read_b128 v[200:203], v163 offset:17408
	ds_read_b128 v[204:207], v163 offset:18432
	ds_read_b128 v[208:211], v163 offset:19456
	ds_read_b128 v[216:219], v163 offset:20480
	ds_read_b128 v[220:223], v163 offset:21504
	ds_read_b128 v[224:227], v163 offset:22528
	ds_read_b128 v[228:231], v163 offset:23552
	global_load_lds_dwordx4 v[232:233], off
	v_lshl_add_u64 v[234:235], v[214:215], 0, v[134:135]
	s_mov_b32 m0, s57
	v_lshl_add_u64 v[214:215], v[214:215], 0, s[14:15]
	global_load_lds_dwordx4 v[234:235], off
	v_lshl_add_u64 v[236:237], v[214:215], 0, v[138:139]
	s_mov_b32 m0, s58
	v_lshl_add_u64 v[214:215], v[214:215], 0, v[134:135]
	global_load_lds_dwordx4 v[236:237], off
	s_mov_b32 m0, s59
	v_lshl_add_u64 v[238:239], v[212:213], 0, v[140:141]
	global_load_lds_dwordx4 v[214:215], off
	s_mov_b32 m0, s37
	v_lshl_add_u64 v[240:241], v[212:213], 0, v[136:137]
	global_load_lds_dwordx4 v[238:239], off
	s_mov_b32 m0, s41
	s_nop 0
	global_load_lds_dwordx4 v[240:241], off
	s_waitcnt vmcnt(8) lgkmcnt(0)
	s_setprio 1
	s_barrier
	v_mfma_f32_16x16x32_bf16 v[60:63], v[164:167], v[196:199], v[60:63]
	v_mfma_f32_16x16x32_bf16 v[56:59], v[172:175], v[196:199], v[56:59]
	v_mfma_f32_16x16x32_bf16 v[44:47], v[164:167], v[204:207], v[44:47]
	v_mfma_f32_16x16x32_bf16 v[40:43], v[172:175], v[204:207], v[40:43]
	v_mfma_f32_16x16x32_bf16 v[28:31], v[164:167], v[216:219], v[28:31]
	v_mfma_f32_16x16x32_bf16 v[24:27], v[172:175], v[216:219], v[24:27]
	v_mfma_f32_16x16x32_bf16 v[12:15], v[164:167], v[224:227], v[12:15]
	v_mfma_f32_16x16x32_bf16 v[8:11], v[172:175], v[224:227], v[8:11]
	v_mfma_f32_16x16x32_bf16 v[60:63], v[168:171], v[200:203], v[60:63]
	v_mfma_f32_16x16x32_bf16 v[56:59], v[176:179], v[200:203], v[56:59]
	v_mfma_f32_16x16x32_bf16 v[44:47], v[168:171], v[208:211], v[44:47]
	v_mfma_f32_16x16x32_bf16 v[40:43], v[176:179], v[208:211], v[40:43]
	v_mfma_f32_16x16x32_bf16 v[28:31], v[168:171], v[220:223], v[28:31]
	v_mfma_f32_16x16x32_bf16 v[24:27], v[176:179], v[220:223], v[24:27]
	v_mfma_f32_16x16x32_bf16 v[12:15], v[168:171], v[228:231], v[12:15]
	v_mfma_f32_16x16x32_bf16 v[8:11], v[176:179], v[228:231], v[8:11]
	v_mfma_f32_16x16x32_bf16 v[52:55], v[180:183], v[196:199], v[52:55]
	v_mfma_f32_16x16x32_bf16 v[48:51], v[188:191], v[196:199], v[48:51]
	v_mfma_f32_16x16x32_bf16 v[36:39], v[180:183], v[204:207], v[36:39]
	v_mfma_f32_16x16x32_bf16 v[32:35], v[188:191], v[204:207], v[32:35]
	v_mfma_f32_16x16x32_bf16 v[20:23], v[180:183], v[216:219], v[20:23]
	v_mfma_f32_16x16x32_bf16 v[16:19], v[188:191], v[216:219], v[16:19]
	v_mfma_f32_16x16x32_bf16 v[4:7], v[180:183], v[224:227], v[4:7]
	v_mfma_f32_16x16x32_bf16 v[0:3], v[188:191], v[224:227], v[0:3]
	v_mfma_f32_16x16x32_bf16 v[52:55], v[184:187], v[200:203], v[52:55]
	v_mfma_f32_16x16x32_bf16 v[48:51], v[192:195], v[200:203], v[48:51]
	v_mfma_f32_16x16x32_bf16 v[36:39], v[184:187], v[208:211], v[36:39]
	v_mfma_f32_16x16x32_bf16 v[32:35], v[192:195], v[208:211], v[32:35]
	v_mfma_f32_16x16x32_bf16 v[20:23], v[184:187], v[220:223], v[20:23]
	v_mfma_f32_16x16x32_bf16 v[16:19], v[192:195], v[220:223], v[16:19]
	v_mfma_f32_16x16x32_bf16 v[4:7], v[184:187], v[228:231], v[4:7]
	v_mfma_f32_16x16x32_bf16 v[0:3], v[192:195], v[228:231], v[0:3]
	s_setprio 0
	s_barrier
; #define PG8_STAGE(bufoff, gbase, voff) do { _Pragma("unroll") for (int _i = 0; _i < 2; ++_i) \
;         __builtin_amdgcn_global_load_lds((const unsigned*)((const char*)(gbase) + (voff)[_i]), (PG8_LAS unsigned*)(lds + (bufoff) + ldsw + _i * 8192), 16, 0, 0); } while (0)
; #define PG8_LDA(dst, b, h) do { _Pragma("unroll") for (int m = 0; m < 4; ++m) _Pragma("unroll") for (int k = 0; k < 2; ++k) dst[m][k] = *(const PG8_LAS bf16x8*)(lds + PG8_SA(b, h) + aoff + m * 2048 + k * 1024); } while (0)
; #define PG8_LDB(dst, b, h) do { _Pragma("unroll") for (int n = 0; n < 2; ++n) _Pragma("unroll") for (int k = 0; k < 2; ++k) dst[n][k] = *(const PG8_LAS bf16x8*)(lds + PG8_SB(b, h) + boff + n * 2048 + k * 1024); } while (0)
; #define PG8_MMA(ai, bj, At, Bt) do { __builtin_amdgcn_s_setprio(1); _Pragma("unroll") for (int m = 0; m < 4; ++m) _Pragma("unroll") for (int n = 0; n < 2; ++n) _Pragma("unroll") for (int k = 0; k < 2; ++k) \
;         acc[ai][bj][m][n] = __builtin_amdgcn_mfma_f32_16x16x32_bf16(Bt[n][k], At[m][k], acc[ai][bj][m][n], 0, 0, 0); __builtin_amdgcn_s_setprio(0); } while (0)
; #define PG8_WAIT_V(n) asm volatile("s_waitcnt vmcnt(" #n ")" ::: "memory")
; #define PG8_WAIT_L(n) asm volatile("s_waitcnt lgkmcnt(" #n ")" ::: "memory")
; #define PG8_BAR __builtin_amdgcn_s_barrier()
; #define PG8_SCHED __builtin_amdgcn_sched_barrier(0)
; template <class Epi, class Sched, bool ALIGN_EPI = false, bool SP2 = false>
; __device__ __forceinline__ void gemm_phase(PG8_LAS unsigned char* lds, const Gemm g, const Sched& S, const Epi& E) {
;     ...
;         for (int t = 0; t < nt; t += 2) {
;             const bool last = (t == nt - 2);
;             const char* a1 = cA + (size_t)(t + 1) * kstep;
;             const char* a2 = last ? nA : cA + (size_t)(t + 2) * kstep; const char* b2 = last ? nB : cB + (size_t)(t + 2) * kstep;
;     ...
;             PG8_LDB(B0, 1, 0); PG8_LDB(B1, 1, 1); PG8_SCHED; PG8_LDA(At, 1, 0); PG8_STAGE(PG8_SA(0, 1), a2 + hstep, voffA);
;             PG8_WAIT_V(8); PG8_WAIT_L(0); PG8_BAR; PG8_MMA(0, 0, At, B0); PG8_MMA(0, 1, At, B1); PG8_BAR; PG8_SCHED;
;             PG8_LDA(At, 1, 1); PG8_STAGE(PG8_SB(1, 0), b3, voffB); PG8_STAGE(PG8_SB(1, 1), b3 + hstep, voffB); PG8_STAGE(PG8_SA(1, 0), a3, voffA);
;             PG8_WAIT_V(8); PG8_WAIT_L(0); PG8_BAR; PG8_MMA(1, 0, At, B0); PG8_MMA(1, 1, At, B1); PG8_BAR; PG8_SCHED;
	v_add_u32_e32 v176, s60, v161
	v_add_u32_e32 v192, s61, v161
	ds_read_b128 v[164:167], v176
	ds_read_b128 v[168:171], v176 offset:1024
	ds_read_b128 v[172:175], v176 offset:2048
	ds_read_b128 v[176:179], v176 offset:3072
	ds_read_b128 v[180:183], v192
	ds_read_b128 v[184:187], v192 offset:1024
	ds_read_b128 v[188:191], v192 offset:2048
	ds_read_b128 v[192:195], v192 offset:3072
	v_lshl_add_u64 v[212:213], v[212:213], 0, s[14:15]
	s_mov_b32 m0, s46
	v_lshl_add_u64 v[242:243], v[212:213], 0, v[140:141]
	ds_read_b128 v[196:199], v163 offset:32768
	ds_read_b128 v[200:203], v163 offset:33792
	ds_read_b128 v[204:207], v163 offset:34816
	ds_read_b128 v[208:211], v163 offset:35840
	ds_read_b128 v[216:219], v163 offset:36864
	ds_read_b128 v[220:223], v163 offset:37888
	ds_read_b128 v[224:227], v163 offset:38912
	ds_read_b128 v[228:231], v163 offset:39936
	global_load_lds_dwordx4 v[242:243], off
	s_mov_b32 m0, s47
	v_lshl_add_u64 v[212:213], v[212:213], 0, v[136:137]
	global_load_lds_dwordx4 v[212:213], off
	s_waitcnt vmcnt(8) lgkmcnt(0)
	s_setprio 1
	s_barrier
	v_mfma_f32_16x16x32_bf16 v[124:127], v[164:167], v[196:199], v[124:127]
	v_mfma_f32_16x16x32_bf16 v[120:123], v[172:175], v[196:199], v[120:123]
	v_mfma_f32_16x16x32_bf16 v[108:111], v[164:167], v[204:207], v[108:111]
	v_mfma_f32_16x16x32_bf16 v[104:107], v[172:175], v[204:207], v[104:107]
	v_mfma_f32_16x16x32_bf16 v[92:95], v[164:167], v[216:219], v[92:95]
	v_mfma_f32_16x16x32_bf16 v[88:91], v[172:175], v[216:219], v[88:91]
	v_mfma_f32_16x16x32_bf16 v[76:79], v[164:167], v[224:227], v[76:79]
	v_mfma_f32_16x16x32_bf16 v[72:75], v[172:175], v[224:227], v[72:75]
	v_mfma_f32_16x16x32_bf16 v[124:127], v[168:171], v[200:203], v[124:127]
	v_mfma_f32_16x16x32_bf16 v[120:123], v[176:179], v[200:203], v[120:123]
	v_mfma_f32_16x16x32_bf16 v[108:111], v[168:171], v[208:211], v[108:111]
	v_mfma_f32_16x16x32_bf16 v[104:107], v[176:179], v[208:211], v[104:107]
	v_mfma_f32_16x16x32_bf16 v[92:95], v[168:171], v[220:223], v[92:95]
	v_mfma_f32_16x16x32_bf16 v[88:91], v[176:179], v[220:223], v[88:91]
	v_mfma_f32_16x16x32_bf16 v[76:79], v[168:171], v[228:231], v[76:79]
	v_mfma_f32_16x16x32_bf16 v[72:75], v[176:179], v[228:231], v[72:75]
	v_mfma_f32_16x16x32_bf16 v[116:119], v[180:183], v[196:199], v[116:119]
	v_mfma_f32_16x16x32_bf16 v[112:115], v[188:191], v[196:199], v[112:115]
	v_mfma_f32_16x16x32_bf16 v[100:103], v[180:183], v[204:207], v[100:103]
	v_mfma_f32_16x16x32_bf16 v[96:99], v[188:191], v[204:207], v[96:99]
	v_mfma_f32_16x16x32_bf16 v[84:87], v[180:183], v[216:219], v[84:87]
	v_mfma_f32_16x16x32_bf16 v[80:83], v[188:191], v[216:219], v[80:83]
	v_mfma_f32_16x16x32_bf16 v[68:71], v[180:183], v[224:227], v[68:71]
	v_mfma_f32_16x16x32_bf16 v[64:67], v[188:191], v[224:227], v[64:67]
	v_mfma_f32_16x16x32_bf16 v[116:119], v[184:187], v[200:203], v[116:119]
	v_mfma_f32_16x16x32_bf16 v[112:115], v[192:195], v[200:203], v[112:115]
	v_mfma_f32_16x16x32_bf16 v[100:103], v[184:187], v[208:211], v[100:103]
	v_mfma_f32_16x16x32_bf16 v[96:99], v[192:195], v[208:211], v[96:99]
	v_mfma_f32_16x16x32_bf16 v[84:87], v[184:187], v[220:223], v[84:87]
	v_mfma_f32_16x16x32_bf16 v[80:83], v[192:195], v[220:223], v[80:83]
	v_mfma_f32_16x16x32_bf16 v[68:71], v[184:187], v[228:231], v[68:71]
	v_mfma_f32_16x16x32_bf16 v[64:67], v[192:195], v[228:231], v[64:67]
	s_setprio 0
	s_barrier
	s_add_i32 m0, s62, 0xffffff80
	ds_read_b128 v[196:199], v163 offset:49152
	ds_read_b128 v[200:203], v163 offset:50176
	ds_read_b128 v[204:207], v163 offset:51200
	global_load_lds_dwordx4 v[232:233], off offset:128
	s_add_i32 m0, s63, 0xffffff80
	ds_read_b128 v[228:231], v163 offset:56320
	global_load_lds_dwordx4 v[234:235], off offset:128
	s_add_i32 m0, s64, 0xffffff80
	ds_read_b128 v[224:227], v163 offset:55296
	global_load_lds_dwordx4 v[236:237], off offset:128
	s_add_i32 m0, s65, 0xffffff80
	ds_read_b128 v[220:223], v163 offset:54272
	global_load_lds_dwordx4 v[214:215], off offset:128
	s_add_i32 m0, s48, 0xffffff80
	ds_read_b128 v[216:219], v163 offset:53248
	global_load_lds_dwordx4 v[238:239], off offset:128
	s_add_i32 m0, s49, 0xffffff80
	ds_read_b128 v[208:211], v163 offset:52224
	global_load_lds_dwordx4 v[240:241], off offset:128
	s_waitcnt vmcnt(8) lgkmcnt(0)
	s_setprio 1
	s_barrier
	v_mfma_f32_16x16x32_bf16 v[60:63], v[164:167], v[196:199], v[60:63]
	v_mfma_f32_16x16x32_bf16 v[56:59], v[172:175], v[196:199], v[56:59]
	v_mfma_f32_16x16x32_bf16 v[44:47], v[164:167], v[204:207], v[44:47]
	v_mfma_f32_16x16x32_bf16 v[40:43], v[172:175], v[204:207], v[40:43]
	v_mfma_f32_16x16x32_bf16 v[28:31], v[164:167], v[216:219], v[28:31]
	v_mfma_f32_16x16x32_bf16 v[24:27], v[172:175], v[216:219], v[24:27]
	v_mfma_f32_16x16x32_bf16 v[12:15], v[164:167], v[224:227], v[12:15]
	v_mfma_f32_16x16x32_bf16 v[8:11], v[172:175], v[224:227], v[8:11]
	v_mfma_f32_16x16x32_bf16 v[60:63], v[168:171], v[200:203], v[60:63]
	v_mfma_f32_16x16x32_bf16 v[56:59], v[176:179], v[200:203], v[56:59]
	v_mfma_f32_16x16x32_bf16 v[44:47], v[168:171], v[208:211], v[44:47]
	v_mfma_f32_16x16x32_bf16 v[40:43], v[176:179], v[208:211], v[40:43]
	v_mfma_f32_16x16x32_bf16 v[28:31], v[168:171], v[220:223], v[28:31]
	v_mfma_f32_16x16x32_bf16 v[24:27], v[176:179], v[220:223], v[24:27]
	v_mfma_f32_16x16x32_bf16 v[12:15], v[168:171], v[228:231], v[12:15]
	v_mfma_f32_16x16x32_bf16 v[8:11], v[176:179], v[228:231], v[8:11]
	v_mfma_f32_16x16x32_bf16 v[52:55], v[180:183], v[196:199], v[52:55]
	v_mfma_f32_16x16x32_bf16 v[48:51], v[188:191], v[196:199], v[48:51]
	v_mfma_f32_16x16x32_bf16 v[36:39], v[180:183], v[204:207], v[36:39]
	v_mfma_f32_16x16x32_bf16 v[32:35], v[188:191], v[204:207], v[32:35]
	v_mfma_f32_16x16x32_bf16 v[20:23], v[180:183], v[216:219], v[20:23]
	v_mfma_f32_16x16x32_bf16 v[16:19], v[188:191], v[216:219], v[16:19]
	v_mfma_f32_16x16x32_bf16 v[4:7], v[180:183], v[224:227], v[4:7]
	v_mfma_f32_16x16x32_bf16 v[0:3], v[188:191], v[224:227], v[0:3]
	v_mfma_f32_16x16x32_bf16 v[52:55], v[184:187], v[200:203], v[52:55]
	v_mfma_f32_16x16x32_bf16 v[48:51], v[192:195], v[200:203], v[48:51]
	v_mfma_f32_16x16x32_bf16 v[36:39], v[184:187], v[208:211], v[36:39]
	v_mfma_f32_16x16x32_bf16 v[32:35], v[192:195], v[208:211], v[32:35]
	v_mfma_f32_16x16x32_bf16 v[20:23], v[184:187], v[220:223], v[20:23]
	v_mfma_f32_16x16x32_bf16 v[16:19], v[192:195], v[220:223], v[16:19]
	v_mfma_f32_16x16x32_bf16 v[4:7], v[184:187], v[228:231], v[4:7]
	v_mfma_f32_16x16x32_bf16 v[0:3], v[192:195], v[228:231], v[0:3]
	v_lshl_add_u64 v[154:155], v[154:155], 0, s[28:29]
	v_lshl_add_u64 v[158:159], v[158:159], 0, s[28:29]
	s_cmp_ge_i32 s10, s50
	s_cbranch_scc1 .Lrot_exit_9
	s_cmp_eq_u32 s51, s10
	v_lshl_add_u64 v[196:197], v[158:159], 0, s[24:25]
	s_cselect_b64 vcc, -1, 0
	s_add_i32 s10, s10, 2
	v_cndmask_b32_e32 v213, v197, v151, vcc
	v_cndmask_b32_e32 v212, v196, v150, vcc
	v_cndmask_b32_e32 v215, v155, v153, vcc
	v_cndmask_b32_e32 v214, v154, v152, vcc
	s_setprio 0
	s_barrier
	s_branch .LBB0_1169
; #define PG8_MMA(ai, bj, At, Bt) do { __builtin_amdgcn_s_setprio(1); _Pragma("unroll") for (int m = 0; m < 4; ++m) _Pragma("unroll") for (int n = 0; n < 2; ++n) _Pragma("unroll") for (int k = 0; k < 2; ++k) \
;         acc[ai][bj][m][n] = __builtin_amdgcn_mfma_f32_16x16x32_bf16(Bt[n][k], At[m][k], acc[ai][bj][m][n], 0, 0, 0); __builtin_amdgcn_s_setprio(0); } while (0)
; #define PG8_WAIT_V(n) asm volatile("s_waitcnt vmcnt(" #n ")" ::: "memory")
; #define PG8_WAIT_L(n) asm volatile("s_waitcnt lgkmcnt(" #n ")" ::: "memory")
; #define PG8_BAR __builtin_amdgcn_s_barrier()
; #define PG8_SCHED __builtin_amdgcn_sched_barrier(0)
; template <class Epi, class Sched, bool ALIGN_EPI = false, bool SP2 = false>
; __device__ __forceinline__ void gemm_phase(PG8_LAS unsigned char* lds, const Gemm g, const Sched& S, const Epi& E) {
;     ...
;             PG8_WAIT_V(8); PG8_WAIT_L(0); PG8_BAR; PG8_MMA(1, 0, At, B0); PG8_MMA(1, 1, At, B1); PG8_BAR; PG8_SCHED;
;     ...
;         if constexpr (ALIGN_EPI) { if (wr == 0) PG8_BAR; }
.Lrot_exit_9:
	s_setprio 0
	s_barrier
.LBB0_1170:
	s_and_b64 vcc, exec, s[26:27]
	s_cbranch_vccz .LBB0_1172
	s_barrier

; template <class Epi, class Sched, bool ALIGN_EPI = false, bool SP2 = false>
; __device__ __forceinline__ void gemm_phase(PG8_LAS unsigned char* lds, const Gemm g, const Sched& S, const Epi& E) {
;     ...
;     for (;;) {
;         const bool has_next = S.next(ui + 1, nxt);
;         const char* nA = has_next ? (const char*)g.A + (size_t)nxt.pm * tstep : cA; const char* nB = has_next ? (const char*)g.Bt + (size_t)nxt.pn * tstep : cB;
;         for (int t = 0; t < nt; t += 2) {
;             const bool last = (t == nt - 2);
;             const char* a1 = cA + (size_t)(t + 1) * kstep;
;             const char* a2 = last ? nA : cA + (size_t)(t + 2) * kstep; const char* b2 = last ? nB : cB + (size_t)(t + 2) * kstep;
;     ...
; #pragma unroll
;         for (int a = 0; a < 2; ++a)
; #pragma unroll
;             for (int b = 0; b < 2; ++b)
; #pragma unroll
;                 for (int m = 0; m < 4; ++m)
; #pragma unroll
;                     for (int n = 0; n < 2; ++n) acc[a][b][m][n] = (f32x4){0.f, 0.f, 0.f, 0.f};
;         cur = nxt; cA = nA; cB = nB; ++ui;
.LBB0_1190:
	v_mov_b32_e32 v133, 0
	s_andn2_b64 vcc, exec, s[22:23]
	v_mov_b32_e32 v132, v133
	v_mov_b32_e32 v131, v133
	v_mov_b32_e32 v130, v133
	v_mov_b32_e32 v129, v133
	v_mov_b32_e32 v128, v133
	v_mov_b32_e32 v127, v133
	v_mov_b32_e32 v126, v133
	v_mov_b32_e32 v117, v133
	v_mov_b32_e32 v116, v133
	v_mov_b32_e32 v115, v133
	v_mov_b32_e32 v114, v133
	v_mov_b32_e32 v113, v133
	v_mov_b32_e32 v112, v133
	v_mov_b32_e32 v111, v133
	v_mov_b32_e32 v110, v133
	v_mov_b32_e32 v101, v133
	v_mov_b32_e32 v100, v133
	v_mov_b32_e32 v99, v133
	v_mov_b32_e32 v98, v133
	v_mov_b32_e32 v97, v133
	v_mov_b32_e32 v96, v133
	v_mov_b32_e32 v95, v133
	v_mov_b32_e32 v94, v133
	v_mov_b32_e32 v85, v133
	v_mov_b32_e32 v84, v133
	v_mov_b32_e32 v83, v133
	v_mov_b32_e32 v82, v133
	v_mov_b32_e32 v81, v133
	v_mov_b32_e32 v80, v133
	v_mov_b32_e32 v79, v133
	v_mov_b32_e32 v78, v133
	v_mov_b32_e32 v125, v133
	v_mov_b32_e32 v124, v133
	v_mov_b32_e32 v123, v133
	v_mov_b32_e32 v122, v133
	v_mov_b32_e32 v121, v133
	v_mov_b32_e32 v120, v133
	v_mov_b32_e32 v119, v133
	v_mov_b32_e32 v118, v133
	v_mov_b32_e32 v109, v133
	v_mov_b32_e32 v108, v133
	v_mov_b32_e32 v107, v133
	v_mov_b32_e32 v106, v133
	v_mov_b32_e32 v105, v133
	v_mov_b32_e32 v104, v133
	v_mov_b32_e32 v103, v133
	v_mov_b32_e32 v102, v133
	v_mov_b32_e32 v93, v133
	v_mov_b32_e32 v92, v133
	v_mov_b32_e32 v91, v133
	v_mov_b32_e32 v90, v133
	v_mov_b32_e32 v89, v133
	v_mov_b32_e32 v88, v133
	v_mov_b32_e32 v87, v133
	v_mov_b32_e32 v86, v133
	v_mov_b32_e32 v77, v133
	v_mov_b32_e32 v76, v133
	v_mov_b32_e32 v75, v133
	v_mov_b32_e32 v74, v133
	v_mov_b32_e32 v73, v133
	v_mov_b32_e32 v72, v133
	v_mov_b32_e32 v71, v133
	v_mov_b32_e32 v70, v133
	v_mov_b32_e32 v69, v133
	v_mov_b32_e32 v68, v133
	v_mov_b32_e32 v67, v133
	v_mov_b32_e32 v66, v133
	v_mov_b32_e32 v65, v133
	v_mov_b32_e32 v64, v133
	v_mov_b32_e32 v63, v133
	v_mov_b32_e32 v62, v133
	v_mov_b32_e32 v53, v133
	v_mov_b32_e32 v52, v133
	v_mov_b32_e32 v51, v133
	v_mov_b32_e32 v50, v133
	v_mov_b32_e32 v49, v133
	v_mov_b32_e32 v48, v133
	v_mov_b32_e32 v47, v133
	v_mov_b32_e32 v46, v133
	v_mov_b32_e32 v37, v133
	v_mov_b32_e32 v36, v133
	v_mov_b32_e32 v35, v133
	v_mov_b32_e32 v34, v133
	v_mov_b32_e32 v33, v133
	v_mov_b32_e32 v32, v133
	v_mov_b32_e32 v31, v133
	v_mov_b32_e32 v30, v133
	v_mov_b32_e32 v21, v133
	v_mov_b32_e32 v20, v133
	v_mov_b32_e32 v19, v133
	v_mov_b32_e32 v18, v133
	v_mov_b32_e32 v17, v133
	v_mov_b32_e32 v16, v133
	v_mov_b32_e32 v15, v133
	v_mov_b32_e32 v14, v133
	v_mov_b32_e32 v61, v133
	v_mov_b32_e32 v60, v133
	v_mov_b32_e32 v59, v133
	v_mov_b32_e32 v58, v133
	v_mov_b32_e32 v57, v133
	v_mov_b32_e32 v56, v133
	v_mov_b32_e32 v55, v133
	v_mov_b32_e32 v54, v133
	v_mov_b32_e32 v45, v133
	v_mov_b32_e32 v44, v133
	v_mov_b32_e32 v43, v133
	v_mov_b32_e32 v42, v133
	v_mov_b32_e32 v41, v133
	v_mov_b32_e32 v40, v133
	v_mov_b32_e32 v39, v133
	v_mov_b32_e32 v38, v133
	v_mov_b32_e32 v29, v133
	v_mov_b32_e32 v28, v133
	v_mov_b32_e32 v27, v133
	v_mov_b32_e32 v26, v133
	v_mov_b32_e32 v25, v133
	v_mov_b32_e32 v24, v133
	v_mov_b32_e32 v23, v133
	v_mov_b32_e32 v22, v133
	v_mov_b32_e32 v13, v133
	v_mov_b32_e32 v12, v133
	v_mov_b32_e32 v11, v133
	v_mov_b32_e32 v10, v133
	v_mov_b32_e32 v9, v133
	v_mov_b32_e32 v8, v133
	s_waitcnt lgkmcnt(0)
	v_mov_b32_e32 v7, v133
	v_mov_b32_e32 v6, v133
	s_cbranch_vccnz .LBB0_1193
	v_mov_b32_e32 v6, 0
	v_lshl_add_u64 v[134:135], v[134:135], 0, s[26:27]
	v_lshl_add_u64 v[136:137], v[136:137], 0, s[20:21]
	s_mov_b32 s10, 0
	v_mov_b32_e32 v7, v6
	v_mov_b32_e32 v8, v6
	v_mov_b32_e32 v9, v6
	v_mov_b32_e32 v10, v6
	v_mov_b32_e32 v11, v6
	v_mov_b32_e32 v12, v6
	v_mov_b32_e32 v13, v6
	v_mov_b32_e32 v22, v6
	v_mov_b32_e32 v23, v6
	v_mov_b32_e32 v24, v6
	v_mov_b32_e32 v25, v6
	v_mov_b32_e32 v26, v6
	v_mov_b32_e32 v27, v6
	v_mov_b32_e32 v28, v6
	v_mov_b32_e32 v29, v6
	v_mov_b32_e32 v38, v6
	v_mov_b32_e32 v39, v6
	v_mov_b32_e32 v40, v6
	v_mov_b32_e32 v41, v6
	v_mov_b32_e32 v42, v6
	v_mov_b32_e32 v43, v6
	v_mov_b32_e32 v44, v6
	v_mov_b32_e32 v45, v6
	v_mov_b32_e32 v54, v6
	v_mov_b32_e32 v55, v6
	v_mov_b32_e32 v56, v6
	v_mov_b32_e32 v57, v6
	v_mov_b32_e32 v58, v6
	v_mov_b32_e32 v59, v6
	v_mov_b32_e32 v60, v6
	v_mov_b32_e32 v61, v6
	v_mov_b32_e32 v14, v6
	v_mov_b32_e32 v15, v6
	v_mov_b32_e32 v16, v6
	v_mov_b32_e32 v17, v6
	v_mov_b32_e32 v18, v6
	v_mov_b32_e32 v19, v6
	v_mov_b32_e32 v20, v6
	v_mov_b32_e32 v21, v6
	v_mov_b32_e32 v30, v6
	v_mov_b32_e32 v31, v6
	v_mov_b32_e32 v32, v6
	v_mov_b32_e32 v33, v6
	v_mov_b32_e32 v34, v6
	v_mov_b32_e32 v35, v6
	v_mov_b32_e32 v36, v6
	v_mov_b32_e32 v37, v6
	v_mov_b32_e32 v46, v6
	v_mov_b32_e32 v47, v6
	v_mov_b32_e32 v48, v6
	v_mov_b32_e32 v49, v6
	v_mov_b32_e32 v50, v6
	v_mov_b32_e32 v51, v6
	v_mov_b32_e32 v52, v6
	v_mov_b32_e32 v53, v6
	v_mov_b32_e32 v62, v6
	v_mov_b32_e32 v63, v6
	v_mov_b32_e32 v64, v6
	v_mov_b32_e32 v65, v6
	v_mov_b32_e32 v66, v6
	v_mov_b32_e32 v67, v6
	v_mov_b32_e32 v68, v6
	v_mov_b32_e32 v69, v6
	v_mov_b32_e32 v70, v6
	v_mov_b32_e32 v71, v6
	v_mov_b32_e32 v72, v6
	v_mov_b32_e32 v73, v6
	v_mov_b32_e32 v74, v6
	v_mov_b32_e32 v75, v6
	v_mov_b32_e32 v76, v6
	v_mov_b32_e32 v77, v6
	v_mov_b32_e32 v86, v6
	v_mov_b32_e32 v87, v6
	v_mov_b32_e32 v88, v6
	v_mov_b32_e32 v89, v6
	v_mov_b32_e32 v90, v6
	v_mov_b32_e32 v91, v6
	v_mov_b32_e32 v92, v6
	v_mov_b32_e32 v93, v6
	v_mov_b32_e32 v102, v6
	v_mov_b32_e32 v103, v6
	v_mov_b32_e32 v104, v6
	v_mov_b32_e32 v105, v6
	v_mov_b32_e32 v106, v6
	v_mov_b32_e32 v107, v6
	v_mov_b32_e32 v108, v6
	v_mov_b32_e32 v109, v6
	v_mov_b32_e32 v118, v6
	v_mov_b32_e32 v119, v6
	v_mov_b32_e32 v120, v6
	v_mov_b32_e32 v121, v6
	v_mov_b32_e32 v122, v6
	v_mov_b32_e32 v123, v6
	v_mov_b32_e32 v124, v6
	v_mov_b32_e32 v125, v6
	v_mov_b32_e32 v78, v6
	v_mov_b32_e32 v79, v6
	v_mov_b32_e32 v80, v6
	v_mov_b32_e32 v81, v6
	v_mov_b32_e32 v82, v6
	v_mov_b32_e32 v83, v6
	v_mov_b32_e32 v84, v6
	v_mov_b32_e32 v85, v6
	v_mov_b32_e32 v94, v6
	v_mov_b32_e32 v95, v6
	v_mov_b32_e32 v96, v6
	v_mov_b32_e32 v97, v6
	v_mov_b32_e32 v98, v6
	v_mov_b32_e32 v99, v6
	v_mov_b32_e32 v100, v6
	v_mov_b32_e32 v101, v6
	v_mov_b32_e32 v110, v6
	v_mov_b32_e32 v111, v6
	v_mov_b32_e32 v112, v6
	v_mov_b32_e32 v113, v6
	v_mov_b32_e32 v114, v6
	v_mov_b32_e32 v115, v6
	v_mov_b32_e32 v116, v6
	v_mov_b32_e32 v117, v6
	v_mov_b32_e32 v126, v6
	v_mov_b32_e32 v127, v6
	v_mov_b32_e32 v128, v6
	v_mov_b32_e32 v129, v6
	v_mov_b32_e32 v130, v6
	v_mov_b32_e32 v131, v6
	v_mov_b32_e32 v132, v6
	v_mov_b32_e32 v133, v6
	s_cmp_eq_u32 s49, s10
	v_lshl_add_u64 v[198:199], v[136:137], 0, s[20:21]
	s_cselect_b64 vcc, -1, 0
	s_add_i32 s10, s10, 2
	v_cndmask_b32_e32 v215, v199, v175, vcc
	v_cndmask_b32_e32 v214, v198, v174, vcc
	v_cndmask_b32_e32 v237, v135, v177, vcc
	v_cndmask_b32_e32 v236, v134, v176, vcc
	.p2align	6
; #define PG8_STAGE(bufoff, gbase, voff) do { _Pragma("unroll") for (int _i = 0; _i < 2; ++_i) \
;         __builtin_amdgcn_global_load_lds((const unsigned*)((const char*)(gbase) + (voff)[_i]), (PG8_LAS unsigned*)(lds + (bufoff) + ldsw + _i * 8192), 16, 0, 0); } while (0)
; #define PG8_LDA(dst, b, h) do { _Pragma("unroll") for (int m = 0; m < 4; ++m) _Pragma("unroll") for (int k = 0; k < 2; ++k) dst[m][k] = *(const PG8_LAS bf16x8*)(lds + PG8_SA(b, h) + aoff + m * 2048 + k * 1024); } while (0)
; #define PG8_LDB(dst, b, h) do { _Pragma("unroll") for (int n = 0; n < 2; ++n) _Pragma("unroll") for (int k = 0; k < 2; ++k) dst[n][k] = *(const PG8_LAS bf16x8*)(lds + PG8_SB(b, h) + boff + n * 2048 + k * 1024); } while (0)
; #define PG8_MMA(ai, bj, At, Bt) do { __builtin_amdgcn_s_setprio(1); _Pragma("unroll") for (int m = 0; m < 4; ++m) _Pragma("unroll") for (int n = 0; n < 2; ++n) _Pragma("unroll") for (int k = 0; k < 2; ++k) \
;         acc[ai][bj][m][n] = __builtin_amdgcn_mfma_f32_16x16x32_bf16(Bt[n][k], At[m][k], acc[ai][bj][m][n], 0, 0, 0); __builtin_amdgcn_s_setprio(0); } while (0)
; #define PG8_WAIT_V(n) asm volatile("s_waitcnt vmcnt(" #n ")" ::: "memory")
; #define PG8_BAR __builtin_amdgcn_s_barrier()
; template <class Epi, class Sched, bool ALIGN_EPI = false, bool SP2 = false>
; __device__ __forceinline__ void gemm_phase(PG8_LAS unsigned char* lds, const Gemm g, const Sched& S, const Epi& E) {
;     ...
;         for (int t = 0; t < nt; t += 2) {
;             const bool last = (t == nt - 2);
;             const char* a1 = cA + (size_t)(t + 1) * kstep;
;             const char* a2 = last ? nA : cA + (size_t)(t + 2) * kstep; const char* b2 = last ? nB : cB + (size_t)(t + 2) * kstep;
;             const char* a3 = a2 + kstep; const char* b3 = b2 + kstep;
;             if (last && has_next) S.a_ready(nxt);
;             if constexpr (SP2) {
;             PG8_LDB(B0, 0, 0); PG8_LDB(B1, 0, 1); PG8_SCHED; PG8_LDA(At, 0, 0); PG8_STAGE(PG8_SA(1, 1), a1 + hstep, voffA);
;             PG8_WAIT_V(8); PG8_WAIT_L(0); PG8_BAR; PG8_MMA(0, 0, At, B0); PG8_MMA(0, 1, At, B1); PG8_BAR; PG8_SCHED;
;             PG8_LDA(At, 0, 1); PG8_STAGE(PG8_SB(0, 0), b2, voffB); PG8_STAGE(PG8_SB(0, 1), b2 + hstep, voffB); PG8_STAGE(PG8_SA(0, 0), a2, voffA);
;             PG8_WAIT_V(8); PG8_WAIT_L(0); PG8_BAR; PG8_MMA(1, 0, At, B0); PG8_MMA(1, 1, At, B1); PG8_BAR; PG8_SCHED;
.LBB0_1192:
	v_add_u32_e32 v178, s56, v216
	v_add_u32_e32 v194, s57, v216
	ds_read_b128 v[138:141], v178
	ds_read_b128 v[142:145], v178 offset:1024
	ds_read_b128 v[146:149], v178 offset:2048
	ds_read_b128 v[178:181], v178 offset:3072
	ds_read_b128 v[182:185], v194
	ds_read_b128 v[186:189], v194 offset:1024
	ds_read_b128 v[190:193], v194 offset:2048
	ds_read_b128 v[194:197], v194 offset:3072
	v_lshl_add_u64 v[238:239], v[136:137], 0, v[168:169]
	s_add_i32 m0, s34, 0xc000
	ds_read_b128 v[198:201], v218
	ds_read_b128 v[202:205], v218 offset:1024
	ds_read_b128 v[206:209], v218 offset:2048
	ds_read_b128 v[210:213], v218 offset:3072
	ds_read_b128 v[220:223], v218 offset:4096
	ds_read_b128 v[224:227], v218 offset:5120
	ds_read_b128 v[228:231], v218 offset:6144
	ds_read_b128 v[232:235], v218 offset:7168
	global_load_lds_dwordx4 v[238:239], off
	s_add_i32 m0, s34, 0xe000
	v_lshl_add_u64 v[238:239], v[136:137], 0, v[166:167]
	global_load_lds_dwordx4 v[238:239], off
	s_waitcnt vmcnt(8) lgkmcnt(0)
	s_setprio 1
	s_barrier
	v_mfma_f32_16x16x32_bf16 v[130:133], v[138:141], v[198:201], v[130:133]
	v_mfma_f32_16x16x32_bf16 v[126:129], v[146:149], v[198:201], v[126:129]
	v_mfma_f32_16x16x32_bf16 v[114:117], v[138:141], v[206:209], v[114:117]
	v_mfma_f32_16x16x32_bf16 v[110:113], v[146:149], v[206:209], v[110:113]
	v_mfma_f32_16x16x32_bf16 v[98:101], v[138:141], v[220:223], v[98:101]
	v_mfma_f32_16x16x32_bf16 v[94:97], v[146:149], v[220:223], v[94:97]
	v_mfma_f32_16x16x32_bf16 v[82:85], v[138:141], v[228:231], v[82:85]
	v_mfma_f32_16x16x32_bf16 v[78:81], v[146:149], v[228:231], v[78:81]
	v_mfma_f32_16x16x32_bf16 v[130:133], v[142:145], v[202:205], v[130:133]
	v_mfma_f32_16x16x32_bf16 v[126:129], v[178:181], v[202:205], v[126:129]
	v_mfma_f32_16x16x32_bf16 v[114:117], v[142:145], v[210:213], v[114:117]
	v_mfma_f32_16x16x32_bf16 v[110:113], v[178:181], v[210:213], v[110:113]
	v_mfma_f32_16x16x32_bf16 v[98:101], v[142:145], v[224:227], v[98:101]
	v_mfma_f32_16x16x32_bf16 v[94:97], v[178:181], v[224:227], v[94:97]
	v_mfma_f32_16x16x32_bf16 v[82:85], v[142:145], v[232:235], v[82:85]
	v_mfma_f32_16x16x32_bf16 v[78:81], v[178:181], v[232:235], v[78:81]
	v_mfma_f32_16x16x32_bf16 v[122:125], v[182:185], v[198:201], v[122:125]
	v_mfma_f32_16x16x32_bf16 v[118:121], v[190:193], v[198:201], v[118:121]
	v_mfma_f32_16x16x32_bf16 v[106:109], v[182:185], v[206:209], v[106:109]
	v_mfma_f32_16x16x32_bf16 v[102:105], v[190:193], v[206:209], v[102:105]
	v_mfma_f32_16x16x32_bf16 v[90:93], v[182:185], v[220:223], v[90:93]
	v_mfma_f32_16x16x32_bf16 v[86:89], v[190:193], v[220:223], v[86:89]
	v_mfma_f32_16x16x32_bf16 v[74:77], v[182:185], v[228:231], v[74:77]
	v_mfma_f32_16x16x32_bf16 v[70:73], v[190:193], v[228:231], v[70:73]
	v_mfma_f32_16x16x32_bf16 v[122:125], v[186:189], v[202:205], v[122:125]
	v_mfma_f32_16x16x32_bf16 v[118:121], v[194:197], v[202:205], v[118:121]
	v_mfma_f32_16x16x32_bf16 v[106:109], v[186:189], v[210:213], v[106:109]
	v_mfma_f32_16x16x32_bf16 v[102:105], v[194:197], v[210:213], v[102:105]
	v_mfma_f32_16x16x32_bf16 v[90:93], v[186:189], v[224:227], v[90:93]
	v_mfma_f32_16x16x32_bf16 v[86:89], v[194:197], v[224:227], v[86:89]
	v_mfma_f32_16x16x32_bf16 v[74:77], v[186:189], v[232:235], v[74:77]
	v_mfma_f32_16x16x32_bf16 v[70:73], v[194:197], v[232:235], v[70:73]
	s_setprio 0
	s_barrier
	s_add_i32 s11, s56, s29
	v_lshl_add_u64 v[238:239], v[236:237], 0, v[158:159]
	s_mov_b32 m0, s11
	ds_read_b128 v[198:201], v218 offset:16384
	ds_read_b128 v[202:205], v218 offset:17408
	ds_read_b128 v[206:209], v218 offset:18432
	ds_read_b128 v[210:213], v218 offset:19456
	ds_read_b128 v[220:223], v218 offset:20480
	ds_read_b128 v[224:227], v218 offset:21504
	ds_read_b128 v[228:231], v218 offset:22528
	ds_read_b128 v[232:235], v218 offset:23552
	global_load_lds_dwordx4 v[238:239], off
	v_lshl_add_u64 v[240:241], v[236:237], 0, v[162:163]
	s_add_i32 m0, s11, 0x2000
	v_lshl_add_u64 v[236:237], v[236:237], 0, s[12:13]
	s_add_i32 s11, s57, s29
	global_load_lds_dwordx4 v[240:241], off
	v_lshl_add_u64 v[242:243], v[236:237], 0, v[158:159]
	s_mov_b32 m0, s11
	v_lshl_add_u64 v[236:237], v[236:237], 0, v[162:163]
	global_load_lds_dwordx4 v[242:243], off
	s_add_i32 m0, s11, 0x2000
	v_lshl_add_u64 v[244:245], v[214:215], 0, v[154:155]
	global_load_lds_dwordx4 v[236:237], off
	s_mov_b32 m0, s34
	v_lshl_add_u64 v[246:247], v[214:215], 0, v[160:161]
	global_load_lds_dwordx4 v[244:245], off
	s_mov_b32 m0, s35
	s_nop 0
	global_load_lds_dwordx4 v[246:247], off
	s_waitcnt vmcnt(8) lgkmcnt(0)
	s_setprio 1
	s_barrier
; #define PG8_STAGE(bufoff, gbase, voff) do { _Pragma("unroll") for (int _i = 0; _i < 2; ++_i) \
;         __builtin_amdgcn_global_load_lds((const unsigned*)((const char*)(gbase) + (voff)[_i]), (PG8_LAS unsigned*)(lds + (bufoff) + ldsw + _i * 8192), 16, 0, 0); } while (0)
; #define PG8_LDA(dst, b, h) do { _Pragma("unroll") for (int m = 0; m < 4; ++m) _Pragma("unroll") for (int k = 0; k < 2; ++k) dst[m][k] = *(const PG8_LAS bf16x8*)(lds + PG8_SA(b, h) + aoff + m * 2048 + k * 1024); } while (0)
; #define PG8_LDB(dst, b, h) do { _Pragma("unroll") for (int n = 0; n < 2; ++n) _Pragma("unroll") for (int k = 0; k < 2; ++k) dst[n][k] = *(const PG8_LAS bf16x8*)(lds + PG8_SB(b, h) + boff + n * 2048 + k * 1024); } while (0)
; #define PG8_MMA(ai, bj, At, Bt) do { __builtin_amdgcn_s_setprio(1); _Pragma("unroll") for (int m = 0; m < 4; ++m) _Pragma("unroll") for (int n = 0; n < 2; ++n) _Pragma("unroll") for (int k = 0; k < 2; ++k) \
;         acc[ai][bj][m][n] = __builtin_amdgcn_mfma_f32_16x16x32_bf16(Bt[n][k], At[m][k], acc[ai][bj][m][n], 0, 0, 0); __builtin_amdgcn_s_setprio(0); } while (0)
; #define PG8_WAIT_V(n) asm volatile("s_waitcnt vmcnt(" #n ")" ::: "memory")
; #define PG8_WAIT_L(n) asm volatile("s_waitcnt lgkmcnt(" #n ")" ::: "memory")
; #define PG8_BAR __builtin_amdgcn_s_barrier()
; #define PG8_SCHED __builtin_amdgcn_sched_barrier(0)
; template <class Epi, class Sched, bool ALIGN_EPI = false, bool SP2 = false>
; __device__ __forceinline__ void gemm_phase(PG8_LAS unsigned char* lds, const Gemm g, const Sched& S, const Epi& E) {
;     ...
;             PG8_WAIT_V(8); PG8_WAIT_L(0); PG8_BAR; PG8_MMA(1, 0, At, B0); PG8_MMA(1, 1, At, B1); PG8_BAR; PG8_SCHED;
;             PG8_LDB(B0, 1, 0); PG8_LDB(B1, 1, 1); PG8_SCHED; PG8_LDA(At, 1, 0); PG8_STAGE(PG8_SA(0, 1), a2 + hstep, voffA);
;             PG8_WAIT_V(8); PG8_WAIT_L(0); PG8_BAR; PG8_MMA(0, 0, At, B0); PG8_MMA(0, 1, At, B1); PG8_BAR; PG8_SCHED;
	v_mfma_f32_16x16x32_bf16 v[66:69], v[138:141], v[198:201], v[66:69]
	v_mfma_f32_16x16x32_bf16 v[62:65], v[146:149], v[198:201], v[62:65]
	v_mfma_f32_16x16x32_bf16 v[50:53], v[138:141], v[206:209], v[50:53]
	v_mfma_f32_16x16x32_bf16 v[46:49], v[146:149], v[206:209], v[46:49]
	v_mfma_f32_16x16x32_bf16 v[34:37], v[138:141], v[220:223], v[34:37]
	v_mfma_f32_16x16x32_bf16 v[30:33], v[146:149], v[220:223], v[30:33]
	v_mfma_f32_16x16x32_bf16 v[18:21], v[138:141], v[228:231], v[18:21]
	v_mfma_f32_16x16x32_bf16 v[14:17], v[146:149], v[228:231], v[14:17]
	v_mfma_f32_16x16x32_bf16 v[66:69], v[142:145], v[202:205], v[66:69]
	v_mfma_f32_16x16x32_bf16 v[62:65], v[178:181], v[202:205], v[62:65]
	v_mfma_f32_16x16x32_bf16 v[50:53], v[142:145], v[210:213], v[50:53]
	v_mfma_f32_16x16x32_bf16 v[46:49], v[178:181], v[210:213], v[46:49]
	v_mfma_f32_16x16x32_bf16 v[34:37], v[142:145], v[224:227], v[34:37]
	v_mfma_f32_16x16x32_bf16 v[30:33], v[178:181], v[224:227], v[30:33]
	v_mfma_f32_16x16x32_bf16 v[18:21], v[142:145], v[232:235], v[18:21]
	v_mfma_f32_16x16x32_bf16 v[14:17], v[178:181], v[232:235], v[14:17]
	v_mfma_f32_16x16x32_bf16 v[58:61], v[182:185], v[198:201], v[58:61]
	v_mfma_f32_16x16x32_bf16 v[54:57], v[190:193], v[198:201], v[54:57]
	v_mfma_f32_16x16x32_bf16 v[42:45], v[182:185], v[206:209], v[42:45]
	v_mfma_f32_16x16x32_bf16 v[38:41], v[190:193], v[206:209], v[38:41]
	v_mfma_f32_16x16x32_bf16 v[26:29], v[182:185], v[220:223], v[26:29]
	v_mfma_f32_16x16x32_bf16 v[22:25], v[190:193], v[220:223], v[22:25]
	v_mfma_f32_16x16x32_bf16 v[10:13], v[182:185], v[228:231], v[10:13]
	v_mfma_f32_16x16x32_bf16 v[6:9], v[190:193], v[228:231], v[6:9]
	v_mfma_f32_16x16x32_bf16 v[58:61], v[186:189], v[202:205], v[58:61]
	v_mfma_f32_16x16x32_bf16 v[54:57], v[194:197], v[202:205], v[54:57]
	v_mfma_f32_16x16x32_bf16 v[42:45], v[186:189], v[210:213], v[42:45]
	v_mfma_f32_16x16x32_bf16 v[38:41], v[194:197], v[210:213], v[38:41]
	v_mfma_f32_16x16x32_bf16 v[26:29], v[186:189], v[224:227], v[26:29]
	v_mfma_f32_16x16x32_bf16 v[22:25], v[194:197], v[224:227], v[22:25]
	v_mfma_f32_16x16x32_bf16 v[10:13], v[186:189], v[232:235], v[10:13]
	v_mfma_f32_16x16x32_bf16 v[6:9], v[194:197], v[232:235], v[6:9]
	s_setprio 0
	s_barrier
	s_add_i32 s11, 0, 0x18000
	s_add_i32 s31, 0, 0x1c000
	v_add_u32_e32 v178, s11, v216
	v_add_u32_e32 v194, s31, v216
	ds_read_b128 v[138:141], v178
	ds_read_b128 v[142:145], v178 offset:1024
	ds_read_b128 v[146:149], v178 offset:2048
	ds_read_b128 v[178:181], v178 offset:3072
	ds_read_b128 v[182:185], v194
	ds_read_b128 v[186:189], v194 offset:1024
	ds_read_b128 v[190:193], v194 offset:2048
	ds_read_b128 v[194:197], v194 offset:3072
	v_lshl_add_u64 v[214:215], v[214:215], 0, s[12:13]
	s_mov_b32 m0, s36
	v_lshl_add_u64 v[248:249], v[214:215], 0, v[154:155]
	ds_read_b128 v[198:201], v218 offset:32768
	ds_read_b128 v[202:205], v218 offset:33792
	ds_read_b128 v[206:209], v218 offset:34816
	ds_read_b128 v[210:213], v218 offset:35840
	ds_read_b128 v[220:223], v218 offset:36864
	ds_read_b128 v[224:227], v218 offset:37888
	ds_read_b128 v[228:231], v218 offset:38912
	ds_read_b128 v[232:235], v218 offset:39936
	global_load_lds_dwordx4 v[248:249], off
	s_mov_b32 m0, s37
	v_lshl_add_u64 v[214:215], v[214:215], 0, v[160:161]
	global_load_lds_dwordx4 v[214:215], off
	s_waitcnt vmcnt(8) lgkmcnt(0)
	s_setprio 1
	s_barrier
	v_mfma_f32_16x16x32_bf16 v[130:133], v[138:141], v[198:201], v[130:133]
	v_mfma_f32_16x16x32_bf16 v[126:129], v[146:149], v[198:201], v[126:129]
	v_mfma_f32_16x16x32_bf16 v[114:117], v[138:141], v[206:209], v[114:117]
	v_mfma_f32_16x16x32_bf16 v[110:113], v[146:149], v[206:209], v[110:113]
	v_mfma_f32_16x16x32_bf16 v[98:101], v[138:141], v[220:223], v[98:101]
	v_mfma_f32_16x16x32_bf16 v[94:97], v[146:149], v[220:223], v[94:97]
	v_mfma_f32_16x16x32_bf16 v[82:85], v[138:141], v[228:231], v[82:85]
	v_mfma_f32_16x16x32_bf16 v[78:81], v[146:149], v[228:231], v[78:81]
	v_mfma_f32_16x16x32_bf16 v[130:133], v[142:145], v[202:205], v[130:133]
	v_mfma_f32_16x16x32_bf16 v[126:129], v[178:181], v[202:205], v[126:129]
	v_mfma_f32_16x16x32_bf16 v[114:117], v[142:145], v[210:213], v[114:117]
	v_mfma_f32_16x16x32_bf16 v[110:113], v[178:181], v[210:213], v[110:113]
	v_mfma_f32_16x16x32_bf16 v[98:101], v[142:145], v[224:227], v[98:101]
	v_mfma_f32_16x16x32_bf16 v[94:97], v[178:181], v[224:227], v[94:97]
	v_mfma_f32_16x16x32_bf16 v[82:85], v[142:145], v[232:235], v[82:85]
	v_mfma_f32_16x16x32_bf16 v[78:81], v[178:181], v[232:235], v[78:81]
	v_mfma_f32_16x16x32_bf16 v[122:125], v[182:185], v[198:201], v[122:125]
	v_mfma_f32_16x16x32_bf16 v[118:121], v[190:193], v[198:201], v[118:121]
	v_mfma_f32_16x16x32_bf16 v[106:109], v[182:185], v[206:209], v[106:109]
	v_mfma_f32_16x16x32_bf16 v[102:105], v[190:193], v[206:209], v[102:105]
	v_mfma_f32_16x16x32_bf16 v[90:93], v[182:185], v[220:223], v[90:93]
	v_mfma_f32_16x16x32_bf16 v[86:89], v[190:193], v[220:223], v[86:89]
	v_mfma_f32_16x16x32_bf16 v[74:77], v[182:185], v[228:231], v[74:77]
	v_mfma_f32_16x16x32_bf16 v[70:73], v[190:193], v[228:231], v[70:73]
	v_mfma_f32_16x16x32_bf16 v[122:125], v[186:189], v[202:205], v[122:125]
	v_mfma_f32_16x16x32_bf16 v[118:121], v[194:197], v[202:205], v[118:121]
	v_mfma_f32_16x16x32_bf16 v[106:109], v[186:189], v[210:213], v[106:109]
	v_mfma_f32_16x16x32_bf16 v[102:105], v[194:197], v[210:213], v[102:105]
	v_mfma_f32_16x16x32_bf16 v[90:93], v[186:189], v[224:227], v[90:93]
	v_mfma_f32_16x16x32_bf16 v[86:89], v[194:197], v[224:227], v[86:89]
	v_mfma_f32_16x16x32_bf16 v[74:77], v[186:189], v[232:235], v[74:77]
	v_mfma_f32_16x16x32_bf16 v[70:73], v[194:197], v[232:235], v[70:73]
	s_setprio 0
	s_barrier
; #define PG8_STAGE(bufoff, gbase, voff) do { _Pragma("unroll") for (int _i = 0; _i < 2; ++_i) \
;         __builtin_amdgcn_global_load_lds((const unsigned*)((const char*)(gbase) + (voff)[_i]), (PG8_LAS unsigned*)(lds + (bufoff) + ldsw + _i * 8192), 16, 0, 0); } while (0)
; #define PG8_LDA(dst, b, h) do { _Pragma("unroll") for (int m = 0; m < 4; ++m) _Pragma("unroll") for (int k = 0; k < 2; ++k) dst[m][k] = *(const PG8_LAS bf16x8*)(lds + PG8_SA(b, h) + aoff + m * 2048 + k * 1024); } while (0)
; #define PG8_MMA(ai, bj, At, Bt) do { __builtin_amdgcn_s_setprio(1); _Pragma("unroll") for (int m = 0; m < 4; ++m) _Pragma("unroll") for (int n = 0; n < 2; ++n) _Pragma("unroll") for (int k = 0; k < 2; ++k) \
;         acc[ai][bj][m][n] = __builtin_amdgcn_mfma_f32_16x16x32_bf16(Bt[n][k], At[m][k], acc[ai][bj][m][n], 0, 0, 0); __builtin_amdgcn_s_setprio(0); } while (0)
; #define PG8_WAIT_V(n) asm volatile("s_waitcnt vmcnt(" #n ")" ::: "memory")
; #define PG8_WAIT_L(n) asm volatile("s_waitcnt lgkmcnt(" #n ")" ::: "memory")
; #define PG8_BAR __builtin_amdgcn_s_barrier()
; #define PG8_SCHED __builtin_amdgcn_sched_barrier(0)
; template <class Epi, class Sched, bool ALIGN_EPI = false, bool SP2 = false>
; __device__ __forceinline__ void gemm_phase(PG8_LAS unsigned char* lds, const Gemm g, const Sched& S, const Epi& E) {
;     ...
;         for (int t = 0; t < nt; t += 2) {
;             const bool last = (t == nt - 2);
;             const char* a1 = cA + (size_t)(t + 1) * kstep;
;             const char* a2 = last ? nA : cA + (size_t)(t + 2) * kstep; const char* b2 = last ? nB : cB + (size_t)(t + 2) * kstep;
;     ...
;             PG8_LDA(At, 1, 1); PG8_STAGE(PG8_SB(1, 0), b3, voffB); PG8_STAGE(PG8_SB(1, 1), b3 + hstep, voffB); PG8_STAGE(PG8_SA(1, 0), a3, voffA);
;             PG8_WAIT_V(8); PG8_WAIT_L(0); PG8_BAR; PG8_MMA(1, 0, At, B0); PG8_MMA(1, 1, At, B1); PG8_BAR; PG8_SCHED;
	s_add_i32 s11, s11, s29
	s_add_i32 m0, s11, 0xffffff80
	ds_read_b128 v[198:201], v218 offset:49152
	ds_read_b128 v[202:205], v218 offset:50176
	ds_read_b128 v[206:209], v218 offset:51200
	ds_read_b128 v[210:213], v218 offset:52224
	global_load_lds_dwordx4 v[238:239], off offset:128
	s_add_i32 m0, s11, 0x1f80
	s_add_i32 s11, s31, s29
	global_load_lds_dwordx4 v[240:241], off offset:128
	s_add_i32 m0, s11, 0xffffff80
	ds_read_b128 v[232:235], v218 offset:56320
	global_load_lds_dwordx4 v[242:243], off offset:128
	s_add_i32 m0, s11, 0x1f80
	ds_read_b128 v[228:231], v218 offset:55296
	global_load_lds_dwordx4 v[236:237], off offset:128
	s_add_i32 m0, s41, 0xffffff80
	ds_read_b128 v[224:227], v218 offset:54272
	global_load_lds_dwordx4 v[244:245], off offset:128
	s_add_i32 m0, s46, 0xffffff80
	ds_read_b128 v[220:223], v218 offset:53248
	global_load_lds_dwordx4 v[246:247], off offset:128
	s_waitcnt vmcnt(8) lgkmcnt(0)
	s_setprio 1
	s_barrier
	v_mfma_f32_16x16x32_bf16 v[66:69], v[138:141], v[198:201], v[66:69]
	v_mfma_f32_16x16x32_bf16 v[62:65], v[146:149], v[198:201], v[62:65]
	v_mfma_f32_16x16x32_bf16 v[50:53], v[138:141], v[206:209], v[50:53]
	v_mfma_f32_16x16x32_bf16 v[46:49], v[146:149], v[206:209], v[46:49]
	v_mfma_f32_16x16x32_bf16 v[34:37], v[138:141], v[220:223], v[34:37]
	v_mfma_f32_16x16x32_bf16 v[30:33], v[146:149], v[220:223], v[30:33]
	v_mfma_f32_16x16x32_bf16 v[18:21], v[138:141], v[228:231], v[18:21]
	v_mfma_f32_16x16x32_bf16 v[14:17], v[146:149], v[228:231], v[14:17]
	v_mfma_f32_16x16x32_bf16 v[66:69], v[142:145], v[202:205], v[66:69]
	v_mfma_f32_16x16x32_bf16 v[62:65], v[178:181], v[202:205], v[62:65]
	v_mfma_f32_16x16x32_bf16 v[50:53], v[142:145], v[210:213], v[50:53]
	v_mfma_f32_16x16x32_bf16 v[46:49], v[178:181], v[210:213], v[46:49]
	v_mfma_f32_16x16x32_bf16 v[34:37], v[142:145], v[224:227], v[34:37]
	v_mfma_f32_16x16x32_bf16 v[30:33], v[178:181], v[224:227], v[30:33]
	v_mfma_f32_16x16x32_bf16 v[18:21], v[142:145], v[232:235], v[18:21]
	v_mfma_f32_16x16x32_bf16 v[14:17], v[178:181], v[232:235], v[14:17]
	v_mfma_f32_16x16x32_bf16 v[58:61], v[182:185], v[198:201], v[58:61]
	v_mfma_f32_16x16x32_bf16 v[54:57], v[190:193], v[198:201], v[54:57]
	v_mfma_f32_16x16x32_bf16 v[42:45], v[182:185], v[206:209], v[42:45]
	v_mfma_f32_16x16x32_bf16 v[38:41], v[190:193], v[206:209], v[38:41]
	v_mfma_f32_16x16x32_bf16 v[26:29], v[182:185], v[220:223], v[26:29]
	v_mfma_f32_16x16x32_bf16 v[22:25], v[190:193], v[220:223], v[22:25]
	v_mfma_f32_16x16x32_bf16 v[10:13], v[182:185], v[228:231], v[10:13]
	v_mfma_f32_16x16x32_bf16 v[6:9], v[190:193], v[228:231], v[6:9]
	v_mfma_f32_16x16x32_bf16 v[58:61], v[186:189], v[202:205], v[58:61]
	v_mfma_f32_16x16x32_bf16 v[54:57], v[194:197], v[202:205], v[54:57]
	v_mfma_f32_16x16x32_bf16 v[42:45], v[186:189], v[210:213], v[42:45]
	v_mfma_f32_16x16x32_bf16 v[38:41], v[194:197], v[210:213], v[38:41]
	v_mfma_f32_16x16x32_bf16 v[26:29], v[186:189], v[224:227], v[26:29]
	v_mfma_f32_16x16x32_bf16 v[22:25], v[194:197], v[224:227], v[22:25]
	v_mfma_f32_16x16x32_bf16 v[10:13], v[186:189], v[232:235], v[10:13]
	v_mfma_f32_16x16x32_bf16 v[6:9], v[194:197], v[232:235], v[6:9]
	v_lshl_add_u64 v[134:135], v[134:135], 0, s[26:27]
	v_lshl_add_u64 v[136:137], v[136:137], 0, s[26:27]
	s_cmp_ge_i32 s10, s48
	s_cbranch_scc1 .Lrot_exit_8
	s_cmp_eq_u32 s49, s10
	v_lshl_add_u64 v[198:199], v[136:137], 0, s[20:21]
	s_cselect_b64 vcc, -1, 0
	s_add_i32 s10, s10, 2
	v_cndmask_b32_e32 v215, v199, v175, vcc
	v_cndmask_b32_e32 v214, v198, v174, vcc
	v_cndmask_b32_e32 v237, v135, v177, vcc
	v_cndmask_b32_e32 v236, v134, v176, vcc
	s_setprio 0
	s_barrier
	s_branch .LBB0_1192
.Lrot_exit_8:
	s_setprio 0
	s_barrier
.LBB0_1193:
	s_and_b64 vcc, exec, s[24:25]
	s_cbranch_vccz .LBB0_1195
	s_barrier

; #define PG8_MMA(ai, bj, At, Bt) do { __builtin_amdgcn_s_setprio(1); _Pragma("unroll") for (int m = 0; m < 4; ++m) _Pragma("unroll") for (int n = 0; n < 2; ++n) _Pragma("unroll") for (int k = 0; k < 2; ++k) \
;         acc[ai][bj][m][n] = __builtin_amdgcn_mfma_f32_16x16x32_bf16(Bt[n][k], At[m][k], acc[ai][bj][m][n], 0, 0, 0); __builtin_amdgcn_s_setprio(0); } while (0)
; #define PG8_WAIT_V(n) asm volatile("s_waitcnt vmcnt(" #n ")" ::: "memory")
; #define PG8_WAIT_L(n) asm volatile("s_waitcnt lgkmcnt(" #n ")" ::: "memory")
; #define PG8_BAR __builtin_amdgcn_s_barrier()
; #define PG8_SCHED __builtin_amdgcn_sched_barrier(0)
; template <class Epi, class Sched, bool ALIGN_EPI = false, bool SP2 = false>
; __device__ __forceinline__ void gemm_phase(PG8_LAS unsigned char* lds, const Gemm g, const Sched& S, const Epi& E) {
;     ...
;             PG8_WAIT_V(8); PG8_WAIT_L(0); PG8_BAR; PG8_MMA(1, 0, At, B0); PG8_MMA(1, 1, At, B1); PG8_BAR; PG8_SCHED;
;     ...
;         if constexpr (ALIGN_EPI) { if (wr == 0) PG8_BAR; }
.Lrot_exit_7:
	s_setprio 0
	s_barrier
.LBB0_1274:
	s_and_b64 vcc, exec, s[24:25]
	s_cbranch_vccz .LBB0_1276
	s_barrier

; #define PG8_STAGE(bufoff, gbase, voff) do { _Pragma("unroll") for (int _i = 0; _i < 2; ++_i) \
;         __builtin_amdgcn_global_load_lds((const unsigned*)((const char*)(gbase) + (voff)[_i]), (PG8_LAS unsigned*)(lds + (bufoff) + ldsw + _i * 8192), 16, 0, 0); } while (0)
; #define PG8_LDA(dst, b, h) do { _Pragma("unroll") for (int m = 0; m < 4; ++m) _Pragma("unroll") for (int k = 0; k < 2; ++k) dst[m][k] = *(const PG8_LAS bf16x8*)(lds + PG8_SA(b, h) + aoff + m * 2048 + k * 1024); } while (0)
; #define PG8_LDB(dst, b, h) do { _Pragma("unroll") for (int n = 0; n < 2; ++n) _Pragma("unroll") for (int k = 0; k < 2; ++k) dst[n][k] = *(const PG8_LAS bf16x8*)(lds + PG8_SB(b, h) + boff + n * 2048 + k * 1024); } while (0)
; #define PG8_MMA(ai, bj, At, Bt) do { __builtin_amdgcn_s_setprio(1); _Pragma("unroll") for (int m = 0; m < 4; ++m) _Pragma("unroll") for (int n = 0; n < 2; ++n) _Pragma("unroll") for (int k = 0; k < 2; ++k) \
;         acc[ai][bj][m][n] = __builtin_amdgcn_mfma_f32_16x16x32_bf16(Bt[n][k], At[m][k], acc[ai][bj][m][n], 0, 0, 0); __builtin_amdgcn_s_setprio(0); } while (0)
; #define PG8_WAIT_V(n) asm volatile("s_waitcnt vmcnt(" #n ")" ::: "memory")
; #define PG8_BAR __builtin_amdgcn_s_barrier()
; template <class Epi, class Sched, bool ALIGN_EPI = false, bool SP2 = false>
; __device__ __forceinline__ void gemm_phase(PG8_LAS unsigned char* lds, const Gemm g, const Sched& S, const Epi& E) {
;     ...
;         for (int t = 0; t < nt; t += 2) {
;             const bool last = (t == nt - 2);
;             const char* a1 = cA + (size_t)(t + 1) * kstep;
;             const char* a2 = last ? nA : cA + (size_t)(t + 2) * kstep; const char* b2 = last ? nB : cB + (size_t)(t + 2) * kstep;
;             const char* a3 = a2 + kstep; const char* b3 = b2 + kstep;
;             if (last && has_next) S.a_ready(nxt);
;             if constexpr (SP2) {
;             PG8_LDB(B0, 0, 0); PG8_LDB(B1, 0, 1); PG8_SCHED; PG8_LDA(At, 0, 0); PG8_STAGE(PG8_SA(1, 1), a1 + hstep, voffA);
;             PG8_WAIT_V(8); PG8_WAIT_L(0); PG8_BAR; PG8_MMA(0, 0, At, B0); PG8_MMA(0, 1, At, B1); PG8_BAR; PG8_SCHED;
;             PG8_LDA(At, 0, 1); PG8_STAGE(PG8_SB(0, 0), b2, voffB); PG8_STAGE(PG8_SB(0, 1), b2 + hstep, voffB); PG8_STAGE(PG8_SA(0, 0), a2, voffA);
;             PG8_WAIT_V(8); PG8_WAIT_L(0); PG8_BAR; PG8_MMA(1, 0, At, B0); PG8_MMA(1, 1, At, B1); PG8_BAR; PG8_SCHED;
.LBB0_1340:
	v_add_u32_e32 v148, s55, v201
	v_add_u32_e32 v190, s56, v201
	ds_read_b128 v[136:139], v148
	ds_read_b128 v[140:143], v148 offset:1024
	ds_read_b128 v[144:147], v148 offset:2048
	ds_read_b128 v[148:151], v148 offset:3072
	ds_read_b128 v[152:155], v190
	ds_read_b128 v[182:185], v190 offset:1024
	ds_read_b128 v[186:189], v190 offset:2048
	ds_read_b128 v[190:193], v190 offset:3072
	s_mov_b32 m0, s57
	v_lshl_add_u64 v[236:237], v[134:135], 0, v[174:175]
	ds_read_b128 v[194:197], v203
	ds_read_b128 v[206:209], v203 offset:1024
	ds_read_b128 v[210:213], v203 offset:2048
	ds_read_b128 v[216:219], v203 offset:3072
	ds_read_b128 v[220:223], v203 offset:4096
	ds_read_b128 v[224:227], v203 offset:5120
	ds_read_b128 v[228:231], v203 offset:6144
	ds_read_b128 v[232:235], v203 offset:7168
	global_load_lds_dwordx4 v[236:237], off
	s_mov_b32 m0, s58
	v_lshl_add_u64 v[236:237], v[134:135], 0, v[172:173]
	global_load_lds_dwordx4 v[236:237], off
	s_waitcnt vmcnt(8) lgkmcnt(0)
	s_setprio 1
	s_barrier
	v_mfma_f32_16x16x32_bf16 v[124:127], v[136:139], v[194:197], v[124:127]
	v_mfma_f32_16x16x32_bf16 v[128:131], v[144:147], v[194:197], v[128:131]
	v_mfma_f32_16x16x32_bf16 v[112:115], v[136:139], v[210:213], v[112:115]
	v_mfma_f32_16x16x32_bf16 v[108:111], v[144:147], v[210:213], v[108:111]
	v_mfma_f32_16x16x32_bf16 v[96:99], v[136:139], v[220:223], v[96:99]
	v_mfma_f32_16x16x32_bf16 v[92:95], v[144:147], v[220:223], v[92:95]
	v_mfma_f32_16x16x32_bf16 v[80:83], v[136:139], v[228:231], v[80:83]
	v_mfma_f32_16x16x32_bf16 v[76:79], v[144:147], v[228:231], v[76:79]
	v_mfma_f32_16x16x32_bf16 v[124:127], v[140:143], v[206:209], v[124:127]
	v_mfma_f32_16x16x32_bf16 v[128:131], v[148:151], v[206:209], v[128:131]
	v_mfma_f32_16x16x32_bf16 v[112:115], v[140:143], v[216:219], v[112:115]
	v_mfma_f32_16x16x32_bf16 v[108:111], v[148:151], v[216:219], v[108:111]
	v_mfma_f32_16x16x32_bf16 v[96:99], v[140:143], v[224:227], v[96:99]
	v_mfma_f32_16x16x32_bf16 v[92:95], v[148:151], v[224:227], v[92:95]
	v_mfma_f32_16x16x32_bf16 v[80:83], v[140:143], v[232:235], v[80:83]
	v_mfma_f32_16x16x32_bf16 v[76:79], v[148:151], v[232:235], v[76:79]
	v_mfma_f32_16x16x32_bf16 v[120:123], v[152:155], v[194:197], v[120:123]
	v_mfma_f32_16x16x32_bf16 v[116:119], v[186:189], v[194:197], v[116:119]
	v_mfma_f32_16x16x32_bf16 v[104:107], v[152:155], v[210:213], v[104:107]
	v_mfma_f32_16x16x32_bf16 v[100:103], v[186:189], v[210:213], v[100:103]
	v_mfma_f32_16x16x32_bf16 v[88:91], v[152:155], v[220:223], v[88:91]
	v_mfma_f32_16x16x32_bf16 v[84:87], v[186:189], v[220:223], v[84:87]
	v_mfma_f32_16x16x32_bf16 v[72:75], v[152:155], v[228:231], v[72:75]
	v_mfma_f32_16x16x32_bf16 v[68:71], v[186:189], v[228:231], v[68:71]
	v_mfma_f32_16x16x32_bf16 v[120:123], v[182:185], v[206:209], v[120:123]
	v_mfma_f32_16x16x32_bf16 v[116:119], v[190:193], v[206:209], v[116:119]
	v_mfma_f32_16x16x32_bf16 v[104:107], v[182:185], v[216:219], v[104:107]
	v_mfma_f32_16x16x32_bf16 v[100:103], v[190:193], v[216:219], v[100:103]
	v_mfma_f32_16x16x32_bf16 v[88:91], v[182:185], v[224:227], v[88:91]
	v_mfma_f32_16x16x32_bf16 v[84:87], v[190:193], v[224:227], v[84:87]
	v_mfma_f32_16x16x32_bf16 v[72:75], v[182:185], v[232:235], v[72:75]
	v_mfma_f32_16x16x32_bf16 v[68:71], v[190:193], v[232:235], v[68:71]
	s_setprio 0
	s_barrier
	s_mov_b32 m0, s59
	v_lshl_add_u64 v[236:237], v[214:215], 0, v[166:167]
	ds_read_b128 v[194:197], v203 offset:16384
	ds_read_b128 v[206:209], v203 offset:17408
	ds_read_b128 v[210:213], v203 offset:18432
	ds_read_b128 v[216:219], v203 offset:19456
	ds_read_b128 v[220:223], v203 offset:20480
	ds_read_b128 v[224:227], v203 offset:21504
	ds_read_b128 v[228:231], v203 offset:22528
	ds_read_b128 v[232:235], v203 offset:23552
	global_load_lds_dwordx4 v[236:237], off
	v_lshl_add_u64 v[238:239], v[214:215], 0, v[170:171]
	s_mov_b32 m0, s60
	v_lshl_add_u64 v[214:215], v[214:215], 0, s[14:15]
	s_add_i32 s13, s56, s30
	global_load_lds_dwordx4 v[238:239], off
	v_lshl_add_u64 v[240:241], v[214:215], 0, v[166:167]
	s_mov_b32 m0, s13
	v_lshl_add_u64 v[214:215], v[214:215], 0, v[170:171]
	global_load_lds_dwordx4 v[240:241], off
	s_add_i32 m0, s13, 0x2000
	v_lshl_add_u64 v[242:243], v[198:199], 0, v[164:165]
	global_load_lds_dwordx4 v[214:215], off
	s_mov_b32 m0, s31
	v_lshl_add_u64 v[244:245], v[198:199], 0, v[168:169]
	global_load_lds_dwordx4 v[242:243], off
	s_mov_b32 m0, s34
	s_nop 0
	global_load_lds_dwordx4 v[244:245], off
	s_waitcnt vmcnt(8) lgkmcnt(0)
	s_setprio 1
	s_barrier
	v_mfma_f32_16x16x32_bf16 v[64:67], v[136:139], v[194:197], v[64:67]
	v_mfma_f32_16x16x32_bf16 v[60:63], v[144:147], v[194:197], v[60:63]
	v_mfma_f32_16x16x32_bf16 v[48:51], v[136:139], v[210:213], v[48:51]
	v_mfma_f32_16x16x32_bf16 v[44:47], v[144:147], v[210:213], v[44:47]
	v_mfma_f32_16x16x32_bf16 v[32:35], v[136:139], v[220:223], v[32:35]
	v_mfma_f32_16x16x32_bf16 v[28:31], v[144:147], v[220:223], v[28:31]
	v_mfma_f32_16x16x32_bf16 v[16:19], v[136:139], v[228:231], v[16:19]
	v_mfma_f32_16x16x32_bf16 v[12:15], v[144:147], v[228:231], v[12:15]
	v_mfma_f32_16x16x32_bf16 v[64:67], v[140:143], v[206:209], v[64:67]
	v_mfma_f32_16x16x32_bf16 v[60:63], v[148:151], v[206:209], v[60:63]
	v_mfma_f32_16x16x32_bf16 v[48:51], v[140:143], v[216:219], v[48:51]
	v_mfma_f32_16x16x32_bf16 v[44:47], v[148:151], v[216:219], v[44:47]
	v_mfma_f32_16x16x32_bf16 v[32:35], v[140:143], v[224:227], v[32:35]
	v_mfma_f32_16x16x32_bf16 v[28:31], v[148:151], v[224:227], v[28:31]
	v_mfma_f32_16x16x32_bf16 v[16:19], v[140:143], v[232:235], v[16:19]
	v_mfma_f32_16x16x32_bf16 v[12:15], v[148:151], v[232:235], v[12:15]
	v_mfma_f32_16x16x32_bf16 v[56:59], v[152:155], v[194:197], v[56:59]
	v_mfma_f32_16x16x32_bf16 v[52:55], v[186:189], v[194:197], v[52:55]
	v_mfma_f32_16x16x32_bf16 v[40:43], v[152:155], v[210:213], v[40:43]
	v_mfma_f32_16x16x32_bf16 v[36:39], v[186:189], v[210:213], v[36:39]
	v_mfma_f32_16x16x32_bf16 v[24:27], v[152:155], v[220:223], v[24:27]
	v_mfma_f32_16x16x32_bf16 v[20:23], v[186:189], v[220:223], v[20:23]
	v_mfma_f32_16x16x32_bf16 v[8:11], v[152:155], v[228:231], v[8:11]
	v_mfma_f32_16x16x32_bf16 v[4:7], v[186:189], v[228:231], v[4:7]
	v_mfma_f32_16x16x32_bf16 v[56:59], v[182:185], v[206:209], v[56:59]
	v_mfma_f32_16x16x32_bf16 v[52:55], v[190:193], v[206:209], v[52:55]
	v_mfma_f32_16x16x32_bf16 v[40:43], v[182:185], v[216:219], v[40:43]
	v_mfma_f32_16x16x32_bf16 v[36:39], v[190:193], v[216:219], v[36:39]
	v_mfma_f32_16x16x32_bf16 v[24:27], v[182:185], v[224:227], v[24:27]
	v_mfma_f32_16x16x32_bf16 v[20:23], v[190:193], v[224:227], v[20:23]
	v_mfma_f32_16x16x32_bf16 v[8:11], v[182:185], v[232:235], v[8:11]
	v_mfma_f32_16x16x32_bf16 v[4:7], v[190:193], v[232:235], v[4:7]
	s_setprio 0
	s_barrier
; #define PG8_STAGE(bufoff, gbase, voff) do { _Pragma("unroll") for (int _i = 0; _i < 2; ++_i) \
;         __builtin_amdgcn_global_load_lds((const unsigned*)((const char*)(gbase) + (voff)[_i]), (PG8_LAS unsigned*)(lds + (bufoff) + ldsw + _i * 8192), 16, 0, 0); } while (0)
; #define PG8_LDA(dst, b, h) do { _Pragma("unroll") for (int m = 0; m < 4; ++m) _Pragma("unroll") for (int k = 0; k < 2; ++k) dst[m][k] = *(const PG8_LAS bf16x8*)(lds + PG8_SA(b, h) + aoff + m * 2048 + k * 1024); } while (0)
; #define PG8_LDB(dst, b, h) do { _Pragma("unroll") for (int n = 0; n < 2; ++n) _Pragma("unroll") for (int k = 0; k < 2; ++k) dst[n][k] = *(const PG8_LAS bf16x8*)(lds + PG8_SB(b, h) + boff + n * 2048 + k * 1024); } while (0)
; #define PG8_MMA(ai, bj, At, Bt) do { __builtin_amdgcn_s_setprio(1); _Pragma("unroll") for (int m = 0; m < 4; ++m) _Pragma("unroll") for (int n = 0; n < 2; ++n) _Pragma("unroll") for (int k = 0; k < 2; ++k) \
;         acc[ai][bj][m][n] = __builtin_amdgcn_mfma_f32_16x16x32_bf16(Bt[n][k], At[m][k], acc[ai][bj][m][n], 0, 0, 0); __builtin_amdgcn_s_setprio(0); } while (0)
; #define PG8_WAIT_V(n) asm volatile("s_waitcnt vmcnt(" #n ")" ::: "memory")
; #define PG8_WAIT_L(n) asm volatile("s_waitcnt lgkmcnt(" #n ")" ::: "memory")
; #define PG8_BAR __builtin_amdgcn_s_barrier()
; #define PG8_SCHED __builtin_amdgcn_sched_barrier(0)
; template <class Epi, class Sched, bool ALIGN_EPI = false, bool SP2 = false>
; __device__ __forceinline__ void gemm_phase(PG8_LAS unsigned char* lds, const Gemm g, const Sched& S, const Epi& E) {
;     ...
;             PG8_LDB(B0, 1, 0); PG8_LDB(B1, 1, 1); PG8_SCHED; PG8_LDA(At, 1, 0); PG8_STAGE(PG8_SA(0, 1), a2 + hstep, voffA);
;             PG8_WAIT_V(8); PG8_WAIT_L(0); PG8_BAR; PG8_MMA(0, 0, At, B0); PG8_MMA(0, 1, At, B1); PG8_BAR; PG8_SCHED;
	s_add_i32 s13, 0, 0x18000
	s_add_i32 s29, 0, 0x1c000
	v_add_u32_e32 v148, s13, v201
	v_add_u32_e32 v190, s29, v201
	ds_read_b128 v[136:139], v148
	ds_read_b128 v[140:143], v148 offset:1024
	ds_read_b128 v[144:147], v148 offset:2048
	ds_read_b128 v[148:151], v148 offset:3072
	ds_read_b128 v[152:155], v190
	ds_read_b128 v[182:185], v190 offset:1024
	ds_read_b128 v[186:189], v190 offset:2048
	ds_read_b128 v[190:193], v190 offset:3072
	v_lshl_add_u64 v[198:199], v[198:199], 0, s[14:15]
	s_mov_b32 m0, s35
	v_lshl_add_u64 v[246:247], v[198:199], 0, v[164:165]
	ds_read_b128 v[194:197], v203 offset:32768
	ds_read_b128 v[206:209], v203 offset:33792
	ds_read_b128 v[210:213], v203 offset:34816
	ds_read_b128 v[216:219], v203 offset:35840
	ds_read_b128 v[220:223], v203 offset:36864
	ds_read_b128 v[224:227], v203 offset:37888
	ds_read_b128 v[228:231], v203 offset:38912
	ds_read_b128 v[232:235], v203 offset:39936
	global_load_lds_dwordx4 v[246:247], off
	s_mov_b32 m0, s36
	v_lshl_add_u64 v[198:199], v[198:199], 0, v[168:169]
	global_load_lds_dwordx4 v[198:199], off
	s_waitcnt vmcnt(8) lgkmcnt(0)
	s_setprio 1
	s_barrier
	v_mfma_f32_16x16x32_bf16 v[124:127], v[136:139], v[194:197], v[124:127]
	v_mfma_f32_16x16x32_bf16 v[128:131], v[144:147], v[194:197], v[128:131]
	v_mfma_f32_16x16x32_bf16 v[112:115], v[136:139], v[210:213], v[112:115]
	v_mfma_f32_16x16x32_bf16 v[108:111], v[144:147], v[210:213], v[108:111]
	v_mfma_f32_16x16x32_bf16 v[96:99], v[136:139], v[220:223], v[96:99]
	v_mfma_f32_16x16x32_bf16 v[92:95], v[144:147], v[220:223], v[92:95]
	v_mfma_f32_16x16x32_bf16 v[80:83], v[136:139], v[228:231], v[80:83]
	v_mfma_f32_16x16x32_bf16 v[76:79], v[144:147], v[228:231], v[76:79]
	v_mfma_f32_16x16x32_bf16 v[124:127], v[140:143], v[206:209], v[124:127]
	v_mfma_f32_16x16x32_bf16 v[128:131], v[148:151], v[206:209], v[128:131]
	v_mfma_f32_16x16x32_bf16 v[112:115], v[140:143], v[216:219], v[112:115]
	v_mfma_f32_16x16x32_bf16 v[108:111], v[148:151], v[216:219], v[108:111]
	v_mfma_f32_16x16x32_bf16 v[96:99], v[140:143], v[224:227], v[96:99]
	v_mfma_f32_16x16x32_bf16 v[92:95], v[148:151], v[224:227], v[92:95]
	v_mfma_f32_16x16x32_bf16 v[80:83], v[140:143], v[232:235], v[80:83]
	v_mfma_f32_16x16x32_bf16 v[76:79], v[148:151], v[232:235], v[76:79]
	v_mfma_f32_16x16x32_bf16 v[120:123], v[152:155], v[194:197], v[120:123]
	v_mfma_f32_16x16x32_bf16 v[116:119], v[186:189], v[194:197], v[116:119]
	v_mfma_f32_16x16x32_bf16 v[104:107], v[152:155], v[210:213], v[104:107]
	v_mfma_f32_16x16x32_bf16 v[100:103], v[186:189], v[210:213], v[100:103]
	v_mfma_f32_16x16x32_bf16 v[88:91], v[152:155], v[220:223], v[88:91]
	v_mfma_f32_16x16x32_bf16 v[84:87], v[186:189], v[220:223], v[84:87]
	v_mfma_f32_16x16x32_bf16 v[72:75], v[152:155], v[228:231], v[72:75]
	v_mfma_f32_16x16x32_bf16 v[68:71], v[186:189], v[228:231], v[68:71]
	v_mfma_f32_16x16x32_bf16 v[120:123], v[182:185], v[206:209], v[120:123]
	v_mfma_f32_16x16x32_bf16 v[116:119], v[190:193], v[206:209], v[116:119]
	v_mfma_f32_16x16x32_bf16 v[104:107], v[182:185], v[216:219], v[104:107]
	v_mfma_f32_16x16x32_bf16 v[100:103], v[190:193], v[216:219], v[100:103]
	v_mfma_f32_16x16x32_bf16 v[88:91], v[182:185], v[224:227], v[88:91]
	v_mfma_f32_16x16x32_bf16 v[84:87], v[190:193], v[224:227], v[84:87]
	v_mfma_f32_16x16x32_bf16 v[72:75], v[182:185], v[232:235], v[72:75]
	v_mfma_f32_16x16x32_bf16 v[68:71], v[190:193], v[232:235], v[68:71]
	s_setprio 0
	s_barrier
; #define PG8_STAGE(bufoff, gbase, voff) do { _Pragma("unroll") for (int _i = 0; _i < 2; ++_i) \
;         __builtin_amdgcn_global_load_lds((const unsigned*)((const char*)(gbase) + (voff)[_i]), (PG8_LAS unsigned*)(lds + (bufoff) + ldsw + _i * 8192), 16, 0, 0); } while (0)
; #define PG8_LDA(dst, b, h) do { _Pragma("unroll") for (int m = 0; m < 4; ++m) _Pragma("unroll") for (int k = 0; k < 2; ++k) dst[m][k] = *(const PG8_LAS bf16x8*)(lds + PG8_SA(b, h) + aoff + m * 2048 + k * 1024); } while (0)
; #define PG8_MMA(ai, bj, At, Bt) do { __builtin_amdgcn_s_setprio(1); _Pragma("unroll") for (int m = 0; m < 4; ++m) _Pragma("unroll") for (int n = 0; n < 2; ++n) _Pragma("unroll") for (int k = 0; k < 2; ++k) \
;         acc[ai][bj][m][n] = __builtin_amdgcn_mfma_f32_16x16x32_bf16(Bt[n][k], At[m][k], acc[ai][bj][m][n], 0, 0, 0); __builtin_amdgcn_s_setprio(0); } while (0)
; #define PG8_WAIT_V(n) asm volatile("s_waitcnt vmcnt(" #n ")" ::: "memory")
; #define PG8_WAIT_L(n) asm volatile("s_waitcnt lgkmcnt(" #n ")" ::: "memory")
; #define PG8_BAR __builtin_amdgcn_s_barrier()
; #define PG8_SCHED __builtin_amdgcn_sched_barrier(0)
; template <class Epi, class Sched, bool ALIGN_EPI = false, bool SP2 = false>
; __device__ __forceinline__ void gemm_phase(PG8_LAS unsigned char* lds, const Gemm g, const Sched& S, const Epi& E) {
;     ...
;         for (int t = 0; t < nt; t += 2) {
;             const bool last = (t == nt - 2);
;             const char* a1 = cA + (size_t)(t + 1) * kstep;
;             const char* a2 = last ? nA : cA + (size_t)(t + 2) * kstep; const char* b2 = last ? nB : cB + (size_t)(t + 2) * kstep;
;     ...
;             PG8_LDA(At, 1, 1); PG8_STAGE(PG8_SB(1, 0), b3, voffB); PG8_STAGE(PG8_SB(1, 1), b3 + hstep, voffB); PG8_STAGE(PG8_SA(1, 0), a3, voffA);
;             PG8_WAIT_V(8); PG8_WAIT_L(0); PG8_BAR; PG8_MMA(1, 0, At, B0); PG8_MMA(1, 1, At, B1); PG8_BAR; PG8_SCHED;
	s_add_i32 s13, s13, s30
	s_add_i32 m0, s13, 0xffffff80
	ds_read_b128 v[194:197], v203 offset:49152
	ds_read_b128 v[206:209], v203 offset:50176
	ds_read_b128 v[210:213], v203 offset:51200
	ds_read_b128 v[216:219], v203 offset:52224
	global_load_lds_dwordx4 v[236:237], off offset:128
	s_add_i32 m0, s13, 0x1f80
	s_add_i32 s13, s29, s30
	global_load_lds_dwordx4 v[238:239], off offset:128
	s_add_i32 m0, s13, 0xffffff80
	ds_read_b128 v[232:235], v203 offset:56320
	global_load_lds_dwordx4 v[240:241], off offset:128
	s_add_i32 m0, s13, 0x1f80
	ds_read_b128 v[228:231], v203 offset:55296
	global_load_lds_dwordx4 v[214:215], off offset:128
	s_add_i32 m0, s37, 0xffffff80
	ds_read_b128 v[224:227], v203 offset:54272
	global_load_lds_dwordx4 v[242:243], off offset:128
	s_add_i32 m0, s41, 0xffffff80
	ds_read_b128 v[220:223], v203 offset:53248
	global_load_lds_dwordx4 v[244:245], off offset:128
	s_waitcnt vmcnt(8) lgkmcnt(0)
	s_setprio 1
	s_barrier
	v_mfma_f32_16x16x32_bf16 v[64:67], v[136:139], v[194:197], v[64:67]
	v_mfma_f32_16x16x32_bf16 v[60:63], v[144:147], v[194:197], v[60:63]
	v_mfma_f32_16x16x32_bf16 v[48:51], v[136:139], v[210:213], v[48:51]
	v_mfma_f32_16x16x32_bf16 v[44:47], v[144:147], v[210:213], v[44:47]
	v_mfma_f32_16x16x32_bf16 v[32:35], v[136:139], v[220:223], v[32:35]
	v_mfma_f32_16x16x32_bf16 v[28:31], v[144:147], v[220:223], v[28:31]
	v_mfma_f32_16x16x32_bf16 v[16:19], v[136:139], v[228:231], v[16:19]
	v_mfma_f32_16x16x32_bf16 v[12:15], v[144:147], v[228:231], v[12:15]
	v_mfma_f32_16x16x32_bf16 v[64:67], v[140:143], v[206:209], v[64:67]
	v_mfma_f32_16x16x32_bf16 v[60:63], v[148:151], v[206:209], v[60:63]
	v_mfma_f32_16x16x32_bf16 v[48:51], v[140:143], v[216:219], v[48:51]
	v_mfma_f32_16x16x32_bf16 v[44:47], v[148:151], v[216:219], v[44:47]
	v_mfma_f32_16x16x32_bf16 v[32:35], v[140:143], v[224:227], v[32:35]
	v_mfma_f32_16x16x32_bf16 v[28:31], v[148:151], v[224:227], v[28:31]
	v_mfma_f32_16x16x32_bf16 v[16:19], v[140:143], v[232:235], v[16:19]
	v_mfma_f32_16x16x32_bf16 v[12:15], v[148:151], v[232:235], v[12:15]
	v_mfma_f32_16x16x32_bf16 v[56:59], v[152:155], v[194:197], v[56:59]
	v_mfma_f32_16x16x32_bf16 v[52:55], v[186:189], v[194:197], v[52:55]
	v_mfma_f32_16x16x32_bf16 v[40:43], v[152:155], v[210:213], v[40:43]
	v_mfma_f32_16x16x32_bf16 v[36:39], v[186:189], v[210:213], v[36:39]
	v_mfma_f32_16x16x32_bf16 v[24:27], v[152:155], v[220:223], v[24:27]
	v_mfma_f32_16x16x32_bf16 v[20:23], v[186:189], v[220:223], v[20:23]
	v_mfma_f32_16x16x32_bf16 v[8:11], v[152:155], v[228:231], v[8:11]
	v_mfma_f32_16x16x32_bf16 v[4:7], v[186:189], v[228:231], v[4:7]
	v_mfma_f32_16x16x32_bf16 v[56:59], v[182:185], v[206:209], v[56:59]
	v_mfma_f32_16x16x32_bf16 v[52:55], v[190:193], v[206:209], v[52:55]
	v_mfma_f32_16x16x32_bf16 v[40:43], v[182:185], v[216:219], v[40:43]
	v_mfma_f32_16x16x32_bf16 v[36:39], v[190:193], v[216:219], v[36:39]
	v_mfma_f32_16x16x32_bf16 v[24:27], v[182:185], v[224:227], v[24:27]
	v_mfma_f32_16x16x32_bf16 v[20:23], v[190:193], v[224:227], v[20:23]
	v_mfma_f32_16x16x32_bf16 v[8:11], v[182:185], v[232:235], v[8:11]
	v_mfma_f32_16x16x32_bf16 v[4:7], v[190:193], v[232:235], v[4:7]
	v_lshl_add_u64 v[132:133], v[132:133], 0, s[26:27]
	v_lshl_add_u64 v[134:135], v[134:135], 0, s[26:27]
	s_cmp_ge_i32 s12, s47
	s_cbranch_scc1 .Lrot_exit_6
	s_cmp_eq_u32 s48, s12
	v_lshl_add_u64 v[194:195], v[134:135], 0, s[22:23]
	s_cselect_b64 vcc, -1, 0
	s_add_i32 s12, s12, 2
	v_cndmask_b32_e32 v199, v195, v179, vcc
	v_cndmask_b32_e32 v198, v194, v178, vcc
	v_cndmask_b32_e32 v215, v133, v181, vcc
	v_cndmask_b32_e32 v214, v132, v180, vcc
	s_setprio 0
	s_barrier
	s_branch .LBB0_1340
.Lrot_exit_6:
	s_setprio 0
	s_barrier
.LBB0_1341:
	s_and_b64 vcc, exec, s[24:25]
	s_cbranch_vccz .LBB0_1343
	s_barrier

; template <class Epi, class Sched, bool ALIGN_EPI = false, bool SP2 = false>
; __device__ __forceinline__ void gemm_phase(PG8_LAS unsigned char* lds, const Gemm g, const Sched& S, const Epi& E) {
;     ...
;     for (;;) {
;         const bool has_next = S.next(ui + 1, nxt);
;         const char* nA = has_next ? (const char*)g.A + (size_t)nxt.pm * tstep : cA; const char* nB = has_next ? (const char*)g.Bt + (size_t)nxt.pn * tstep : cB;
;         for (int t = 0; t < nt; t += 2) {
;             const bool last = (t == nt - 2);
;             const char* a1 = cA + (size_t)(t + 1) * kstep;
;             const char* a2 = last ? nA : cA + (size_t)(t + 2) * kstep; const char* b2 = last ? nB : cB + (size_t)(t + 2) * kstep;
;     ...
; #pragma unroll
;         for (int a = 0; a < 2; ++a)
; #pragma unroll
;             for (int b = 0; b < 2; ++b)
; #pragma unroll
;                 for (int m = 0; m < 4; ++m)
; #pragma unroll
;                     for (int n = 0; n < 2; ++n) acc[a][b][m][n] = (f32x4){0.f, 0.f, 0.f, 0.f};
;         cur = nxt; cA = nA; cB = nB; ++ui;
.LBB0_1421:
	v_mov_b32_e32 v127, 0
	s_andn2_b64 vcc, exec, s[28:29]
	v_mov_b32_e32 v126, v127
	v_mov_b32_e32 v125, v127
	v_mov_b32_e32 v124, v127
	v_mov_b32_e32 v123, v127
	v_mov_b32_e32 v122, v127
	v_mov_b32_e32 v121, v127
	v_mov_b32_e32 v120, v127
	v_mov_b32_e32 v111, v127
	v_mov_b32_e32 v110, v127
	v_mov_b32_e32 v109, v127
	v_mov_b32_e32 v108, v127
	v_mov_b32_e32 v107, v127
	v_mov_b32_e32 v106, v127
	v_mov_b32_e32 v105, v127
	v_mov_b32_e32 v104, v127
	v_mov_b32_e32 v95, v127
	v_mov_b32_e32 v94, v127
	v_mov_b32_e32 v93, v127
	v_mov_b32_e32 v92, v127
	v_mov_b32_e32 v91, v127
	v_mov_b32_e32 v90, v127
	v_mov_b32_e32 v89, v127
	v_mov_b32_e32 v88, v127
	v_mov_b32_e32 v79, v127
	v_mov_b32_e32 v78, v127
	v_mov_b32_e32 v77, v127
	v_mov_b32_e32 v76, v127
	v_mov_b32_e32 v75, v127
	v_mov_b32_e32 v74, v127
	v_mov_b32_e32 v73, v127
	v_mov_b32_e32 v72, v127
	v_mov_b32_e32 v119, v127
	v_mov_b32_e32 v118, v127
	v_mov_b32_e32 v117, v127
	v_mov_b32_e32 v116, v127
	v_mov_b32_e32 v115, v127
	v_mov_b32_e32 v114, v127
	v_mov_b32_e32 v113, v127
	v_mov_b32_e32 v112, v127
	v_mov_b32_e32 v103, v127
	v_mov_b32_e32 v102, v127
	v_mov_b32_e32 v101, v127
	v_mov_b32_e32 v100, v127
	v_mov_b32_e32 v99, v127
	v_mov_b32_e32 v98, v127
	v_mov_b32_e32 v97, v127
	v_mov_b32_e32 v96, v127
	v_mov_b32_e32 v87, v127
	v_mov_b32_e32 v86, v127
	v_mov_b32_e32 v85, v127
	v_mov_b32_e32 v84, v127
	v_mov_b32_e32 v83, v127
	v_mov_b32_e32 v82, v127
	v_mov_b32_e32 v81, v127
	v_mov_b32_e32 v80, v127
	v_mov_b32_e32 v71, v127
	v_mov_b32_e32 v70, v127
	v_mov_b32_e32 v69, v127
	v_mov_b32_e32 v68, v127
	v_mov_b32_e32 v67, v127
	v_mov_b32_e32 v66, v127
	v_mov_b32_e32 v65, v127
	v_mov_b32_e32 v64, v127
	v_mov_b32_e32 v63, v127
	v_mov_b32_e32 v62, v127
	v_mov_b32_e32 v61, v127
	v_mov_b32_e32 v60, v127
	v_mov_b32_e32 v59, v127
	v_mov_b32_e32 v58, v127
	v_mov_b32_e32 v57, v127
	v_mov_b32_e32 v56, v127
	v_mov_b32_e32 v47, v127
	v_mov_b32_e32 v46, v127
	v_mov_b32_e32 v45, v127
	v_mov_b32_e32 v44, v127
	v_mov_b32_e32 v43, v127
	v_mov_b32_e32 v42, v127
	v_mov_b32_e32 v41, v127
	v_mov_b32_e32 v40, v127
	v_mov_b32_e32 v31, v127
	v_mov_b32_e32 v30, v127
	v_mov_b32_e32 v29, v127
	v_mov_b32_e32 v28, v127
	v_mov_b32_e32 v27, v127
	v_mov_b32_e32 v26, v127
	v_mov_b32_e32 v25, v127
	v_mov_b32_e32 v24, v127
	v_mov_b32_e32 v15, v127
	v_mov_b32_e32 v14, v127
	v_mov_b32_e32 v13, v127
	v_mov_b32_e32 v12, v127
	v_mov_b32_e32 v11, v127
	v_mov_b32_e32 v10, v127
	v_mov_b32_e32 v9, v127
	v_mov_b32_e32 v8, v127
	v_mov_b32_e32 v55, v127
	v_mov_b32_e32 v54, v127
	v_mov_b32_e32 v53, v127
	v_mov_b32_e32 v52, v127
	v_mov_b32_e32 v51, v127
	v_mov_b32_e32 v50, v127
	v_mov_b32_e32 v49, v127
	v_mov_b32_e32 v48, v127
	v_mov_b32_e32 v39, v127
	v_mov_b32_e32 v38, v127
	v_mov_b32_e32 v37, v127
	v_mov_b32_e32 v36, v127
	v_mov_b32_e32 v35, v127
	v_mov_b32_e32 v34, v127
	v_mov_b32_e32 v33, v127
	v_mov_b32_e32 v32, v127
	v_mov_b32_e32 v23, v127
	v_mov_b32_e32 v22, v127
	v_mov_b32_e32 v21, v127
	v_mov_b32_e32 v20, v127
	v_mov_b32_e32 v19, v127
	v_mov_b32_e32 v18, v127
	v_mov_b32_e32 v17, v127
	v_mov_b32_e32 v16, v127
	v_mov_b32_e32 v7, v127
	v_mov_b32_e32 v6, v127
	v_mov_b32_e32 v5, v127
	v_mov_b32_e32 v4, v127
	v_mov_b32_e32 v3, v127
	v_mov_b32_e32 v2, v127
	v_mov_b32_e32 v1, v127
	v_mov_b32_e32 v0, v127
	s_cbranch_vccnz .LBB0_1424
	v_mov_b32_e32 v0, 0
	v_lshl_add_u64 v[128:129], v[128:129], 0, s[36:37]
	v_lshl_add_u64 v[130:131], v[130:131], 0, s[26:27]
	s_mov_b32 s10, 0
	v_mov_b32_e32 v1, v0
	v_mov_b32_e32 v2, v0
	v_mov_b32_e32 v3, v0
	v_mov_b32_e32 v4, v0
	v_mov_b32_e32 v5, v0
	v_mov_b32_e32 v6, v0
	v_mov_b32_e32 v7, v0
	v_mov_b32_e32 v16, v0
	v_mov_b32_e32 v17, v0
	v_mov_b32_e32 v18, v0
	v_mov_b32_e32 v19, v0
	v_mov_b32_e32 v20, v0
	v_mov_b32_e32 v21, v0
	v_mov_b32_e32 v22, v0
	v_mov_b32_e32 v23, v0
	v_mov_b32_e32 v32, v0
	v_mov_b32_e32 v33, v0
	v_mov_b32_e32 v34, v0
	v_mov_b32_e32 v35, v0
	v_mov_b32_e32 v36, v0
	v_mov_b32_e32 v37, v0
	v_mov_b32_e32 v38, v0
	v_mov_b32_e32 v39, v0
	v_mov_b32_e32 v48, v0
	v_mov_b32_e32 v49, v0
	v_mov_b32_e32 v50, v0
	v_mov_b32_e32 v51, v0
	v_mov_b32_e32 v52, v0
	v_mov_b32_e32 v53, v0
	v_mov_b32_e32 v54, v0
	v_mov_b32_e32 v55, v0
	v_mov_b32_e32 v8, v0
	v_mov_b32_e32 v9, v0
	v_mov_b32_e32 v10, v0
	v_mov_b32_e32 v11, v0
	v_mov_b32_e32 v12, v0
	v_mov_b32_e32 v13, v0
	v_mov_b32_e32 v14, v0
	v_mov_b32_e32 v15, v0
	v_mov_b32_e32 v24, v0
	v_mov_b32_e32 v25, v0
	v_mov_b32_e32 v26, v0
	v_mov_b32_e32 v27, v0
	v_mov_b32_e32 v28, v0
	v_mov_b32_e32 v29, v0
	v_mov_b32_e32 v30, v0
	v_mov_b32_e32 v31, v0
	v_mov_b32_e32 v40, v0
	v_mov_b32_e32 v41, v0
	v_mov_b32_e32 v42, v0
	v_mov_b32_e32 v43, v0
	v_mov_b32_e32 v44, v0
	v_mov_b32_e32 v45, v0
	v_mov_b32_e32 v46, v0
	v_mov_b32_e32 v47, v0
	v_mov_b32_e32 v56, v0
	v_mov_b32_e32 v57, v0
	v_mov_b32_e32 v58, v0
	v_mov_b32_e32 v59, v0
	v_mov_b32_e32 v60, v0
	v_mov_b32_e32 v61, v0
	v_mov_b32_e32 v62, v0
	v_mov_b32_e32 v63, v0
	v_mov_b32_e32 v64, v0
	v_mov_b32_e32 v65, v0
	v_mov_b32_e32 v66, v0
	v_mov_b32_e32 v67, v0
	v_mov_b32_e32 v68, v0
	v_mov_b32_e32 v69, v0
	v_mov_b32_e32 v70, v0
	v_mov_b32_e32 v71, v0
	v_mov_b32_e32 v80, v0
	v_mov_b32_e32 v81, v0
	v_mov_b32_e32 v82, v0
	v_mov_b32_e32 v83, v0
	v_mov_b32_e32 v84, v0
	v_mov_b32_e32 v85, v0
	v_mov_b32_e32 v86, v0
	v_mov_b32_e32 v87, v0
	v_mov_b32_e32 v96, v0
	v_mov_b32_e32 v97, v0
	v_mov_b32_e32 v98, v0
	v_mov_b32_e32 v99, v0
	v_mov_b32_e32 v100, v0
	v_mov_b32_e32 v101, v0
	v_mov_b32_e32 v102, v0
	v_mov_b32_e32 v103, v0
	v_mov_b32_e32 v112, v0
	v_mov_b32_e32 v113, v0
	v_mov_b32_e32 v114, v0
	v_mov_b32_e32 v115, v0
	v_mov_b32_e32 v116, v0
	v_mov_b32_e32 v117, v0
	v_mov_b32_e32 v118, v0
	v_mov_b32_e32 v119, v0
	v_mov_b32_e32 v72, v0
	v_mov_b32_e32 v73, v0
	v_mov_b32_e32 v74, v0
	v_mov_b32_e32 v75, v0
	v_mov_b32_e32 v76, v0
	v_mov_b32_e32 v77, v0
	v_mov_b32_e32 v78, v0
	v_mov_b32_e32 v79, v0
	v_mov_b32_e32 v88, v0
	v_mov_b32_e32 v89, v0
	v_mov_b32_e32 v90, v0
	v_mov_b32_e32 v91, v0
	v_mov_b32_e32 v92, v0
	v_mov_b32_e32 v93, v0
	v_mov_b32_e32 v94, v0
	v_mov_b32_e32 v95, v0
	v_mov_b32_e32 v104, v0
	v_mov_b32_e32 v105, v0
	v_mov_b32_e32 v106, v0
	v_mov_b32_e32 v107, v0
	v_mov_b32_e32 v108, v0
	v_mov_b32_e32 v109, v0
	v_mov_b32_e32 v110, v0
	v_mov_b32_e32 v111, v0
	v_mov_b32_e32 v120, v0
	v_mov_b32_e32 v121, v0
	v_mov_b32_e32 v122, v0
	v_mov_b32_e32 v123, v0
	v_mov_b32_e32 v124, v0
	v_mov_b32_e32 v125, v0
	v_mov_b32_e32 v126, v0
	v_mov_b32_e32 v127, v0
	s_cmp_eq_u32 s74, s10
	v_lshl_add_u64 v[198:199], v[130:131], 0, s[26:27]
	s_cselect_b64 vcc, -1, 0
	s_add_i32 s10, s10, 2
	v_cndmask_b32_e32 v211, v199, v171, vcc
	v_cndmask_b32_e32 v210, v198, v170, vcc
	v_cndmask_b32_e32 v215, v129, v173, vcc
	v_cndmask_b32_e32 v214, v128, v172, vcc
	.p2align	6
; #define PG8_STAGE(bufoff, gbase, voff) do { _Pragma("unroll") for (int _i = 0; _i < 2; ++_i) \
;         __builtin_amdgcn_global_load_lds((const unsigned*)((const char*)(gbase) + (voff)[_i]), (PG8_LAS unsigned*)(lds + (bufoff) + ldsw + _i * 8192), 16, 0, 0); } while (0)
; #define PG8_LDA(dst, b, h) do { _Pragma("unroll") for (int m = 0; m < 4; ++m) _Pragma("unroll") for (int k = 0; k < 2; ++k) dst[m][k] = *(const PG8_LAS bf16x8*)(lds + PG8_SA(b, h) + aoff + m * 2048 + k * 1024); } while (0)
; #define PG8_LDB(dst, b, h) do { _Pragma("unroll") for (int n = 0; n < 2; ++n) _Pragma("unroll") for (int k = 0; k < 2; ++k) dst[n][k] = *(const PG8_LAS bf16x8*)(lds + PG8_SB(b, h) + boff + n * 2048 + k * 1024); } while (0)
; #define PG8_MMA(ai, bj, At, Bt) do { __builtin_amdgcn_s_setprio(1); _Pragma("unroll") for (int m = 0; m < 4; ++m) _Pragma("unroll") for (int n = 0; n < 2; ++n) _Pragma("unroll") for (int k = 0; k < 2; ++k) \
;         acc[ai][bj][m][n] = __builtin_amdgcn_mfma_f32_16x16x32_bf16(Bt[n][k], At[m][k], acc[ai][bj][m][n], 0, 0, 0); __builtin_amdgcn_s_setprio(0); } while (0)
; #define PG8_WAIT_V(n) asm volatile("s_waitcnt vmcnt(" #n ")" ::: "memory")
; #define PG8_WAIT_L(n) asm volatile("s_waitcnt lgkmcnt(" #n ")" ::: "memory")
; #define PG8_BAR __builtin_amdgcn_s_barrier()
; #define PG8_SCHED __builtin_amdgcn_sched_barrier(0)
; template <class Epi, class Sched, bool ALIGN_EPI = false, bool SP2 = false>
; __device__ __forceinline__ void gemm_phase(PG8_LAS unsigned char* lds, const Gemm g, const Sched& S, const Epi& E) {
;     ...
;         for (int t = 0; t < nt; t += 2) {
;             const bool last = (t == nt - 2);
;             const char* a1 = cA + (size_t)(t + 1) * kstep;
;             const char* a2 = last ? nA : cA + (size_t)(t + 2) * kstep; const char* b2 = last ? nB : cB + (size_t)(t + 2) * kstep;
;             const char* a3 = a2 + kstep; const char* b3 = b2 + kstep;
;             if (last && has_next) S.a_ready(nxt);
;             if constexpr (SP2) {
;             PG8_LDB(B0, 0, 0); PG8_LDB(B1, 0, 1); PG8_SCHED; PG8_LDA(At, 0, 0); PG8_STAGE(PG8_SA(1, 1), a1 + hstep, voffA);
;             PG8_WAIT_V(8); PG8_WAIT_L(0); PG8_BAR; PG8_MMA(0, 0, At, B0); PG8_MMA(0, 1, At, B1); PG8_BAR; PG8_SCHED;
.LBB0_1423:
	v_add_u32_e32 v152, s81, v169
	v_add_u32_e32 v165, s82, v169
	ds_read_b128 v[132:135], v152
	ds_read_b128 v[136:139], v152 offset:1024
	ds_read_b128 v[174:177], v152 offset:2048
	ds_read_b128 v[178:181], v152 offset:3072
	ds_read_b128 v[182:185], v165
	ds_read_b128 v[186:189], v165 offset:1024
	ds_read_b128 v[190:193], v165 offset:2048
	ds_read_b128 v[194:197], v165 offset:3072
	v_lshl_add_u64 v[240:241], v[130:131], 0, v[160:161]
	s_add_i32 m0, s47, 0xc000
	ds_read_b128 v[198:201], v213
	ds_read_b128 v[202:205], v213 offset:1024
	ds_read_b128 v[206:209], v213 offset:2048
	ds_read_b128 v[220:223], v213 offset:3072
	ds_read_b128 v[224:227], v213 offset:4096
	ds_read_b128 v[228:231], v213 offset:5120
	ds_read_b128 v[232:235], v213 offset:6144
	ds_read_b128 v[236:239], v213 offset:7168
	global_load_lds_dwordx4 v[240:241], off
	s_add_i32 m0, s47, 0xe000
	v_lshl_add_u64 v[240:241], v[130:131], 0, v[158:159]
	global_load_lds_dwordx4 v[240:241], off
	s_waitcnt vmcnt(8) lgkmcnt(0)
	s_setprio 1
	s_barrier
	v_mfma_f32_16x16x32_bf16 v[124:127], v[132:135], v[198:201], v[124:127]
	v_mfma_f32_16x16x32_bf16 v[120:123], v[174:177], v[198:201], v[120:123]
	v_mfma_f32_16x16x32_bf16 v[108:111], v[132:135], v[206:209], v[108:111]
	v_mfma_f32_16x16x32_bf16 v[104:107], v[174:177], v[206:209], v[104:107]
	v_mfma_f32_16x16x32_bf16 v[92:95], v[132:135], v[224:227], v[92:95]
	v_mfma_f32_16x16x32_bf16 v[88:91], v[174:177], v[224:227], v[88:91]
	v_mfma_f32_16x16x32_bf16 v[76:79], v[132:135], v[232:235], v[76:79]
	v_mfma_f32_16x16x32_bf16 v[72:75], v[174:177], v[232:235], v[72:75]
	v_mfma_f32_16x16x32_bf16 v[124:127], v[136:139], v[202:205], v[124:127]
	v_mfma_f32_16x16x32_bf16 v[120:123], v[178:181], v[202:205], v[120:123]
	v_mfma_f32_16x16x32_bf16 v[108:111], v[136:139], v[220:223], v[108:111]
	v_mfma_f32_16x16x32_bf16 v[104:107], v[178:181], v[220:223], v[104:107]
	v_mfma_f32_16x16x32_bf16 v[92:95], v[136:139], v[228:231], v[92:95]
	v_mfma_f32_16x16x32_bf16 v[88:91], v[178:181], v[228:231], v[88:91]
	v_mfma_f32_16x16x32_bf16 v[76:79], v[136:139], v[236:239], v[76:79]
	v_mfma_f32_16x16x32_bf16 v[72:75], v[178:181], v[236:239], v[72:75]
	s_cmp_eq_u32 s22, 12
	s_cbranch_scc1 .Lio_skipk0
	v_mfma_f32_16x16x32_bf16 v[116:119], v[182:185], v[198:201], v[116:119]
	v_mfma_f32_16x16x32_bf16 v[112:115], v[190:193], v[198:201], v[112:115]
	v_mfma_f32_16x16x32_bf16 v[100:103], v[182:185], v[206:209], v[100:103]
	v_mfma_f32_16x16x32_bf16 v[96:99], v[190:193], v[206:209], v[96:99]
	v_mfma_f32_16x16x32_bf16 v[84:87], v[182:185], v[224:227], v[84:87]
	v_mfma_f32_16x16x32_bf16 v[80:83], v[190:193], v[224:227], v[80:83]
	v_mfma_f32_16x16x32_bf16 v[68:71], v[182:185], v[232:235], v[68:71]
	v_mfma_f32_16x16x32_bf16 v[64:67], v[190:193], v[232:235], v[64:67]
	v_mfma_f32_16x16x32_bf16 v[116:119], v[186:189], v[202:205], v[116:119]
	v_mfma_f32_16x16x32_bf16 v[112:115], v[194:197], v[202:205], v[112:115]
	v_mfma_f32_16x16x32_bf16 v[100:103], v[186:189], v[220:223], v[100:103]
	v_mfma_f32_16x16x32_bf16 v[96:99], v[194:197], v[220:223], v[96:99]
	v_mfma_f32_16x16x32_bf16 v[84:87], v[186:189], v[228:231], v[84:87]
	v_mfma_f32_16x16x32_bf16 v[80:83], v[194:197], v[228:231], v[80:83]
	v_mfma_f32_16x16x32_bf16 v[68:71], v[186:189], v[236:239], v[68:71]
	v_mfma_f32_16x16x32_bf16 v[64:67], v[194:197], v[236:239], v[64:67]

; #define PG8_MMA(ai, bj, At, Bt) do { __builtin_amdgcn_s_setprio(1); _Pragma("unroll") for (int m = 0; m < 4; ++m) _Pragma("unroll") for (int n = 0; n < 2; ++n) _Pragma("unroll") for (int k = 0; k < 2; ++k) \
;         acc[ai][bj][m][n] = __builtin_amdgcn_mfma_f32_16x16x32_bf16(Bt[n][k], At[m][k], acc[ai][bj][m][n], 0, 0, 0); __builtin_amdgcn_s_setprio(0); } while (0)
; #define PG8_WAIT_V(n) asm volatile("s_waitcnt vmcnt(" #n ")" ::: "memory")
; #define PG8_WAIT_L(n) asm volatile("s_waitcnt lgkmcnt(" #n ")" ::: "memory")
; #define PG8_BAR __builtin_amdgcn_s_barrier()
; #define PG8_SCHED __builtin_amdgcn_sched_barrier(0)
; template <class Epi, class Sched, bool ALIGN_EPI = false, bool SP2 = false>
; __device__ __forceinline__ void gemm_phase(PG8_LAS unsigned char* lds, const Gemm g, const Sched& S, const Epi& E) {
;     ...
;         for (int t = 0; t < nt; t += 2) {
;             const bool last = (t == nt - 2);
;             const char* a1 = cA + (size_t)(t + 1) * kstep;
;             const char* a2 = last ? nA : cA + (size_t)(t + 2) * kstep; const char* b2 = last ? nB : cB + (size_t)(t + 2) * kstep;
;     ...
;             PG8_WAIT_V(8); PG8_WAIT_L(0); PG8_BAR; PG8_MMA(1, 0, At, B0); PG8_MMA(1, 1, At, B1); PG8_BAR; PG8_SCHED;
.Lio_skipk3:
	v_lshl_add_u64 v[128:129], v[128:129], 0, s[36:37]
	v_lshl_add_u64 v[130:131], v[130:131], 0, s[36:37]
	s_cmp_ge_i32 s10, s67
	s_cbranch_scc1 .Lrot_exit_5
	s_cmp_eq_u32 s74, s10
	v_lshl_add_u64 v[198:199], v[130:131], 0, s[26:27]
	s_cselect_b64 vcc, -1, 0
	s_add_i32 s10, s10, 2
	v_cndmask_b32_e32 v211, v199, v171, vcc
	v_cndmask_b32_e32 v210, v198, v170, vcc
	v_cndmask_b32_e32 v215, v129, v173, vcc
	v_cndmask_b32_e32 v214, v128, v172, vcc
	s_setprio 0
	s_barrier
	s_branch .LBB0_1423
.Lrot_exit_5:
	s_setprio 0
	s_barrier
.LBB0_1424:
	s_and_b64 vcc, exec, s[30:31]
	s_cbranch_vccz .LBB0_1426
	s_barrier

; #define PG8_STAGE(bufoff, gbase, voff) do { _Pragma("unroll") for (int _i = 0; _i < 2; ++_i) \
;         __builtin_amdgcn_global_load_lds((const unsigned*)((const char*)(gbase) + (voff)[_i]), (PG8_LAS unsigned*)(lds + (bufoff) + ldsw + _i * 8192), 16, 0, 0); } while (0)
; #define PG8_LDA(dst, b, h) do { _Pragma("unroll") for (int m = 0; m < 4; ++m) _Pragma("unroll") for (int k = 0; k < 2; ++k) dst[m][k] = *(const PG8_LAS bf16x8*)(lds + PG8_SA(b, h) + aoff + m * 2048 + k * 1024); } while (0)
; #define PG8_LDB(dst, b, h) do { _Pragma("unroll") for (int n = 0; n < 2; ++n) _Pragma("unroll") for (int k = 0; k < 2; ++k) dst[n][k] = *(const PG8_LAS bf16x8*)(lds + PG8_SB(b, h) + boff + n * 2048 + k * 1024); } while (0)
; #define PG8_MMA(ai, bj, At, Bt) do { __builtin_amdgcn_s_setprio(1); _Pragma("unroll") for (int m = 0; m < 4; ++m) _Pragma("unroll") for (int n = 0; n < 2; ++n) _Pragma("unroll") for (int k = 0; k < 2; ++k) \
;         acc[ai][bj][m][n] = __builtin_amdgcn_mfma_f32_16x16x32_bf16(Bt[n][k], At[m][k], acc[ai][bj][m][n], 0, 0, 0); __builtin_amdgcn_s_setprio(0); } while (0)
; #define PG8_WAIT_V(n) asm volatile("s_waitcnt vmcnt(" #n ")" ::: "memory")
; #define PG8_BAR __builtin_amdgcn_s_barrier()
; template <class Epi, class Sched, bool ALIGN_EPI = false, bool SP2 = false>
; __device__ __forceinline__ void gemm_phase(PG8_LAS unsigned char* lds, const Gemm g, const Sched& S, const Epi& E) {
;     ...
;         for (int t = 0; t < nt; t += 2) {
;             const bool last = (t == nt - 2);
;             const char* a1 = cA + (size_t)(t + 1) * kstep;
;             const char* a2 = last ? nA : cA + (size_t)(t + 2) * kstep; const char* b2 = last ? nB : cB + (size_t)(t + 2) * kstep;
;             const char* a3 = a2 + kstep; const char* b3 = b2 + kstep;
;             if (last && has_next) S.a_ready(nxt);
;             if constexpr (SP2) {
;             PG8_LDB(B0, 0, 0); PG8_LDB(B1, 0, 1); PG8_SCHED; PG8_LDA(At, 0, 0); PG8_STAGE(PG8_SA(1, 1), a1 + hstep, voffA);
;             PG8_WAIT_V(8); PG8_WAIT_L(0); PG8_BAR; PG8_MMA(0, 0, At, B0); PG8_MMA(0, 1, At, B1); PG8_BAR; PG8_SCHED;
;             PG8_LDA(At, 0, 1); PG8_STAGE(PG8_SB(0, 0), b2, voffB); PG8_STAGE(PG8_SB(0, 1), b2 + hstep, voffB); PG8_STAGE(PG8_SA(0, 0), a2, voffA);
;             PG8_WAIT_V(8); PG8_WAIT_L(0); PG8_BAR; PG8_MMA(1, 0, At, B0); PG8_MMA(1, 1, At, B1); PG8_BAR; PG8_SCHED;
.LBB0_1695:
	v_add_u32_e32 v188, s54, v199
	ds_read_b128 v[132:135], v201
	ds_read_b128 v[136:139], v201 offset:1024
	ds_read_b128 v[140:143], v201 offset:2048
	ds_read_b128 v[144:147], v201 offset:3072
	ds_read_b128 v[148:151], v188
	ds_read_b128 v[180:183], v188 offset:1024
	ds_read_b128 v[184:187], v188 offset:2048
	ds_read_b128 v[188:191], v188 offset:3072
	s_mov_b32 m0, s55
	v_lshl_add_u64 v[214:215], v[130:131], 0, v[172:173]
	ds_read_b128 v[192:195], v202
	ds_read_b128 v[204:207], v202 offset:1024
	ds_read_b128 v[208:211], v202 offset:2048
	ds_read_b128 v[216:219], v202 offset:3072
	ds_read_b128 v[220:223], v202 offset:4096
	ds_read_b128 v[224:227], v202 offset:5120
	ds_read_b128 v[228:231], v202 offset:6144
	ds_read_b128 v[232:235], v202 offset:7168
	global_load_lds_dwordx4 v[214:215], off
	s_mov_b32 m0, s56
	v_lshl_add_u64 v[214:215], v[130:131], 0, v[170:171]
	global_load_lds_dwordx4 v[214:215], off
	s_waitcnt vmcnt(8) lgkmcnt(0)
	s_setprio 1
	s_barrier
	v_mfma_f32_16x16x32_bf16 v[120:123], v[132:135], v[192:195], v[120:123]
	v_mfma_f32_16x16x32_bf16 v[124:127], v[140:143], v[192:195], v[124:127]
	v_mfma_f32_16x16x32_bf16 v[108:111], v[132:135], v[208:211], v[108:111]
	v_mfma_f32_16x16x32_bf16 v[104:107], v[140:143], v[208:211], v[104:107]
	v_mfma_f32_16x16x32_bf16 v[92:95], v[132:135], v[220:223], v[92:95]
	v_mfma_f32_16x16x32_bf16 v[88:91], v[140:143], v[220:223], v[88:91]
	v_mfma_f32_16x16x32_bf16 v[76:79], v[132:135], v[228:231], v[76:79]
	v_mfma_f32_16x16x32_bf16 v[72:75], v[140:143], v[228:231], v[72:75]
	v_mfma_f32_16x16x32_bf16 v[120:123], v[136:139], v[204:207], v[120:123]
	v_mfma_f32_16x16x32_bf16 v[124:127], v[144:147], v[204:207], v[124:127]
	v_mfma_f32_16x16x32_bf16 v[108:111], v[136:139], v[216:219], v[108:111]
	v_mfma_f32_16x16x32_bf16 v[104:107], v[144:147], v[216:219], v[104:107]
	v_mfma_f32_16x16x32_bf16 v[92:95], v[136:139], v[224:227], v[92:95]
	v_mfma_f32_16x16x32_bf16 v[88:91], v[144:147], v[224:227], v[88:91]
	v_mfma_f32_16x16x32_bf16 v[76:79], v[136:139], v[232:235], v[76:79]
	v_mfma_f32_16x16x32_bf16 v[72:75], v[144:147], v[232:235], v[72:75]
	v_mfma_f32_16x16x32_bf16 v[116:119], v[148:151], v[192:195], v[116:119]
	v_mfma_f32_16x16x32_bf16 v[112:115], v[184:187], v[192:195], v[112:115]
	v_mfma_f32_16x16x32_bf16 v[100:103], v[148:151], v[208:211], v[100:103]
	v_mfma_f32_16x16x32_bf16 v[96:99], v[184:187], v[208:211], v[96:99]
	v_mfma_f32_16x16x32_bf16 v[84:87], v[148:151], v[220:223], v[84:87]
	v_mfma_f32_16x16x32_bf16 v[80:83], v[184:187], v[220:223], v[80:83]
	v_mfma_f32_16x16x32_bf16 v[68:71], v[148:151], v[228:231], v[68:71]
	v_mfma_f32_16x16x32_bf16 v[64:67], v[184:187], v[228:231], v[64:67]
	v_mfma_f32_16x16x32_bf16 v[116:119], v[180:183], v[204:207], v[116:119]
	v_mfma_f32_16x16x32_bf16 v[112:115], v[188:191], v[204:207], v[112:115]
	v_mfma_f32_16x16x32_bf16 v[100:103], v[180:183], v[216:219], v[100:103]
	v_mfma_f32_16x16x32_bf16 v[96:99], v[188:191], v[216:219], v[96:99]
	v_mfma_f32_16x16x32_bf16 v[84:87], v[180:183], v[224:227], v[84:87]
	v_mfma_f32_16x16x32_bf16 v[80:83], v[188:191], v[224:227], v[80:83]
	v_mfma_f32_16x16x32_bf16 v[68:71], v[180:183], v[232:235], v[68:71]
	v_mfma_f32_16x16x32_bf16 v[64:67], v[188:191], v[232:235], v[64:67]
	s_setprio 0
	s_barrier
	s_mov_b32 m0, s57
	v_lshl_add_u64 v[214:215], v[212:213], 0, v[164:165]
	ds_read_b128 v[192:195], v202 offset:16384
	ds_read_b128 v[204:207], v202 offset:17408
	ds_read_b128 v[208:211], v202 offset:18432
	ds_read_b128 v[216:219], v202 offset:19456
	ds_read_b128 v[220:223], v202 offset:20480
	ds_read_b128 v[224:227], v202 offset:21504
	ds_read_b128 v[228:231], v202 offset:22528
	ds_read_b128 v[232:235], v202 offset:23552
	global_load_lds_dwordx4 v[214:215], off
	v_lshl_add_u64 v[236:237], v[212:213], 0, v[168:169]
	s_mov_b32 m0, s58
	v_lshl_add_u64 v[212:213], v[212:213], 0, s[14:15]
	s_add_i32 s13, s54, s30
	global_load_lds_dwordx4 v[236:237], off
	v_lshl_add_u64 v[238:239], v[212:213], 0, v[164:165]
	s_mov_b32 m0, s13
	v_lshl_add_u64 v[212:213], v[212:213], 0, v[168:169]
	global_load_lds_dwordx4 v[238:239], off
	s_add_i32 m0, s13, 0x2000
	v_lshl_add_u64 v[240:241], v[196:197], 0, v[162:163]
	global_load_lds_dwordx4 v[212:213], off
	s_mov_b32 m0, s31
	v_lshl_add_u64 v[242:243], v[196:197], 0, v[166:167]
	global_load_lds_dwordx4 v[240:241], off
	s_mov_b32 m0, s34
	s_nop 0
	global_load_lds_dwordx4 v[242:243], off
	s_waitcnt vmcnt(8) lgkmcnt(0)
	s_setprio 1
	s_barrier
	v_mfma_f32_16x16x32_bf16 v[60:63], v[132:135], v[192:195], v[60:63]
	v_mfma_f32_16x16x32_bf16 v[56:59], v[140:143], v[192:195], v[56:59]
	v_mfma_f32_16x16x32_bf16 v[44:47], v[132:135], v[208:211], v[44:47]
	v_mfma_f32_16x16x32_bf16 v[40:43], v[140:143], v[208:211], v[40:43]
	v_mfma_f32_16x16x32_bf16 v[28:31], v[132:135], v[220:223], v[28:31]
	v_mfma_f32_16x16x32_bf16 v[24:27], v[140:143], v[220:223], v[24:27]
	v_mfma_f32_16x16x32_bf16 v[12:15], v[132:135], v[228:231], v[12:15]
	v_mfma_f32_16x16x32_bf16 v[8:11], v[140:143], v[228:231], v[8:11]
	v_mfma_f32_16x16x32_bf16 v[60:63], v[136:139], v[204:207], v[60:63]
	v_mfma_f32_16x16x32_bf16 v[56:59], v[144:147], v[204:207], v[56:59]
	v_mfma_f32_16x16x32_bf16 v[44:47], v[136:139], v[216:219], v[44:47]
	v_mfma_f32_16x16x32_bf16 v[40:43], v[144:147], v[216:219], v[40:43]
	v_mfma_f32_16x16x32_bf16 v[28:31], v[136:139], v[224:227], v[28:31]
	v_mfma_f32_16x16x32_bf16 v[24:27], v[144:147], v[224:227], v[24:27]
	v_mfma_f32_16x16x32_bf16 v[12:15], v[136:139], v[232:235], v[12:15]
	v_mfma_f32_16x16x32_bf16 v[8:11], v[144:147], v[232:235], v[8:11]
	v_mfma_f32_16x16x32_bf16 v[52:55], v[148:151], v[192:195], v[52:55]
	v_mfma_f32_16x16x32_bf16 v[48:51], v[184:187], v[192:195], v[48:51]
	v_mfma_f32_16x16x32_bf16 v[36:39], v[148:151], v[208:211], v[36:39]
	v_mfma_f32_16x16x32_bf16 v[32:35], v[184:187], v[208:211], v[32:35]
	v_mfma_f32_16x16x32_bf16 v[20:23], v[148:151], v[220:223], v[20:23]
	v_mfma_f32_16x16x32_bf16 v[16:19], v[184:187], v[220:223], v[16:19]
	v_mfma_f32_16x16x32_bf16 v[4:7], v[148:151], v[228:231], v[4:7]
	v_mfma_f32_16x16x32_bf16 v[0:3], v[184:187], v[228:231], v[0:3]
	v_mfma_f32_16x16x32_bf16 v[52:55], v[180:183], v[204:207], v[52:55]
	v_mfma_f32_16x16x32_bf16 v[48:51], v[188:191], v[204:207], v[48:51]
	v_mfma_f32_16x16x32_bf16 v[36:39], v[180:183], v[216:219], v[36:39]
	v_mfma_f32_16x16x32_bf16 v[32:35], v[188:191], v[216:219], v[32:35]
	v_mfma_f32_16x16x32_bf16 v[20:23], v[180:183], v[224:227], v[20:23]
	v_mfma_f32_16x16x32_bf16 v[16:19], v[188:191], v[224:227], v[16:19]
	v_mfma_f32_16x16x32_bf16 v[4:7], v[180:183], v[232:235], v[4:7]
	v_mfma_f32_16x16x32_bf16 v[0:3], v[188:191], v[232:235], v[0:3]
	s_setprio 0
	s_barrier
; #define PG8_STAGE(bufoff, gbase, voff) do { _Pragma("unroll") for (int _i = 0; _i < 2; ++_i) \
;         __builtin_amdgcn_global_load_lds((const unsigned*)((const char*)(gbase) + (voff)[_i]), (PG8_LAS unsigned*)(lds + (bufoff) + ldsw + _i * 8192), 16, 0, 0); } while (0)
; #define PG8_LDA(dst, b, h) do { _Pragma("unroll") for (int m = 0; m < 4; ++m) _Pragma("unroll") for (int k = 0; k < 2; ++k) dst[m][k] = *(const PG8_LAS bf16x8*)(lds + PG8_SA(b, h) + aoff + m * 2048 + k * 1024); } while (0)
; #define PG8_LDB(dst, b, h) do { _Pragma("unroll") for (int n = 0; n < 2; ++n) _Pragma("unroll") for (int k = 0; k < 2; ++k) dst[n][k] = *(const PG8_LAS bf16x8*)(lds + PG8_SB(b, h) + boff + n * 2048 + k * 1024); } while (0)
; #define PG8_MMA(ai, bj, At, Bt) do { __builtin_amdgcn_s_setprio(1); _Pragma("unroll") for (int m = 0; m < 4; ++m) _Pragma("unroll") for (int n = 0; n < 2; ++n) _Pragma("unroll") for (int k = 0; k < 2; ++k) \
;         acc[ai][bj][m][n] = __builtin_amdgcn_mfma_f32_16x16x32_bf16(Bt[n][k], At[m][k], acc[ai][bj][m][n], 0, 0, 0); __builtin_amdgcn_s_setprio(0); } while (0)
; #define PG8_WAIT_V(n) asm volatile("s_waitcnt vmcnt(" #n ")" ::: "memory")
; #define PG8_WAIT_L(n) asm volatile("s_waitcnt lgkmcnt(" #n ")" ::: "memory")
; #define PG8_BAR __builtin_amdgcn_s_barrier()
; #define PG8_SCHED __builtin_amdgcn_sched_barrier(0)
; template <class Epi, class Sched, bool ALIGN_EPI = false, bool SP2 = false>
; __device__ __forceinline__ void gemm_phase(PG8_LAS unsigned char* lds, const Gemm g, const Sched& S, const Epi& E) {
;     ...
;         for (int t = 0; t < nt; t += 2) {
;             const bool last = (t == nt - 2);
;             const char* a1 = cA + (size_t)(t + 1) * kstep;
;             const char* a2 = last ? nA : cA + (size_t)(t + 2) * kstep; const char* b2 = last ? nB : cB + (size_t)(t + 2) * kstep;
;     ...
;             PG8_LDB(B0, 1, 0); PG8_LDB(B1, 1, 1); PG8_SCHED; PG8_LDA(At, 1, 0); PG8_STAGE(PG8_SA(0, 1), a2 + hstep, voffA);
;             PG8_WAIT_V(8); PG8_WAIT_L(0); PG8_BAR; PG8_MMA(0, 0, At, B0); PG8_MMA(0, 1, At, B1); PG8_BAR; PG8_SCHED;
;             PG8_LDA(At, 1, 1); PG8_STAGE(PG8_SB(1, 0), b3, voffB); PG8_STAGE(PG8_SB(1, 1), b3 + hstep, voffB); PG8_STAGE(PG8_SA(1, 0), a3, voffA);
;             PG8_WAIT_V(8); PG8_WAIT_L(0); PG8_BAR; PG8_MMA(1, 0, At, B0); PG8_MMA(1, 1, At, B1); PG8_BAR; PG8_SCHED;
	s_add_i32 s13, 0, 0x18000
	s_add_i32 s29, 0, 0x1c000
	v_add_u32_e32 v144, s13, v199
	v_add_u32_e32 v188, s29, v199
	ds_read_b128 v[132:135], v144
	ds_read_b128 v[136:139], v144 offset:1024
	ds_read_b128 v[140:143], v144 offset:2048
	ds_read_b128 v[144:147], v144 offset:3072
	ds_read_b128 v[148:151], v188
	ds_read_b128 v[180:183], v188 offset:1024
	ds_read_b128 v[184:187], v188 offset:2048
	ds_read_b128 v[188:191], v188 offset:3072
	v_lshl_add_u64 v[196:197], v[196:197], 0, s[14:15]
	s_mov_b32 m0, s35
	v_lshl_add_u64 v[244:245], v[196:197], 0, v[162:163]
	ds_read_b128 v[192:195], v202 offset:32768
	ds_read_b128 v[204:207], v202 offset:33792
	ds_read_b128 v[208:211], v202 offset:34816
	ds_read_b128 v[216:219], v202 offset:35840
	ds_read_b128 v[220:223], v202 offset:36864
	ds_read_b128 v[224:227], v202 offset:37888
	ds_read_b128 v[228:231], v202 offset:38912
	ds_read_b128 v[232:235], v202 offset:39936
	global_load_lds_dwordx4 v[244:245], off
	s_mov_b32 m0, s36
	v_lshl_add_u64 v[196:197], v[196:197], 0, v[166:167]
	global_load_lds_dwordx4 v[196:197], off
	s_waitcnt vmcnt(8) lgkmcnt(0)
	s_setprio 1
	s_barrier
	v_mfma_f32_16x16x32_bf16 v[120:123], v[132:135], v[192:195], v[120:123]
	v_mfma_f32_16x16x32_bf16 v[124:127], v[140:143], v[192:195], v[124:127]
	v_mfma_f32_16x16x32_bf16 v[108:111], v[132:135], v[208:211], v[108:111]
	v_mfma_f32_16x16x32_bf16 v[104:107], v[140:143], v[208:211], v[104:107]
	v_mfma_f32_16x16x32_bf16 v[92:95], v[132:135], v[220:223], v[92:95]
	v_mfma_f32_16x16x32_bf16 v[88:91], v[140:143], v[220:223], v[88:91]
	v_mfma_f32_16x16x32_bf16 v[76:79], v[132:135], v[228:231], v[76:79]
	v_mfma_f32_16x16x32_bf16 v[72:75], v[140:143], v[228:231], v[72:75]
	v_mfma_f32_16x16x32_bf16 v[120:123], v[136:139], v[204:207], v[120:123]
	v_mfma_f32_16x16x32_bf16 v[124:127], v[144:147], v[204:207], v[124:127]
	v_mfma_f32_16x16x32_bf16 v[108:111], v[136:139], v[216:219], v[108:111]
	v_mfma_f32_16x16x32_bf16 v[104:107], v[144:147], v[216:219], v[104:107]
	v_mfma_f32_16x16x32_bf16 v[92:95], v[136:139], v[224:227], v[92:95]
	v_mfma_f32_16x16x32_bf16 v[88:91], v[144:147], v[224:227], v[88:91]
	v_mfma_f32_16x16x32_bf16 v[76:79], v[136:139], v[232:235], v[76:79]
	v_mfma_f32_16x16x32_bf16 v[72:75], v[144:147], v[232:235], v[72:75]
	v_mfma_f32_16x16x32_bf16 v[116:119], v[148:151], v[192:195], v[116:119]
	v_mfma_f32_16x16x32_bf16 v[112:115], v[184:187], v[192:195], v[112:115]
	v_mfma_f32_16x16x32_bf16 v[100:103], v[148:151], v[208:211], v[100:103]
	v_mfma_f32_16x16x32_bf16 v[96:99], v[184:187], v[208:211], v[96:99]
	v_mfma_f32_16x16x32_bf16 v[84:87], v[148:151], v[220:223], v[84:87]
	v_mfma_f32_16x16x32_bf16 v[80:83], v[184:187], v[220:223], v[80:83]
	v_mfma_f32_16x16x32_bf16 v[68:71], v[148:151], v[228:231], v[68:71]
	v_mfma_f32_16x16x32_bf16 v[64:67], v[184:187], v[228:231], v[64:67]
	v_mfma_f32_16x16x32_bf16 v[116:119], v[180:183], v[204:207], v[116:119]
	v_mfma_f32_16x16x32_bf16 v[112:115], v[188:191], v[204:207], v[112:115]
	v_mfma_f32_16x16x32_bf16 v[100:103], v[180:183], v[216:219], v[100:103]
	v_mfma_f32_16x16x32_bf16 v[96:99], v[188:191], v[216:219], v[96:99]
	v_mfma_f32_16x16x32_bf16 v[84:87], v[180:183], v[224:227], v[84:87]
	v_mfma_f32_16x16x32_bf16 v[80:83], v[188:191], v[224:227], v[80:83]
	v_mfma_f32_16x16x32_bf16 v[68:71], v[180:183], v[232:235], v[68:71]
	v_mfma_f32_16x16x32_bf16 v[64:67], v[188:191], v[232:235], v[64:67]
	s_setprio 0
	s_barrier
	s_add_i32 s13, s13, s30
	s_add_i32 m0, s13, 0xffffff80
	ds_read_b128 v[192:195], v202 offset:49152
	ds_read_b128 v[204:207], v202 offset:50176
	ds_read_b128 v[208:211], v202 offset:51200
	ds_read_b128 v[216:219], v202 offset:52224
	global_load_lds_dwordx4 v[214:215], off offset:128
	s_add_i32 m0, s13, 0x1f80
	s_add_i32 s13, s29, s30
	global_load_lds_dwordx4 v[236:237], off offset:128
	s_add_i32 m0, s13, 0xffffff80
	ds_read_b128 v[232:235], v202 offset:56320
	global_load_lds_dwordx4 v[238:239], off offset:128
	s_add_i32 m0, s13, 0x1f80
	ds_read_b128 v[228:231], v202 offset:55296
	global_load_lds_dwordx4 v[212:213], off offset:128
	s_add_i32 m0, s37, 0xffffff80
	ds_read_b128 v[224:227], v202 offset:54272
	global_load_lds_dwordx4 v[240:241], off offset:128
	s_add_i32 m0, s41, 0xffffff80
	ds_read_b128 v[220:223], v202 offset:53248
	global_load_lds_dwordx4 v[242:243], off offset:128
	s_waitcnt vmcnt(8) lgkmcnt(0)
	s_setprio 1
	s_barrier
	v_mfma_f32_16x16x32_bf16 v[60:63], v[132:135], v[192:195], v[60:63]
	v_mfma_f32_16x16x32_bf16 v[56:59], v[140:143], v[192:195], v[56:59]
	v_mfma_f32_16x16x32_bf16 v[44:47], v[132:135], v[208:211], v[44:47]
	v_mfma_f32_16x16x32_bf16 v[40:43], v[140:143], v[208:211], v[40:43]
	v_mfma_f32_16x16x32_bf16 v[28:31], v[132:135], v[220:223], v[28:31]
	v_mfma_f32_16x16x32_bf16 v[24:27], v[140:143], v[220:223], v[24:27]
	v_mfma_f32_16x16x32_bf16 v[12:15], v[132:135], v[228:231], v[12:15]
	v_mfma_f32_16x16x32_bf16 v[8:11], v[140:143], v[228:231], v[8:11]
	v_mfma_f32_16x16x32_bf16 v[60:63], v[136:139], v[204:207], v[60:63]
	v_mfma_f32_16x16x32_bf16 v[56:59], v[144:147], v[204:207], v[56:59]
	v_mfma_f32_16x16x32_bf16 v[44:47], v[136:139], v[216:219], v[44:47]
	v_mfma_f32_16x16x32_bf16 v[40:43], v[144:147], v[216:219], v[40:43]
	v_mfma_f32_16x16x32_bf16 v[28:31], v[136:139], v[224:227], v[28:31]
	v_mfma_f32_16x16x32_bf16 v[24:27], v[144:147], v[224:227], v[24:27]
	v_mfma_f32_16x16x32_bf16 v[12:15], v[136:139], v[232:235], v[12:15]
	v_mfma_f32_16x16x32_bf16 v[8:11], v[144:147], v[232:235], v[8:11]
	v_mfma_f32_16x16x32_bf16 v[52:55], v[148:151], v[192:195], v[52:55]
	v_mfma_f32_16x16x32_bf16 v[48:51], v[184:187], v[192:195], v[48:51]
	v_mfma_f32_16x16x32_bf16 v[36:39], v[148:151], v[208:211], v[36:39]
	v_mfma_f32_16x16x32_bf16 v[32:35], v[184:187], v[208:211], v[32:35]
	v_mfma_f32_16x16x32_bf16 v[20:23], v[148:151], v[220:223], v[20:23]
	v_mfma_f32_16x16x32_bf16 v[16:19], v[184:187], v[220:223], v[16:19]
	v_mfma_f32_16x16x32_bf16 v[4:7], v[148:151], v[228:231], v[4:7]
	v_mfma_f32_16x16x32_bf16 v[0:3], v[184:187], v[228:231], v[0:3]
	v_mfma_f32_16x16x32_bf16 v[52:55], v[180:183], v[204:207], v[52:55]
	v_mfma_f32_16x16x32_bf16 v[48:51], v[188:191], v[204:207], v[48:51]
	v_mfma_f32_16x16x32_bf16 v[36:39], v[180:183], v[216:219], v[36:39]
	v_mfma_f32_16x16x32_bf16 v[32:35], v[188:191], v[216:219], v[32:35]
	v_mfma_f32_16x16x32_bf16 v[20:23], v[180:183], v[224:227], v[20:23]
	v_mfma_f32_16x16x32_bf16 v[16:19], v[188:191], v[224:227], v[16:19]
	v_mfma_f32_16x16x32_bf16 v[4:7], v[180:183], v[232:235], v[4:7]
	v_mfma_f32_16x16x32_bf16 v[0:3], v[188:191], v[232:235], v[0:3]
	v_lshl_add_u64 v[128:129], v[128:129], 0, s[26:27]
	v_lshl_add_u64 v[130:131], v[130:131], 0, s[26:27]
	s_cmp_ge_i32 s12, s47
	s_cbranch_scc1 .Lrot_exit_4
	s_cmp_eq_u32 s48, s12
	v_lshl_add_u64 v[192:193], v[130:131], 0, s[22:23]
	s_cselect_b64 vcc, -1, 0
	s_add_i32 s12, s12, 2
	v_cndmask_b32_e32 v197, v193, v177, vcc
	v_cndmask_b32_e32 v196, v192, v176, vcc
	v_cndmask_b32_e32 v213, v129, v179, vcc
	v_cndmask_b32_e32 v212, v128, v178, vcc
	s_setprio 0
	s_barrier
	s_branch .LBB0_1695
; #define PG8_MMA(ai, bj, At, Bt) do { __builtin_amdgcn_s_setprio(1); _Pragma("unroll") for (int m = 0; m < 4; ++m) _Pragma("unroll") for (int n = 0; n < 2; ++n) _Pragma("unroll") for (int k = 0; k < 2; ++k) \
;         acc[ai][bj][m][n] = __builtin_amdgcn_mfma_f32_16x16x32_bf16(Bt[n][k], At[m][k], acc[ai][bj][m][n], 0, 0, 0); __builtin_amdgcn_s_setprio(0); } while (0)
; #define PG8_WAIT_V(n) asm volatile("s_waitcnt vmcnt(" #n ")" ::: "memory")
; #define PG8_WAIT_L(n) asm volatile("s_waitcnt lgkmcnt(" #n ")" ::: "memory")
; #define PG8_BAR __builtin_amdgcn_s_barrier()
; #define PG8_SCHED __builtin_amdgcn_sched_barrier(0)
; template <class Epi, class Sched, bool ALIGN_EPI = false, bool SP2 = false>
; __device__ __forceinline__ void gemm_phase(PG8_LAS unsigned char* lds, const Gemm g, const Sched& S, const Epi& E) {
;     ...
;             PG8_WAIT_V(8); PG8_WAIT_L(0); PG8_BAR; PG8_MMA(1, 0, At, B0); PG8_MMA(1, 1, At, B1); PG8_BAR; PG8_SCHED;
;     ...
;         if constexpr (ALIGN_EPI) { if (wr == 0) PG8_BAR; }
.Lrot_exit_4:
	s_setprio 0
	s_barrier
.LBB0_1696:
	s_and_b64 vcc, exec, s[24:25]
	s_cbranch_vccz .LBB0_1698
	s_barrier

; template <class Epi, class Sched, bool ALIGN_EPI = false, bool SP2 = false>
; __device__ __forceinline__ void gemm_phase(PG8_LAS unsigned char* lds, const Gemm g, const Sched& S, const Epi& E) {
;     ...
;     for (;;) {
;         const bool has_next = S.next(ui + 1, nxt);
;         const char* nA = has_next ? (const char*)g.A + (size_t)nxt.pm * tstep : cA; const char* nB = has_next ? (const char*)g.Bt + (size_t)nxt.pn * tstep : cB;
;         for (int t = 0; t < nt; t += 2) {
;             const bool last = (t == nt - 2);
;             const char* a1 = cA + (size_t)(t + 1) * kstep;
;             const char* a2 = last ? nA : cA + (size_t)(t + 2) * kstep; const char* b2 = last ? nB : cB + (size_t)(t + 2) * kstep;
;     ...
; #pragma unroll
;         for (int a = 0; a < 2; ++a)
; #pragma unroll
;             for (int b = 0; b < 2; ++b)
; #pragma unroll
;                 for (int m = 0; m < 4; ++m)
; #pragma unroll
;                     for (int n = 0; n < 2; ++n) acc[a][b][m][n] = (f32x4){0.f, 0.f, 0.f, 0.f};
;         cur = nxt; cA = nA; cB = nB; ++ui;
.LBB0_1774:
	v_mov_b32_e32 v127, 0
	s_and_b64 vcc, exec, s[6:7]
	v_mov_b32_e32 v126, v127
	v_mov_b32_e32 v125, v127
	v_mov_b32_e32 v124, v127
	v_mov_b32_e32 v119, v127
	v_mov_b32_e32 v118, v127
	v_mov_b32_e32 v117, v127
	v_mov_b32_e32 v116, v127
	v_mov_b32_e32 v111, v127
	v_mov_b32_e32 v110, v127
	v_mov_b32_e32 v109, v127
	v_mov_b32_e32 v108, v127
	v_mov_b32_e32 v103, v127
	v_mov_b32_e32 v102, v127
	v_mov_b32_e32 v101, v127
	v_mov_b32_e32 v100, v127
	v_mov_b32_e32 v95, v127
	v_mov_b32_e32 v94, v127
	v_mov_b32_e32 v93, v127
	v_mov_b32_e32 v92, v127
	v_mov_b32_e32 v87, v127
	v_mov_b32_e32 v86, v127
	v_mov_b32_e32 v85, v127
	v_mov_b32_e32 v84, v127
	v_mov_b32_e32 v79, v127
	v_mov_b32_e32 v78, v127
	v_mov_b32_e32 v77, v127
	v_mov_b32_e32 v76, v127
	v_mov_b32_e32 v71, v127
	v_mov_b32_e32 v70, v127
	v_mov_b32_e32 v69, v127
	v_mov_b32_e32 v68, v127
	v_mov_b32_e32 v123, v127
	v_mov_b32_e32 v122, v127
	v_mov_b32_e32 v121, v127
	v_mov_b32_e32 v120, v127
	v_mov_b32_e32 v115, v127
	v_mov_b32_e32 v114, v127
	v_mov_b32_e32 v113, v127
	v_mov_b32_e32 v112, v127
	v_mov_b32_e32 v107, v127
	v_mov_b32_e32 v106, v127
	v_mov_b32_e32 v105, v127
	v_mov_b32_e32 v104, v127
	v_mov_b32_e32 v99, v127
	v_mov_b32_e32 v98, v127
	v_mov_b32_e32 v97, v127
	v_mov_b32_e32 v96, v127
	v_mov_b32_e32 v91, v127
	v_mov_b32_e32 v90, v127
	v_mov_b32_e32 v89, v127
	v_mov_b32_e32 v88, v127
	v_mov_b32_e32 v83, v127
	v_mov_b32_e32 v82, v127
	v_mov_b32_e32 v81, v127
	v_mov_b32_e32 v80, v127
	v_mov_b32_e32 v75, v127
	v_mov_b32_e32 v74, v127
	v_mov_b32_e32 v73, v127
	v_mov_b32_e32 v72, v127
	v_mov_b32_e32 v67, v127
	v_mov_b32_e32 v66, v127
	v_mov_b32_e32 v65, v127
	v_mov_b32_e32 v64, v127
	v_mov_b32_e32 v63, v127
	v_mov_b32_e32 v62, v127
	v_mov_b32_e32 v61, v127
	v_mov_b32_e32 v60, v127
	v_mov_b32_e32 v55, v127
	v_mov_b32_e32 v54, v127
	v_mov_b32_e32 v53, v127
	v_mov_b32_e32 v52, v127
	v_mov_b32_e32 v47, v127
	v_mov_b32_e32 v46, v127
	v_mov_b32_e32 v45, v127
	v_mov_b32_e32 v44, v127
	v_mov_b32_e32 v39, v127
	v_mov_b32_e32 v38, v127
	v_mov_b32_e32 v37, v127
	v_mov_b32_e32 v36, v127
	v_mov_b32_e32 v31, v127
	v_mov_b32_e32 v30, v127
	v_mov_b32_e32 v29, v127
	v_mov_b32_e32 v28, v127
	v_mov_b32_e32 v23, v127
	v_mov_b32_e32 v22, v127
	v_mov_b32_e32 v21, v127
	v_mov_b32_e32 v20, v127
	v_mov_b32_e32 v15, v127
	v_mov_b32_e32 v14, v127
	v_mov_b32_e32 v13, v127
	v_mov_b32_e32 v12, v127
	v_mov_b32_e32 v7, v127
	v_mov_b32_e32 v6, v127
	v_mov_b32_e32 v5, v127
	v_mov_b32_e32 v4, v127
	v_mov_b32_e32 v59, v127
	v_mov_b32_e32 v58, v127
	v_mov_b32_e32 v57, v127
	v_mov_b32_e32 v56, v127
	v_mov_b32_e32 v51, v127
	v_mov_b32_e32 v50, v127
	v_mov_b32_e32 v49, v127
	v_mov_b32_e32 v48, v127
	v_mov_b32_e32 v43, v127
	v_mov_b32_e32 v42, v127
	v_mov_b32_e32 v41, v127
	v_mov_b32_e32 v40, v127
	v_mov_b32_e32 v35, v127
	v_mov_b32_e32 v34, v127
	v_mov_b32_e32 v33, v127
	v_mov_b32_e32 v32, v127
	v_mov_b32_e32 v27, v127
	v_mov_b32_e32 v26, v127
	v_mov_b32_e32 v25, v127
	v_mov_b32_e32 v24, v127
	v_mov_b32_e32 v19, v127
	v_mov_b32_e32 v18, v127
	v_mov_b32_e32 v17, v127
	v_mov_b32_e32 v16, v127
	v_mov_b32_e32 v11, v127
	v_mov_b32_e32 v10, v127
	v_mov_b32_e32 v9, v127
	v_mov_b32_e32 v8, v127
	v_mov_b32_e32 v3, v127
	v_mov_b32_e32 v2, v127
	v_mov_b32_e32 v1, v127
	v_mov_b32_e32 v0, v127
	s_cbranch_vccnz .LBB0_1777
	v_mov_b32_e32 v0, 0
	v_lshl_add_u64 v[158:159], v[158:159], 0, s[26:27]
	v_lshl_add_u64 v[160:161], v[160:161], 0, s[22:23]
	s_mov_b32 s10, 0
	v_mov_b32_e32 v1, v0
	v_mov_b32_e32 v2, v0
	v_mov_b32_e32 v3, v0
	v_mov_b32_e32 v8, v0
	v_mov_b32_e32 v9, v0
	v_mov_b32_e32 v10, v0
	v_mov_b32_e32 v11, v0
	v_mov_b32_e32 v16, v0
	v_mov_b32_e32 v17, v0
	v_mov_b32_e32 v18, v0
	v_mov_b32_e32 v19, v0
	v_mov_b32_e32 v24, v0
	v_mov_b32_e32 v25, v0
	v_mov_b32_e32 v26, v0
	v_mov_b32_e32 v27, v0
	v_mov_b32_e32 v32, v0
	v_mov_b32_e32 v33, v0
	v_mov_b32_e32 v34, v0
	v_mov_b32_e32 v35, v0
	v_mov_b32_e32 v40, v0
	v_mov_b32_e32 v41, v0
	v_mov_b32_e32 v42, v0
	v_mov_b32_e32 v43, v0
	v_mov_b32_e32 v48, v0
	v_mov_b32_e32 v49, v0
	v_mov_b32_e32 v50, v0
	v_mov_b32_e32 v51, v0
	v_mov_b32_e32 v56, v0
	v_mov_b32_e32 v57, v0
	v_mov_b32_e32 v58, v0
	v_mov_b32_e32 v59, v0
	v_mov_b32_e32 v4, v0
	v_mov_b32_e32 v5, v0
	v_mov_b32_e32 v6, v0
	v_mov_b32_e32 v7, v0
	v_mov_b32_e32 v12, v0
	v_mov_b32_e32 v13, v0
	v_mov_b32_e32 v14, v0
	v_mov_b32_e32 v15, v0
	v_mov_b32_e32 v20, v0
	v_mov_b32_e32 v21, v0
	v_mov_b32_e32 v22, v0
	v_mov_b32_e32 v23, v0
	v_mov_b32_e32 v28, v0
	v_mov_b32_e32 v29, v0
	v_mov_b32_e32 v30, v0
	v_mov_b32_e32 v31, v0
	v_mov_b32_e32 v36, v0
	v_mov_b32_e32 v37, v0
	v_mov_b32_e32 v38, v0
	v_mov_b32_e32 v39, v0
	v_mov_b32_e32 v44, v0
	v_mov_b32_e32 v45, v0
	v_mov_b32_e32 v46, v0
	v_mov_b32_e32 v47, v0
	v_mov_b32_e32 v52, v0
	v_mov_b32_e32 v53, v0
	v_mov_b32_e32 v54, v0
	v_mov_b32_e32 v55, v0
	v_mov_b32_e32 v60, v0
	v_mov_b32_e32 v61, v0
	v_mov_b32_e32 v62, v0
	v_mov_b32_e32 v63, v0
	v_mov_b32_e32 v64, v0
	v_mov_b32_e32 v65, v0
	v_mov_b32_e32 v66, v0
	v_mov_b32_e32 v67, v0
	v_mov_b32_e32 v72, v0
	v_mov_b32_e32 v73, v0
	v_mov_b32_e32 v74, v0
	v_mov_b32_e32 v75, v0
	v_mov_b32_e32 v80, v0
	v_mov_b32_e32 v81, v0
	v_mov_b32_e32 v82, v0
	v_mov_b32_e32 v83, v0
	v_mov_b32_e32 v88, v0
	v_mov_b32_e32 v89, v0
	v_mov_b32_e32 v90, v0
	v_mov_b32_e32 v91, v0
	v_mov_b32_e32 v96, v0
	v_mov_b32_e32 v97, v0
	v_mov_b32_e32 v98, v0
	v_mov_b32_e32 v99, v0
	v_mov_b32_e32 v104, v0
	v_mov_b32_e32 v105, v0
	v_mov_b32_e32 v106, v0
	v_mov_b32_e32 v107, v0
	v_mov_b32_e32 v112, v0
	v_mov_b32_e32 v113, v0
	v_mov_b32_e32 v114, v0
	v_mov_b32_e32 v115, v0
	v_mov_b32_e32 v120, v0
	v_mov_b32_e32 v121, v0
	v_mov_b32_e32 v122, v0
	v_mov_b32_e32 v123, v0
	v_mov_b32_e32 v68, v0
	v_mov_b32_e32 v69, v0
	v_mov_b32_e32 v70, v0
	v_mov_b32_e32 v71, v0
	v_mov_b32_e32 v76, v0
	v_mov_b32_e32 v77, v0
	v_mov_b32_e32 v78, v0
	v_mov_b32_e32 v79, v0
	v_mov_b32_e32 v84, v0
	v_mov_b32_e32 v85, v0
	v_mov_b32_e32 v86, v0
	v_mov_b32_e32 v87, v0
	v_mov_b32_e32 v92, v0
	v_mov_b32_e32 v93, v0
	v_mov_b32_e32 v94, v0
	v_mov_b32_e32 v95, v0
	v_mov_b32_e32 v100, v0
	v_mov_b32_e32 v101, v0
	v_mov_b32_e32 v102, v0
	v_mov_b32_e32 v103, v0
	v_mov_b32_e32 v108, v0
	v_mov_b32_e32 v109, v0
	v_mov_b32_e32 v110, v0
	v_mov_b32_e32 v111, v0
	v_mov_b32_e32 v116, v0
	v_mov_b32_e32 v117, v0
	v_mov_b32_e32 v118, v0
	v_mov_b32_e32 v119, v0
	v_mov_b32_e32 v124, v0
	v_mov_b32_e32 v125, v0
	v_mov_b32_e32 v126, v0
	v_mov_b32_e32 v127, v0
	s_cmp_eq_u32 s53, s10
	v_lshl_add_u64 v[172:173], v[160:161], 0, s[22:23]
	s_cselect_b64 vcc, -1, 0
	s_add_i32 s10, s10, 2
	v_cndmask_b32_e32 v173, v173, v153, vcc
	v_cndmask_b32_e32 v172, v172, v152, vcc
	v_cndmask_b32_e32 v215, v159, v155, vcc
	v_cndmask_b32_e32 v214, v158, v154, vcc
	.p2align	6
; #define PG8_STAGE(bufoff, gbase, voff) do { _Pragma("unroll") for (int _i = 0; _i < 2; ++_i) \
;         __builtin_amdgcn_global_load_lds((const unsigned*)((const char*)(gbase) + (voff)[_i]), (PG8_LAS unsigned*)(lds + (bufoff) + ldsw + _i * 8192), 16, 0, 0); } while (0)
; #define PG8_LDA(dst, b, h) do { _Pragma("unroll") for (int m = 0; m < 4; ++m) _Pragma("unroll") for (int k = 0; k < 2; ++k) dst[m][k] = *(const PG8_LAS bf16x8*)(lds + PG8_SA(b, h) + aoff + m * 2048 + k * 1024); } while (0)
; #define PG8_LDB(dst, b, h) do { _Pragma("unroll") for (int n = 0; n < 2; ++n) _Pragma("unroll") for (int k = 0; k < 2; ++k) dst[n][k] = *(const PG8_LAS bf16x8*)(lds + PG8_SB(b, h) + boff + n * 2048 + k * 1024); } while (0)
; #define PG8_MMA(ai, bj, At, Bt) do { __builtin_amdgcn_s_setprio(1); _Pragma("unroll") for (int m = 0; m < 4; ++m) _Pragma("unroll") for (int n = 0; n < 2; ++n) _Pragma("unroll") for (int k = 0; k < 2; ++k) \
;         acc[ai][bj][m][n] = __builtin_amdgcn_mfma_f32_16x16x32_bf16(Bt[n][k], At[m][k], acc[ai][bj][m][n], 0, 0, 0); __builtin_amdgcn_s_setprio(0); } while (0)
; #define PG8_WAIT_V(n) asm volatile("s_waitcnt vmcnt(" #n ")" ::: "memory")
; #define PG8_BAR __builtin_amdgcn_s_barrier()
; template <class Epi, class Sched, bool ALIGN_EPI = false, bool SP2 = false>
; __device__ __forceinline__ void gemm_phase(PG8_LAS unsigned char* lds, const Gemm g, const Sched& S, const Epi& E) {
;     ...
;         for (int t = 0; t < nt; t += 2) {
;             const bool last = (t == nt - 2);
;             const char* a1 = cA + (size_t)(t + 1) * kstep;
;             const char* a2 = last ? nA : cA + (size_t)(t + 2) * kstep; const char* b2 = last ? nB : cB + (size_t)(t + 2) * kstep;
;             const char* a3 = a2 + kstep; const char* b3 = b2 + kstep;
;             if (last && has_next) S.a_ready(nxt);
;             if constexpr (SP2) {
;             PG8_LDB(B0, 0, 0); PG8_LDB(B1, 0, 1); PG8_SCHED; PG8_LDA(At, 0, 0); PG8_STAGE(PG8_SA(1, 1), a1 + hstep, voffA);
;             PG8_WAIT_V(8); PG8_WAIT_L(0); PG8_BAR; PG8_MMA(0, 0, At, B0); PG8_MMA(0, 1, At, B1); PG8_BAR; PG8_SCHED;
;             PG8_LDA(At, 0, 1); PG8_STAGE(PG8_SB(0, 0), b2, voffB); PG8_STAGE(PG8_SB(0, 1), b2 + hstep, voffB); PG8_STAGE(PG8_SA(0, 0), a2, voffA);
;             PG8_WAIT_V(8); PG8_WAIT_L(0); PG8_BAR; PG8_MMA(1, 0, At, B0); PG8_MMA(1, 1, At, B1); PG8_BAR; PG8_SCHED;
.LBB0_1776:
	v_add_u32_e32 v166, s54, v169
	v_add_u32_e32 v168, s55, v169
	ds_read_b128 v[162:165], v166
	ds_read_b128 v[182:185], v166 offset:1024
	ds_read_b128 v[186:189], v166 offset:2048
	ds_read_b128 v[190:193], v166 offset:3072
	ds_read_b128 v[194:197], v168
	ds_read_b128 v[198:201], v168 offset:1024
	ds_read_b128 v[202:205], v168 offset:2048
	ds_read_b128 v[206:209], v168 offset:3072
	s_mov_b32 m0, s56
	v_lshl_add_u64 v[244:245], v[160:161], 0, v[148:149]
	ds_read_b128 v[210:213], v179
	ds_read_b128 v[216:219], v179 offset:1024
	ds_read_b128 v[220:223], v179 offset:2048
	ds_read_b128 v[224:227], v179 offset:3072
	ds_read_b128 v[228:231], v179 offset:4096
	ds_read_b128 v[232:235], v179 offset:5120
	ds_read_b128 v[236:239], v179 offset:6144
	ds_read_b128 v[240:243], v179 offset:7168
	global_load_lds_dwordx4 v[244:245], off
	s_mov_b32 m0, s57
	v_lshl_add_u64 v[244:245], v[160:161], 0, v[146:147]
	global_load_lds_dwordx4 v[244:245], off
	s_waitcnt vmcnt(8) lgkmcnt(0)
	s_setprio 1
	s_barrier
	v_mfma_f32_16x16x32_bf16 v[124:127], v[162:165], v[210:213], v[124:127]
	v_mfma_f32_16x16x32_bf16 v[116:119], v[186:189], v[210:213], v[116:119]
	v_mfma_f32_16x16x32_bf16 v[108:111], v[162:165], v[220:223], v[108:111]
	v_mfma_f32_16x16x32_bf16 v[100:103], v[186:189], v[220:223], v[100:103]
	v_mfma_f32_16x16x32_bf16 v[92:95], v[162:165], v[228:231], v[92:95]
	v_mfma_f32_16x16x32_bf16 v[84:87], v[186:189], v[228:231], v[84:87]
	v_mfma_f32_16x16x32_bf16 v[76:79], v[162:165], v[236:239], v[76:79]
	v_mfma_f32_16x16x32_bf16 v[68:71], v[186:189], v[236:239], v[68:71]
	v_mfma_f32_16x16x32_bf16 v[124:127], v[182:185], v[216:219], v[124:127]
	v_mfma_f32_16x16x32_bf16 v[116:119], v[190:193], v[216:219], v[116:119]
	v_mfma_f32_16x16x32_bf16 v[108:111], v[182:185], v[224:227], v[108:111]
	v_mfma_f32_16x16x32_bf16 v[100:103], v[190:193], v[224:227], v[100:103]
	v_mfma_f32_16x16x32_bf16 v[92:95], v[182:185], v[232:235], v[92:95]
	v_mfma_f32_16x16x32_bf16 v[84:87], v[190:193], v[232:235], v[84:87]
	v_mfma_f32_16x16x32_bf16 v[76:79], v[182:185], v[240:243], v[76:79]
	v_mfma_f32_16x16x32_bf16 v[68:71], v[190:193], v[240:243], v[68:71]
	v_mfma_f32_16x16x32_bf16 v[120:123], v[194:197], v[210:213], v[120:123]
	v_mfma_f32_16x16x32_bf16 v[112:115], v[202:205], v[210:213], v[112:115]
	v_mfma_f32_16x16x32_bf16 v[104:107], v[194:197], v[220:223], v[104:107]
	v_mfma_f32_16x16x32_bf16 v[96:99], v[202:205], v[220:223], v[96:99]
	v_mfma_f32_16x16x32_bf16 v[88:91], v[194:197], v[228:231], v[88:91]
	v_mfma_f32_16x16x32_bf16 v[80:83], v[202:205], v[228:231], v[80:83]
	v_mfma_f32_16x16x32_bf16 v[72:75], v[194:197], v[236:239], v[72:75]
	v_mfma_f32_16x16x32_bf16 v[64:67], v[202:205], v[236:239], v[64:67]
	v_mfma_f32_16x16x32_bf16 v[120:123], v[198:201], v[216:219], v[120:123]
	v_mfma_f32_16x16x32_bf16 v[112:115], v[206:209], v[216:219], v[112:115]
	v_mfma_f32_16x16x32_bf16 v[104:107], v[198:201], v[224:227], v[104:107]
	v_mfma_f32_16x16x32_bf16 v[96:99], v[206:209], v[224:227], v[96:99]
	v_mfma_f32_16x16x32_bf16 v[88:91], v[198:201], v[232:235], v[88:91]
	v_mfma_f32_16x16x32_bf16 v[80:83], v[206:209], v[232:235], v[80:83]
	v_mfma_f32_16x16x32_bf16 v[72:75], v[198:201], v[240:243], v[72:75]
	v_mfma_f32_16x16x32_bf16 v[64:67], v[206:209], v[240:243], v[64:67]
	s_setprio 0
	s_barrier
	s_mov_b32 m0, s60
	v_lshl_add_u64 v[244:245], v[214:215], 0, v[138:139]
	ds_read_b128 v[210:213], v179 offset:16384
	ds_read_b128 v[216:219], v179 offset:17408
	ds_read_b128 v[220:223], v179 offset:18432
	ds_read_b128 v[224:227], v179 offset:19456
	ds_read_b128 v[228:231], v179 offset:20480
	ds_read_b128 v[232:235], v179 offset:21504
	ds_read_b128 v[236:239], v179 offset:22528
	ds_read_b128 v[240:243], v179 offset:23552
	global_load_lds_dwordx4 v[244:245], off
	v_lshl_add_u64 v[246:247], v[214:215], 0, v[134:135]
	s_mov_b32 m0, s61
	v_lshl_add_u64 v[214:215], v[214:215], 0, s[14:15]
	global_load_lds_dwordx4 v[246:247], off
	v_lshl_add_u64 v[248:249], v[214:215], 0, v[138:139]
	s_mov_b32 m0, s62
	v_lshl_add_u64 v[214:215], v[214:215], 0, v[134:135]
	global_load_lds_dwordx4 v[248:249], off
	s_add_i32 m0, s62, 0x2000
	v_lshl_add_u64 v[250:251], v[172:173], 0, v[140:141]
	global_load_lds_dwordx4 v[214:215], off
	s_mov_b32 m0, s46
	v_lshl_add_u64 v[252:253], v[172:173], 0, v[136:137]
	global_load_lds_dwordx4 v[250:251], off
	s_mov_b32 m0, s47
	s_nop 0
	global_load_lds_dwordx4 v[252:253], off
	s_waitcnt vmcnt(8) lgkmcnt(0)
	s_setprio 1
	s_barrier
	v_mfma_f32_16x16x32_bf16 v[60:63], v[162:165], v[210:213], v[60:63]
	v_mfma_f32_16x16x32_bf16 v[52:55], v[186:189], v[210:213], v[52:55]
	v_mfma_f32_16x16x32_bf16 v[44:47], v[162:165], v[220:223], v[44:47]
	v_mfma_f32_16x16x32_bf16 v[36:39], v[186:189], v[220:223], v[36:39]
	v_mfma_f32_16x16x32_bf16 v[28:31], v[162:165], v[228:231], v[28:31]
	v_mfma_f32_16x16x32_bf16 v[20:23], v[186:189], v[228:231], v[20:23]
	v_mfma_f32_16x16x32_bf16 v[12:15], v[162:165], v[236:239], v[12:15]
	v_mfma_f32_16x16x32_bf16 v[4:7], v[186:189], v[236:239], v[4:7]
	v_mfma_f32_16x16x32_bf16 v[60:63], v[182:185], v[216:219], v[60:63]
	v_mfma_f32_16x16x32_bf16 v[52:55], v[190:193], v[216:219], v[52:55]
	v_mfma_f32_16x16x32_bf16 v[44:47], v[182:185], v[224:227], v[44:47]
	v_mfma_f32_16x16x32_bf16 v[36:39], v[190:193], v[224:227], v[36:39]
	v_mfma_f32_16x16x32_bf16 v[28:31], v[182:185], v[232:235], v[28:31]
	v_mfma_f32_16x16x32_bf16 v[20:23], v[190:193], v[232:235], v[20:23]
	v_mfma_f32_16x16x32_bf16 v[12:15], v[182:185], v[240:243], v[12:15]
	v_mfma_f32_16x16x32_bf16 v[4:7], v[190:193], v[240:243], v[4:7]
	v_mfma_f32_16x16x32_bf16 v[56:59], v[194:197], v[210:213], v[56:59]
	v_mfma_f32_16x16x32_bf16 v[48:51], v[202:205], v[210:213], v[48:51]
	v_mfma_f32_16x16x32_bf16 v[40:43], v[194:197], v[220:223], v[40:43]
	v_mfma_f32_16x16x32_bf16 v[32:35], v[202:205], v[220:223], v[32:35]
	v_mfma_f32_16x16x32_bf16 v[24:27], v[194:197], v[228:231], v[24:27]
	v_mfma_f32_16x16x32_bf16 v[16:19], v[202:205], v[228:231], v[16:19]
	v_mfma_f32_16x16x32_bf16 v[8:11], v[194:197], v[236:239], v[8:11]
	v_mfma_f32_16x16x32_bf16 v[0:3], v[202:205], v[236:239], v[0:3]
	v_mfma_f32_16x16x32_bf16 v[56:59], v[198:201], v[216:219], v[56:59]
	v_mfma_f32_16x16x32_bf16 v[48:51], v[206:209], v[216:219], v[48:51]
	v_mfma_f32_16x16x32_bf16 v[40:43], v[198:201], v[224:227], v[40:43]
	v_mfma_f32_16x16x32_bf16 v[32:35], v[206:209], v[224:227], v[32:35]
	v_mfma_f32_16x16x32_bf16 v[24:27], v[198:201], v[232:235], v[24:27]
	v_mfma_f32_16x16x32_bf16 v[16:19], v[206:209], v[232:235], v[16:19]
	v_mfma_f32_16x16x32_bf16 v[8:11], v[198:201], v[240:243], v[8:11]
	v_mfma_f32_16x16x32_bf16 v[0:3], v[206:209], v[240:243], v[0:3]
	s_setprio 0
	s_barrier
; #define PG8_STAGE(bufoff, gbase, voff) do { _Pragma("unroll") for (int _i = 0; _i < 2; ++_i) \
;         __builtin_amdgcn_global_load_lds((const unsigned*)((const char*)(gbase) + (voff)[_i]), (PG8_LAS unsigned*)(lds + (bufoff) + ldsw + _i * 8192), 16, 0, 0); } while (0)
; #define PG8_LDA(dst, b, h) do { _Pragma("unroll") for (int m = 0; m < 4; ++m) _Pragma("unroll") for (int k = 0; k < 2; ++k) dst[m][k] = *(const PG8_LAS bf16x8*)(lds + PG8_SA(b, h) + aoff + m * 2048 + k * 1024); } while (0)
; #define PG8_LDB(dst, b, h) do { _Pragma("unroll") for (int n = 0; n < 2; ++n) _Pragma("unroll") for (int k = 0; k < 2; ++k) dst[n][k] = *(const PG8_LAS bf16x8*)(lds + PG8_SB(b, h) + boff + n * 2048 + k * 1024); } while (0)
; #define PG8_MMA(ai, bj, At, Bt) do { __builtin_amdgcn_s_setprio(1); _Pragma("unroll") for (int m = 0; m < 4; ++m) _Pragma("unroll") for (int n = 0; n < 2; ++n) _Pragma("unroll") for (int k = 0; k < 2; ++k) \
;         acc[ai][bj][m][n] = __builtin_amdgcn_mfma_f32_16x16x32_bf16(Bt[n][k], At[m][k], acc[ai][bj][m][n], 0, 0, 0); __builtin_amdgcn_s_setprio(0); } while (0)
; #define PG8_WAIT_V(n) asm volatile("s_waitcnt vmcnt(" #n ")" ::: "memory")
; #define PG8_WAIT_L(n) asm volatile("s_waitcnt lgkmcnt(" #n ")" ::: "memory")
; #define PG8_BAR __builtin_amdgcn_s_barrier()
; #define PG8_SCHED __builtin_amdgcn_sched_barrier(0)
; template <class Epi, class Sched, bool ALIGN_EPI = false, bool SP2 = false>
; __device__ __forceinline__ void gemm_phase(PG8_LAS unsigned char* lds, const Gemm g, const Sched& S, const Epi& E) {
;     ...
;         for (int t = 0; t < nt; t += 2) {
;             const bool last = (t == nt - 2);
;             const char* a1 = cA + (size_t)(t + 1) * kstep;
;             const char* a2 = last ? nA : cA + (size_t)(t + 2) * kstep; const char* b2 = last ? nB : cB + (size_t)(t + 2) * kstep;
;     ...
;             PG8_LDB(B0, 1, 0); PG8_LDB(B1, 1, 1); PG8_SCHED; PG8_LDA(At, 1, 0); PG8_STAGE(PG8_SA(0, 1), a2 + hstep, voffA);
;             PG8_WAIT_V(8); PG8_WAIT_L(0); PG8_BAR; PG8_MMA(0, 0, At, B0); PG8_MMA(0, 1, At, B1); PG8_BAR; PG8_SCHED;
;             PG8_LDA(At, 1, 1); PG8_STAGE(PG8_SB(1, 0), b3, voffB); PG8_STAGE(PG8_SB(1, 1), b3 + hstep, voffB); PG8_STAGE(PG8_SA(1, 0), a3, voffA);
;             PG8_WAIT_V(8); PG8_WAIT_L(0); PG8_BAR; PG8_MMA(1, 0, At, B0); PG8_MMA(1, 1, At, B1); PG8_BAR; PG8_SCHED;
	s_add_i32 s11, 0, 0x18000
	v_add_u32_e32 v166, s11, v169
	s_add_i32 s13, 0, 0x1c000
	ds_read_b128 v[162:165], v166
	ds_read_b128 v[182:185], v166 offset:1024
	ds_read_b128 v[186:189], v166 offset:2048
	ds_read_b128 v[190:193], v166 offset:3072
	v_add_u32_e32 v166, s13, v169
	ds_read_b128 v[194:197], v166
	ds_read_b128 v[198:201], v166 offset:1024
	ds_read_b128 v[202:205], v166 offset:2048
	ds_read_b128 v[206:209], v166 offset:3072
	v_lshl_add_u64 v[172:173], v[172:173], 0, s[14:15]
	s_mov_b32 m0, s48
	v_lshl_add_u64 v[170:171], v[172:173], 0, v[140:141]
	ds_read_b128 v[210:213], v179 offset:32768
	ds_read_b128 v[216:219], v179 offset:33792
	ds_read_b128 v[220:223], v179 offset:34816
	ds_read_b128 v[224:227], v179 offset:35840
	ds_read_b128 v[228:231], v179 offset:36864
	ds_read_b128 v[232:235], v179 offset:37888
	ds_read_b128 v[236:239], v179 offset:38912
	ds_read_b128 v[240:243], v179 offset:39936
	global_load_lds_dwordx4 v[170:171], off
	s_mov_b32 m0, s49
	v_lshl_add_u64 v[170:171], v[172:173], 0, v[136:137]
	global_load_lds_dwordx4 v[170:171], off
	s_waitcnt vmcnt(8) lgkmcnt(0)
	s_setprio 1
	s_barrier
	v_mfma_f32_16x16x32_bf16 v[124:127], v[162:165], v[210:213], v[124:127]
	v_mfma_f32_16x16x32_bf16 v[116:119], v[186:189], v[210:213], v[116:119]
	v_mfma_f32_16x16x32_bf16 v[108:111], v[162:165], v[220:223], v[108:111]
	v_mfma_f32_16x16x32_bf16 v[100:103], v[186:189], v[220:223], v[100:103]
	v_mfma_f32_16x16x32_bf16 v[92:95], v[162:165], v[228:231], v[92:95]
	v_mfma_f32_16x16x32_bf16 v[84:87], v[186:189], v[228:231], v[84:87]
	v_mfma_f32_16x16x32_bf16 v[76:79], v[162:165], v[236:239], v[76:79]
	v_mfma_f32_16x16x32_bf16 v[68:71], v[186:189], v[236:239], v[68:71]
	v_mfma_f32_16x16x32_bf16 v[124:127], v[182:185], v[216:219], v[124:127]
	v_mfma_f32_16x16x32_bf16 v[116:119], v[190:193], v[216:219], v[116:119]
	v_mfma_f32_16x16x32_bf16 v[108:111], v[182:185], v[224:227], v[108:111]
	v_mfma_f32_16x16x32_bf16 v[100:103], v[190:193], v[224:227], v[100:103]
	v_mfma_f32_16x16x32_bf16 v[92:95], v[182:185], v[232:235], v[92:95]
	v_mfma_f32_16x16x32_bf16 v[84:87], v[190:193], v[232:235], v[84:87]
	v_mfma_f32_16x16x32_bf16 v[76:79], v[182:185], v[240:243], v[76:79]
	v_mfma_f32_16x16x32_bf16 v[68:71], v[190:193], v[240:243], v[68:71]
	v_mfma_f32_16x16x32_bf16 v[120:123], v[194:197], v[210:213], v[120:123]
	v_mfma_f32_16x16x32_bf16 v[112:115], v[202:205], v[210:213], v[112:115]
	v_mfma_f32_16x16x32_bf16 v[104:107], v[194:197], v[220:223], v[104:107]
	v_mfma_f32_16x16x32_bf16 v[96:99], v[202:205], v[220:223], v[96:99]
	v_mfma_f32_16x16x32_bf16 v[88:91], v[194:197], v[228:231], v[88:91]
	v_mfma_f32_16x16x32_bf16 v[80:83], v[202:205], v[228:231], v[80:83]
	v_mfma_f32_16x16x32_bf16 v[72:75], v[194:197], v[236:239], v[72:75]
	v_mfma_f32_16x16x32_bf16 v[64:67], v[202:205], v[236:239], v[64:67]
	v_mfma_f32_16x16x32_bf16 v[120:123], v[198:201], v[216:219], v[120:123]
	v_mfma_f32_16x16x32_bf16 v[112:115], v[206:209], v[216:219], v[112:115]
	v_mfma_f32_16x16x32_bf16 v[104:107], v[198:201], v[224:227], v[104:107]
	v_mfma_f32_16x16x32_bf16 v[96:99], v[206:209], v[224:227], v[96:99]
	v_mfma_f32_16x16x32_bf16 v[88:91], v[198:201], v[232:235], v[88:91]
	v_mfma_f32_16x16x32_bf16 v[80:83], v[206:209], v[232:235], v[80:83]
	v_mfma_f32_16x16x32_bf16 v[72:75], v[198:201], v[240:243], v[72:75]
	v_mfma_f32_16x16x32_bf16 v[64:67], v[206:209], v[240:243], v[64:67]
	s_setprio 0
	s_barrier
	s_add_i32 s11, s11, s29
	s_add_i32 m0, s11, 0xffffff80
	ds_read_b128 v[210:213], v179 offset:49152
	ds_read_b128 v[216:219], v179 offset:50176
	ds_read_b128 v[220:223], v179 offset:51200
	ds_read_b128 v[224:227], v179 offset:52224
	global_load_lds_dwordx4 v[244:245], off offset:128
	s_add_i32 m0, s11, 0x1f80
	s_add_i32 s11, s13, s29
	global_load_lds_dwordx4 v[246:247], off offset:128
	s_add_i32 m0, s11, 0xffffff80
	ds_read_b128 v[240:243], v179 offset:56320
	global_load_lds_dwordx4 v[248:249], off offset:128
	s_add_i32 m0, s11, 0x1f80
	ds_read_b128 v[236:239], v179 offset:55296
	global_load_lds_dwordx4 v[214:215], off offset:128
	s_add_i32 m0, s50, 0xffffff80
	ds_read_b128 v[232:235], v179 offset:54272
	global_load_lds_dwordx4 v[250:251], off offset:128
	s_add_i32 m0, s51, 0xffffff80
	ds_read_b128 v[228:231], v179 offset:53248
	global_load_lds_dwordx4 v[252:253], off offset:128
	s_waitcnt vmcnt(8) lgkmcnt(0)
	s_setprio 1
	s_barrier
	v_mfma_f32_16x16x32_bf16 v[60:63], v[162:165], v[210:213], v[60:63]
	v_mfma_f32_16x16x32_bf16 v[52:55], v[186:189], v[210:213], v[52:55]
	v_mfma_f32_16x16x32_bf16 v[44:47], v[162:165], v[220:223], v[44:47]
	v_mfma_f32_16x16x32_bf16 v[36:39], v[186:189], v[220:223], v[36:39]
	v_mfma_f32_16x16x32_bf16 v[28:31], v[162:165], v[228:231], v[28:31]
	v_mfma_f32_16x16x32_bf16 v[20:23], v[186:189], v[228:231], v[20:23]
	v_mfma_f32_16x16x32_bf16 v[12:15], v[162:165], v[236:239], v[12:15]
	v_mfma_f32_16x16x32_bf16 v[4:7], v[186:189], v[236:239], v[4:7]
	v_mfma_f32_16x16x32_bf16 v[60:63], v[182:185], v[216:219], v[60:63]
	v_mfma_f32_16x16x32_bf16 v[52:55], v[190:193], v[216:219], v[52:55]
	v_mfma_f32_16x16x32_bf16 v[44:47], v[182:185], v[224:227], v[44:47]
	v_mfma_f32_16x16x32_bf16 v[36:39], v[190:193], v[224:227], v[36:39]
	v_mfma_f32_16x16x32_bf16 v[28:31], v[182:185], v[232:235], v[28:31]
	v_mfma_f32_16x16x32_bf16 v[20:23], v[190:193], v[232:235], v[20:23]
	v_mfma_f32_16x16x32_bf16 v[12:15], v[182:185], v[240:243], v[12:15]
	v_mfma_f32_16x16x32_bf16 v[4:7], v[190:193], v[240:243], v[4:7]
	v_mfma_f32_16x16x32_bf16 v[56:59], v[194:197], v[210:213], v[56:59]
	v_mfma_f32_16x16x32_bf16 v[48:51], v[202:205], v[210:213], v[48:51]
	v_mfma_f32_16x16x32_bf16 v[40:43], v[194:197], v[220:223], v[40:43]
	v_mfma_f32_16x16x32_bf16 v[32:35], v[202:205], v[220:223], v[32:35]
	v_mfma_f32_16x16x32_bf16 v[24:27], v[194:197], v[228:231], v[24:27]
	v_mfma_f32_16x16x32_bf16 v[16:19], v[202:205], v[228:231], v[16:19]
	v_mfma_f32_16x16x32_bf16 v[8:11], v[194:197], v[236:239], v[8:11]
	v_mfma_f32_16x16x32_bf16 v[0:3], v[202:205], v[236:239], v[0:3]
	v_mfma_f32_16x16x32_bf16 v[56:59], v[198:201], v[216:219], v[56:59]
	v_mfma_f32_16x16x32_bf16 v[48:51], v[206:209], v[216:219], v[48:51]
	v_mfma_f32_16x16x32_bf16 v[40:43], v[198:201], v[224:227], v[40:43]
	v_mfma_f32_16x16x32_bf16 v[32:35], v[206:209], v[224:227], v[32:35]
	v_mfma_f32_16x16x32_bf16 v[24:27], v[198:201], v[232:235], v[24:27]
	v_mfma_f32_16x16x32_bf16 v[16:19], v[206:209], v[232:235], v[16:19]
	v_mfma_f32_16x16x32_bf16 v[8:11], v[198:201], v[240:243], v[8:11]
	v_mfma_f32_16x16x32_bf16 v[0:3], v[206:209], v[240:243], v[0:3]
	v_lshl_add_u64 v[158:159], v[158:159], 0, s[26:27]
	v_lshl_add_u64 v[160:161], v[160:161], 0, s[26:27]
	s_cmp_ge_i32 s10, s52
	s_cbranch_scc1 .Lrot_exit_3
	s_cmp_eq_u32 s53, s10
	v_lshl_add_u64 v[172:173], v[160:161], 0, s[22:23]
	s_cselect_b64 vcc, -1, 0
	s_add_i32 s10, s10, 2
	v_cndmask_b32_e32 v173, v173, v153, vcc
	v_cndmask_b32_e32 v172, v172, v152, vcc
	v_cndmask_b32_e32 v215, v159, v155, vcc
	v_cndmask_b32_e32 v214, v158, v154, vcc
	s_setprio 0
	s_barrier
	s_branch .LBB0_1776
; #define PG8_MMA(ai, bj, At, Bt) do { __builtin_amdgcn_s_setprio(1); _Pragma("unroll") for (int m = 0; m < 4; ++m) _Pragma("unroll") for (int n = 0; n < 2; ++n) _Pragma("unroll") for (int k = 0; k < 2; ++k) \
;         acc[ai][bj][m][n] = __builtin_amdgcn_mfma_f32_16x16x32_bf16(Bt[n][k], At[m][k], acc[ai][bj][m][n], 0, 0, 0); __builtin_amdgcn_s_setprio(0); } while (0)
; #define PG8_WAIT_V(n) asm volatile("s_waitcnt vmcnt(" #n ")" ::: "memory")
; #define PG8_WAIT_L(n) asm volatile("s_waitcnt lgkmcnt(" #n ")" ::: "memory")
; #define PG8_BAR __builtin_amdgcn_s_barrier()
; #define PG8_SCHED __builtin_amdgcn_sched_barrier(0)
; template <class Epi, class Sched, bool ALIGN_EPI = false, bool SP2 = false>
; __device__ __forceinline__ void gemm_phase(PG8_LAS unsigned char* lds, const Gemm g, const Sched& S, const Epi& E) {
;     ...
;             PG8_WAIT_V(8); PG8_WAIT_L(0); PG8_BAR; PG8_MMA(1, 0, At, B0); PG8_MMA(1, 1, At, B1); PG8_BAR; PG8_SCHED;
;     ...
;         if constexpr (ALIGN_EPI) { if (wr == 0) PG8_BAR; }
.Lrot_exit_3:
	s_setprio 0
	s_barrier
.LBB0_1777:
	s_and_b64 vcc, exec, s[24:25]
	s_cbranch_vccz .LBB0_1779
	s_barrier

; #define PG8_MMA(ai, bj, At, Bt) do { __builtin_amdgcn_s_setprio(1); _Pragma("unroll") for (int m = 0; m < 4; ++m) _Pragma("unroll") for (int n = 0; n < 2; ++n) _Pragma("unroll") for (int k = 0; k < 2; ++k) \
;         acc[ai][bj][m][n] = __builtin_amdgcn_mfma_f32_16x16x32_bf16(Bt[n][k], At[m][k], acc[ai][bj][m][n], 0, 0, 0); __builtin_amdgcn_s_setprio(0); } while (0)
; #define PG8_WAIT_V(n) asm volatile("s_waitcnt vmcnt(" #n ")" ::: "memory")
; #define PG8_WAIT_L(n) asm volatile("s_waitcnt lgkmcnt(" #n ")" ::: "memory")
; #define PG8_BAR __builtin_amdgcn_s_barrier()
; #define PG8_SCHED __builtin_amdgcn_sched_barrier(0)
; template <class Epi, class Sched, bool ALIGN_EPI = false, bool SP2 = false>
; __device__ __forceinline__ void gemm_phase(PG8_LAS unsigned char* lds, const Gemm g, const Sched& S, const Epi& E) {
;     ...
;             PG8_WAIT_V(8); PG8_WAIT_L(0); PG8_BAR; PG8_MMA(1, 0, At, B0); PG8_MMA(1, 1, At, B1); PG8_BAR; PG8_SCHED;
;     ...
;         if constexpr (ALIGN_EPI) { if (wr == 0) PG8_BAR; }
.Lrot_exit_2:
	s_setprio 0
	s_barrier
.LBB0_1844:
	s_and_b64 vcc, exec, s[24:25]
	s_cbranch_vccz .LBB0_1846
	s_barrier

; template <class Epi, class Sched, bool ALIGN_EPI = false, bool SP2 = false>
; __device__ __forceinline__ void gemm_phase(PG8_LAS unsigned char* lds, const Gemm g, const Sched& S, const Epi& E) {
;     ...
;     for (;;) {
;         const bool has_next = S.next(ui + 1, nxt);
;         const char* nA = has_next ? (const char*)g.A + (size_t)nxt.pm * tstep : cA; const char* nB = has_next ? (const char*)g.Bt + (size_t)nxt.pn * tstep : cB;
;         for (int t = 0; t < nt; t += 2) {
;             const bool last = (t == nt - 2);
;             const char* a1 = cA + (size_t)(t + 1) * kstep;
;             const char* a2 = last ? nA : cA + (size_t)(t + 2) * kstep; const char* b2 = last ? nB : cB + (size_t)(t + 2) * kstep;
;     ...
; #pragma unroll
;         for (int a = 0; a < 2; ++a)
; #pragma unroll
;             for (int b = 0; b < 2; ++b)
; #pragma unroll
;                 for (int m = 0; m < 4; ++m)
; #pragma unroll
;                     for (int n = 0; n < 2; ++n) acc[a][b][m][n] = (f32x4){0.f, 0.f, 0.f, 0.f};
;         cur = nxt; cA = nA; cB = nB; ++ui;
.LBB0_1922:
	v_mov_b32_e32 v127, 0
	s_and_b64 vcc, exec, s[6:7]
	v_mov_b32_e32 v126, v127
	v_mov_b32_e32 v125, v127
	v_mov_b32_e32 v124, v127
	v_mov_b32_e32 v123, v127
	v_mov_b32_e32 v122, v127
	v_mov_b32_e32 v121, v127
	v_mov_b32_e32 v120, v127
	v_mov_b32_e32 v111, v127
	v_mov_b32_e32 v110, v127
	v_mov_b32_e32 v109, v127
	v_mov_b32_e32 v108, v127
	v_mov_b32_e32 v107, v127
	v_mov_b32_e32 v106, v127
	v_mov_b32_e32 v105, v127
	v_mov_b32_e32 v104, v127
	v_mov_b32_e32 v95, v127
	v_mov_b32_e32 v94, v127
	v_mov_b32_e32 v93, v127
	v_mov_b32_e32 v92, v127
	v_mov_b32_e32 v91, v127
	v_mov_b32_e32 v90, v127
	v_mov_b32_e32 v89, v127
	v_mov_b32_e32 v88, v127
	v_mov_b32_e32 v79, v127
	v_mov_b32_e32 v78, v127
	v_mov_b32_e32 v77, v127
	v_mov_b32_e32 v76, v127
	v_mov_b32_e32 v75, v127
	v_mov_b32_e32 v74, v127
	v_mov_b32_e32 v73, v127
	v_mov_b32_e32 v72, v127
	v_mov_b32_e32 v119, v127
	v_mov_b32_e32 v118, v127
	v_mov_b32_e32 v117, v127
	v_mov_b32_e32 v116, v127
	v_mov_b32_e32 v115, v127
	v_mov_b32_e32 v114, v127
	v_mov_b32_e32 v113, v127
	v_mov_b32_e32 v112, v127
	v_mov_b32_e32 v103, v127
	v_mov_b32_e32 v102, v127
	v_mov_b32_e32 v101, v127
	v_mov_b32_e32 v100, v127
	v_mov_b32_e32 v99, v127
	v_mov_b32_e32 v98, v127
	v_mov_b32_e32 v97, v127
	v_mov_b32_e32 v96, v127
	v_mov_b32_e32 v87, v127
	v_mov_b32_e32 v86, v127
	v_mov_b32_e32 v85, v127
	v_mov_b32_e32 v84, v127
	v_mov_b32_e32 v83, v127
	v_mov_b32_e32 v82, v127
	v_mov_b32_e32 v81, v127
	v_mov_b32_e32 v80, v127
	v_mov_b32_e32 v71, v127
	v_mov_b32_e32 v70, v127
	v_mov_b32_e32 v69, v127
	v_mov_b32_e32 v68, v127
	v_mov_b32_e32 v67, v127
	v_mov_b32_e32 v66, v127
	v_mov_b32_e32 v65, v127
	v_mov_b32_e32 v64, v127
	v_mov_b32_e32 v63, v127
	v_mov_b32_e32 v62, v127
	v_mov_b32_e32 v61, v127
	v_mov_b32_e32 v60, v127
	v_mov_b32_e32 v59, v127
	v_mov_b32_e32 v58, v127
	v_mov_b32_e32 v57, v127
	v_mov_b32_e32 v56, v127
	v_mov_b32_e32 v47, v127
	v_mov_b32_e32 v46, v127
	v_mov_b32_e32 v45, v127
	v_mov_b32_e32 v44, v127
	v_mov_b32_e32 v43, v127
	v_mov_b32_e32 v42, v127
	v_mov_b32_e32 v41, v127
	v_mov_b32_e32 v40, v127
	v_mov_b32_e32 v31, v127
	v_mov_b32_e32 v30, v127
	v_mov_b32_e32 v29, v127
	v_mov_b32_e32 v28, v127
	v_mov_b32_e32 v27, v127
	v_mov_b32_e32 v26, v127
	v_mov_b32_e32 v25, v127
	v_mov_b32_e32 v24, v127
	v_mov_b32_e32 v15, v127
	v_mov_b32_e32 v14, v127
	v_mov_b32_e32 v13, v127
	v_mov_b32_e32 v12, v127
	v_mov_b32_e32 v11, v127
	v_mov_b32_e32 v10, v127
	v_mov_b32_e32 v9, v127
	v_mov_b32_e32 v8, v127
	v_mov_b32_e32 v55, v127
	v_mov_b32_e32 v54, v127
	v_mov_b32_e32 v53, v127
	v_mov_b32_e32 v52, v127
	v_mov_b32_e32 v51, v127
	v_mov_b32_e32 v50, v127
	v_mov_b32_e32 v49, v127
	v_mov_b32_e32 v48, v127
	v_mov_b32_e32 v39, v127
	v_mov_b32_e32 v38, v127
	v_mov_b32_e32 v37, v127
	v_mov_b32_e32 v36, v127
	v_mov_b32_e32 v35, v127
	v_mov_b32_e32 v34, v127
	v_mov_b32_e32 v33, v127
	v_mov_b32_e32 v32, v127
	v_mov_b32_e32 v23, v127
	v_mov_b32_e32 v22, v127
	v_mov_b32_e32 v21, v127
	v_mov_b32_e32 v20, v127
	v_mov_b32_e32 v19, v127
	v_mov_b32_e32 v18, v127
	v_mov_b32_e32 v17, v127
	v_mov_b32_e32 v16, v127
	v_mov_b32_e32 v7, v127
	v_mov_b32_e32 v6, v127
	v_mov_b32_e32 v5, v127
	v_mov_b32_e32 v4, v127
	v_mov_b32_e32 v3, v127
	v_mov_b32_e32 v2, v127
	v_mov_b32_e32 v1, v127
	v_mov_b32_e32 v0, v127
	s_cbranch_vccnz .LBB0_1925
	v_mov_b32_e32 v0, 0
	v_lshl_add_u64 v[154:155], v[154:155], 0, s[28:29]
	v_lshl_add_u64 v[158:159], v[158:159], 0, s[24:25]
	s_mov_b32 s10, 0
	v_mov_b32_e32 v1, v0
	v_mov_b32_e32 v2, v0
	v_mov_b32_e32 v3, v0
	v_mov_b32_e32 v4, v0
	v_mov_b32_e32 v5, v0
	v_mov_b32_e32 v6, v0
	v_mov_b32_e32 v7, v0
	v_mov_b32_e32 v16, v0
	v_mov_b32_e32 v17, v0
	v_mov_b32_e32 v18, v0
	v_mov_b32_e32 v19, v0
	v_mov_b32_e32 v20, v0
	v_mov_b32_e32 v21, v0
	v_mov_b32_e32 v22, v0
	v_mov_b32_e32 v23, v0
	v_mov_b32_e32 v32, v0
	v_mov_b32_e32 v33, v0
	v_mov_b32_e32 v34, v0
	v_mov_b32_e32 v35, v0
	v_mov_b32_e32 v36, v0
	v_mov_b32_e32 v37, v0
	v_mov_b32_e32 v38, v0
	v_mov_b32_e32 v39, v0
	v_mov_b32_e32 v48, v0
	v_mov_b32_e32 v49, v0
	v_mov_b32_e32 v50, v0
	v_mov_b32_e32 v51, v0
	v_mov_b32_e32 v52, v0
	v_mov_b32_e32 v53, v0
	v_mov_b32_e32 v54, v0
	v_mov_b32_e32 v55, v0
	v_mov_b32_e32 v8, v0
	v_mov_b32_e32 v9, v0
	v_mov_b32_e32 v10, v0
	v_mov_b32_e32 v11, v0
	v_mov_b32_e32 v12, v0
	v_mov_b32_e32 v13, v0
	v_mov_b32_e32 v14, v0
	v_mov_b32_e32 v15, v0
	v_mov_b32_e32 v24, v0
	v_mov_b32_e32 v25, v0
	v_mov_b32_e32 v26, v0
	v_mov_b32_e32 v27, v0
	v_mov_b32_e32 v28, v0
	v_mov_b32_e32 v29, v0
	v_mov_b32_e32 v30, v0
	v_mov_b32_e32 v31, v0
	v_mov_b32_e32 v40, v0
	v_mov_b32_e32 v41, v0
	v_mov_b32_e32 v42, v0
	v_mov_b32_e32 v43, v0
	v_mov_b32_e32 v44, v0
	v_mov_b32_e32 v45, v0
	v_mov_b32_e32 v46, v0
	v_mov_b32_e32 v47, v0
	v_mov_b32_e32 v56, v0
	v_mov_b32_e32 v57, v0
	v_mov_b32_e32 v58, v0
	v_mov_b32_e32 v59, v0
	v_mov_b32_e32 v60, v0
	v_mov_b32_e32 v61, v0
	v_mov_b32_e32 v62, v0
	v_mov_b32_e32 v63, v0
	v_mov_b32_e32 v64, v0
	v_mov_b32_e32 v65, v0
	v_mov_b32_e32 v66, v0
	v_mov_b32_e32 v67, v0
	v_mov_b32_e32 v68, v0
	v_mov_b32_e32 v69, v0
	v_mov_b32_e32 v70, v0
	v_mov_b32_e32 v71, v0
	v_mov_b32_e32 v80, v0
	v_mov_b32_e32 v81, v0
	v_mov_b32_e32 v82, v0
	v_mov_b32_e32 v83, v0
	v_mov_b32_e32 v84, v0
	v_mov_b32_e32 v85, v0
	v_mov_b32_e32 v86, v0
	v_mov_b32_e32 v87, v0
	v_mov_b32_e32 v96, v0
	v_mov_b32_e32 v97, v0
	v_mov_b32_e32 v98, v0
	v_mov_b32_e32 v99, v0
	v_mov_b32_e32 v100, v0
	v_mov_b32_e32 v101, v0
	v_mov_b32_e32 v102, v0
	v_mov_b32_e32 v103, v0
	v_mov_b32_e32 v112, v0
	v_mov_b32_e32 v113, v0
	v_mov_b32_e32 v114, v0
	v_mov_b32_e32 v115, v0
	v_mov_b32_e32 v116, v0
	v_mov_b32_e32 v117, v0
	v_mov_b32_e32 v118, v0
	v_mov_b32_e32 v119, v0
	v_mov_b32_e32 v72, v0
	v_mov_b32_e32 v73, v0
	v_mov_b32_e32 v74, v0
	v_mov_b32_e32 v75, v0
	v_mov_b32_e32 v76, v0
	v_mov_b32_e32 v77, v0
	v_mov_b32_e32 v78, v0
	v_mov_b32_e32 v79, v0
	v_mov_b32_e32 v88, v0
	v_mov_b32_e32 v89, v0
	v_mov_b32_e32 v90, v0
	v_mov_b32_e32 v91, v0
	v_mov_b32_e32 v92, v0
	v_mov_b32_e32 v93, v0
	v_mov_b32_e32 v94, v0
	v_mov_b32_e32 v95, v0
	v_mov_b32_e32 v104, v0
	v_mov_b32_e32 v105, v0
	v_mov_b32_e32 v106, v0
	v_mov_b32_e32 v107, v0
	v_mov_b32_e32 v108, v0
	v_mov_b32_e32 v109, v0
	v_mov_b32_e32 v110, v0
	v_mov_b32_e32 v111, v0
	v_mov_b32_e32 v120, v0
	v_mov_b32_e32 v121, v0
	v_mov_b32_e32 v122, v0
	v_mov_b32_e32 v123, v0
	v_mov_b32_e32 v124, v0
	v_mov_b32_e32 v125, v0
	v_mov_b32_e32 v126, v0
	v_mov_b32_e32 v127, v0
	s_cmp_eq_u32 s49, s10
	v_lshl_add_u64 v[196:197], v[158:159], 0, s[24:25]
	s_cselect_b64 vcc, -1, 0
	s_add_i32 s10, s10, 2
	v_cndmask_b32_e32 v213, v197, v151, vcc
	v_cndmask_b32_e32 v212, v196, v150, vcc
	v_cndmask_b32_e32 v215, v155, v153, vcc
	v_cndmask_b32_e32 v214, v154, v152, vcc
	.p2align	6
; #define PG8_STAGE(bufoff, gbase, voff) do { _Pragma("unroll") for (int _i = 0; _i < 2; ++_i) \
;         __builtin_amdgcn_global_load_lds((const unsigned*)((const char*)(gbase) + (voff)[_i]), (PG8_LAS unsigned*)(lds + (bufoff) + ldsw + _i * 8192), 16, 0, 0); } while (0)
; #define PG8_LDA(dst, b, h) do { _Pragma("unroll") for (int m = 0; m < 4; ++m) _Pragma("unroll") for (int k = 0; k < 2; ++k) dst[m][k] = *(const PG8_LAS bf16x8*)(lds + PG8_SA(b, h) + aoff + m * 2048 + k * 1024); } while (0)
; #define PG8_LDB(dst, b, h) do { _Pragma("unroll") for (int n = 0; n < 2; ++n) _Pragma("unroll") for (int k = 0; k < 2; ++k) dst[n][k] = *(const PG8_LAS bf16x8*)(lds + PG8_SB(b, h) + boff + n * 2048 + k * 1024); } while (0)
; #define PG8_MMA(ai, bj, At, Bt) do { __builtin_amdgcn_s_setprio(1); _Pragma("unroll") for (int m = 0; m < 4; ++m) _Pragma("unroll") for (int n = 0; n < 2; ++n) _Pragma("unroll") for (int k = 0; k < 2; ++k) \
;         acc[ai][bj][m][n] = __builtin_amdgcn_mfma_f32_16x16x32_bf16(Bt[n][k], At[m][k], acc[ai][bj][m][n], 0, 0, 0); __builtin_amdgcn_s_setprio(0); } while (0)
; #define PG8_WAIT_V(n) asm volatile("s_waitcnt vmcnt(" #n ")" ::: "memory")
; #define PG8_BAR __builtin_amdgcn_s_barrier()
; template <class Epi, class Sched, bool ALIGN_EPI = false, bool SP2 = false>
; __device__ __forceinline__ void gemm_phase(PG8_LAS unsigned char* lds, const Gemm g, const Sched& S, const Epi& E) {
;     ...
;         for (int t = 0; t < nt; t += 2) {
;             const bool last = (t == nt - 2);
;             const char* a1 = cA + (size_t)(t + 1) * kstep;
;             const char* a2 = last ? nA : cA + (size_t)(t + 2) * kstep; const char* b2 = last ? nB : cB + (size_t)(t + 2) * kstep;
;             const char* a3 = a2 + kstep; const char* b3 = b2 + kstep;
;             if (last && has_next) S.a_ready(nxt);
;             if constexpr (SP2) {
;             PG8_LDB(B0, 0, 0); PG8_LDB(B1, 0, 1); PG8_SCHED; PG8_LDA(At, 0, 0); PG8_STAGE(PG8_SA(1, 1), a1 + hstep, voffA);
;             PG8_WAIT_V(8); PG8_WAIT_L(0); PG8_BAR; PG8_MMA(0, 0, At, B0); PG8_MMA(0, 1, At, B1); PG8_BAR; PG8_SCHED;
;             PG8_LDA(At, 0, 1); PG8_STAGE(PG8_SB(0, 0), b2, voffB); PG8_STAGE(PG8_SB(0, 1), b2 + hstep, voffB); PG8_STAGE(PG8_SA(0, 0), a2, voffA);
;             PG8_WAIT_V(8); PG8_WAIT_L(0); PG8_BAR; PG8_MMA(1, 0, At, B0); PG8_MMA(1, 1, At, B1); PG8_BAR; PG8_SCHED;
.LBB0_1924:
	v_add_u32_e32 v192, s50, v161
	ds_read_b128 v[164:167], v162
	ds_read_b128 v[168:171], v162 offset:1024
	ds_read_b128 v[172:175], v162 offset:2048
	ds_read_b128 v[176:179], v162 offset:3072
	ds_read_b128 v[180:183], v192
	ds_read_b128 v[184:187], v192 offset:1024
	ds_read_b128 v[188:191], v192 offset:2048
	ds_read_b128 v[192:195], v192 offset:3072
	s_mov_b32 m0, s51
	v_lshl_add_u64 v[232:233], v[158:159], 0, v[146:147]
	ds_read_b128 v[196:199], v163
	ds_read_b128 v[200:203], v163 offset:1024
	ds_read_b128 v[204:207], v163 offset:2048
	ds_read_b128 v[208:211], v163 offset:3072
	ds_read_b128 v[216:219], v163 offset:4096
	ds_read_b128 v[220:223], v163 offset:5120
	ds_read_b128 v[224:227], v163 offset:6144
	ds_read_b128 v[228:231], v163 offset:7168
	global_load_lds_dwordx4 v[232:233], off
	s_mov_b32 m0, s52
	v_lshl_add_u64 v[232:233], v[158:159], 0, v[144:145]
	global_load_lds_dwordx4 v[232:233], off
	s_waitcnt vmcnt(8) lgkmcnt(0)
	s_setprio 1
	s_barrier
	v_mfma_f32_16x16x32_bf16 v[124:127], v[164:167], v[196:199], v[124:127]
	v_mfma_f32_16x16x32_bf16 v[120:123], v[172:175], v[196:199], v[120:123]
	v_mfma_f32_16x16x32_bf16 v[108:111], v[164:167], v[204:207], v[108:111]
	v_mfma_f32_16x16x32_bf16 v[104:107], v[172:175], v[204:207], v[104:107]
	v_mfma_f32_16x16x32_bf16 v[92:95], v[164:167], v[216:219], v[92:95]
	v_mfma_f32_16x16x32_bf16 v[88:91], v[172:175], v[216:219], v[88:91]
	v_mfma_f32_16x16x32_bf16 v[76:79], v[164:167], v[224:227], v[76:79]
	v_mfma_f32_16x16x32_bf16 v[72:75], v[172:175], v[224:227], v[72:75]
	v_mfma_f32_16x16x32_bf16 v[124:127], v[168:171], v[200:203], v[124:127]
	v_mfma_f32_16x16x32_bf16 v[120:123], v[176:179], v[200:203], v[120:123]
	v_mfma_f32_16x16x32_bf16 v[108:111], v[168:171], v[208:211], v[108:111]
	v_mfma_f32_16x16x32_bf16 v[104:107], v[176:179], v[208:211], v[104:107]
	v_mfma_f32_16x16x32_bf16 v[92:95], v[168:171], v[220:223], v[92:95]
	v_mfma_f32_16x16x32_bf16 v[88:91], v[176:179], v[220:223], v[88:91]
	v_mfma_f32_16x16x32_bf16 v[76:79], v[168:171], v[228:231], v[76:79]
	v_mfma_f32_16x16x32_bf16 v[72:75], v[176:179], v[228:231], v[72:75]
	v_mfma_f32_16x16x32_bf16 v[116:119], v[180:183], v[196:199], v[116:119]
	v_mfma_f32_16x16x32_bf16 v[112:115], v[188:191], v[196:199], v[112:115]
	v_mfma_f32_16x16x32_bf16 v[100:103], v[180:183], v[204:207], v[100:103]
	v_mfma_f32_16x16x32_bf16 v[96:99], v[188:191], v[204:207], v[96:99]
	v_mfma_f32_16x16x32_bf16 v[84:87], v[180:183], v[216:219], v[84:87]
	v_mfma_f32_16x16x32_bf16 v[80:83], v[188:191], v[216:219], v[80:83]
	v_mfma_f32_16x16x32_bf16 v[68:71], v[180:183], v[224:227], v[68:71]
	v_mfma_f32_16x16x32_bf16 v[64:67], v[188:191], v[224:227], v[64:67]
	v_mfma_f32_16x16x32_bf16 v[116:119], v[184:187], v[200:203], v[116:119]
	v_mfma_f32_16x16x32_bf16 v[112:115], v[192:195], v[200:203], v[112:115]
	v_mfma_f32_16x16x32_bf16 v[100:103], v[184:187], v[208:211], v[100:103]
	v_mfma_f32_16x16x32_bf16 v[96:99], v[192:195], v[208:211], v[96:99]
	v_mfma_f32_16x16x32_bf16 v[84:87], v[184:187], v[220:223], v[84:87]
	v_mfma_f32_16x16x32_bf16 v[80:83], v[192:195], v[220:223], v[80:83]
	v_mfma_f32_16x16x32_bf16 v[68:71], v[184:187], v[228:231], v[68:71]
	v_mfma_f32_16x16x32_bf16 v[64:67], v[192:195], v[228:231], v[64:67]
	s_setprio 0
	s_barrier
	s_mov_b32 m0, s53
	v_lshl_add_u64 v[232:233], v[214:215], 0, v[138:139]
	ds_read_b128 v[196:199], v163 offset:16384
	ds_read_b128 v[200:203], v163 offset:17408
	ds_read_b128 v[204:207], v163 offset:18432
	ds_read_b128 v[208:211], v163 offset:19456
	ds_read_b128 v[216:219], v163 offset:20480
	ds_read_b128 v[220:223], v163 offset:21504
	ds_read_b128 v[224:227], v163 offset:22528
	ds_read_b128 v[228:231], v163 offset:23552
	global_load_lds_dwordx4 v[232:233], off
	v_lshl_add_u64 v[234:235], v[214:215], 0, v[134:135]
	s_mov_b32 m0, s54
	v_lshl_add_u64 v[214:215], v[214:215], 0, s[14:15]
	global_load_lds_dwordx4 v[234:235], off
	v_lshl_add_u64 v[236:237], v[214:215], 0, v[138:139]
	s_mov_b32 m0, s55
	v_lshl_add_u64 v[214:215], v[214:215], 0, v[134:135]
	global_load_lds_dwordx4 v[236:237], off
	s_mov_b32 m0, s56
	v_lshl_add_u64 v[238:239], v[212:213], 0, v[140:141]
	global_load_lds_dwordx4 v[214:215], off
	s_mov_b32 m0, s37
	v_lshl_add_u64 v[240:241], v[212:213], 0, v[136:137]
	global_load_lds_dwordx4 v[238:239], off
	s_mov_b32 m0, s41
	s_nop 0
	global_load_lds_dwordx4 v[240:241], off
	s_waitcnt vmcnt(8) lgkmcnt(0)
	s_setprio 1
	s_barrier
	v_mfma_f32_16x16x32_bf16 v[60:63], v[164:167], v[196:199], v[60:63]
	v_mfma_f32_16x16x32_bf16 v[56:59], v[172:175], v[196:199], v[56:59]
	v_mfma_f32_16x16x32_bf16 v[44:47], v[164:167], v[204:207], v[44:47]
	v_mfma_f32_16x16x32_bf16 v[40:43], v[172:175], v[204:207], v[40:43]
	v_mfma_f32_16x16x32_bf16 v[28:31], v[164:167], v[216:219], v[28:31]
	v_mfma_f32_16x16x32_bf16 v[24:27], v[172:175], v[216:219], v[24:27]
	v_mfma_f32_16x16x32_bf16 v[12:15], v[164:167], v[224:227], v[12:15]
	v_mfma_f32_16x16x32_bf16 v[8:11], v[172:175], v[224:227], v[8:11]
	v_mfma_f32_16x16x32_bf16 v[60:63], v[168:171], v[200:203], v[60:63]
	v_mfma_f32_16x16x32_bf16 v[56:59], v[176:179], v[200:203], v[56:59]
	v_mfma_f32_16x16x32_bf16 v[44:47], v[168:171], v[208:211], v[44:47]
	v_mfma_f32_16x16x32_bf16 v[40:43], v[176:179], v[208:211], v[40:43]
	v_mfma_f32_16x16x32_bf16 v[28:31], v[168:171], v[220:223], v[28:31]
	v_mfma_f32_16x16x32_bf16 v[24:27], v[176:179], v[220:223], v[24:27]
	v_mfma_f32_16x16x32_bf16 v[12:15], v[168:171], v[228:231], v[12:15]
	v_mfma_f32_16x16x32_bf16 v[8:11], v[176:179], v[228:231], v[8:11]
	v_mfma_f32_16x16x32_bf16 v[52:55], v[180:183], v[196:199], v[52:55]
	v_mfma_f32_16x16x32_bf16 v[48:51], v[188:191], v[196:199], v[48:51]
	v_mfma_f32_16x16x32_bf16 v[36:39], v[180:183], v[204:207], v[36:39]
	v_mfma_f32_16x16x32_bf16 v[32:35], v[188:191], v[204:207], v[32:35]
	v_mfma_f32_16x16x32_bf16 v[20:23], v[180:183], v[216:219], v[20:23]
	v_mfma_f32_16x16x32_bf16 v[16:19], v[188:191], v[216:219], v[16:19]
	v_mfma_f32_16x16x32_bf16 v[4:7], v[180:183], v[224:227], v[4:7]
	v_mfma_f32_16x16x32_bf16 v[0:3], v[188:191], v[224:227], v[0:3]
	v_mfma_f32_16x16x32_bf16 v[52:55], v[184:187], v[200:203], v[52:55]
	v_mfma_f32_16x16x32_bf16 v[48:51], v[192:195], v[200:203], v[48:51]
	v_mfma_f32_16x16x32_bf16 v[36:39], v[184:187], v[208:211], v[36:39]
	v_mfma_f32_16x16x32_bf16 v[32:35], v[192:195], v[208:211], v[32:35]
	v_mfma_f32_16x16x32_bf16 v[20:23], v[184:187], v[220:223], v[20:23]
	v_mfma_f32_16x16x32_bf16 v[16:19], v[192:195], v[220:223], v[16:19]
	v_mfma_f32_16x16x32_bf16 v[4:7], v[184:187], v[228:231], v[4:7]
	v_mfma_f32_16x16x32_bf16 v[0:3], v[192:195], v[228:231], v[0:3]
	s_setprio 0
	s_barrier
; #define PG8_STAGE(bufoff, gbase, voff) do { _Pragma("unroll") for (int _i = 0; _i < 2; ++_i) \
;         __builtin_amdgcn_global_load_lds((const unsigned*)((const char*)(gbase) + (voff)[_i]), (PG8_LAS unsigned*)(lds + (bufoff) + ldsw + _i * 8192), 16, 0, 0); } while (0)
; #define PG8_LDA(dst, b, h) do { _Pragma("unroll") for (int m = 0; m < 4; ++m) _Pragma("unroll") for (int k = 0; k < 2; ++k) dst[m][k] = *(const PG8_LAS bf16x8*)(lds + PG8_SA(b, h) + aoff + m * 2048 + k * 1024); } while (0)
; #define PG8_LDB(dst, b, h) do { _Pragma("unroll") for (int n = 0; n < 2; ++n) _Pragma("unroll") for (int k = 0; k < 2; ++k) dst[n][k] = *(const PG8_LAS bf16x8*)(lds + PG8_SB(b, h) + boff + n * 2048 + k * 1024); } while (0)
; #define PG8_MMA(ai, bj, At, Bt) do { __builtin_amdgcn_s_setprio(1); _Pragma("unroll") for (int m = 0; m < 4; ++m) _Pragma("unroll") for (int n = 0; n < 2; ++n) _Pragma("unroll") for (int k = 0; k < 2; ++k) \
;         acc[ai][bj][m][n] = __builtin_amdgcn_mfma_f32_16x16x32_bf16(Bt[n][k], At[m][k], acc[ai][bj][m][n], 0, 0, 0); __builtin_amdgcn_s_setprio(0); } while (0)
; #define PG8_WAIT_V(n) asm volatile("s_waitcnt vmcnt(" #n ")" ::: "memory")
; #define PG8_WAIT_L(n) asm volatile("s_waitcnt lgkmcnt(" #n ")" ::: "memory")
; #define PG8_BAR __builtin_amdgcn_s_barrier()
; #define PG8_SCHED __builtin_amdgcn_sched_barrier(0)
; template <class Epi, class Sched, bool ALIGN_EPI = false, bool SP2 = false>
; __device__ __forceinline__ void gemm_phase(PG8_LAS unsigned char* lds, const Gemm g, const Sched& S, const Epi& E) {
;     ...
;         for (int t = 0; t < nt; t += 2) {
;             const bool last = (t == nt - 2);
;             const char* a1 = cA + (size_t)(t + 1) * kstep;
;             const char* a2 = last ? nA : cA + (size_t)(t + 2) * kstep; const char* b2 = last ? nB : cB + (size_t)(t + 2) * kstep;
;     ...
;             PG8_LDB(B0, 1, 0); PG8_LDB(B1, 1, 1); PG8_SCHED; PG8_LDA(At, 1, 0); PG8_STAGE(PG8_SA(0, 1), a2 + hstep, voffA);
;             PG8_WAIT_V(8); PG8_WAIT_L(0); PG8_BAR; PG8_MMA(0, 0, At, B0); PG8_MMA(0, 1, At, B1); PG8_BAR; PG8_SCHED;
;             PG8_LDA(At, 1, 1); PG8_STAGE(PG8_SB(1, 0), b3, voffB); PG8_STAGE(PG8_SB(1, 1), b3 + hstep, voffB); PG8_STAGE(PG8_SA(1, 0), a3, voffA);
;             PG8_WAIT_V(8); PG8_WAIT_L(0); PG8_BAR; PG8_MMA(1, 0, At, B0); PG8_MMA(1, 1, At, B1); PG8_BAR; PG8_SCHED;
	v_add_u32_e32 v176, s57, v161
	v_add_u32_e32 v192, s58, v161
	ds_read_b128 v[164:167], v176
	ds_read_b128 v[168:171], v176 offset:1024
	ds_read_b128 v[172:175], v176 offset:2048
	ds_read_b128 v[176:179], v176 offset:3072
	ds_read_b128 v[180:183], v192
	ds_read_b128 v[184:187], v192 offset:1024
	ds_read_b128 v[188:191], v192 offset:2048
	ds_read_b128 v[192:195], v192 offset:3072
	v_lshl_add_u64 v[212:213], v[212:213], 0, s[14:15]
	s_mov_b32 m0, s44
	v_lshl_add_u64 v[242:243], v[212:213], 0, v[140:141]
	ds_read_b128 v[196:199], v163 offset:32768
	ds_read_b128 v[200:203], v163 offset:33792
	ds_read_b128 v[204:207], v163 offset:34816
	ds_read_b128 v[208:211], v163 offset:35840
	ds_read_b128 v[216:219], v163 offset:36864
	ds_read_b128 v[220:223], v163 offset:37888
	ds_read_b128 v[224:227], v163 offset:38912
	ds_read_b128 v[228:231], v163 offset:39936
	global_load_lds_dwordx4 v[242:243], off
	s_mov_b32 m0, s45
	v_lshl_add_u64 v[212:213], v[212:213], 0, v[136:137]
	global_load_lds_dwordx4 v[212:213], off
	s_waitcnt vmcnt(8) lgkmcnt(0)
	s_setprio 1
	s_barrier
	v_mfma_f32_16x16x32_bf16 v[124:127], v[164:167], v[196:199], v[124:127]
	v_mfma_f32_16x16x32_bf16 v[120:123], v[172:175], v[196:199], v[120:123]
	v_mfma_f32_16x16x32_bf16 v[108:111], v[164:167], v[204:207], v[108:111]
	v_mfma_f32_16x16x32_bf16 v[104:107], v[172:175], v[204:207], v[104:107]
	v_mfma_f32_16x16x32_bf16 v[92:95], v[164:167], v[216:219], v[92:95]
	v_mfma_f32_16x16x32_bf16 v[88:91], v[172:175], v[216:219], v[88:91]
	v_mfma_f32_16x16x32_bf16 v[76:79], v[164:167], v[224:227], v[76:79]
	v_mfma_f32_16x16x32_bf16 v[72:75], v[172:175], v[224:227], v[72:75]
	v_mfma_f32_16x16x32_bf16 v[124:127], v[168:171], v[200:203], v[124:127]
	v_mfma_f32_16x16x32_bf16 v[120:123], v[176:179], v[200:203], v[120:123]
	v_mfma_f32_16x16x32_bf16 v[108:111], v[168:171], v[208:211], v[108:111]
	v_mfma_f32_16x16x32_bf16 v[104:107], v[176:179], v[208:211], v[104:107]
	v_mfma_f32_16x16x32_bf16 v[92:95], v[168:171], v[220:223], v[92:95]
	v_mfma_f32_16x16x32_bf16 v[88:91], v[176:179], v[220:223], v[88:91]
	v_mfma_f32_16x16x32_bf16 v[76:79], v[168:171], v[228:231], v[76:79]
	v_mfma_f32_16x16x32_bf16 v[72:75], v[176:179], v[228:231], v[72:75]
	v_mfma_f32_16x16x32_bf16 v[116:119], v[180:183], v[196:199], v[116:119]
	v_mfma_f32_16x16x32_bf16 v[112:115], v[188:191], v[196:199], v[112:115]
	v_mfma_f32_16x16x32_bf16 v[100:103], v[180:183], v[204:207], v[100:103]
	v_mfma_f32_16x16x32_bf16 v[96:99], v[188:191], v[204:207], v[96:99]
	v_mfma_f32_16x16x32_bf16 v[84:87], v[180:183], v[216:219], v[84:87]
	v_mfma_f32_16x16x32_bf16 v[80:83], v[188:191], v[216:219], v[80:83]
	v_mfma_f32_16x16x32_bf16 v[68:71], v[180:183], v[224:227], v[68:71]
	v_mfma_f32_16x16x32_bf16 v[64:67], v[188:191], v[224:227], v[64:67]
	v_mfma_f32_16x16x32_bf16 v[116:119], v[184:187], v[200:203], v[116:119]
	v_mfma_f32_16x16x32_bf16 v[112:115], v[192:195], v[200:203], v[112:115]
	v_mfma_f32_16x16x32_bf16 v[100:103], v[184:187], v[208:211], v[100:103]
	v_mfma_f32_16x16x32_bf16 v[96:99], v[192:195], v[208:211], v[96:99]
	v_mfma_f32_16x16x32_bf16 v[84:87], v[184:187], v[220:223], v[84:87]
	v_mfma_f32_16x16x32_bf16 v[80:83], v[192:195], v[220:223], v[80:83]
	v_mfma_f32_16x16x32_bf16 v[68:71], v[184:187], v[228:231], v[68:71]
	v_mfma_f32_16x16x32_bf16 v[64:67], v[192:195], v[228:231], v[64:67]
	s_setprio 0
	s_barrier
	s_add_i32 m0, s59, 0xffffff80
	ds_read_b128 v[196:199], v163 offset:49152
	ds_read_b128 v[200:203], v163 offset:50176
	ds_read_b128 v[204:207], v163 offset:51200
	global_load_lds_dwordx4 v[232:233], off offset:128
	s_add_i32 m0, s60, 0xffffff80
	ds_read_b128 v[228:231], v163 offset:56320
	global_load_lds_dwordx4 v[234:235], off offset:128
	s_add_i32 m0, s61, 0xffffff80
	ds_read_b128 v[224:227], v163 offset:55296
	global_load_lds_dwordx4 v[236:237], off offset:128
	s_add_i32 m0, s62, 0xffffff80
	ds_read_b128 v[220:223], v163 offset:54272
	global_load_lds_dwordx4 v[214:215], off offset:128
	s_add_i32 m0, s46, 0xffffff80
	ds_read_b128 v[216:219], v163 offset:53248
	global_load_lds_dwordx4 v[238:239], off offset:128
	s_add_i32 m0, s47, 0xffffff80
	ds_read_b128 v[208:211], v163 offset:52224
	global_load_lds_dwordx4 v[240:241], off offset:128
	s_waitcnt vmcnt(8) lgkmcnt(0)
	s_setprio 1
	s_barrier
	v_mfma_f32_16x16x32_bf16 v[60:63], v[164:167], v[196:199], v[60:63]
	v_mfma_f32_16x16x32_bf16 v[56:59], v[172:175], v[196:199], v[56:59]
	v_mfma_f32_16x16x32_bf16 v[44:47], v[164:167], v[204:207], v[44:47]
	v_mfma_f32_16x16x32_bf16 v[40:43], v[172:175], v[204:207], v[40:43]
	v_mfma_f32_16x16x32_bf16 v[28:31], v[164:167], v[216:219], v[28:31]
	v_mfma_f32_16x16x32_bf16 v[24:27], v[172:175], v[216:219], v[24:27]
	v_mfma_f32_16x16x32_bf16 v[12:15], v[164:167], v[224:227], v[12:15]
	v_mfma_f32_16x16x32_bf16 v[8:11], v[172:175], v[224:227], v[8:11]
	v_mfma_f32_16x16x32_bf16 v[60:63], v[168:171], v[200:203], v[60:63]
	v_mfma_f32_16x16x32_bf16 v[56:59], v[176:179], v[200:203], v[56:59]
	v_mfma_f32_16x16x32_bf16 v[44:47], v[168:171], v[208:211], v[44:47]
	v_mfma_f32_16x16x32_bf16 v[40:43], v[176:179], v[208:211], v[40:43]
	v_mfma_f32_16x16x32_bf16 v[28:31], v[168:171], v[220:223], v[28:31]
	v_mfma_f32_16x16x32_bf16 v[24:27], v[176:179], v[220:223], v[24:27]
	v_mfma_f32_16x16x32_bf16 v[12:15], v[168:171], v[228:231], v[12:15]
	v_mfma_f32_16x16x32_bf16 v[8:11], v[176:179], v[228:231], v[8:11]
	v_mfma_f32_16x16x32_bf16 v[52:55], v[180:183], v[196:199], v[52:55]
	v_mfma_f32_16x16x32_bf16 v[48:51], v[188:191], v[196:199], v[48:51]
	v_mfma_f32_16x16x32_bf16 v[36:39], v[180:183], v[204:207], v[36:39]
	v_mfma_f32_16x16x32_bf16 v[32:35], v[188:191], v[204:207], v[32:35]
	v_mfma_f32_16x16x32_bf16 v[20:23], v[180:183], v[216:219], v[20:23]
	v_mfma_f32_16x16x32_bf16 v[16:19], v[188:191], v[216:219], v[16:19]
	v_mfma_f32_16x16x32_bf16 v[4:7], v[180:183], v[224:227], v[4:7]
	v_mfma_f32_16x16x32_bf16 v[0:3], v[188:191], v[224:227], v[0:3]
	v_mfma_f32_16x16x32_bf16 v[52:55], v[184:187], v[200:203], v[52:55]
	v_mfma_f32_16x16x32_bf16 v[48:51], v[192:195], v[200:203], v[48:51]
	v_mfma_f32_16x16x32_bf16 v[36:39], v[184:187], v[208:211], v[36:39]
	v_mfma_f32_16x16x32_bf16 v[32:35], v[192:195], v[208:211], v[32:35]
	v_mfma_f32_16x16x32_bf16 v[20:23], v[184:187], v[220:223], v[20:23]
	v_mfma_f32_16x16x32_bf16 v[16:19], v[192:195], v[220:223], v[16:19]
	v_mfma_f32_16x16x32_bf16 v[4:7], v[184:187], v[228:231], v[4:7]
	v_mfma_f32_16x16x32_bf16 v[0:3], v[192:195], v[228:231], v[0:3]
	v_lshl_add_u64 v[154:155], v[154:155], 0, s[28:29]
	v_lshl_add_u64 v[158:159], v[158:159], 0, s[28:29]
	s_cmp_ge_i32 s10, s48
	s_cbranch_scc1 .Lrot_exit_1
	s_cmp_eq_u32 s49, s10
	v_lshl_add_u64 v[196:197], v[158:159], 0, s[24:25]
	s_cselect_b64 vcc, -1, 0
	s_add_i32 s10, s10, 2
	v_cndmask_b32_e32 v213, v197, v151, vcc
	v_cndmask_b32_e32 v212, v196, v150, vcc
	v_cndmask_b32_e32 v215, v155, v153, vcc
	v_cndmask_b32_e32 v214, v154, v152, vcc
	s_setprio 0
	s_barrier
	s_branch .LBB0_1924
; #define PG8_MMA(ai, bj, At, Bt) do { __builtin_amdgcn_s_setprio(1); _Pragma("unroll") for (int m = 0; m < 4; ++m) _Pragma("unroll") for (int n = 0; n < 2; ++n) _Pragma("unroll") for (int k = 0; k < 2; ++k) \
;         acc[ai][bj][m][n] = __builtin_amdgcn_mfma_f32_16x16x32_bf16(Bt[n][k], At[m][k], acc[ai][bj][m][n], 0, 0, 0); __builtin_amdgcn_s_setprio(0); } while (0)
; #define PG8_WAIT_V(n) asm volatile("s_waitcnt vmcnt(" #n ")" ::: "memory")
; #define PG8_WAIT_L(n) asm volatile("s_waitcnt lgkmcnt(" #n ")" ::: "memory")
; #define PG8_BAR __builtin_amdgcn_s_barrier()
; #define PG8_SCHED __builtin_amdgcn_sched_barrier(0)
; template <class Epi, class Sched, bool ALIGN_EPI = false, bool SP2 = false>
; __device__ __forceinline__ void gemm_phase(PG8_LAS unsigned char* lds, const Gemm g, const Sched& S, const Epi& E) {
;     ...
;             PG8_WAIT_V(8); PG8_WAIT_L(0); PG8_BAR; PG8_MMA(1, 0, At, B0); PG8_MMA(1, 1, At, B1); PG8_BAR; PG8_SCHED;
;     ...
;         if constexpr (ALIGN_EPI) { if (wr == 0) PG8_BAR; }
.Lrot_exit_1:
	s_setprio 0
	s_barrier
.LBB0_1925:
	s_and_b64 vcc, exec, s[26:27]
	s_cbranch_vccz .LBB0_1927
	s_barrier

; template <class Epi, class Sched, bool ALIGN_EPI = false, bool SP2 = false>
; __device__ __forceinline__ void gemm_phase(PG8_LAS unsigned char* lds, const Gemm g, const Sched& S, const Epi& E) {
;     ...
;     for (;;) {
;         const bool has_next = S.next(ui + 1, nxt);
;         const char* nA = has_next ? (const char*)g.A + (size_t)nxt.pm * tstep : cA; const char* nB = has_next ? (const char*)g.Bt + (size_t)nxt.pn * tstep : cB;
;         for (int t = 0; t < nt; t += 2) {
;             const bool last = (t == nt - 2);
;             const char* a1 = cA + (size_t)(t + 1) * kstep;
;             const char* a2 = last ? nA : cA + (size_t)(t + 2) * kstep; const char* b2 = last ? nB : cB + (size_t)(t + 2) * kstep;
;     ...
; #pragma unroll
;         for (int a = 0; a < 2; ++a)
; #pragma unroll
;             for (int b = 0; b < 2; ++b)
; #pragma unroll
;                 for (int m = 0; m < 4; ++m)
; #pragma unroll
;                     for (int n = 0; n < 2; ++n) acc[a][b][m][n] = (f32x4){0.f, 0.f, 0.f, 0.f};
;         cur = nxt; cA = nA; cB = nB; ++ui;
.LBB0_1945:
	v_mov_b32_e32 v133, 0
	s_andn2_b64 vcc, exec, s[22:23]
	v_mov_b32_e32 v132, v133
	v_mov_b32_e32 v131, v133
	v_mov_b32_e32 v130, v133
	v_mov_b32_e32 v129, v133
	v_mov_b32_e32 v128, v133
	v_mov_b32_e32 v127, v133
	v_mov_b32_e32 v126, v133
	v_mov_b32_e32 v117, v133
	v_mov_b32_e32 v116, v133
	v_mov_b32_e32 v115, v133
	v_mov_b32_e32 v114, v133
	v_mov_b32_e32 v113, v133
	v_mov_b32_e32 v112, v133
	v_mov_b32_e32 v111, v133
	v_mov_b32_e32 v110, v133
	v_mov_b32_e32 v101, v133
	v_mov_b32_e32 v100, v133
	v_mov_b32_e32 v99, v133
	v_mov_b32_e32 v98, v133
	v_mov_b32_e32 v97, v133
	v_mov_b32_e32 v96, v133
	v_mov_b32_e32 v95, v133
	v_mov_b32_e32 v94, v133
	v_mov_b32_e32 v85, v133
	v_mov_b32_e32 v84, v133
	v_mov_b32_e32 v83, v133
	v_mov_b32_e32 v82, v133
	v_mov_b32_e32 v81, v133
	v_mov_b32_e32 v80, v133
	v_mov_b32_e32 v79, v133
	v_mov_b32_e32 v78, v133
	v_mov_b32_e32 v125, v133
	v_mov_b32_e32 v124, v133
	v_mov_b32_e32 v123, v133
	v_mov_b32_e32 v122, v133
	v_mov_b32_e32 v121, v133
	v_mov_b32_e32 v120, v133
	v_mov_b32_e32 v119, v133
	v_mov_b32_e32 v118, v133
	v_mov_b32_e32 v109, v133
	v_mov_b32_e32 v108, v133
	v_mov_b32_e32 v107, v133
	v_mov_b32_e32 v106, v133
	v_mov_b32_e32 v105, v133
	v_mov_b32_e32 v104, v133
	v_mov_b32_e32 v103, v133
	v_mov_b32_e32 v102, v133
	v_mov_b32_e32 v93, v133
	v_mov_b32_e32 v92, v133
	v_mov_b32_e32 v91, v133
	v_mov_b32_e32 v90, v133
	v_mov_b32_e32 v89, v133
	v_mov_b32_e32 v88, v133
	v_mov_b32_e32 v87, v133
	v_mov_b32_e32 v86, v133
	v_mov_b32_e32 v77, v133
	v_mov_b32_e32 v76, v133
	v_mov_b32_e32 v75, v133
	v_mov_b32_e32 v74, v133
	v_mov_b32_e32 v73, v133
	v_mov_b32_e32 v72, v133
	v_mov_b32_e32 v71, v133
	v_mov_b32_e32 v70, v133
	v_mov_b32_e32 v69, v133
	v_mov_b32_e32 v68, v133
	v_mov_b32_e32 v67, v133
	v_mov_b32_e32 v66, v133
	v_mov_b32_e32 v65, v133
	v_mov_b32_e32 v64, v133
	v_mov_b32_e32 v63, v133
	v_mov_b32_e32 v62, v133
	v_mov_b32_e32 v53, v133
	v_mov_b32_e32 v52, v133
	v_mov_b32_e32 v51, v133
	v_mov_b32_e32 v50, v133
	v_mov_b32_e32 v49, v133
	v_mov_b32_e32 v48, v133
	v_mov_b32_e32 v47, v133
	v_mov_b32_e32 v46, v133
	v_mov_b32_e32 v37, v133
	v_mov_b32_e32 v36, v133
	v_mov_b32_e32 v35, v133
	v_mov_b32_e32 v34, v133
	v_mov_b32_e32 v33, v133
	v_mov_b32_e32 v32, v133
	v_mov_b32_e32 v31, v133
	v_mov_b32_e32 v30, v133
	v_mov_b32_e32 v21, v133
	v_mov_b32_e32 v20, v133
	v_mov_b32_e32 v19, v133
	v_mov_b32_e32 v18, v133
	v_mov_b32_e32 v17, v133
	v_mov_b32_e32 v16, v133
	v_mov_b32_e32 v15, v133
	v_mov_b32_e32 v14, v133
	v_mov_b32_e32 v61, v133
	v_mov_b32_e32 v60, v133
	v_mov_b32_e32 v59, v133
	v_mov_b32_e32 v58, v133
	v_mov_b32_e32 v57, v133
	v_mov_b32_e32 v56, v133
	v_mov_b32_e32 v55, v133
	v_mov_b32_e32 v54, v133
	v_mov_b32_e32 v45, v133
	v_mov_b32_e32 v44, v133
	v_mov_b32_e32 v43, v133
	v_mov_b32_e32 v42, v133
	v_mov_b32_e32 v41, v133
	v_mov_b32_e32 v40, v133
	v_mov_b32_e32 v39, v133
	v_mov_b32_e32 v38, v133
	v_mov_b32_e32 v29, v133
	v_mov_b32_e32 v28, v133
	v_mov_b32_e32 v27, v133
	v_mov_b32_e32 v26, v133
	v_mov_b32_e32 v25, v133
	v_mov_b32_e32 v24, v133
	v_mov_b32_e32 v23, v133
	v_mov_b32_e32 v22, v133
	v_mov_b32_e32 v13, v133
	v_mov_b32_e32 v12, v133
	v_mov_b32_e32 v11, v133
	v_mov_b32_e32 v10, v133
	v_mov_b32_e32 v9, v133
	v_mov_b32_e32 v8, v133
	s_waitcnt lgkmcnt(0)
	v_mov_b32_e32 v7, v133
	v_mov_b32_e32 v6, v133
	s_cbranch_vccnz .LBB0_1948
	v_mov_b32_e32 v6, 0
	v_lshl_add_u64 v[134:135], v[134:135], 0, s[26:27]
	v_lshl_add_u64 v[136:137], v[136:137], 0, s[20:21]
	s_mov_b32 s10, 0
	v_mov_b32_e32 v7, v6
	v_mov_b32_e32 v8, v6
	v_mov_b32_e32 v9, v6
	v_mov_b32_e32 v10, v6
	v_mov_b32_e32 v11, v6
	v_mov_b32_e32 v12, v6
	v_mov_b32_e32 v13, v6
	v_mov_b32_e32 v22, v6
	v_mov_b32_e32 v23, v6
	v_mov_b32_e32 v24, v6
	v_mov_b32_e32 v25, v6
	v_mov_b32_e32 v26, v6
	v_mov_b32_e32 v27, v6
	v_mov_b32_e32 v28, v6
	v_mov_b32_e32 v29, v6
	v_mov_b32_e32 v38, v6
	v_mov_b32_e32 v39, v6
	v_mov_b32_e32 v40, v6
	v_mov_b32_e32 v41, v6
	v_mov_b32_e32 v42, v6
	v_mov_b32_e32 v43, v6
	v_mov_b32_e32 v44, v6
	v_mov_b32_e32 v45, v6
	v_mov_b32_e32 v54, v6
	v_mov_b32_e32 v55, v6
	v_mov_b32_e32 v56, v6
	v_mov_b32_e32 v57, v6
	v_mov_b32_e32 v58, v6
	v_mov_b32_e32 v59, v6
	v_mov_b32_e32 v60, v6
	v_mov_b32_e32 v61, v6
	v_mov_b32_e32 v14, v6
	v_mov_b32_e32 v15, v6
	v_mov_b32_e32 v16, v6
	v_mov_b32_e32 v17, v6
	v_mov_b32_e32 v18, v6
	v_mov_b32_e32 v19, v6
	v_mov_b32_e32 v20, v6
	v_mov_b32_e32 v21, v6
	v_mov_b32_e32 v30, v6
	v_mov_b32_e32 v31, v6
	v_mov_b32_e32 v32, v6
	v_mov_b32_e32 v33, v6
	v_mov_b32_e32 v34, v6
	v_mov_b32_e32 v35, v6
	v_mov_b32_e32 v36, v6
	v_mov_b32_e32 v37, v6
	v_mov_b32_e32 v46, v6
	v_mov_b32_e32 v47, v6
	v_mov_b32_e32 v48, v6
	v_mov_b32_e32 v49, v6
	v_mov_b32_e32 v50, v6
	v_mov_b32_e32 v51, v6
	v_mov_b32_e32 v52, v6
	v_mov_b32_e32 v53, v6
	v_mov_b32_e32 v62, v6
	v_mov_b32_e32 v63, v6
	v_mov_b32_e32 v64, v6
	v_mov_b32_e32 v65, v6
	v_mov_b32_e32 v66, v6
	v_mov_b32_e32 v67, v6
	v_mov_b32_e32 v68, v6
	v_mov_b32_e32 v69, v6
	v_mov_b32_e32 v70, v6
	v_mov_b32_e32 v71, v6
	v_mov_b32_e32 v72, v6
	v_mov_b32_e32 v73, v6
	v_mov_b32_e32 v74, v6
	v_mov_b32_e32 v75, v6
	v_mov_b32_e32 v76, v6
	v_mov_b32_e32 v77, v6
	v_mov_b32_e32 v86, v6
	v_mov_b32_e32 v87, v6
	v_mov_b32_e32 v88, v6
	v_mov_b32_e32 v89, v6
	v_mov_b32_e32 v90, v6
	v_mov_b32_e32 v91, v6
	v_mov_b32_e32 v92, v6
	v_mov_b32_e32 v93, v6
	v_mov_b32_e32 v102, v6
	v_mov_b32_e32 v103, v6
	v_mov_b32_e32 v104, v6
	v_mov_b32_e32 v105, v6
	v_mov_b32_e32 v106, v6
	v_mov_b32_e32 v107, v6
	v_mov_b32_e32 v108, v6
	v_mov_b32_e32 v109, v6
	v_mov_b32_e32 v118, v6
	v_mov_b32_e32 v119, v6
	v_mov_b32_e32 v120, v6
	v_mov_b32_e32 v121, v6
	v_mov_b32_e32 v122, v6
	v_mov_b32_e32 v123, v6
	v_mov_b32_e32 v124, v6
	v_mov_b32_e32 v125, v6
	v_mov_b32_e32 v78, v6
	v_mov_b32_e32 v79, v6
	v_mov_b32_e32 v80, v6
	v_mov_b32_e32 v81, v6
	v_mov_b32_e32 v82, v6
	v_mov_b32_e32 v83, v6
	v_mov_b32_e32 v84, v6
	v_mov_b32_e32 v85, v6
	v_mov_b32_e32 v94, v6
	v_mov_b32_e32 v95, v6
	v_mov_b32_e32 v96, v6
	v_mov_b32_e32 v97, v6
	v_mov_b32_e32 v98, v6
	v_mov_b32_e32 v99, v6
	v_mov_b32_e32 v100, v6
	v_mov_b32_e32 v101, v6
	v_mov_b32_e32 v110, v6
	v_mov_b32_e32 v111, v6
	v_mov_b32_e32 v112, v6
	v_mov_b32_e32 v113, v6
	v_mov_b32_e32 v114, v6
	v_mov_b32_e32 v115, v6
	v_mov_b32_e32 v116, v6
	v_mov_b32_e32 v117, v6
	v_mov_b32_e32 v126, v6
	v_mov_b32_e32 v127, v6
	v_mov_b32_e32 v128, v6
	v_mov_b32_e32 v129, v6
	v_mov_b32_e32 v130, v6
	v_mov_b32_e32 v131, v6
	v_mov_b32_e32 v132, v6
	v_mov_b32_e32 v133, v6
	s_cmp_eq_u32 s47, s10
	v_lshl_add_u64 v[198:199], v[136:137], 0, s[20:21]
	s_cselect_b64 vcc, -1, 0
	s_add_i32 s10, s10, 2
	v_cndmask_b32_e32 v215, v199, v175, vcc
	v_cndmask_b32_e32 v214, v198, v174, vcc
	v_cndmask_b32_e32 v237, v135, v177, vcc
	v_cndmask_b32_e32 v236, v134, v176, vcc
	.p2align	6
; #define PG8_STAGE(bufoff, gbase, voff) do { _Pragma("unroll") for (int _i = 0; _i < 2; ++_i) \
;         __builtin_amdgcn_global_load_lds((const unsigned*)((const char*)(gbase) + (voff)[_i]), (PG8_LAS unsigned*)(lds + (bufoff) + ldsw + _i * 8192), 16, 0, 0); } while (0)
; #define PG8_LDA(dst, b, h) do { _Pragma("unroll") for (int m = 0; m < 4; ++m) _Pragma("unroll") for (int k = 0; k < 2; ++k) dst[m][k] = *(const PG8_LAS bf16x8*)(lds + PG8_SA(b, h) + aoff + m * 2048 + k * 1024); } while (0)
; #define PG8_LDB(dst, b, h) do { _Pragma("unroll") for (int n = 0; n < 2; ++n) _Pragma("unroll") for (int k = 0; k < 2; ++k) dst[n][k] = *(const PG8_LAS bf16x8*)(lds + PG8_SB(b, h) + boff + n * 2048 + k * 1024); } while (0)
; #define PG8_MMA(ai, bj, At, Bt) do { __builtin_amdgcn_s_setprio(1); _Pragma("unroll") for (int m = 0; m < 4; ++m) _Pragma("unroll") for (int n = 0; n < 2; ++n) _Pragma("unroll") for (int k = 0; k < 2; ++k) \
;         acc[ai][bj][m][n] = __builtin_amdgcn_mfma_f32_16x16x32_bf16(Bt[n][k], At[m][k], acc[ai][bj][m][n], 0, 0, 0); __builtin_amdgcn_s_setprio(0); } while (0)
; #define PG8_WAIT_V(n) asm volatile("s_waitcnt vmcnt(" #n ")" ::: "memory")
; #define PG8_WAIT_L(n) asm volatile("s_waitcnt lgkmcnt(" #n ")" ::: "memory")
; #define PG8_BAR __builtin_amdgcn_s_barrier()
; #define PG8_SCHED __builtin_amdgcn_sched_barrier(0)
; template <class Epi, class Sched, bool ALIGN_EPI = false, bool SP2 = false>
; __device__ __forceinline__ void gemm_phase(PG8_LAS unsigned char* lds, const Gemm g, const Sched& S, const Epi& E) {
;     ...
;             PG8_LDB(B0, 0, 0); PG8_LDB(B1, 0, 1); PG8_SCHED; PG8_LDA(At, 0, 0); PG8_STAGE(PG8_SA(1, 1), a1 + hstep, voffA);
;             PG8_WAIT_V(8); PG8_WAIT_L(0); PG8_BAR; PG8_MMA(0, 0, At, B0); PG8_MMA(0, 1, At, B1); PG8_BAR; PG8_SCHED;
;             PG8_LDA(At, 0, 1); PG8_STAGE(PG8_SB(0, 0), b2, voffB); PG8_STAGE(PG8_SB(0, 1), b2 + hstep, voffB); PG8_STAGE(PG8_SA(0, 0), a2, voffA);
;             PG8_WAIT_V(8); PG8_WAIT_L(0); PG8_BAR; PG8_MMA(1, 0, At, B0); PG8_MMA(1, 1, At, B1); PG8_BAR; PG8_SCHED;
.LBB0_1947:
	v_add_u32_e32 v178, s53, v216
	v_add_u32_e32 v194, s54, v216
	ds_read_b128 v[138:141], v178
	ds_read_b128 v[142:145], v178 offset:1024
	ds_read_b128 v[146:149], v178 offset:2048
	ds_read_b128 v[178:181], v178 offset:3072
	ds_read_b128 v[182:185], v194
	ds_read_b128 v[186:189], v194 offset:1024
	ds_read_b128 v[190:193], v194 offset:2048
	ds_read_b128 v[194:197], v194 offset:3072
	v_lshl_add_u64 v[238:239], v[136:137], 0, v[168:169]
	s_add_i32 m0, s34, 0xc000
	ds_read_b128 v[198:201], v218
	ds_read_b128 v[202:205], v218 offset:1024
	ds_read_b128 v[206:209], v218 offset:2048
	ds_read_b128 v[210:213], v218 offset:3072
	ds_read_b128 v[220:223], v218 offset:4096
	ds_read_b128 v[224:227], v218 offset:5120
	ds_read_b128 v[228:231], v218 offset:6144
	ds_read_b128 v[232:235], v218 offset:7168
	global_load_lds_dwordx4 v[238:239], off
	s_add_i32 m0, s34, 0xe000
	v_lshl_add_u64 v[238:239], v[136:137], 0, v[166:167]
	global_load_lds_dwordx4 v[238:239], off
	s_waitcnt vmcnt(8) lgkmcnt(0)
	s_setprio 1
	s_barrier
	v_mfma_f32_16x16x32_bf16 v[130:133], v[138:141], v[198:201], v[130:133]
	v_mfma_f32_16x16x32_bf16 v[126:129], v[146:149], v[198:201], v[126:129]
	v_mfma_f32_16x16x32_bf16 v[114:117], v[138:141], v[206:209], v[114:117]
	v_mfma_f32_16x16x32_bf16 v[110:113], v[146:149], v[206:209], v[110:113]
	v_mfma_f32_16x16x32_bf16 v[98:101], v[138:141], v[220:223], v[98:101]
	v_mfma_f32_16x16x32_bf16 v[94:97], v[146:149], v[220:223], v[94:97]
	v_mfma_f32_16x16x32_bf16 v[82:85], v[138:141], v[228:231], v[82:85]
	v_mfma_f32_16x16x32_bf16 v[78:81], v[146:149], v[228:231], v[78:81]
	v_mfma_f32_16x16x32_bf16 v[130:133], v[142:145], v[202:205], v[130:133]
	v_mfma_f32_16x16x32_bf16 v[126:129], v[178:181], v[202:205], v[126:129]
	v_mfma_f32_16x16x32_bf16 v[114:117], v[142:145], v[210:213], v[114:117]
	v_mfma_f32_16x16x32_bf16 v[110:113], v[178:181], v[210:213], v[110:113]
	v_mfma_f32_16x16x32_bf16 v[98:101], v[142:145], v[224:227], v[98:101]
	v_mfma_f32_16x16x32_bf16 v[94:97], v[178:181], v[224:227], v[94:97]
	v_mfma_f32_16x16x32_bf16 v[82:85], v[142:145], v[232:235], v[82:85]
	v_mfma_f32_16x16x32_bf16 v[78:81], v[178:181], v[232:235], v[78:81]
	v_mfma_f32_16x16x32_bf16 v[122:125], v[182:185], v[198:201], v[122:125]
	v_mfma_f32_16x16x32_bf16 v[118:121], v[190:193], v[198:201], v[118:121]
	v_mfma_f32_16x16x32_bf16 v[106:109], v[182:185], v[206:209], v[106:109]
	v_mfma_f32_16x16x32_bf16 v[102:105], v[190:193], v[206:209], v[102:105]
	v_mfma_f32_16x16x32_bf16 v[90:93], v[182:185], v[220:223], v[90:93]
	v_mfma_f32_16x16x32_bf16 v[86:89], v[190:193], v[220:223], v[86:89]
	v_mfma_f32_16x16x32_bf16 v[74:77], v[182:185], v[228:231], v[74:77]
	v_mfma_f32_16x16x32_bf16 v[70:73], v[190:193], v[228:231], v[70:73]
	v_mfma_f32_16x16x32_bf16 v[122:125], v[186:189], v[202:205], v[122:125]
	v_mfma_f32_16x16x32_bf16 v[118:121], v[194:197], v[202:205], v[118:121]
	v_mfma_f32_16x16x32_bf16 v[106:109], v[186:189], v[210:213], v[106:109]
	v_mfma_f32_16x16x32_bf16 v[102:105], v[194:197], v[210:213], v[102:105]
	v_mfma_f32_16x16x32_bf16 v[90:93], v[186:189], v[224:227], v[90:93]
	v_mfma_f32_16x16x32_bf16 v[86:89], v[194:197], v[224:227], v[86:89]
	v_mfma_f32_16x16x32_bf16 v[74:77], v[186:189], v[232:235], v[74:77]
	v_mfma_f32_16x16x32_bf16 v[70:73], v[194:197], v[232:235], v[70:73]
	s_setprio 0
	s_barrier
	s_add_i32 s11, s53, s29
	v_lshl_add_u64 v[238:239], v[236:237], 0, v[158:159]
	s_mov_b32 m0, s11
	ds_read_b128 v[198:201], v218 offset:16384
	ds_read_b128 v[202:205], v218 offset:17408
	ds_read_b128 v[206:209], v218 offset:18432
	ds_read_b128 v[210:213], v218 offset:19456
	ds_read_b128 v[220:223], v218 offset:20480
	ds_read_b128 v[224:227], v218 offset:21504
	ds_read_b128 v[228:231], v218 offset:22528
	ds_read_b128 v[232:235], v218 offset:23552
	global_load_lds_dwordx4 v[238:239], off
	v_lshl_add_u64 v[240:241], v[236:237], 0, v[162:163]
	s_add_i32 m0, s11, 0x2000
	v_lshl_add_u64 v[236:237], v[236:237], 0, s[12:13]
	s_add_i32 s11, s54, s29
	global_load_lds_dwordx4 v[240:241], off
	v_lshl_add_u64 v[242:243], v[236:237], 0, v[158:159]
	s_mov_b32 m0, s11
	v_lshl_add_u64 v[236:237], v[236:237], 0, v[162:163]
	global_load_lds_dwordx4 v[242:243], off
	s_add_i32 m0, s11, 0x2000
	v_lshl_add_u64 v[244:245], v[214:215], 0, v[154:155]
	global_load_lds_dwordx4 v[236:237], off
	s_mov_b32 m0, s34
	v_lshl_add_u64 v[246:247], v[214:215], 0, v[160:161]
	global_load_lds_dwordx4 v[244:245], off
	s_mov_b32 m0, s35
	s_nop 0
	global_load_lds_dwordx4 v[246:247], off
	s_waitcnt vmcnt(8) lgkmcnt(0)
	s_setprio 1
	s_barrier
; #define PG8_STAGE(bufoff, gbase, voff) do { _Pragma("unroll") for (int _i = 0; _i < 2; ++_i) \
;         __builtin_amdgcn_global_load_lds((const unsigned*)((const char*)(gbase) + (voff)[_i]), (PG8_LAS unsigned*)(lds + (bufoff) + ldsw + _i * 8192), 16, 0, 0); } while (0)
; #define PG8_LDA(dst, b, h) do { _Pragma("unroll") for (int m = 0; m < 4; ++m) _Pragma("unroll") for (int k = 0; k < 2; ++k) dst[m][k] = *(const PG8_LAS bf16x8*)(lds + PG8_SA(b, h) + aoff + m * 2048 + k * 1024); } while (0)
; #define PG8_LDB(dst, b, h) do { _Pragma("unroll") for (int n = 0; n < 2; ++n) _Pragma("unroll") for (int k = 0; k < 2; ++k) dst[n][k] = *(const PG8_LAS bf16x8*)(lds + PG8_SB(b, h) + boff + n * 2048 + k * 1024); } while (0)
; #define PG8_MMA(ai, bj, At, Bt) do { __builtin_amdgcn_s_setprio(1); _Pragma("unroll") for (int m = 0; m < 4; ++m) _Pragma("unroll") for (int n = 0; n < 2; ++n) _Pragma("unroll") for (int k = 0; k < 2; ++k) \
;         acc[ai][bj][m][n] = __builtin_amdgcn_mfma_f32_16x16x32_bf16(Bt[n][k], At[m][k], acc[ai][bj][m][n], 0, 0, 0); __builtin_amdgcn_s_setprio(0); } while (0)
; #define PG8_WAIT_V(n) asm volatile("s_waitcnt vmcnt(" #n ")" ::: "memory")
; #define PG8_WAIT_L(n) asm volatile("s_waitcnt lgkmcnt(" #n ")" ::: "memory")
; #define PG8_BAR __builtin_amdgcn_s_barrier()
; #define PG8_SCHED __builtin_amdgcn_sched_barrier(0)
; template <class Epi, class Sched, bool ALIGN_EPI = false, bool SP2 = false>
; __device__ __forceinline__ void gemm_phase(PG8_LAS unsigned char* lds, const Gemm g, const Sched& S, const Epi& E) {
;     ...
;             PG8_WAIT_V(8); PG8_WAIT_L(0); PG8_BAR; PG8_MMA(1, 0, At, B0); PG8_MMA(1, 1, At, B1); PG8_BAR; PG8_SCHED;
;             PG8_LDB(B0, 1, 0); PG8_LDB(B1, 1, 1); PG8_SCHED; PG8_LDA(At, 1, 0); PG8_STAGE(PG8_SA(0, 1), a2 + hstep, voffA);
;             PG8_WAIT_V(8); PG8_WAIT_L(0); PG8_BAR; PG8_MMA(0, 0, At, B0); PG8_MMA(0, 1, At, B1); PG8_BAR; PG8_SCHED;
	v_mfma_f32_16x16x32_bf16 v[66:69], v[138:141], v[198:201], v[66:69]
	v_mfma_f32_16x16x32_bf16 v[62:65], v[146:149], v[198:201], v[62:65]
	v_mfma_f32_16x16x32_bf16 v[50:53], v[138:141], v[206:209], v[50:53]
	v_mfma_f32_16x16x32_bf16 v[46:49], v[146:149], v[206:209], v[46:49]
	v_mfma_f32_16x16x32_bf16 v[34:37], v[138:141], v[220:223], v[34:37]
	v_mfma_f32_16x16x32_bf16 v[30:33], v[146:149], v[220:223], v[30:33]
	v_mfma_f32_16x16x32_bf16 v[18:21], v[138:141], v[228:231], v[18:21]
	v_mfma_f32_16x16x32_bf16 v[14:17], v[146:149], v[228:231], v[14:17]
	v_mfma_f32_16x16x32_bf16 v[66:69], v[142:145], v[202:205], v[66:69]
	v_mfma_f32_16x16x32_bf16 v[62:65], v[178:181], v[202:205], v[62:65]
	v_mfma_f32_16x16x32_bf16 v[50:53], v[142:145], v[210:213], v[50:53]
	v_mfma_f32_16x16x32_bf16 v[46:49], v[178:181], v[210:213], v[46:49]
	v_mfma_f32_16x16x32_bf16 v[34:37], v[142:145], v[224:227], v[34:37]
	v_mfma_f32_16x16x32_bf16 v[30:33], v[178:181], v[224:227], v[30:33]
	v_mfma_f32_16x16x32_bf16 v[18:21], v[142:145], v[232:235], v[18:21]
	v_mfma_f32_16x16x32_bf16 v[14:17], v[178:181], v[232:235], v[14:17]
	v_mfma_f32_16x16x32_bf16 v[58:61], v[182:185], v[198:201], v[58:61]
	v_mfma_f32_16x16x32_bf16 v[54:57], v[190:193], v[198:201], v[54:57]
	v_mfma_f32_16x16x32_bf16 v[42:45], v[182:185], v[206:209], v[42:45]
	v_mfma_f32_16x16x32_bf16 v[38:41], v[190:193], v[206:209], v[38:41]
	v_mfma_f32_16x16x32_bf16 v[26:29], v[182:185], v[220:223], v[26:29]
	v_mfma_f32_16x16x32_bf16 v[22:25], v[190:193], v[220:223], v[22:25]
	v_mfma_f32_16x16x32_bf16 v[10:13], v[182:185], v[228:231], v[10:13]
	v_mfma_f32_16x16x32_bf16 v[6:9], v[190:193], v[228:231], v[6:9]
	v_mfma_f32_16x16x32_bf16 v[58:61], v[186:189], v[202:205], v[58:61]
	v_mfma_f32_16x16x32_bf16 v[54:57], v[194:197], v[202:205], v[54:57]
	v_mfma_f32_16x16x32_bf16 v[42:45], v[186:189], v[210:213], v[42:45]
	v_mfma_f32_16x16x32_bf16 v[38:41], v[194:197], v[210:213], v[38:41]
	v_mfma_f32_16x16x32_bf16 v[26:29], v[186:189], v[224:227], v[26:29]
	v_mfma_f32_16x16x32_bf16 v[22:25], v[194:197], v[224:227], v[22:25]
	v_mfma_f32_16x16x32_bf16 v[10:13], v[186:189], v[232:235], v[10:13]
	v_mfma_f32_16x16x32_bf16 v[6:9], v[194:197], v[232:235], v[6:9]
	s_setprio 0
	s_barrier
	s_add_i32 s11, 0, 0x18000
	s_add_i32 s31, 0, 0x1c000
	v_add_u32_e32 v178, s11, v216
	v_add_u32_e32 v194, s31, v216
	ds_read_b128 v[138:141], v178
	ds_read_b128 v[142:145], v178 offset:1024
	ds_read_b128 v[146:149], v178 offset:2048
	ds_read_b128 v[178:181], v178 offset:3072
	ds_read_b128 v[182:185], v194
	ds_read_b128 v[186:189], v194 offset:1024
	ds_read_b128 v[190:193], v194 offset:2048
	ds_read_b128 v[194:197], v194 offset:3072
	v_lshl_add_u64 v[214:215], v[214:215], 0, s[12:13]
	s_mov_b32 m0, s36
	v_lshl_add_u64 v[248:249], v[214:215], 0, v[154:155]
	ds_read_b128 v[198:201], v218 offset:32768
	ds_read_b128 v[202:205], v218 offset:33792
	ds_read_b128 v[206:209], v218 offset:34816
	ds_read_b128 v[210:213], v218 offset:35840
	ds_read_b128 v[220:223], v218 offset:36864
	ds_read_b128 v[224:227], v218 offset:37888
	ds_read_b128 v[228:231], v218 offset:38912
	ds_read_b128 v[232:235], v218 offset:39936
	global_load_lds_dwordx4 v[248:249], off
	s_mov_b32 m0, s37
	v_lshl_add_u64 v[214:215], v[214:215], 0, v[160:161]
	global_load_lds_dwordx4 v[214:215], off
	s_waitcnt vmcnt(8) lgkmcnt(0)
	s_setprio 1
	s_barrier
	v_mfma_f32_16x16x32_bf16 v[130:133], v[138:141], v[198:201], v[130:133]
	v_mfma_f32_16x16x32_bf16 v[126:129], v[146:149], v[198:201], v[126:129]
	v_mfma_f32_16x16x32_bf16 v[114:117], v[138:141], v[206:209], v[114:117]
	v_mfma_f32_16x16x32_bf16 v[110:113], v[146:149], v[206:209], v[110:113]
	v_mfma_f32_16x16x32_bf16 v[98:101], v[138:141], v[220:223], v[98:101]
	v_mfma_f32_16x16x32_bf16 v[94:97], v[146:149], v[220:223], v[94:97]
	v_mfma_f32_16x16x32_bf16 v[82:85], v[138:141], v[228:231], v[82:85]
	v_mfma_f32_16x16x32_bf16 v[78:81], v[146:149], v[228:231], v[78:81]
	v_mfma_f32_16x16x32_bf16 v[130:133], v[142:145], v[202:205], v[130:133]
	v_mfma_f32_16x16x32_bf16 v[126:129], v[178:181], v[202:205], v[126:129]
	v_mfma_f32_16x16x32_bf16 v[114:117], v[142:145], v[210:213], v[114:117]
	v_mfma_f32_16x16x32_bf16 v[110:113], v[178:181], v[210:213], v[110:113]
	v_mfma_f32_16x16x32_bf16 v[98:101], v[142:145], v[224:227], v[98:101]
	v_mfma_f32_16x16x32_bf16 v[94:97], v[178:181], v[224:227], v[94:97]
	v_mfma_f32_16x16x32_bf16 v[82:85], v[142:145], v[232:235], v[82:85]
	v_mfma_f32_16x16x32_bf16 v[78:81], v[178:181], v[232:235], v[78:81]
	v_mfma_f32_16x16x32_bf16 v[122:125], v[182:185], v[198:201], v[122:125]
	v_mfma_f32_16x16x32_bf16 v[118:121], v[190:193], v[198:201], v[118:121]
	v_mfma_f32_16x16x32_bf16 v[106:109], v[182:185], v[206:209], v[106:109]
	v_mfma_f32_16x16x32_bf16 v[102:105], v[190:193], v[206:209], v[102:105]
	v_mfma_f32_16x16x32_bf16 v[90:93], v[182:185], v[220:223], v[90:93]
	v_mfma_f32_16x16x32_bf16 v[86:89], v[190:193], v[220:223], v[86:89]
	v_mfma_f32_16x16x32_bf16 v[74:77], v[182:185], v[228:231], v[74:77]
	v_mfma_f32_16x16x32_bf16 v[70:73], v[190:193], v[228:231], v[70:73]
	v_mfma_f32_16x16x32_bf16 v[122:125], v[186:189], v[202:205], v[122:125]
	v_mfma_f32_16x16x32_bf16 v[118:121], v[194:197], v[202:205], v[118:121]
	v_mfma_f32_16x16x32_bf16 v[106:109], v[186:189], v[210:213], v[106:109]
	v_mfma_f32_16x16x32_bf16 v[102:105], v[194:197], v[210:213], v[102:105]
	v_mfma_f32_16x16x32_bf16 v[90:93], v[186:189], v[224:227], v[90:93]
	v_mfma_f32_16x16x32_bf16 v[86:89], v[194:197], v[224:227], v[86:89]
	v_mfma_f32_16x16x32_bf16 v[74:77], v[186:189], v[232:235], v[74:77]
	v_mfma_f32_16x16x32_bf16 v[70:73], v[194:197], v[232:235], v[70:73]
	s_setprio 0
	s_barrier
; #define PG8_STAGE(bufoff, gbase, voff) do { _Pragma("unroll") for (int _i = 0; _i < 2; ++_i) \
;         __builtin_amdgcn_global_load_lds((const unsigned*)((const char*)(gbase) + (voff)[_i]), (PG8_LAS unsigned*)(lds + (bufoff) + ldsw + _i * 8192), 16, 0, 0); } while (0)
; #define PG8_LDA(dst, b, h) do { _Pragma("unroll") for (int m = 0; m < 4; ++m) _Pragma("unroll") for (int k = 0; k < 2; ++k) dst[m][k] = *(const PG8_LAS bf16x8*)(lds + PG8_SA(b, h) + aoff + m * 2048 + k * 1024); } while (0)
; #define PG8_MMA(ai, bj, At, Bt) do { __builtin_amdgcn_s_setprio(1); _Pragma("unroll") for (int m = 0; m < 4; ++m) _Pragma("unroll") for (int n = 0; n < 2; ++n) _Pragma("unroll") for (int k = 0; k < 2; ++k) \
;         acc[ai][bj][m][n] = __builtin_amdgcn_mfma_f32_16x16x32_bf16(Bt[n][k], At[m][k], acc[ai][bj][m][n], 0, 0, 0); __builtin_amdgcn_s_setprio(0); } while (0)
; #define PG8_WAIT_V(n) asm volatile("s_waitcnt vmcnt(" #n ")" ::: "memory")
; #define PG8_WAIT_L(n) asm volatile("s_waitcnt lgkmcnt(" #n ")" ::: "memory")
; #define PG8_BAR __builtin_amdgcn_s_barrier()
; #define PG8_SCHED __builtin_amdgcn_sched_barrier(0)
; template <class Epi, class Sched, bool ALIGN_EPI = false, bool SP2 = false>
; __device__ __forceinline__ void gemm_phase(PG8_LAS unsigned char* lds, const Gemm g, const Sched& S, const Epi& E) {
;     ...
;         for (int t = 0; t < nt; t += 2) {
;             const bool last = (t == nt - 2);
;             const char* a1 = cA + (size_t)(t + 1) * kstep;
;             const char* a2 = last ? nA : cA + (size_t)(t + 2) * kstep; const char* b2 = last ? nB : cB + (size_t)(t + 2) * kstep;
;             const char* a3 = a2 + kstep; const char* b3 = b2 + kstep;
;     ...
;             PG8_LDA(At, 1, 1); PG8_STAGE(PG8_SB(1, 0), b3, voffB); PG8_STAGE(PG8_SB(1, 1), b3 + hstep, voffB); PG8_STAGE(PG8_SA(1, 0), a3, voffA);
;             PG8_WAIT_V(8); PG8_WAIT_L(0); PG8_BAR; PG8_MMA(1, 0, At, B0); PG8_MMA(1, 1, At, B1); PG8_BAR; PG8_SCHED;
	s_add_i32 s11, s11, s29
	s_add_i32 m0, s11, 0xffffff80
	ds_read_b128 v[198:201], v218 offset:49152
	ds_read_b128 v[202:205], v218 offset:50176
	ds_read_b128 v[206:209], v218 offset:51200
	ds_read_b128 v[210:213], v218 offset:52224
	global_load_lds_dwordx4 v[238:239], off offset:128
	s_add_i32 m0, s11, 0x1f80
	s_add_i32 s11, s31, s29
	global_load_lds_dwordx4 v[240:241], off offset:128
	s_add_i32 m0, s11, 0xffffff80
	ds_read_b128 v[232:235], v218 offset:56320
	global_load_lds_dwordx4 v[242:243], off offset:128
	s_add_i32 m0, s11, 0x1f80
	ds_read_b128 v[228:231], v218 offset:55296
	global_load_lds_dwordx4 v[236:237], off offset:128
	s_add_i32 m0, s41, 0xffffff80
	ds_read_b128 v[224:227], v218 offset:54272
	global_load_lds_dwordx4 v[244:245], off offset:128
	s_add_i32 m0, s44, 0xffffff80
	ds_read_b128 v[220:223], v218 offset:53248
	global_load_lds_dwordx4 v[246:247], off offset:128
	s_waitcnt vmcnt(8) lgkmcnt(0)
	s_setprio 1
	s_barrier
	v_mfma_f32_16x16x32_bf16 v[66:69], v[138:141], v[198:201], v[66:69]
	v_mfma_f32_16x16x32_bf16 v[62:65], v[146:149], v[198:201], v[62:65]
	v_mfma_f32_16x16x32_bf16 v[50:53], v[138:141], v[206:209], v[50:53]
	v_mfma_f32_16x16x32_bf16 v[46:49], v[146:149], v[206:209], v[46:49]
	v_mfma_f32_16x16x32_bf16 v[34:37], v[138:141], v[220:223], v[34:37]
	v_mfma_f32_16x16x32_bf16 v[30:33], v[146:149], v[220:223], v[30:33]
	v_mfma_f32_16x16x32_bf16 v[18:21], v[138:141], v[228:231], v[18:21]
	v_mfma_f32_16x16x32_bf16 v[14:17], v[146:149], v[228:231], v[14:17]
	v_mfma_f32_16x16x32_bf16 v[66:69], v[142:145], v[202:205], v[66:69]
	v_mfma_f32_16x16x32_bf16 v[62:65], v[178:181], v[202:205], v[62:65]
	v_mfma_f32_16x16x32_bf16 v[50:53], v[142:145], v[210:213], v[50:53]
	v_mfma_f32_16x16x32_bf16 v[46:49], v[178:181], v[210:213], v[46:49]
	v_mfma_f32_16x16x32_bf16 v[34:37], v[142:145], v[224:227], v[34:37]
	v_mfma_f32_16x16x32_bf16 v[30:33], v[178:181], v[224:227], v[30:33]
	v_mfma_f32_16x16x32_bf16 v[18:21], v[142:145], v[232:235], v[18:21]
	v_mfma_f32_16x16x32_bf16 v[14:17], v[178:181], v[232:235], v[14:17]
	v_mfma_f32_16x16x32_bf16 v[58:61], v[182:185], v[198:201], v[58:61]
	v_mfma_f32_16x16x32_bf16 v[54:57], v[190:193], v[198:201], v[54:57]
	v_mfma_f32_16x16x32_bf16 v[42:45], v[182:185], v[206:209], v[42:45]
	v_mfma_f32_16x16x32_bf16 v[38:41], v[190:193], v[206:209], v[38:41]
	v_mfma_f32_16x16x32_bf16 v[26:29], v[182:185], v[220:223], v[26:29]
	v_mfma_f32_16x16x32_bf16 v[22:25], v[190:193], v[220:223], v[22:25]
	v_mfma_f32_16x16x32_bf16 v[10:13], v[182:185], v[228:231], v[10:13]
	v_mfma_f32_16x16x32_bf16 v[6:9], v[190:193], v[228:231], v[6:9]
	v_mfma_f32_16x16x32_bf16 v[58:61], v[186:189], v[202:205], v[58:61]
	v_mfma_f32_16x16x32_bf16 v[54:57], v[194:197], v[202:205], v[54:57]
	v_mfma_f32_16x16x32_bf16 v[42:45], v[186:189], v[210:213], v[42:45]
	v_mfma_f32_16x16x32_bf16 v[38:41], v[194:197], v[210:213], v[38:41]
	v_mfma_f32_16x16x32_bf16 v[26:29], v[186:189], v[224:227], v[26:29]
	v_mfma_f32_16x16x32_bf16 v[22:25], v[194:197], v[224:227], v[22:25]
	v_mfma_f32_16x16x32_bf16 v[10:13], v[186:189], v[232:235], v[10:13]
	v_mfma_f32_16x16x32_bf16 v[6:9], v[194:197], v[232:235], v[6:9]
	v_lshl_add_u64 v[134:135], v[134:135], 0, s[26:27]
	v_lshl_add_u64 v[136:137], v[136:137], 0, s[26:27]
	s_cmp_ge_i32 s10, s46
	s_cbranch_scc1 .Lrot_exit_0
	s_cmp_eq_u32 s47, s10
	v_lshl_add_u64 v[198:199], v[136:137], 0, s[20:21]
	s_cselect_b64 vcc, -1, 0
	s_add_i32 s10, s10, 2
	v_cndmask_b32_e32 v215, v199, v175, vcc
	v_cndmask_b32_e32 v214, v198, v174, vcc
	v_cndmask_b32_e32 v237, v135, v177, vcc
	v_cndmask_b32_e32 v236, v134, v176, vcc
	s_setprio 0
	s_barrier
	s_branch .LBB0_1947
.Lrot_exit_0:
	s_setprio 0
	s_barrier
.LBB0_1948:
	s_and_b64 vcc, exec, s[24:25]
	s_cbranch_vccz .LBB0_1950
	s_barrier
